# weight-copy items: transposed LDS reads issued in 4 batches of 8 (next batch in flight while the previous is converted and stored), stacked on previous
# baseline (speedup 1.0000x reference)
.LBB0_33:
	s_waitcnt vmcnt(0)
	v_pk_mul_f32 v[2:3], v[2:3], v[10:11] op_sel_hi:[1,0]
	v_add_u32_e32 v6, 0x1450, v27
	s_mulk_i32 s2, 0xea00
	ds_write2_b32 v6, v2, v3 offset1:1
	v_pk_mul_f32 v[2:3], v[4:5], v[10:11] op_sel_hi:[1,0]
	v_add_u32_e32 v4, 0x1458, v27
	s_add_i32 s2, s38, s2
	ds_write2_b32 v4, v2, v3 offset1:1
	s_and_b32 s8, s28, 64
	s_and_b32 s2, s2, 0xffffff00
	s_waitcnt lgkmcnt(0)
	s_or_b32 s2, s2, s8
	v_or_b32_e32 v10, s2, v82
	v_add_u32_e32 v12, 0x400, v83
	ds_read2_b32 v[188:189], v83 offset1:65
	ds_read2_b32 v[190:191], v83 offset0:130 offset1:195
	ds_read2_b32 v[192:193], v12 offset0:4 offset1:69
	ds_read2_b32 v[194:195], v12 offset0:134 offset1:199
	ds_read2_b32 v[196:197], v83 offset0:8 offset1:73
	ds_read2_b32 v[198:199], v83 offset0:138 offset1:203
	ds_read2_b32 v[200:201], v12 offset0:12 offset1:77
	ds_read2_b32 v[202:203], v12 offset0:142 offset1:207
	v_ashrrev_i32_e32 v11, 31, v10
	s_waitcnt lgkmcnt(7)
	ds_read2_b32 v[204:205], v83 offset0:16 offset1:81
	ds_read2_b32 v[206:207], v83 offset0:146 offset1:211
	ds_read2_b32 v[208:209], v12 offset0:20 offset1:85
	ds_read2_b32 v[210:211], v12 offset0:150 offset1:215
	ds_read2_b32 v[212:213], v83 offset0:24 offset1:89
	ds_read2_b32 v[214:215], v83 offset0:154 offset1:219
	ds_read2_b32 v[216:217], v12 offset0:28 offset1:93
	ds_read2_b32 v[218:219], v12 offset0:158 offset1:223
	s_waitcnt lgkmcnt(8)
	v_cvt_pk_bf16_f32 v2, v188, v189
	v_lshl_add_u64 v[6:7], s[30:31], 1, v[72:73]
	v_lshlrev_b64 v[10:11], 11, v[10:11]
	v_cvt_pk_bf16_f32 v3, v190, v191
	v_lshl_add_u64 v[10:11], v[6:7], 0, v[10:11]
	v_cvt_pk_bf16_f32 v4, v192, v193
	v_cvt_pk_bf16_f32 v5, v194, v195
	global_store_dwordx4 v[10:11], v[2:5], off
	s_nop 1
	v_or_b32_e32 v10, s2, v88
	v_ashrrev_i32_e32 v11, 31, v10
	v_cvt_pk_bf16_f32 v2, v196, v197
	v_lshlrev_b64 v[10:11], 11, v[10:11]
	v_cvt_pk_bf16_f32 v3, v198, v199
	v_lshl_add_u64 v[10:11], v[6:7], 0, v[10:11]
	v_cvt_pk_bf16_f32 v4, v200, v201
	v_cvt_pk_bf16_f32 v5, v202, v203
	global_store_dwordx4 v[10:11], v[2:5], off
	s_nop 1
	v_or_b32_e32 v10, s2, v89
	v_ashrrev_i32_e32 v11, 31, v10
	s_waitcnt lgkmcnt(7)
	ds_read2_b32 v[188:189], v83 offset0:32 offset1:97
	ds_read2_b32 v[190:191], v83 offset0:162 offset1:227
	ds_read2_b32 v[192:193], v12 offset0:36 offset1:101
	ds_read2_b32 v[194:195], v12 offset0:166 offset1:231
	ds_read2_b32 v[196:197], v83 offset0:40 offset1:105
	ds_read2_b32 v[198:199], v83 offset0:170 offset1:235
	ds_read2_b32 v[200:201], v12 offset0:44 offset1:109
	ds_read2_b32 v[202:203], v12 offset0:174 offset1:239
	s_waitcnt lgkmcnt(8)
	v_cvt_pk_bf16_f32 v2, v204, v205
	v_lshlrev_b64 v[10:11], 11, v[10:11]
	v_cvt_pk_bf16_f32 v3, v206, v207
	v_lshl_add_u64 v[10:11], v[6:7], 0, v[10:11]
	v_cvt_pk_bf16_f32 v4, v208, v209
	v_cvt_pk_bf16_f32 v5, v210, v211
	global_store_dwordx4 v[10:11], v[2:5], off
	s_nop 1
	v_or_b32_e32 v10, s2, v90
	v_ashrrev_i32_e32 v11, 31, v10
	v_cvt_pk_bf16_f32 v2, v212, v213
	v_lshlrev_b64 v[10:11], 11, v[10:11]
	v_cvt_pk_bf16_f32 v3, v214, v215
	v_lshl_add_u64 v[10:11], v[6:7], 0, v[10:11]
	v_cvt_pk_bf16_f32 v4, v216, v217
	v_cvt_pk_bf16_f32 v5, v218, v219
	global_store_dwordx4 v[10:11], v[2:5], off
	s_nop 1
	v_or_b32_e32 v10, s2, v91
	v_ashrrev_i32_e32 v11, 31, v10
	s_waitcnt lgkmcnt(7)
	ds_read2_b32 v[204:205], v83 offset0:48 offset1:113
	ds_read2_b32 v[206:207], v83 offset0:178 offset1:243
	ds_read2_b32 v[208:209], v12 offset0:52 offset1:117
	ds_read2_b32 v[210:211], v12 offset0:182 offset1:247
	ds_read2_b32 v[212:213], v83 offset0:56 offset1:121
	ds_read2_b32 v[214:215], v83 offset0:186 offset1:251
	ds_read2_b32 v[216:217], v12 offset0:60 offset1:125
	ds_read2_b32 v[218:219], v12 offset0:190 offset1:255
	s_waitcnt lgkmcnt(8)
	v_cvt_pk_bf16_f32 v2, v188, v189
	v_lshlrev_b64 v[10:11], 11, v[10:11]
	v_cvt_pk_bf16_f32 v3, v190, v191
	v_lshl_add_u64 v[10:11], v[6:7], 0, v[10:11]
	v_cvt_pk_bf16_f32 v4, v192, v193
	v_cvt_pk_bf16_f32 v5, v194, v195
	global_store_dwordx4 v[10:11], v[2:5], off
	s_nop 1
	v_or_b32_e32 v10, s2, v92
	v_ashrrev_i32_e32 v11, 31, v10
	v_cvt_pk_bf16_f32 v2, v196, v197
	v_lshlrev_b64 v[10:11], 11, v[10:11]
	v_cvt_pk_bf16_f32 v3, v198, v199
	v_lshl_add_u64 v[10:11], v[6:7], 0, v[10:11]
	v_cvt_pk_bf16_f32 v4, v200, v201
	v_cvt_pk_bf16_f32 v5, v202, v203
	global_store_dwordx4 v[10:11], v[2:5], off
	s_nop 1
	v_or_b32_e32 v10, s2, v93
	v_ashrrev_i32_e32 v11, 31, v10
	s_waitcnt lgkmcnt(0)
	v_cvt_pk_bf16_f32 v2, v204, v205
	v_lshlrev_b64 v[10:11], 11, v[10:11]
	v_cvt_pk_bf16_f32 v3, v206, v207
	v_lshl_add_u64 v[10:11], v[6:7], 0, v[10:11]
	v_cvt_pk_bf16_f32 v4, v208, v209
	v_cvt_pk_bf16_f32 v5, v210, v211
	global_store_dwordx4 v[10:11], v[2:5], off
	s_nop 1
	v_or_b32_e32 v10, s2, v94
	v_ashrrev_i32_e32 v11, 31, v10
	v_cvt_pk_bf16_f32 v2, v212, v213
	v_lshlrev_b64 v[10:11], 11, v[10:11]
	v_cvt_pk_bf16_f32 v3, v214, v215
	v_lshl_add_u64 v[6:7], v[6:7], 0, v[10:11]
	v_cvt_pk_bf16_f32 v4, v216, v217
	v_cvt_pk_bf16_f32 v5, v218, v219
	global_store_dwordx4 v[6:7], v[2:5], off
	s_nop 1
	s_waitcnt lgkmcnt(0)

.LBB0_60:
	s_waitcnt vmcnt(0)
	v_pk_mul_f32 v[2:3], v[2:3], v[218:219] op_sel_hi:[1,0]
	v_add_u32_e32 v6, 0x1450, v19
	s_lshl_b32 s8, s30, 6
	ds_write2_b32 v6, v2, v3 offset1:1
	v_pk_mul_f32 v[2:3], v[4:5], v[218:219] op_sel_hi:[1,0]
	v_add_u32_e32 v4, 0x1458, v19
	s_and_b32 s8, 0xffff, s8
	ds_write2_b32 v4, v2, v3 offset1:1
	s_lshl_b32 s9, s8, 1
	s_waitcnt lgkmcnt(0)
	s_and_b32 s8, s8, 64
	s_and_b32 s9, s9, 0x1f00
	s_or_b32 s28, s8, s9
	v_add_u32_e32 v12, 0x400, v83
	ds_read2_b32 v[188:189], v83 offset1:65
	ds_read2_b32 v[190:191], v83 offset0:130 offset1:195
	ds_read2_b32 v[192:193], v12 offset0:4 offset1:69
	ds_read2_b32 v[194:195], v12 offset0:134 offset1:199
	ds_read2_b32 v[196:197], v83 offset0:8 offset1:73
	ds_read2_b32 v[198:199], v83 offset0:138 offset1:203
	ds_read2_b32 v[200:201], v12 offset0:12 offset1:77
	ds_read2_b32 v[202:203], v12 offset0:142 offset1:207
	s_bitset1_b32 s28, 7
	s_waitcnt lgkmcnt(7)
	ds_read2_b32 v[204:205], v83 offset0:16 offset1:81
	ds_read2_b32 v[206:207], v83 offset0:146 offset1:211
	ds_read2_b32 v[208:209], v12 offset0:20 offset1:85
	ds_read2_b32 v[210:211], v12 offset0:150 offset1:215
	ds_read2_b32 v[212:213], v83 offset0:24 offset1:89
	ds_read2_b32 v[214:215], v83 offset0:154 offset1:219
	ds_read2_b32 v[216:217], v12 offset0:28 offset1:93
	ds_read2_b32 v[218:219], v12 offset0:158 offset1:223
	s_waitcnt lgkmcnt(8)
	v_cvt_pk_bf16_f32 v2, v188, v189
	s_lshl_b32 s26, s2, 1
	v_or_b32_e32 v10, s28, v82
	v_cvt_pk_bf16_f32 v3, v190, v191
	v_lshl_add_u64 v[8:9], v[72:73], 0, s[26:27]
	v_lshlrev_b32_e32 v70, 11, v10
	v_cvt_pk_bf16_f32 v4, v192, v193
	v_cvt_pk_bf16_f32 v5, v194, v195
	v_lshl_add_u64 v[10:11], v[8:9], 0, v[70:71]
	global_store_dwordx4 v[10:11], v[2:5], off
	s_nop 1
	v_or_b32_e32 v10, s28, v88
	v_lshlrev_b32_e32 v70, 11, v10
	v_cvt_pk_bf16_f32 v2, v196, v197
	v_cvt_pk_bf16_f32 v3, v198, v199
	v_cvt_pk_bf16_f32 v4, v200, v201
	v_cvt_pk_bf16_f32 v5, v202, v203
	v_lshl_add_u64 v[10:11], v[8:9], 0, v[70:71]
	global_store_dwordx4 v[10:11], v[2:5], off
	s_nop 1
	v_or_b32_e32 v10, s28, v89
	v_lshlrev_b32_e32 v70, 11, v10
	s_waitcnt lgkmcnt(7)
	ds_read2_b32 v[188:189], v83 offset0:32 offset1:97
	ds_read2_b32 v[190:191], v83 offset0:162 offset1:227
	ds_read2_b32 v[192:193], v12 offset0:36 offset1:101
	ds_read2_b32 v[194:195], v12 offset0:166 offset1:231
	ds_read2_b32 v[196:197], v83 offset0:40 offset1:105
	ds_read2_b32 v[198:199], v83 offset0:170 offset1:235
	ds_read2_b32 v[200:201], v12 offset0:44 offset1:109
	ds_read2_b32 v[202:203], v12 offset0:174 offset1:239
	s_waitcnt lgkmcnt(8)
	v_cvt_pk_bf16_f32 v2, v204, v205
	v_cvt_pk_bf16_f32 v3, v206, v207
	v_cvt_pk_bf16_f32 v4, v208, v209
	v_cvt_pk_bf16_f32 v5, v210, v211
	v_lshl_add_u64 v[10:11], v[8:9], 0, v[70:71]
	global_store_dwordx4 v[10:11], v[2:5], off
	s_nop 1
	v_or_b32_e32 v10, s28, v90
	v_lshlrev_b32_e32 v70, 11, v10
	v_cvt_pk_bf16_f32 v2, v212, v213
	v_cvt_pk_bf16_f32 v3, v214, v215
	v_cvt_pk_bf16_f32 v4, v216, v217
	v_cvt_pk_bf16_f32 v5, v218, v219
	v_lshl_add_u64 v[10:11], v[8:9], 0, v[70:71]
	global_store_dwordx4 v[10:11], v[2:5], off
	s_nop 1
	v_or_b32_e32 v10, s28, v91
	v_lshlrev_b32_e32 v70, 11, v10
	s_waitcnt lgkmcnt(7)
	ds_read2_b32 v[204:205], v83 offset0:48 offset1:113
	ds_read2_b32 v[206:207], v83 offset0:178 offset1:243
	ds_read2_b32 v[208:209], v12 offset0:52 offset1:117
	ds_read2_b32 v[210:211], v12 offset0:182 offset1:247
	ds_read2_b32 v[212:213], v83 offset0:56 offset1:121
	ds_read2_b32 v[214:215], v83 offset0:186 offset1:251
	ds_read2_b32 v[216:217], v12 offset0:60 offset1:125
	ds_read2_b32 v[218:219], v12 offset0:190 offset1:255
	s_waitcnt lgkmcnt(8)
	v_cvt_pk_bf16_f32 v2, v188, v189
	v_cvt_pk_bf16_f32 v3, v190, v191
	v_cvt_pk_bf16_f32 v4, v192, v193
	v_cvt_pk_bf16_f32 v5, v194, v195
	v_lshl_add_u64 v[10:11], v[8:9], 0, v[70:71]
	global_store_dwordx4 v[10:11], v[2:5], off
	s_nop 1
	v_or_b32_e32 v10, s28, v92
	v_lshlrev_b32_e32 v70, 11, v10
	v_cvt_pk_bf16_f32 v2, v196, v197
	v_cvt_pk_bf16_f32 v3, v198, v199
	v_cvt_pk_bf16_f32 v4, v200, v201
	v_cvt_pk_bf16_f32 v5, v202, v203
	v_lshl_add_u64 v[10:11], v[8:9], 0, v[70:71]
	global_store_dwordx4 v[10:11], v[2:5], off
	s_nop 1
	v_or_b32_e32 v10, s28, v93
	v_lshlrev_b32_e32 v70, 11, v10
	s_waitcnt lgkmcnt(0)
	v_cvt_pk_bf16_f32 v2, v204, v205
	v_cvt_pk_bf16_f32 v3, v206, v207
	v_cvt_pk_bf16_f32 v4, v208, v209
	v_cvt_pk_bf16_f32 v5, v210, v211
	v_lshl_add_u64 v[10:11], v[8:9], 0, v[70:71]
	global_store_dwordx4 v[10:11], v[2:5], off
	s_nop 1
	s_nop 0
	v_cvt_pk_bf16_f32 v2, v212, v213
	v_cvt_pk_bf16_f32 v3, v214, v215
	v_cvt_pk_bf16_f32 v4, v216, v217
	v_or_b32_e32 v5, s28, v94
	v_lshlrev_b32_e32 v70, 11, v5
	v_cvt_pk_bf16_f32 v5, v218, v219
	v_lshl_add_u64 v[6:7], v[8:9], 0, v[70:71]
	global_store_dwordx4 v[6:7], v[2:5], off
	s_nop 1
	s_waitcnt lgkmcnt(0)
	s_mov_b64 s[28:29], 0

.LBB0_217:
	s_waitcnt vmcnt(0)
	v_pk_mul_f32 v[2:3], v[2:3], v[10:11] op_sel_hi:[1,0]
	v_add_u32_e32 v6, 0x1450, v27
	s_mulk_i32 s2, 0xea00
	ds_write2_b32 v6, v2, v3 offset1:1
	v_pk_mul_f32 v[2:3], v[4:5], v[10:11] op_sel_hi:[1,0]
	v_add_u32_e32 v4, 0x1458, v27
	s_add_i32 s1, s31, s2
	ds_write2_b32 v4, v2, v3 offset1:1
	s_and_b32 s0, s10, 64
	s_and_b32 s1, s1, 0xffffff00
	s_waitcnt lgkmcnt(0)
	s_or_b32 s0, s1, s0
	v_or_b32_e32 v10, s0, v83
	v_add_u32_e32 v12, 0x400, v84
	ds_read2_b32 v[188:189], v84 offset1:65
	ds_read2_b32 v[190:191], v84 offset0:130 offset1:195
	ds_read2_b32 v[192:193], v12 offset0:4 offset1:69
	ds_read2_b32 v[194:195], v12 offset0:134 offset1:199
	ds_read2_b32 v[196:197], v84 offset0:8 offset1:73
	ds_read2_b32 v[198:199], v84 offset0:138 offset1:203
	ds_read2_b32 v[200:201], v12 offset0:12 offset1:77
	ds_read2_b32 v[202:203], v12 offset0:142 offset1:207
	v_ashrrev_i32_e32 v11, 31, v10
	s_waitcnt lgkmcnt(7)
	ds_read2_b32 v[204:205], v84 offset0:16 offset1:81
	ds_read2_b32 v[206:207], v84 offset0:146 offset1:211
	ds_read2_b32 v[208:209], v12 offset0:20 offset1:85
	ds_read2_b32 v[210:211], v12 offset0:150 offset1:215
	ds_read2_b32 v[212:213], v84 offset0:24 offset1:89
	ds_read2_b32 v[214:215], v84 offset0:154 offset1:219
	ds_read2_b32 v[216:217], v12 offset0:28 offset1:93
	ds_read2_b32 v[218:219], v12 offset0:158 offset1:223
	s_waitcnt lgkmcnt(8)
	v_cvt_pk_bf16_f32 v2, v188, v189
	v_lshl_add_u64 v[6:7], s[24:25], 1, v[72:73]
	v_lshlrev_b64 v[10:11], 11, v[10:11]
	v_cvt_pk_bf16_f32 v3, v190, v191
	v_lshl_add_u64 v[10:11], v[6:7], 0, v[10:11]
	v_cvt_pk_bf16_f32 v4, v192, v193
	v_cvt_pk_bf16_f32 v5, v194, v195
	global_store_dwordx4 v[10:11], v[2:5], off
	s_nop 1
	v_or_b32_e32 v10, s0, v85
	v_ashrrev_i32_e32 v11, 31, v10
	v_cvt_pk_bf16_f32 v2, v196, v197
	v_lshlrev_b64 v[10:11], 11, v[10:11]
	v_cvt_pk_bf16_f32 v3, v198, v199
	v_lshl_add_u64 v[10:11], v[6:7], 0, v[10:11]
	v_cvt_pk_bf16_f32 v4, v200, v201
	v_cvt_pk_bf16_f32 v5, v202, v203
	global_store_dwordx4 v[10:11], v[2:5], off
	s_nop 1
	v_or_b32_e32 v10, s0, v86
	v_ashrrev_i32_e32 v11, 31, v10
	s_waitcnt lgkmcnt(7)
	ds_read2_b32 v[188:189], v84 offset0:32 offset1:97
	ds_read2_b32 v[190:191], v84 offset0:162 offset1:227
	ds_read2_b32 v[192:193], v12 offset0:36 offset1:101
	ds_read2_b32 v[194:195], v12 offset0:166 offset1:231
	ds_read2_b32 v[196:197], v84 offset0:40 offset1:105
	ds_read2_b32 v[198:199], v84 offset0:170 offset1:235
	ds_read2_b32 v[200:201], v12 offset0:44 offset1:109
	ds_read2_b32 v[202:203], v12 offset0:174 offset1:239
	s_waitcnt lgkmcnt(8)
	v_cvt_pk_bf16_f32 v2, v204, v205
	v_lshlrev_b64 v[10:11], 11, v[10:11]
	v_cvt_pk_bf16_f32 v3, v206, v207
	v_lshl_add_u64 v[10:11], v[6:7], 0, v[10:11]
	v_cvt_pk_bf16_f32 v4, v208, v209
	v_cvt_pk_bf16_f32 v5, v210, v211
	global_store_dwordx4 v[10:11], v[2:5], off
	s_nop 1
	v_or_b32_e32 v10, s0, v87
	v_ashrrev_i32_e32 v11, 31, v10
	v_cvt_pk_bf16_f32 v2, v212, v213
	v_lshlrev_b64 v[10:11], 11, v[10:11]
	v_cvt_pk_bf16_f32 v3, v214, v215
	v_lshl_add_u64 v[10:11], v[6:7], 0, v[10:11]
	v_cvt_pk_bf16_f32 v4, v216, v217
	v_cvt_pk_bf16_f32 v5, v218, v219
	global_store_dwordx4 v[10:11], v[2:5], off
	s_nop 1
	v_or_b32_e32 v10, s0, v88
	v_ashrrev_i32_e32 v11, 31, v10
	s_waitcnt lgkmcnt(7)
	ds_read2_b32 v[204:205], v84 offset0:48 offset1:113
	ds_read2_b32 v[206:207], v84 offset0:178 offset1:243
	ds_read2_b32 v[208:209], v12 offset0:52 offset1:117
	ds_read2_b32 v[210:211], v12 offset0:182 offset1:247
	ds_read2_b32 v[212:213], v84 offset0:56 offset1:121
	ds_read2_b32 v[214:215], v84 offset0:186 offset1:251
	ds_read2_b32 v[216:217], v12 offset0:60 offset1:125
	ds_read2_b32 v[218:219], v12 offset0:190 offset1:255
	s_waitcnt lgkmcnt(8)
	v_cvt_pk_bf16_f32 v2, v188, v189
	v_lshlrev_b64 v[10:11], 11, v[10:11]
	v_cvt_pk_bf16_f32 v3, v190, v191
	v_lshl_add_u64 v[10:11], v[6:7], 0, v[10:11]
	v_cvt_pk_bf16_f32 v4, v192, v193
	v_cvt_pk_bf16_f32 v5, v194, v195
	global_store_dwordx4 v[10:11], v[2:5], off
	s_nop 1
	v_or_b32_e32 v10, s0, v89
	v_ashrrev_i32_e32 v11, 31, v10
	v_cvt_pk_bf16_f32 v2, v196, v197
	v_lshlrev_b64 v[10:11], 11, v[10:11]
	v_cvt_pk_bf16_f32 v3, v198, v199
	v_lshl_add_u64 v[10:11], v[6:7], 0, v[10:11]
	v_cvt_pk_bf16_f32 v4, v200, v201
	v_cvt_pk_bf16_f32 v5, v202, v203
	global_store_dwordx4 v[10:11], v[2:5], off
	s_nop 1
	v_or_b32_e32 v10, s0, v90
	v_ashrrev_i32_e32 v11, 31, v10
	s_waitcnt lgkmcnt(0)
	v_cvt_pk_bf16_f32 v2, v204, v205
	v_lshlrev_b64 v[10:11], 11, v[10:11]
	v_cvt_pk_bf16_f32 v3, v206, v207
	v_lshl_add_u64 v[10:11], v[6:7], 0, v[10:11]
	v_cvt_pk_bf16_f32 v4, v208, v209
	v_cvt_pk_bf16_f32 v5, v210, v211
	global_store_dwordx4 v[10:11], v[2:5], off
	s_nop 1
	v_or_b32_e32 v10, s0, v91
	v_ashrrev_i32_e32 v11, 31, v10
	v_cvt_pk_bf16_f32 v2, v212, v213
	v_lshlrev_b64 v[10:11], 11, v[10:11]
	v_cvt_pk_bf16_f32 v3, v214, v215
	v_lshl_add_u64 v[6:7], v[6:7], 0, v[10:11]
	v_cvt_pk_bf16_f32 v4, v216, v217
	v_cvt_pk_bf16_f32 v5, v218, v219
	global_store_dwordx4 v[6:7], v[2:5], off
	s_nop 1
	s_waitcnt lgkmcnt(0)

.LBB0_219:
	s_cmpk_gt_i32 s28, 0x2bf
	s_mov_b64 s[0:1], -1
	s_cbranch_scc0 .LBB0_249
	s_cmpk_gt_u32 s28, 0x57f
	s_cbranch_scc0 .LBB0_222
	s_and_b32 s0, s35, 0x7fffffc0
	s_addk_i32 s0, 0xea00
	s_and_b32 s2, s29, 0x3c0
	v_or_b32_e32 v68, s0, v66
	s_lshl_b32 s4, s2, 2
	v_or_b32_e32 v4, 4, v68
	v_mov_b32_e32 v5, v69
	v_or_b32_e32 v10, 8, v68
	v_mov_b32_e32 v11, v69
	v_or_b32_e32 v12, 12, v68
	v_mov_b32_e32 v13, v69
	v_or_b32_e32 v18, 16, v68
	v_mov_b32_e32 v19, v69
	v_or_b32_e32 v20, 20, v68
	v_mov_b32_e32 v21, v69
	v_or_b32_e32 v26, 24, v68
	v_mov_b32_e32 v27, v69
	v_or_b32_e32 v28, 28, v68
	v_mov_b32_e32 v29, v69
	v_or_b32_e32 v34, 32, v68
	v_mov_b32_e32 v35, v69
	v_or_b32_e32 v36, 36, v68
	v_mov_b32_e32 v37, v69
	v_lshl_add_u64 v[62:63], v[74:75], 0, s[4:5]
	v_lshlrev_b64 v[2:3], 12, v[68:69]
	v_lshlrev_b64 v[4:5], 12, v[4:5]
	v_lshlrev_b64 v[10:11], 12, v[10:11]
	v_lshlrev_b64 v[12:13], 12, v[12:13]
	v_lshlrev_b64 v[18:19], 12, v[18:19]
	v_lshlrev_b64 v[20:21], 12, v[20:21]
	v_lshlrev_b64 v[26:27], 12, v[26:27]
	v_lshlrev_b64 v[28:29], 12, v[28:29]
	v_lshlrev_b64 v[34:35], 12, v[34:35]
	v_lshlrev_b64 v[36:37], 12, v[36:37]
	v_lshl_add_u64 v[2:3], v[62:63], 0, v[2:3]
	v_lshl_add_u64 v[6:7], v[62:63], 0, v[4:5]
	v_lshl_add_u64 v[10:11], v[62:63], 0, v[10:11]
	v_lshl_add_u64 v[14:15], v[62:63], 0, v[12:13]
	v_lshl_add_u64 v[18:19], v[62:63], 0, v[18:19]
	v_lshl_add_u64 v[22:23], v[62:63], 0, v[20:21]
	v_lshl_add_u64 v[26:27], v[62:63], 0, v[26:27]
	v_lshl_add_u64 v[30:31], v[62:63], 0, v[28:29]
	v_lshl_add_u64 v[34:35], v[62:63], 0, v[34:35]
	v_lshl_add_u64 v[38:39], v[62:63], 0, v[36:37]
	v_or_b32_e32 v42, 40, v68
	v_mov_b32_e32 v43, v69
	v_or_b32_e32 v44, 44, v68
	v_mov_b32_e32 v45, v69
	global_load_dwordx4 v[2:5], v[2:3], off nt
	s_nop 0
	global_load_dwordx4 v[6:9], v[6:7], off nt
	s_nop 0
	global_load_dwordx4 v[10:13], v[10:11], off nt
	s_nop 0
	global_load_dwordx4 v[14:17], v[14:15], off nt
	s_nop 0
	global_load_dwordx4 v[18:21], v[18:19], off nt
	s_nop 0
	global_load_dwordx4 v[22:25], v[22:23], off nt
	s_nop 0
	global_load_dwordx4 v[26:29], v[26:27], off nt
	s_nop 0
	global_load_dwordx4 v[30:33], v[30:31], off nt
	s_nop 0
	global_load_dwordx4 v[34:37], v[34:35], off nt
	s_nop 0
	global_load_dwordx4 v[38:41], v[38:39], off nt
	v_lshlrev_b64 v[42:43], 12, v[42:43]
	v_lshlrev_b64 v[44:45], 12, v[44:45]
	v_lshl_add_u64 v[42:43], v[62:63], 0, v[42:43]
	v_lshl_add_u64 v[46:47], v[62:63], 0, v[44:45]
	global_load_dwordx4 v[42:45], v[42:43], off nt
	s_nop 0
	global_load_dwordx4 v[46:49], v[46:47], off nt
	v_or_b32_e32 v50, 48, v68
	v_mov_b32_e32 v51, v69
	v_lshlrev_b64 v[50:51], 12, v[50:51]
	v_lshl_add_u64 v[50:51], v[62:63], 0, v[50:51]
	v_or_b32_e32 v54, 52, v68
	v_mov_b32_e32 v55, v69
	global_load_dwordx4 v[50:53], v[50:51], off nt
	v_lshlrev_b64 v[54:55], 12, v[54:55]
	v_lshl_add_u64 v[54:55], v[62:63], 0, v[54:55]
	v_or_b32_e32 v58, 56, v68
	v_mov_b32_e32 v59, v69
	global_load_dwordx4 v[54:57], v[54:55], off nt
	v_lshlrev_b64 v[58:59], 12, v[58:59]
	v_lshl_add_u64 v[58:59], v[62:63], 0, v[58:59]
	v_or_b32_e32 v68, 60, v68
	global_load_dwordx4 v[58:61], v[58:59], off nt
	v_lshlrev_b64 v[64:65], 12, v[68:69]
	v_lshl_add_u64 v[62:63], v[62:63], 0, v[64:65]
	global_load_dwordx4 v[62:65], v[62:63], off nt
	s_mov_b32 s1, s5
	s_waitcnt vmcnt(15)
	ds_write2_b32 v102, v2, v3 offset1:1
	ds_write2_b32 v102, v4, v5 offset0:2 offset1:3
	s_waitcnt vmcnt(14)
	ds_write2_b32 v103, v6, v7 offset1:1
	ds_write2_b32 v104, v8, v9 offset1:1
	s_waitcnt vmcnt(13)
	ds_write2_b32 v105, v10, v11 offset1:1
	ds_write2_b32 v106, v12, v13 offset1:1
	s_waitcnt vmcnt(12)
	ds_write2_b32 v107, v14, v15 offset1:1
	ds_write2_b32 v108, v16, v17 offset1:1
	s_waitcnt vmcnt(11)
	ds_write2_b32 v109, v18, v19 offset1:1
	ds_write2_b32 v110, v20, v21 offset1:1
	s_waitcnt vmcnt(10)
	ds_write2_b32 v111, v22, v23 offset1:1
	ds_write2_b32 v112, v24, v25 offset1:1
	s_waitcnt vmcnt(9)
	ds_write2_b32 v113, v26, v27 offset1:1
	ds_write2_b32 v114, v28, v29 offset1:1
	s_waitcnt vmcnt(8)
	ds_write2_b32 v115, v30, v31 offset1:1
	ds_write2_b32 v116, v32, v33 offset1:1
	s_waitcnt vmcnt(7)
	ds_write2_b32 v117, v34, v35 offset1:1
	ds_write2_b32 v118, v36, v37 offset1:1
	s_waitcnt vmcnt(6)
	ds_write2_b32 v119, v38, v39 offset1:1
	ds_write2_b32 v120, v40, v41 offset1:1
	v_add_u32_e32 v2, 0x28a0, v102
	v_or_b32_e32 v10, s2, v83
	v_mul_u32_u24_e32 v10, 0xb00, v10
	s_waitcnt vmcnt(5)
	ds_write2_b32 v2, v42, v43 offset1:1
	v_add_u32_e32 v2, 0x28a8, v102
	ds_write2_b32 v2, v44, v45 offset1:1
	v_add_u32_e32 v2, 0x2cb0, v102
	s_waitcnt vmcnt(4)
	ds_write2_b32 v2, v46, v47 offset1:1
	v_add_u32_e32 v2, 0x2cb8, v102
	ds_write2_b32 v2, v48, v49 offset1:1
	v_add_u32_e32 v2, 0x30c0, v102
	s_waitcnt vmcnt(3)
	ds_write2_b32 v2, v50, v51 offset1:1
	v_add_u32_e32 v2, 0x30c8, v102
	ds_write2_b32 v2, v52, v53 offset1:1
	v_add_u32_e32 v2, 0x34d0, v102
	v_add_u32_e32 v12, 0x400, v84
	s_waitcnt vmcnt(2)
	ds_write2_b32 v2, v54, v55 offset1:1
	v_add_u32_e32 v2, 0x34d8, v102
	ds_write2_b32 v2, v56, v57 offset1:1
	v_add_u32_e32 v2, 0x38e0, v102
	s_waitcnt vmcnt(1)
	ds_write2_b32 v2, v58, v59 offset1:1
	v_add_u32_e32 v2, 0x38e8, v102
	ds_write2_b32 v2, v60, v61 offset1:1
	v_add_u32_e32 v2, 0x3cf0, v102
	s_waitcnt vmcnt(0)
	ds_write2_b32 v2, v62, v63 offset1:1
	v_add_u32_e32 v2, 0x3cf8, v102
	ds_write2_b32 v2, v64, v65 offset1:1
	s_waitcnt lgkmcnt(0)
	ds_read2_b32 v[188:189], v84 offset1:65
	ds_read2_b32 v[190:191], v84 offset0:130 offset1:195
	ds_read2_b32 v[192:193], v12 offset0:4 offset1:69
	ds_read2_b32 v[194:195], v12 offset0:134 offset1:199
	ds_read2_b32 v[196:197], v84 offset0:8 offset1:73
	ds_read2_b32 v[198:199], v84 offset0:138 offset1:203
	ds_read2_b32 v[200:201], v12 offset0:12 offset1:77
	ds_read2_b32 v[202:203], v12 offset0:142 offset1:207
	s_waitcnt lgkmcnt(7)
	ds_read2_b32 v[204:205], v84 offset0:16 offset1:81
	ds_read2_b32 v[206:207], v84 offset0:146 offset1:211
	ds_read2_b32 v[208:209], v12 offset0:20 offset1:85
	ds_read2_b32 v[210:211], v12 offset0:150 offset1:215
	ds_read2_b32 v[212:213], v84 offset0:24 offset1:89
	ds_read2_b32 v[214:215], v84 offset0:154 offset1:219
	ds_read2_b32 v[216:217], v12 offset0:28 offset1:93
	ds_read2_b32 v[218:219], v12 offset0:158 offset1:223
	s_waitcnt lgkmcnt(8)
	v_cvt_pk_bf16_f32 v2, v188, v189
	v_lshl_add_u64 v[8:9], s[0:1], 1, v[70:71]
	v_lshlrev_b32_e32 v68, 1, v10
	v_cvt_pk_bf16_f32 v3, v190, v191
	v_lshl_add_u64 v[10:11], v[8:9], 0, v[68:69]
	v_cvt_pk_bf16_f32 v4, v192, v193
	v_cvt_pk_bf16_f32 v5, v194, v195
	global_store_dwordx4 v[10:11], v[2:5], off
	s_nop 1
	v_or_b32_e32 v10, s2, v85
	v_mul_u32_u24_e32 v10, 0xb00, v10
	v_cvt_pk_bf16_f32 v2, v196, v197
	v_lshlrev_b32_e32 v68, 1, v10
	v_cvt_pk_bf16_f32 v3, v198, v199
	v_lshl_add_u64 v[10:11], v[8:9], 0, v[68:69]
	v_cvt_pk_bf16_f32 v4, v200, v201
	v_cvt_pk_bf16_f32 v5, v202, v203
	global_store_dwordx4 v[10:11], v[2:5], off
	s_nop 1
	v_or_b32_e32 v10, s2, v86
	v_mul_u32_u24_e32 v10, 0xb00, v10
	s_waitcnt lgkmcnt(7)
	ds_read2_b32 v[188:189], v84 offset0:32 offset1:97
	ds_read2_b32 v[190:191], v84 offset0:162 offset1:227
	ds_read2_b32 v[192:193], v12 offset0:36 offset1:101
	ds_read2_b32 v[194:195], v12 offset0:166 offset1:231
	ds_read2_b32 v[196:197], v84 offset0:40 offset1:105
	ds_read2_b32 v[198:199], v84 offset0:170 offset1:235
	ds_read2_b32 v[200:201], v12 offset0:44 offset1:109
	ds_read2_b32 v[202:203], v12 offset0:174 offset1:239
	s_waitcnt lgkmcnt(8)
	v_cvt_pk_bf16_f32 v2, v204, v205
	v_lshlrev_b32_e32 v68, 1, v10
	v_cvt_pk_bf16_f32 v3, v206, v207
	v_lshl_add_u64 v[10:11], v[8:9], 0, v[68:69]
	v_cvt_pk_bf16_f32 v4, v208, v209
	v_cvt_pk_bf16_f32 v5, v210, v211
	global_store_dwordx4 v[10:11], v[2:5], off
	s_nop 1
	v_or_b32_e32 v10, s2, v87
	v_mul_u32_u24_e32 v10, 0xb00, v10
	v_cvt_pk_bf16_f32 v2, v212, v213
	v_lshlrev_b32_e32 v68, 1, v10
	v_cvt_pk_bf16_f32 v3, v214, v215
	v_lshl_add_u64 v[10:11], v[8:9], 0, v[68:69]
	v_cvt_pk_bf16_f32 v4, v216, v217
	v_cvt_pk_bf16_f32 v5, v218, v219
	global_store_dwordx4 v[10:11], v[2:5], off
	s_nop 1
	v_or_b32_e32 v10, s2, v88
	v_mul_u32_u24_e32 v10, 0xb00, v10
	s_waitcnt lgkmcnt(7)
	ds_read2_b32 v[204:205], v84 offset0:48 offset1:113
	ds_read2_b32 v[206:207], v84 offset0:178 offset1:243
	ds_read2_b32 v[208:209], v12 offset0:52 offset1:117
	ds_read2_b32 v[210:211], v12 offset0:182 offset1:247
	ds_read2_b32 v[212:213], v84 offset0:56 offset1:121
	ds_read2_b32 v[214:215], v84 offset0:186 offset1:251
	ds_read2_b32 v[216:217], v12 offset0:60 offset1:125
	ds_read2_b32 v[218:219], v12 offset0:190 offset1:255
	s_waitcnt lgkmcnt(8)
	v_cvt_pk_bf16_f32 v2, v188, v189
	v_lshlrev_b32_e32 v68, 1, v10
	v_cvt_pk_bf16_f32 v3, v190, v191
	v_lshl_add_u64 v[10:11], v[8:9], 0, v[68:69]
	v_cvt_pk_bf16_f32 v4, v192, v193
	v_cvt_pk_bf16_f32 v5, v194, v195
	global_store_dwordx4 v[10:11], v[2:5], off
	s_nop 1
	v_or_b32_e32 v10, s2, v89
	v_mul_u32_u24_e32 v10, 0xb00, v10
	v_cvt_pk_bf16_f32 v2, v196, v197
	v_lshlrev_b32_e32 v68, 1, v10
	v_cvt_pk_bf16_f32 v3, v198, v199
	v_lshl_add_u64 v[10:11], v[8:9], 0, v[68:69]
	v_cvt_pk_bf16_f32 v4, v200, v201
	v_cvt_pk_bf16_f32 v5, v202, v203
	global_store_dwordx4 v[10:11], v[2:5], off
	s_nop 1
	v_or_b32_e32 v10, s2, v90
	s_waitcnt lgkmcnt(0)
	v_cvt_pk_bf16_f32 v2, v204, v205
	v_mul_u32_u24_e32 v10, 0xb00, v10
	v_cvt_pk_bf16_f32 v3, v206, v207
	v_lshlrev_b32_e32 v68, 1, v10
	v_cvt_pk_bf16_f32 v4, v208, v209
	v_cvt_pk_bf16_f32 v5, v210, v211
	v_lshl_add_u64 v[10:11], v[8:9], 0, v[68:69]
	global_store_dwordx4 v[10:11], v[2:5], off
	s_nop 1
	s_mov_b64 s[0:1], 0
	v_cvt_pk_bf16_f32 v2, v212, v213
	v_cvt_pk_bf16_f32 v3, v214, v215
	v_cvt_pk_bf16_f32 v4, v216, v217
	v_or_b32_e32 v5, s2, v91
	v_mul_u32_u24_e32 v5, 0xb00, v5
	v_lshlrev_b32_e32 v68, 1, v5
	v_cvt_pk_bf16_f32 v5, v218, v219
	v_lshl_add_u64 v[6:7], v[8:9], 0, v[68:69]
	global_store_dwordx4 v[6:7], v[2:5], off
	s_nop 1
	s_waitcnt lgkmcnt(0)

.LBB0_247:
	s_waitcnt vmcnt(0)
	v_pk_mul_f32 v[2:3], v[2:3], v[10:11] op_sel_hi:[1,0]
	v_add_u32_e32 v6, 0x1450, v19
	s_lshl_b32 s0, s8, 6
	ds_write2_b32 v6, v2, v3 offset1:1
	v_pk_mul_f32 v[2:3], v[4:5], v[10:11] op_sel_hi:[1,0]
	v_add_u32_e32 v4, 0x1458, v19
	s_and_b32 s0, 0xffff, s0
	ds_write2_b32 v4, v2, v3 offset1:1
	s_lshl_b32 s1, s0, 1
	s_waitcnt lgkmcnt(0)
	s_and_b32 s0, s0, 64
	s_and_b32 s1, s1, 0x1f00
	s_or_b32 s0, s0, s1
	v_add_u32_e32 v12, 0x400, v84
	ds_read2_b32 v[188:189], v84 offset1:65
	ds_read2_b32 v[190:191], v84 offset0:130 offset1:195
	ds_read2_b32 v[192:193], v12 offset0:4 offset1:69
	ds_read2_b32 v[194:195], v12 offset0:134 offset1:199
	ds_read2_b32 v[196:197], v84 offset0:8 offset1:73
	ds_read2_b32 v[198:199], v84 offset0:138 offset1:203
	ds_read2_b32 v[200:201], v12 offset0:12 offset1:77
	ds_read2_b32 v[202:203], v12 offset0:142 offset1:207
	s_bitset1_b32 s0, 7
	s_waitcnt lgkmcnt(7)
	ds_read2_b32 v[204:205], v84 offset0:16 offset1:81
	ds_read2_b32 v[206:207], v84 offset0:146 offset1:211
	ds_read2_b32 v[208:209], v12 offset0:20 offset1:85
	ds_read2_b32 v[210:211], v12 offset0:150 offset1:215
	ds_read2_b32 v[212:213], v84 offset0:24 offset1:89
	ds_read2_b32 v[214:215], v84 offset0:154 offset1:219
	ds_read2_b32 v[216:217], v12 offset0:28 offset1:93
	ds_read2_b32 v[218:219], v12 offset0:158 offset1:223
	s_waitcnt lgkmcnt(8)
	v_cvt_pk_bf16_f32 v2, v188, v189
	s_lshl_b32 s4, s2, 1
	v_or_b32_e32 v10, s0, v83
	v_cvt_pk_bf16_f32 v3, v190, v191
	v_lshl_add_u64 v[8:9], v[72:73], 0, s[4:5]
	v_lshlrev_b32_e32 v68, 11, v10
	v_cvt_pk_bf16_f32 v4, v192, v193
	v_cvt_pk_bf16_f32 v5, v194, v195
	v_lshl_add_u64 v[10:11], v[8:9], 0, v[68:69]
	global_store_dwordx4 v[10:11], v[2:5], off
	s_nop 1
	v_or_b32_e32 v10, s0, v85
	v_lshlrev_b32_e32 v68, 11, v10
	v_cvt_pk_bf16_f32 v2, v196, v197
	v_cvt_pk_bf16_f32 v3, v198, v199
	v_cvt_pk_bf16_f32 v4, v200, v201
	v_cvt_pk_bf16_f32 v5, v202, v203
	v_lshl_add_u64 v[10:11], v[8:9], 0, v[68:69]
	global_store_dwordx4 v[10:11], v[2:5], off
	s_nop 1
	v_or_b32_e32 v10, s0, v86
	v_lshlrev_b32_e32 v68, 11, v10
	s_waitcnt lgkmcnt(7)
	ds_read2_b32 v[188:189], v84 offset0:32 offset1:97
	ds_read2_b32 v[190:191], v84 offset0:162 offset1:227
	ds_read2_b32 v[192:193], v12 offset0:36 offset1:101
	ds_read2_b32 v[194:195], v12 offset0:166 offset1:231
	ds_read2_b32 v[196:197], v84 offset0:40 offset1:105
	ds_read2_b32 v[198:199], v84 offset0:170 offset1:235
	ds_read2_b32 v[200:201], v12 offset0:44 offset1:109
	ds_read2_b32 v[202:203], v12 offset0:174 offset1:239
	s_waitcnt lgkmcnt(8)
	v_cvt_pk_bf16_f32 v2, v204, v205
	v_cvt_pk_bf16_f32 v3, v206, v207
	v_cvt_pk_bf16_f32 v4, v208, v209
	v_cvt_pk_bf16_f32 v5, v210, v211
	v_lshl_add_u64 v[10:11], v[8:9], 0, v[68:69]
	global_store_dwordx4 v[10:11], v[2:5], off
	s_nop 1
	v_or_b32_e32 v10, s0, v87
	v_lshlrev_b32_e32 v68, 11, v10
	v_cvt_pk_bf16_f32 v2, v212, v213
	v_cvt_pk_bf16_f32 v3, v214, v215
	v_cvt_pk_bf16_f32 v4, v216, v217
	v_cvt_pk_bf16_f32 v5, v218, v219
	v_lshl_add_u64 v[10:11], v[8:9], 0, v[68:69]
	global_store_dwordx4 v[10:11], v[2:5], off
	s_nop 1
	v_or_b32_e32 v10, s0, v88
	v_lshlrev_b32_e32 v68, 11, v10
	s_waitcnt lgkmcnt(7)
	ds_read2_b32 v[204:205], v84 offset0:48 offset1:113
	ds_read2_b32 v[206:207], v84 offset0:178 offset1:243
	ds_read2_b32 v[208:209], v12 offset0:52 offset1:117
	ds_read2_b32 v[210:211], v12 offset0:182 offset1:247
	ds_read2_b32 v[212:213], v84 offset0:56 offset1:121
	ds_read2_b32 v[214:215], v84 offset0:186 offset1:251
	ds_read2_b32 v[216:217], v12 offset0:60 offset1:125
	ds_read2_b32 v[218:219], v12 offset0:190 offset1:255
	s_waitcnt lgkmcnt(8)
	v_cvt_pk_bf16_f32 v2, v188, v189
	v_cvt_pk_bf16_f32 v3, v190, v191
	v_cvt_pk_bf16_f32 v4, v192, v193
	v_cvt_pk_bf16_f32 v5, v194, v195
	v_lshl_add_u64 v[10:11], v[8:9], 0, v[68:69]
	global_store_dwordx4 v[10:11], v[2:5], off
	s_nop 1
	v_or_b32_e32 v10, s0, v89
	v_lshlrev_b32_e32 v68, 11, v10
	v_cvt_pk_bf16_f32 v2, v196, v197
	v_cvt_pk_bf16_f32 v3, v198, v199
	v_cvt_pk_bf16_f32 v4, v200, v201
	v_cvt_pk_bf16_f32 v5, v202, v203
	v_lshl_add_u64 v[10:11], v[8:9], 0, v[68:69]
	global_store_dwordx4 v[10:11], v[2:5], off
	s_nop 1
	v_or_b32_e32 v10, s0, v90
	v_lshlrev_b32_e32 v68, 11, v10
	s_waitcnt lgkmcnt(0)
	v_cvt_pk_bf16_f32 v2, v204, v205
	v_cvt_pk_bf16_f32 v3, v206, v207
	v_cvt_pk_bf16_f32 v4, v208, v209
	v_cvt_pk_bf16_f32 v5, v210, v211
	v_lshl_add_u64 v[10:11], v[8:9], 0, v[68:69]
	global_store_dwordx4 v[10:11], v[2:5], off
	s_nop 1
	s_nop 0
	v_cvt_pk_bf16_f32 v2, v212, v213
	v_cvt_pk_bf16_f32 v3, v214, v215
	v_cvt_pk_bf16_f32 v4, v216, v217
	v_or_b32_e32 v5, s0, v91
	v_lshlrev_b32_e32 v68, 11, v5
	v_cvt_pk_bf16_f32 v5, v218, v219
	v_lshl_add_u64 v[6:7], v[8:9], 0, v[68:69]
	global_store_dwordx4 v[6:7], v[2:5], off
	s_nop 1
	s_waitcnt lgkmcnt(0)

.LBB0_438:
	s_waitcnt vmcnt(0)
	v_pk_mul_f32 v[2:3], v[2:3], v[10:11] op_sel_hi:[1,0]
	v_add_u32_e32 v6, 0x1040, v19
	ds_write2_b32 v6, v2, v3 offset1:1
	v_pk_mul_f32 v[2:3], v[4:5], v[10:11] op_sel_hi:[1,0]
	v_add_u32_e32 v4, 0x1048, v19
	ds_write2_b32 v4, v2, v3 offset1:1
	s_waitcnt lgkmcnt(0)
	s_mulk_i32 s3, 0xea00
	v_add_u32_e32 v10, 0x400, v111
	ds_read2_b32 v[188:189], v111 offset1:65
	ds_read2_b32 v[190:191], v111 offset0:130 offset1:195
	ds_read2_b32 v[192:193], v10 offset0:4 offset1:69
	ds_read2_b32 v[194:195], v10 offset0:134 offset1:199
	ds_read2_b32 v[196:197], v111 offset0:8 offset1:73
	ds_read2_b32 v[198:199], v111 offset0:138 offset1:203
	ds_read2_b32 v[200:201], v10 offset0:12 offset1:77
	ds_read2_b32 v[202:203], v10 offset0:142 offset1:207
	s_add_i32 s0, s35, s3
	s_waitcnt lgkmcnt(7)
	ds_read2_b32 v[204:205], v111 offset0:16 offset1:81
	ds_read2_b32 v[206:207], v111 offset0:146 offset1:211
	ds_read2_b32 v[208:209], v10 offset0:20 offset1:85
	ds_read2_b32 v[210:211], v10 offset0:150 offset1:215
	ds_read2_b32 v[212:213], v111 offset0:24 offset1:89
	ds_read2_b32 v[214:215], v111 offset0:154 offset1:219
	ds_read2_b32 v[216:217], v10 offset0:28 offset1:93
	ds_read2_b32 v[218:219], v10 offset0:158 offset1:223
	s_waitcnt lgkmcnt(8)
	v_cvt_pk_bf16_f32 v4, v188, v189
	s_and_b32 s0, s0, 0xffffff00
	s_and_b32 s1, s24, 64
	v_cvt_pk_bf16_f32 v5, v190, v191
	s_or_b32 s0, s0, s1
	v_cvt_pk_bf16_f32 v6, v192, v193
	v_cvt_pk_bf16_f32 v7, v194, v195
	v_or_b32_e32 v8, s0, v110
	v_ashrrev_i32_e32 v9, 31, v8
	v_lshl_add_u64 v[2:3], s[10:11], 1, v[84:85]
	v_lshlrev_b64 v[8:9], 11, v[8:9]
	v_lshl_add_u64 v[8:9], v[2:3], 0, v[8:9]
	global_store_dwordx4 v[8:9], v[4:7], off
	s_nop 1
	v_cvt_pk_bf16_f32 v4, v196, v197
	v_cvt_pk_bf16_f32 v5, v198, v199
	v_cvt_pk_bf16_f32 v6, v200, v201
	v_cvt_pk_bf16_f32 v7, v202, v203
	v_or_b32_e32 v8, s0, v112
	v_ashrrev_i32_e32 v9, 31, v8
	v_lshlrev_b64 v[8:9], 11, v[8:9]
	v_lshl_add_u64 v[8:9], v[2:3], 0, v[8:9]
	global_store_dwordx4 v[8:9], v[4:7], off
	s_nop 1
	s_waitcnt lgkmcnt(7)
	ds_read2_b32 v[188:189], v111 offset0:32 offset1:97
	ds_read2_b32 v[190:191], v111 offset0:162 offset1:227
	ds_read2_b32 v[192:193], v10 offset0:36 offset1:101
	ds_read2_b32 v[194:195], v10 offset0:166 offset1:231
	ds_read2_b32 v[196:197], v111 offset0:40 offset1:105
	ds_read2_b32 v[198:199], v111 offset0:170 offset1:235
	ds_read2_b32 v[200:201], v10 offset0:44 offset1:109
	ds_read2_b32 v[202:203], v10 offset0:174 offset1:239
	s_waitcnt lgkmcnt(8)
	v_cvt_pk_bf16_f32 v4, v204, v205
	v_cvt_pk_bf16_f32 v5, v206, v207
	v_cvt_pk_bf16_f32 v6, v208, v209
	v_cvt_pk_bf16_f32 v7, v210, v211
	v_or_b32_e32 v8, s0, v113
	v_ashrrev_i32_e32 v9, 31, v8
	v_lshlrev_b64 v[8:9], 11, v[8:9]
	v_lshl_add_u64 v[8:9], v[2:3], 0, v[8:9]
	global_store_dwordx4 v[8:9], v[4:7], off
	s_nop 1
	v_cvt_pk_bf16_f32 v4, v212, v213
	v_cvt_pk_bf16_f32 v5, v214, v215
	v_cvt_pk_bf16_f32 v6, v216, v217
	v_cvt_pk_bf16_f32 v7, v218, v219
	v_or_b32_e32 v8, s0, v114
	v_ashrrev_i32_e32 v9, 31, v8
	v_lshlrev_b64 v[8:9], 11, v[8:9]
	v_lshl_add_u64 v[8:9], v[2:3], 0, v[8:9]
	global_store_dwordx4 v[8:9], v[4:7], off
	s_nop 1
	s_waitcnt lgkmcnt(7)
	ds_read2_b32 v[204:205], v111 offset0:48 offset1:113
	ds_read2_b32 v[206:207], v111 offset0:178 offset1:243
	ds_read2_b32 v[208:209], v10 offset0:52 offset1:117
	ds_read2_b32 v[210:211], v10 offset0:182 offset1:247
	ds_read2_b32 v[212:213], v111 offset0:56 offset1:121
	ds_read2_b32 v[214:215], v111 offset0:186 offset1:251
	ds_read2_b32 v[216:217], v10 offset0:60 offset1:125
	ds_read2_b32 v[218:219], v10 offset0:190 offset1:255
	s_waitcnt lgkmcnt(8)
	v_cvt_pk_bf16_f32 v4, v188, v189
	v_cvt_pk_bf16_f32 v5, v190, v191
	v_cvt_pk_bf16_f32 v6, v192, v193
	v_cvt_pk_bf16_f32 v7, v194, v195
	v_or_b32_e32 v8, s0, v115
	v_ashrrev_i32_e32 v9, 31, v8
	v_lshlrev_b64 v[8:9], 11, v[8:9]
	v_lshl_add_u64 v[8:9], v[2:3], 0, v[8:9]
	global_store_dwordx4 v[8:9], v[4:7], off
	s_nop 1
	v_cvt_pk_bf16_f32 v4, v196, v197
	v_cvt_pk_bf16_f32 v5, v198, v199
	v_cvt_pk_bf16_f32 v6, v200, v201
	v_cvt_pk_bf16_f32 v7, v202, v203
	v_or_b32_e32 v8, s0, v116
	v_ashrrev_i32_e32 v9, 31, v8
	v_lshlrev_b64 v[8:9], 11, v[8:9]
	v_lshl_add_u64 v[8:9], v[2:3], 0, v[8:9]
	global_store_dwordx4 v[8:9], v[4:7], off
	s_nop 1
	s_waitcnt lgkmcnt(0)
	v_cvt_pk_bf16_f32 v4, v204, v205
	v_cvt_pk_bf16_f32 v5, v206, v207
	v_cvt_pk_bf16_f32 v6, v208, v209
	v_cvt_pk_bf16_f32 v7, v210, v211
	v_or_b32_e32 v8, s0, v117
	v_ashrrev_i32_e32 v9, 31, v8
	v_lshlrev_b64 v[8:9], 11, v[8:9]
	v_lshl_add_u64 v[8:9], v[2:3], 0, v[8:9]
	global_store_dwordx4 v[8:9], v[4:7], off
	s_nop 1
	v_cvt_pk_bf16_f32 v4, v212, v213
	v_cvt_pk_bf16_f32 v5, v214, v215
	v_cvt_pk_bf16_f32 v6, v216, v217
	v_cvt_pk_bf16_f32 v7, v218, v219
	v_or_b32_e32 v8, s0, v118
	v_ashrrev_i32_e32 v9, 31, v8
	v_lshlrev_b64 v[8:9], 11, v[8:9]
	v_lshl_add_u64 v[2:3], v[2:3], 0, v[8:9]
	global_store_dwordx4 v[2:3], v[4:7], off
	s_nop 1
	s_waitcnt lgkmcnt(0)

.LBB0_440:
	s_cmpk_gt_i32 s29, 0x83f
	s_mov_b64 s[0:1], -1
	s_cbranch_scc0 .LBB0_545
	s_cmpk_gt_u32 s29, 0x107f
	s_cbranch_scc0 .LBB0_487
	s_cmpk_gt_u32 s29, 0x167f
	s_cbranch_scc0 .LBB0_456
	s_cmpk_gt_u32 s29, 0x177f
	s_cbranch_scc0 .LBB0_453
	s_cmpk_gt_u32 s29, 0x197f
	s_cbranch_scc0 .LBB0_446
	s_and_b32 s0, s39, 0x7fffffc0
	s_addk_i32 s0, 0x9a00
	s_and_b32 s2, s31, 0x3c0
	v_or_b32_e32 v68, s0, v66
	s_lshl_b32 s12, s2, 2
	v_or_b32_e32 v4, 4, v68
	v_mov_b32_e32 v5, v69
	v_lshl_add_u64 v[62:63], v[86:87], 0, s[12:13]
	v_lshlrev_b64 v[2:3], 12, v[68:69]
	v_lshlrev_b64 v[4:5], 12, v[4:5]
	v_lshl_add_u64 v[2:3], v[62:63], 0, v[2:3]
	s_waitcnt vmcnt(0)
	v_lshl_add_u64 v[6:7], v[62:63], 0, v[4:5]
	global_load_dwordx4 v[2:5], v[2:3], off nt
	s_nop 0
	global_load_dwordx4 v[6:9], v[6:7], off nt
	v_or_b32_e32 v10, 8, v68
	v_mov_b32_e32 v11, v69
	v_or_b32_e32 v12, 12, v68
	v_mov_b32_e32 v13, v69
	v_lshlrev_b64 v[10:11], 12, v[10:11]
	v_lshlrev_b64 v[12:13], 12, v[12:13]
	v_lshl_add_u64 v[10:11], v[62:63], 0, v[10:11]
	v_lshl_add_u64 v[14:15], v[62:63], 0, v[12:13]
	global_load_dwordx4 v[10:13], v[10:11], off nt
	s_nop 0
	global_load_dwordx4 v[14:17], v[14:15], off nt
	v_or_b32_e32 v18, 16, v68
	v_mov_b32_e32 v19, v69
	v_or_b32_e32 v20, 20, v68
	v_mov_b32_e32 v21, v69
	v_lshlrev_b64 v[18:19], 12, v[18:19]
	v_lshlrev_b64 v[20:21], 12, v[20:21]
	v_lshl_add_u64 v[18:19], v[62:63], 0, v[18:19]
	v_lshl_add_u64 v[22:23], v[62:63], 0, v[20:21]
	global_load_dwordx4 v[18:21], v[18:19], off nt
	s_nop 0
	global_load_dwordx4 v[22:25], v[22:23], off nt
	v_or_b32_e32 v26, 24, v68
	v_mov_b32_e32 v27, v69
	v_or_b32_e32 v28, 28, v68
	v_mov_b32_e32 v29, v69
	v_lshlrev_b64 v[26:27], 12, v[26:27]
	v_lshlrev_b64 v[28:29], 12, v[28:29]
	v_lshl_add_u64 v[26:27], v[62:63], 0, v[26:27]
	v_lshl_add_u64 v[30:31], v[62:63], 0, v[28:29]
	global_load_dwordx4 v[26:29], v[26:27], off nt
	s_nop 0
	global_load_dwordx4 v[30:33], v[30:31], off nt
	v_or_b32_e32 v34, 32, v68
	v_mov_b32_e32 v35, v69
	v_or_b32_e32 v36, 36, v68
	v_mov_b32_e32 v37, v69
	v_lshlrev_b64 v[34:35], 12, v[34:35]
	v_lshlrev_b64 v[36:37], 12, v[36:37]
	v_lshl_add_u64 v[34:35], v[62:63], 0, v[34:35]
	v_lshl_add_u64 v[38:39], v[62:63], 0, v[36:37]
	global_load_dwordx4 v[34:37], v[34:35], off nt
	s_nop 0
	global_load_dwordx4 v[38:41], v[38:39], off nt
	v_or_b32_e32 v42, 40, v68
	v_mov_b32_e32 v43, v69
	v_or_b32_e32 v44, 44, v68
	v_mov_b32_e32 v45, v69
	v_lshlrev_b64 v[42:43], 12, v[42:43]
	v_lshlrev_b64 v[44:45], 12, v[44:45]
	v_lshl_add_u64 v[42:43], v[62:63], 0, v[42:43]
	v_lshl_add_u64 v[46:47], v[62:63], 0, v[44:45]
	global_load_dwordx4 v[42:45], v[42:43], off nt
	s_nop 0
	global_load_dwordx4 v[46:49], v[46:47], off nt
	v_or_b32_e32 v50, 48, v68
	v_mov_b32_e32 v51, v69
	v_lshlrev_b64 v[50:51], 12, v[50:51]
	v_lshl_add_u64 v[50:51], v[62:63], 0, v[50:51]
	v_or_b32_e32 v54, 52, v68
	v_mov_b32_e32 v55, v69
	global_load_dwordx4 v[50:53], v[50:51], off nt
	v_lshlrev_b64 v[54:55], 12, v[54:55]
	v_lshl_add_u64 v[54:55], v[62:63], 0, v[54:55]
	v_or_b32_e32 v58, 56, v68
	v_mov_b32_e32 v59, v69
	global_load_dwordx4 v[54:57], v[54:55], off nt
	v_lshlrev_b64 v[58:59], 12, v[58:59]
	v_lshl_add_u64 v[58:59], v[62:63], 0, v[58:59]
	v_or_b32_e32 v68, 60, v68
	global_load_dwordx4 v[58:61], v[58:59], off nt
	v_lshlrev_b64 v[64:65], 12, v[68:69]
	v_lshl_add_u64 v[62:63], v[62:63], 0, v[64:65]
	global_load_dwordx4 v[62:65], v[62:63], off nt
	v_add_u32_e32 v68, 0x410, v109
	s_mov_b32 s1, s13
	s_waitcnt vmcnt(15)
	ds_write2_b32 v109, v2, v3 offset1:1
	ds_write2_b32 v109, v4, v5 offset0:2 offset1:3
	s_waitcnt vmcnt(14)
	ds_write2_b32 v68, v6, v7 offset1:1
	v_add_u32_e32 v2, 0x418, v109
	ds_write2_b32 v2, v8, v9 offset1:1
	v_add_u32_e32 v2, 0x820, v109
	v_lshl_add_u64 v[8:9], s[0:1], 1, v[70:71]
	s_mov_b64 s[0:1], 0
	s_waitcnt vmcnt(13)
	ds_write2_b32 v2, v10, v11 offset1:1
	v_add_u32_e32 v2, 0x828, v109
	ds_write2_b32 v2, v12, v13 offset1:1
	v_add_u32_e32 v2, 0xc30, v109
	s_waitcnt vmcnt(12)
	ds_write2_b32 v2, v14, v15 offset1:1
	v_add_u32_e32 v2, 0xc38, v109
	ds_write2_b32 v2, v16, v17 offset1:1
	v_add_u32_e32 v2, 0x1040, v109
	v_add_u32_e32 v12, 0x400, v111
	s_waitcnt vmcnt(11)
	ds_write2_b32 v2, v18, v19 offset1:1
	v_add_u32_e32 v2, 0x1048, v109
	ds_write2_b32 v2, v20, v21 offset1:1
	v_add_u32_e32 v2, 0x1450, v109
	s_waitcnt vmcnt(10)
	ds_write2_b32 v2, v22, v23 offset1:1
	v_add_u32_e32 v2, 0x1458, v109
	ds_write2_b32 v2, v24, v25 offset1:1
	v_add_u32_e32 v2, 0x1860, v109
	v_or_b32_e32 v10, s2, v110
	s_waitcnt vmcnt(9)
	ds_write2_b32 v2, v26, v27 offset1:1
	v_add_u32_e32 v2, 0x1868, v109
	ds_write2_b32 v2, v28, v29 offset1:1
	v_add_u32_e32 v2, 0x1c70, v109
	s_waitcnt vmcnt(8)
	ds_write2_b32 v2, v30, v31 offset1:1
	v_add_u32_e32 v2, 0x1c78, v109
	ds_write2_b32 v2, v32, v33 offset1:1
	v_add_u32_e32 v2, 0x2080, v109
	v_lshlrev_b32_e32 v68, 11, v10
	s_waitcnt vmcnt(7)
	ds_write2_b32 v2, v34, v35 offset1:1
	v_add_u32_e32 v2, 0x2088, v109
	ds_write2_b32 v2, v36, v37 offset1:1
	v_add_u32_e32 v2, 0x2490, v109
	s_waitcnt vmcnt(6)
	ds_write2_b32 v2, v38, v39 offset1:1
	v_add_u32_e32 v2, 0x2498, v109
	ds_write2_b32 v2, v40, v41 offset1:1
	v_add_u32_e32 v2, 0x28a0, v109
	v_lshl_add_u64 v[10:11], v[8:9], 0, v[68:69]
	s_waitcnt vmcnt(5)
	ds_write2_b32 v2, v42, v43 offset1:1
	v_add_u32_e32 v2, 0x28a8, v109
	ds_write2_b32 v2, v44, v45 offset1:1
	v_add_u32_e32 v2, 0x2cb0, v109
	s_waitcnt vmcnt(4)
	ds_write2_b32 v2, v46, v47 offset1:1
	v_add_u32_e32 v2, 0x2cb8, v109
	ds_write2_b32 v2, v48, v49 offset1:1
	v_add_u32_e32 v2, 0x30c0, v109
	s_waitcnt vmcnt(3)
	ds_write2_b32 v2, v50, v51 offset1:1
	v_add_u32_e32 v2, 0x30c8, v109
	ds_write2_b32 v2, v52, v53 offset1:1
	v_add_u32_e32 v2, 0x34d0, v109
	s_waitcnt vmcnt(2)
	ds_write2_b32 v2, v54, v55 offset1:1
	v_add_u32_e32 v2, 0x34d8, v109
	ds_write2_b32 v2, v56, v57 offset1:1
	v_add_u32_e32 v2, 0x38e0, v109
	s_waitcnt vmcnt(1)
	ds_write2_b32 v2, v58, v59 offset1:1
	v_add_u32_e32 v2, 0x38e8, v109
	ds_write2_b32 v2, v60, v61 offset1:1
	v_add_u32_e32 v2, 0x3cf0, v109
	s_waitcnt vmcnt(0)
	ds_write2_b32 v2, v62, v63 offset1:1
	v_add_u32_e32 v2, 0x3cf8, v109
	ds_write2_b32 v2, v64, v65 offset1:1
	s_waitcnt lgkmcnt(0)
	ds_read2_b32 v[188:189], v111 offset1:65
	ds_read2_b32 v[190:191], v111 offset0:130 offset1:195
	ds_read2_b32 v[192:193], v12 offset0:4 offset1:69
	ds_read2_b32 v[194:195], v12 offset0:134 offset1:199
	ds_read2_b32 v[196:197], v111 offset0:8 offset1:73
	ds_read2_b32 v[198:199], v111 offset0:138 offset1:203
	ds_read2_b32 v[200:201], v12 offset0:12 offset1:77
	ds_read2_b32 v[202:203], v12 offset0:142 offset1:207
	s_waitcnt lgkmcnt(7)
	ds_read2_b32 v[204:205], v111 offset0:16 offset1:81
	ds_read2_b32 v[206:207], v111 offset0:146 offset1:211
	ds_read2_b32 v[208:209], v12 offset0:20 offset1:85
	ds_read2_b32 v[210:211], v12 offset0:150 offset1:215
	ds_read2_b32 v[212:213], v111 offset0:24 offset1:89
	ds_read2_b32 v[214:215], v111 offset0:154 offset1:219
	ds_read2_b32 v[216:217], v12 offset0:28 offset1:93
	ds_read2_b32 v[218:219], v12 offset0:158 offset1:223
	s_waitcnt lgkmcnt(8)
	v_cvt_pk_bf16_f32 v2, v188, v189
	v_cvt_pk_bf16_f32 v3, v190, v191
	v_cvt_pk_bf16_f32 v4, v192, v193
	v_cvt_pk_bf16_f32 v5, v194, v195
	global_store_dwordx4 v[10:11], v[2:5], off
	s_nop 1
	v_or_b32_e32 v10, s2, v112
	v_lshlrev_b32_e32 v68, 11, v10
	v_cvt_pk_bf16_f32 v2, v196, v197
	v_cvt_pk_bf16_f32 v3, v198, v199
	v_cvt_pk_bf16_f32 v4, v200, v201
	v_cvt_pk_bf16_f32 v5, v202, v203
	v_lshl_add_u64 v[10:11], v[8:9], 0, v[68:69]
	global_store_dwordx4 v[10:11], v[2:5], off
	s_nop 1
	v_or_b32_e32 v10, s2, v113
	v_lshlrev_b32_e32 v68, 11, v10
	s_waitcnt lgkmcnt(7)
	ds_read2_b32 v[188:189], v111 offset0:32 offset1:97
	ds_read2_b32 v[190:191], v111 offset0:162 offset1:227
	ds_read2_b32 v[192:193], v12 offset0:36 offset1:101
	ds_read2_b32 v[194:195], v12 offset0:166 offset1:231
	ds_read2_b32 v[196:197], v111 offset0:40 offset1:105
	ds_read2_b32 v[198:199], v111 offset0:170 offset1:235
	ds_read2_b32 v[200:201], v12 offset0:44 offset1:109
	ds_read2_b32 v[202:203], v12 offset0:174 offset1:239
	s_waitcnt lgkmcnt(8)
	v_cvt_pk_bf16_f32 v2, v204, v205
	v_cvt_pk_bf16_f32 v3, v206, v207
	v_cvt_pk_bf16_f32 v4, v208, v209
	v_cvt_pk_bf16_f32 v5, v210, v211
	v_lshl_add_u64 v[10:11], v[8:9], 0, v[68:69]
	global_store_dwordx4 v[10:11], v[2:5], off
	s_nop 1
	v_or_b32_e32 v10, s2, v114
	v_lshlrev_b32_e32 v68, 11, v10
	v_cvt_pk_bf16_f32 v2, v212, v213
	v_cvt_pk_bf16_f32 v3, v214, v215
	v_cvt_pk_bf16_f32 v4, v216, v217
	v_cvt_pk_bf16_f32 v5, v218, v219
	v_lshl_add_u64 v[10:11], v[8:9], 0, v[68:69]
	global_store_dwordx4 v[10:11], v[2:5], off
	s_nop 1
	v_or_b32_e32 v10, s2, v115
	v_lshlrev_b32_e32 v68, 11, v10
	s_waitcnt lgkmcnt(7)
	ds_read2_b32 v[204:205], v111 offset0:48 offset1:113
	ds_read2_b32 v[206:207], v111 offset0:178 offset1:243
	ds_read2_b32 v[208:209], v12 offset0:52 offset1:117
	ds_read2_b32 v[210:211], v12 offset0:182 offset1:247
	ds_read2_b32 v[212:213], v111 offset0:56 offset1:121
	ds_read2_b32 v[214:215], v111 offset0:186 offset1:251
	ds_read2_b32 v[216:217], v12 offset0:60 offset1:125
	ds_read2_b32 v[218:219], v12 offset0:190 offset1:255
	s_waitcnt lgkmcnt(8)
	v_cvt_pk_bf16_f32 v2, v188, v189
	v_cvt_pk_bf16_f32 v3, v190, v191
	v_cvt_pk_bf16_f32 v4, v192, v193
	v_cvt_pk_bf16_f32 v5, v194, v195
	v_lshl_add_u64 v[10:11], v[8:9], 0, v[68:69]
	global_store_dwordx4 v[10:11], v[2:5], off
	s_nop 1
	v_or_b32_e32 v10, s2, v116
	v_lshlrev_b32_e32 v68, 11, v10
	v_cvt_pk_bf16_f32 v2, v196, v197
	v_cvt_pk_bf16_f32 v3, v198, v199
	v_cvt_pk_bf16_f32 v4, v200, v201
	v_cvt_pk_bf16_f32 v5, v202, v203
	v_lshl_add_u64 v[10:11], v[8:9], 0, v[68:69]
	global_store_dwordx4 v[10:11], v[2:5], off
	s_nop 1
	v_or_b32_e32 v10, s2, v117
	v_lshlrev_b32_e32 v68, 11, v10
	s_waitcnt lgkmcnt(0)
	v_cvt_pk_bf16_f32 v2, v204, v205
	v_cvt_pk_bf16_f32 v3, v206, v207
	v_cvt_pk_bf16_f32 v4, v208, v209
	v_cvt_pk_bf16_f32 v5, v210, v211
	v_lshl_add_u64 v[10:11], v[8:9], 0, v[68:69]
	global_store_dwordx4 v[10:11], v[2:5], off
	s_nop 1
	s_nop 0
	v_cvt_pk_bf16_f32 v2, v212, v213
	v_cvt_pk_bf16_f32 v3, v214, v215
	v_cvt_pk_bf16_f32 v4, v216, v217
	v_or_b32_e32 v5, s2, v118
	v_lshlrev_b32_e32 v68, 11, v5
	v_cvt_pk_bf16_f32 v5, v218, v219
	v_lshl_add_u64 v[6:7], v[8:9], 0, v[68:69]
	global_store_dwordx4 v[6:7], v[2:5], off
	s_nop 1
	s_waitcnt lgkmcnt(0)

.LBB0_451:
	s_and_b32 s0, s41, 0x3fc0
	s_addk_i32 s0, 0xd100
	v_or_b32_e32 v68, s0, v66
	s_lshl_b32 s12, s3, 2
	v_or_b32_e32 v4, 4, v68
	v_mov_b32_e32 v5, v69
	v_lshl_add_u64 v[62:63], v[88:89], 0, s[12:13]
	v_lshlrev_b64 v[2:3], 13, v[68:69]
	v_lshlrev_b64 v[4:5], 13, v[4:5]
	v_lshl_add_u64 v[2:3], v[62:63], 0, v[2:3]
	s_waitcnt vmcnt(0)
	v_lshl_add_u64 v[6:7], v[62:63], 0, v[4:5]
	v_or_b32_e32 v10, 8, v68
	v_mov_b32_e32 v11, v69
	v_or_b32_e32 v12, 12, v68
	v_mov_b32_e32 v13, v69
	global_load_dwordx4 v[2:5], v[2:3], off nt
	s_nop 0
	global_load_dwordx4 v[6:9], v[6:7], off nt
	v_lshlrev_b64 v[10:11], 13, v[10:11]
	v_lshlrev_b64 v[12:13], 13, v[12:13]
	v_lshl_add_u64 v[10:11], v[62:63], 0, v[10:11]
	v_lshl_add_u64 v[14:15], v[62:63], 0, v[12:13]
	global_load_dwordx4 v[10:13], v[10:11], off nt
	s_nop 0
	global_load_dwordx4 v[14:17], v[14:15], off nt
	v_or_b32_e32 v18, 16, v68
	v_mov_b32_e32 v19, v69
	v_or_b32_e32 v20, 20, v68
	v_mov_b32_e32 v21, v69
	v_lshlrev_b64 v[18:19], 13, v[18:19]
	v_lshlrev_b64 v[20:21], 13, v[20:21]
	v_lshl_add_u64 v[18:19], v[62:63], 0, v[18:19]
	v_lshl_add_u64 v[22:23], v[62:63], 0, v[20:21]
	global_load_dwordx4 v[18:21], v[18:19], off nt
	s_nop 0
	global_load_dwordx4 v[22:25], v[22:23], off nt
	v_or_b32_e32 v26, 24, v68
	v_mov_b32_e32 v27, v69
	v_or_b32_e32 v28, 28, v68
	v_mov_b32_e32 v29, v69
	v_lshlrev_b64 v[26:27], 13, v[26:27]
	v_lshlrev_b64 v[28:29], 13, v[28:29]
	v_lshl_add_u64 v[26:27], v[62:63], 0, v[26:27]
	v_lshl_add_u64 v[30:31], v[62:63], 0, v[28:29]
	global_load_dwordx4 v[26:29], v[26:27], off nt
	s_nop 0
	global_load_dwordx4 v[30:33], v[30:31], off nt
	v_or_b32_e32 v34, 32, v68
	v_mov_b32_e32 v35, v69
	v_or_b32_e32 v36, 36, v68
	v_mov_b32_e32 v37, v69
	v_lshlrev_b64 v[34:35], 13, v[34:35]
	v_lshlrev_b64 v[36:37], 13, v[36:37]
	v_lshl_add_u64 v[34:35], v[62:63], 0, v[34:35]
	v_lshl_add_u64 v[38:39], v[62:63], 0, v[36:37]
	global_load_dwordx4 v[34:37], v[34:35], off nt
	s_nop 0
	global_load_dwordx4 v[38:41], v[38:39], off nt
	v_or_b32_e32 v42, 40, v68
	v_mov_b32_e32 v43, v69
	v_or_b32_e32 v44, 44, v68
	v_mov_b32_e32 v45, v69
	v_lshlrev_b64 v[42:43], 13, v[42:43]
	v_lshlrev_b64 v[44:45], 13, v[44:45]
	v_lshl_add_u64 v[42:43], v[62:63], 0, v[42:43]
	v_lshl_add_u64 v[46:47], v[62:63], 0, v[44:45]
	global_load_dwordx4 v[42:45], v[42:43], off nt
	s_nop 0
	global_load_dwordx4 v[46:49], v[46:47], off nt
	v_or_b32_e32 v50, 48, v68
	v_mov_b32_e32 v51, v69
	v_lshlrev_b64 v[50:51], 13, v[50:51]
	v_lshl_add_u64 v[50:51], v[62:63], 0, v[50:51]
	v_or_b32_e32 v54, 52, v68
	v_mov_b32_e32 v55, v69
	global_load_dwordx4 v[50:53], v[50:51], off nt
	v_lshlrev_b64 v[54:55], 13, v[54:55]
	v_lshl_add_u64 v[54:55], v[62:63], 0, v[54:55]
	v_or_b32_e32 v58, 56, v68
	v_mov_b32_e32 v59, v69
	global_load_dwordx4 v[54:57], v[54:55], off nt
	v_lshlrev_b64 v[58:59], 13, v[58:59]
	v_lshl_add_u64 v[58:59], v[62:63], 0, v[58:59]
	v_or_b32_e32 v68, 60, v68
	global_load_dwordx4 v[58:61], v[58:59], off nt
	v_lshlrev_b64 v[64:65], 13, v[68:69]
	v_lshl_add_u64 v[62:63], v[62:63], 0, v[64:65]
	global_load_dwordx4 v[62:65], v[62:63], off nt
	v_add_u32_e32 v68, 0x410, v109
	v_add_u32_e32 v106, 0x418, v109
	s_mov_b32 s1, s13
	s_waitcnt vmcnt(15)
	ds_write2_b32 v109, v2, v3 offset1:1
	ds_write2_b32 v109, v4, v5 offset0:2 offset1:3
	s_waitcnt vmcnt(14)
	ds_write2_b32 v68, v6, v7 offset1:1
	ds_write2_b32 v106, v8, v9 offset1:1
	v_add_u32_e32 v2, 0x820, v109
	v_add_u32_e32 v68, s2, v110
	v_lshl_add_u64 v[8:9], s[0:1], 1, v[72:73]
	s_waitcnt vmcnt(13)
	ds_write2_b32 v2, v10, v11 offset1:1
	v_add_u32_e32 v2, 0x828, v109
	ds_write2_b32 v2, v12, v13 offset1:1
	v_add_u32_e32 v2, 0xc30, v109
	s_waitcnt vmcnt(12)
	ds_write2_b32 v2, v14, v15 offset1:1
	v_add_u32_e32 v2, 0xc38, v109
	ds_write2_b32 v2, v16, v17 offset1:1
	v_add_u32_e32 v2, 0x1040, v109
	v_add_u32_e32 v12, 0x400, v111
	s_waitcnt vmcnt(11)
	ds_write2_b32 v2, v18, v19 offset1:1
	v_add_u32_e32 v2, 0x1048, v109
	ds_write2_b32 v2, v20, v21 offset1:1
	v_add_u32_e32 v2, 0x1450, v109
	s_waitcnt vmcnt(10)
	ds_write2_b32 v2, v22, v23 offset1:1
	v_add_u32_e32 v2, 0x1458, v109
	ds_write2_b32 v2, v24, v25 offset1:1
	v_add_u32_e32 v2, 0x1860, v109
	v_lshlrev_b64 v[10:11], 11, v[68:69]
	s_waitcnt vmcnt(9)
	ds_write2_b32 v2, v26, v27 offset1:1
	v_add_u32_e32 v2, 0x1868, v109
	ds_write2_b32 v2, v28, v29 offset1:1
	v_add_u32_e32 v2, 0x1c70, v109
	s_waitcnt vmcnt(8)
	ds_write2_b32 v2, v30, v31 offset1:1
	v_add_u32_e32 v2, 0x1c78, v109
	ds_write2_b32 v2, v32, v33 offset1:1
	v_add_u32_e32 v2, 0x2080, v109
	v_lshl_add_u64 v[10:11], v[8:9], 0, v[10:11]
	s_waitcnt vmcnt(7)
	ds_write2_b32 v2, v34, v35 offset1:1
	v_add_u32_e32 v2, 0x2088, v109
	ds_write2_b32 v2, v36, v37 offset1:1
	v_add_u32_e32 v2, 0x2490, v109
	s_waitcnt vmcnt(6)
	ds_write2_b32 v2, v38, v39 offset1:1
	v_add_u32_e32 v2, 0x2498, v109
	ds_write2_b32 v2, v40, v41 offset1:1
	v_add_u32_e32 v2, 0x28a0, v109
	v_add_u32_e32 v68, s2, v112
	s_waitcnt vmcnt(5)
	ds_write2_b32 v2, v42, v43 offset1:1
	v_add_u32_e32 v2, 0x28a8, v109
	ds_write2_b32 v2, v44, v45 offset1:1
	v_add_u32_e32 v2, 0x2cb0, v109
	s_waitcnt vmcnt(4)
	ds_write2_b32 v2, v46, v47 offset1:1
	v_add_u32_e32 v2, 0x2cb8, v109
	ds_write2_b32 v2, v48, v49 offset1:1
	v_add_u32_e32 v2, 0x30c0, v109
	s_waitcnt vmcnt(3)
	ds_write2_b32 v2, v50, v51 offset1:1
	v_add_u32_e32 v2, 0x30c8, v109
	ds_write2_b32 v2, v52, v53 offset1:1
	v_add_u32_e32 v2, 0x34d0, v109
	s_waitcnt vmcnt(2)
	ds_write2_b32 v2, v54, v55 offset1:1
	v_add_u32_e32 v2, 0x34d8, v109
	ds_write2_b32 v2, v56, v57 offset1:1
	v_add_u32_e32 v2, 0x38e0, v109
	s_waitcnt vmcnt(1)
	ds_write2_b32 v2, v58, v59 offset1:1
	v_add_u32_e32 v2, 0x38e8, v109
	ds_write2_b32 v2, v60, v61 offset1:1
	v_add_u32_e32 v2, 0x3cf0, v109
	s_waitcnt vmcnt(0)
	ds_write2_b32 v2, v62, v63 offset1:1
	v_add_u32_e32 v2, 0x3cf8, v109
	ds_write2_b32 v2, v64, v65 offset1:1
	s_waitcnt lgkmcnt(0)
	ds_read2_b32 v[188:189], v111 offset1:65
	ds_read2_b32 v[190:191], v111 offset0:130 offset1:195
	ds_read2_b32 v[192:193], v12 offset0:4 offset1:69
	ds_read2_b32 v[194:195], v12 offset0:134 offset1:199
	ds_read2_b32 v[196:197], v111 offset0:8 offset1:73
	ds_read2_b32 v[198:199], v111 offset0:138 offset1:203
	ds_read2_b32 v[200:201], v12 offset0:12 offset1:77
	ds_read2_b32 v[202:203], v12 offset0:142 offset1:207
	s_waitcnt lgkmcnt(7)
	ds_read2_b32 v[204:205], v111 offset0:16 offset1:81
	ds_read2_b32 v[206:207], v111 offset0:146 offset1:211
	ds_read2_b32 v[208:209], v12 offset0:20 offset1:85
	ds_read2_b32 v[210:211], v12 offset0:150 offset1:215
	ds_read2_b32 v[212:213], v111 offset0:24 offset1:89
	ds_read2_b32 v[214:215], v111 offset0:154 offset1:219
	ds_read2_b32 v[216:217], v12 offset0:28 offset1:93
	ds_read2_b32 v[218:219], v12 offset0:158 offset1:223
	s_waitcnt lgkmcnt(8)
	v_cvt_pk_bf16_f32 v2, v188, v189
	v_cvt_pk_bf16_f32 v3, v190, v191
	v_cvt_pk_bf16_f32 v4, v192, v193
	v_cvt_pk_bf16_f32 v5, v194, v195
	global_store_dwordx4 v[10:11], v[2:5], off
	s_nop 1
	v_lshlrev_b64 v[10:11], 11, v[68:69]
	v_lshl_add_u64 v[10:11], v[8:9], 0, v[10:11]
	v_cvt_pk_bf16_f32 v2, v196, v197
	v_cvt_pk_bf16_f32 v3, v198, v199
	v_cvt_pk_bf16_f32 v4, v200, v201
	v_cvt_pk_bf16_f32 v5, v202, v203
	global_store_dwordx4 v[10:11], v[2:5], off
	s_nop 1
	v_add_u32_e32 v68, s2, v113
	v_lshlrev_b64 v[10:11], 11, v[68:69]
	s_waitcnt lgkmcnt(7)
	ds_read2_b32 v[188:189], v111 offset0:32 offset1:97
	ds_read2_b32 v[190:191], v111 offset0:162 offset1:227
	ds_read2_b32 v[192:193], v12 offset0:36 offset1:101
	ds_read2_b32 v[194:195], v12 offset0:166 offset1:231
	ds_read2_b32 v[196:197], v111 offset0:40 offset1:105
	ds_read2_b32 v[198:199], v111 offset0:170 offset1:235
	ds_read2_b32 v[200:201], v12 offset0:44 offset1:109
	ds_read2_b32 v[202:203], v12 offset0:174 offset1:239
	s_waitcnt lgkmcnt(8)
	v_cvt_pk_bf16_f32 v2, v204, v205
	v_cvt_pk_bf16_f32 v3, v206, v207
	v_cvt_pk_bf16_f32 v4, v208, v209
	v_cvt_pk_bf16_f32 v5, v210, v211
	v_lshl_add_u64 v[10:11], v[8:9], 0, v[10:11]
	global_store_dwordx4 v[10:11], v[2:5], off
	s_nop 1
	v_add_u32_e32 v68, s2, v114
	v_lshlrev_b64 v[10:11], 11, v[68:69]
	v_cvt_pk_bf16_f32 v2, v212, v213
	v_cvt_pk_bf16_f32 v3, v214, v215
	v_cvt_pk_bf16_f32 v4, v216, v217
	v_cvt_pk_bf16_f32 v5, v218, v219
	v_lshl_add_u64 v[10:11], v[8:9], 0, v[10:11]
	global_store_dwordx4 v[10:11], v[2:5], off
	s_nop 1
	v_add_u32_e32 v68, s2, v115
	v_lshlrev_b64 v[10:11], 11, v[68:69]
	s_waitcnt lgkmcnt(7)
	ds_read2_b32 v[204:205], v111 offset0:48 offset1:113
	ds_read2_b32 v[206:207], v111 offset0:178 offset1:243
	ds_read2_b32 v[208:209], v12 offset0:52 offset1:117
	ds_read2_b32 v[210:211], v12 offset0:182 offset1:247
	ds_read2_b32 v[212:213], v111 offset0:56 offset1:121
	ds_read2_b32 v[214:215], v111 offset0:186 offset1:251
	ds_read2_b32 v[216:217], v12 offset0:60 offset1:125
	ds_read2_b32 v[218:219], v12 offset0:190 offset1:255
	s_waitcnt lgkmcnt(8)
	v_cvt_pk_bf16_f32 v2, v188, v189
	v_cvt_pk_bf16_f32 v3, v190, v191
	v_cvt_pk_bf16_f32 v4, v192, v193
	v_cvt_pk_bf16_f32 v5, v194, v195
	v_lshl_add_u64 v[10:11], v[8:9], 0, v[10:11]
	global_store_dwordx4 v[10:11], v[2:5], off
	s_nop 1
	v_add_u32_e32 v68, s2, v116
	v_lshlrev_b64 v[10:11], 11, v[68:69]
	v_cvt_pk_bf16_f32 v2, v196, v197
	v_cvt_pk_bf16_f32 v3, v198, v199
	v_cvt_pk_bf16_f32 v4, v200, v201
	v_cvt_pk_bf16_f32 v5, v202, v203
	v_lshl_add_u64 v[10:11], v[8:9], 0, v[10:11]
	global_store_dwordx4 v[10:11], v[2:5], off
	s_nop 1
	v_add_u32_e32 v68, s2, v117
	v_lshlrev_b64 v[10:11], 11, v[68:69]
	s_waitcnt lgkmcnt(0)
	v_cvt_pk_bf16_f32 v2, v204, v205
	v_cvt_pk_bf16_f32 v3, v206, v207
	v_cvt_pk_bf16_f32 v4, v208, v209
	v_cvt_pk_bf16_f32 v5, v210, v211
	v_lshl_add_u64 v[10:11], v[8:9], 0, v[10:11]
	global_store_dwordx4 v[10:11], v[2:5], off
	s_nop 1
	v_add_u32_e32 v68, s2, v118
	v_lshlrev_b64 v[10:11], 11, v[68:69]
	v_cvt_pk_bf16_f32 v2, v212, v213
	v_cvt_pk_bf16_f32 v3, v214, v215
	v_cvt_pk_bf16_f32 v4, v216, v217
	v_cvt_pk_bf16_f32 v5, v218, v219
	v_lshl_add_u64 v[6:7], v[8:9], 0, v[10:11]
	global_store_dwordx4 v[6:7], v[2:5], off
	s_nop 1
	s_waitcnt lgkmcnt(0)

.LBB0_453:
	s_andn2_b64 vcc, exec, s[0:1]
	s_cbranch_vccnz .LBB0_455
	s_and_b32 s0, s39, 0x7fc0
	s_addk_i32 s0, 0xa600
	s_and_b32 s2, s31, 0x3c0
	v_or_b32_e32 v68, s0, v66
	s_lshl_b32 s12, s2, 2
	v_or_b32_e32 v4, 4, v68
	v_mov_b32_e32 v5, v69
	v_lshl_add_u64 v[62:63], v[90:91], 0, s[12:13]
	v_lshlrev_b64 v[2:3], 12, v[68:69]
	v_lshlrev_b64 v[4:5], 12, v[4:5]
	v_lshl_add_u64 v[2:3], v[62:63], 0, v[2:3]
	s_waitcnt vmcnt(0)
	v_lshl_add_u64 v[6:7], v[62:63], 0, v[4:5]
	global_load_dwordx4 v[2:5], v[2:3], off nt
	s_nop 0
	global_load_dwordx4 v[6:9], v[6:7], off nt
	v_or_b32_e32 v10, 8, v68
	v_mov_b32_e32 v11, v69
	v_or_b32_e32 v12, 12, v68
	v_mov_b32_e32 v13, v69
	v_lshlrev_b64 v[10:11], 12, v[10:11]
	v_lshlrev_b64 v[12:13], 12, v[12:13]
	v_lshl_add_u64 v[10:11], v[62:63], 0, v[10:11]
	v_lshl_add_u64 v[14:15], v[62:63], 0, v[12:13]
	global_load_dwordx4 v[10:13], v[10:11], off nt
	s_nop 0
	global_load_dwordx4 v[14:17], v[14:15], off nt
	v_or_b32_e32 v18, 16, v68
	v_mov_b32_e32 v19, v69
	v_or_b32_e32 v20, 20, v68
	v_mov_b32_e32 v21, v69
	v_lshlrev_b64 v[18:19], 12, v[18:19]
	v_lshlrev_b64 v[20:21], 12, v[20:21]
	v_lshl_add_u64 v[18:19], v[62:63], 0, v[18:19]
	v_lshl_add_u64 v[22:23], v[62:63], 0, v[20:21]
	global_load_dwordx4 v[18:21], v[18:19], off nt
	s_nop 0
	global_load_dwordx4 v[22:25], v[22:23], off nt
	v_or_b32_e32 v26, 24, v68
	v_mov_b32_e32 v27, v69
	v_or_b32_e32 v28, 28, v68
	v_mov_b32_e32 v29, v69
	v_lshlrev_b64 v[26:27], 12, v[26:27]
	v_lshlrev_b64 v[28:29], 12, v[28:29]
	v_lshl_add_u64 v[26:27], v[62:63], 0, v[26:27]
	v_lshl_add_u64 v[30:31], v[62:63], 0, v[28:29]
	global_load_dwordx4 v[26:29], v[26:27], off nt
	s_nop 0
	global_load_dwordx4 v[30:33], v[30:31], off nt
	v_or_b32_e32 v34, 32, v68
	v_mov_b32_e32 v35, v69
	v_or_b32_e32 v36, 36, v68
	v_mov_b32_e32 v37, v69
	v_lshlrev_b64 v[34:35], 12, v[34:35]
	v_lshlrev_b64 v[36:37], 12, v[36:37]
	v_lshl_add_u64 v[34:35], v[62:63], 0, v[34:35]
	v_lshl_add_u64 v[38:39], v[62:63], 0, v[36:37]
	global_load_dwordx4 v[34:37], v[34:35], off nt
	s_nop 0
	global_load_dwordx4 v[38:41], v[38:39], off nt
	v_or_b32_e32 v42, 40, v68
	v_mov_b32_e32 v43, v69
	v_or_b32_e32 v44, 44, v68
	v_mov_b32_e32 v45, v69
	v_lshlrev_b64 v[42:43], 12, v[42:43]
	v_lshlrev_b64 v[44:45], 12, v[44:45]
	v_lshl_add_u64 v[42:43], v[62:63], 0, v[42:43]
	v_lshl_add_u64 v[46:47], v[62:63], 0, v[44:45]
	global_load_dwordx4 v[42:45], v[42:43], off nt
	s_nop 0
	global_load_dwordx4 v[46:49], v[46:47], off nt
	v_or_b32_e32 v50, 48, v68
	v_mov_b32_e32 v51, v69
	v_lshlrev_b64 v[50:51], 12, v[50:51]
	v_lshl_add_u64 v[50:51], v[62:63], 0, v[50:51]
	v_or_b32_e32 v54, 52, v68
	v_mov_b32_e32 v55, v69
	global_load_dwordx4 v[50:53], v[50:51], off nt
	v_lshlrev_b64 v[54:55], 12, v[54:55]
	v_lshl_add_u64 v[54:55], v[62:63], 0, v[54:55]
	v_or_b32_e32 v58, 56, v68
	v_mov_b32_e32 v59, v69
	global_load_dwordx4 v[54:57], v[54:55], off nt
	v_lshlrev_b64 v[58:59], 12, v[58:59]
	v_lshl_add_u64 v[58:59], v[62:63], 0, v[58:59]
	v_or_b32_e32 v68, 60, v68
	global_load_dwordx4 v[58:61], v[58:59], off nt
	v_lshlrev_b64 v[64:65], 12, v[68:69]
	v_lshl_add_u64 v[62:63], v[62:63], 0, v[64:65]
	global_load_dwordx4 v[62:65], v[62:63], off nt
	v_add_u32_e32 v68, 0x410, v109
	s_mov_b32 s1, s13
	s_waitcnt vmcnt(15)
	ds_write2_b32 v109, v2, v3 offset1:1
	ds_write2_b32 v109, v4, v5 offset0:2 offset1:3
	s_waitcnt vmcnt(14)
	ds_write2_b32 v68, v6, v7 offset1:1
	v_add_u32_e32 v2, 0x418, v109
	ds_write2_b32 v2, v8, v9 offset1:1
	v_add_u32_e32 v2, 0x820, v109
	v_lshl_add_u64 v[8:9], s[0:1], 1, v[74:75]
	s_waitcnt vmcnt(13)
	ds_write2_b32 v2, v10, v11 offset1:1
	v_add_u32_e32 v2, 0x828, v109
	ds_write2_b32 v2, v12, v13 offset1:1
	v_add_u32_e32 v2, 0xc30, v109
	s_waitcnt vmcnt(12)
	ds_write2_b32 v2, v14, v15 offset1:1
	v_add_u32_e32 v2, 0xc38, v109
	ds_write2_b32 v2, v16, v17 offset1:1
	v_add_u32_e32 v2, 0x1040, v109
	v_add_u32_e32 v12, 0x400, v111
	s_waitcnt vmcnt(11)
	ds_write2_b32 v2, v18, v19 offset1:1
	v_add_u32_e32 v2, 0x1048, v109
	ds_write2_b32 v2, v20, v21 offset1:1
	v_add_u32_e32 v2, 0x1450, v109
	s_waitcnt vmcnt(10)
	ds_write2_b32 v2, v22, v23 offset1:1
	v_add_u32_e32 v2, 0x1458, v109
	ds_write2_b32 v2, v24, v25 offset1:1
	v_add_u32_e32 v2, 0x1860, v109
	v_or_b32_e32 v10, s2, v110
	s_waitcnt vmcnt(9)
	ds_write2_b32 v2, v26, v27 offset1:1
	v_add_u32_e32 v2, 0x1868, v109
	ds_write2_b32 v2, v28, v29 offset1:1
	v_add_u32_e32 v2, 0x1c70, v109
	s_waitcnt vmcnt(8)
	ds_write2_b32 v2, v30, v31 offset1:1
	v_add_u32_e32 v2, 0x1c78, v109
	ds_write2_b32 v2, v32, v33 offset1:1
	v_add_u32_e32 v2, 0x2080, v109
	v_lshlrev_b32_e32 v68, 11, v10
	s_waitcnt vmcnt(7)
	ds_write2_b32 v2, v34, v35 offset1:1
	v_add_u32_e32 v2, 0x2088, v109
	ds_write2_b32 v2, v36, v37 offset1:1
	v_add_u32_e32 v2, 0x2490, v109
	s_waitcnt vmcnt(6)
	ds_write2_b32 v2, v38, v39 offset1:1
	v_add_u32_e32 v2, 0x2498, v109
	ds_write2_b32 v2, v40, v41 offset1:1
	v_add_u32_e32 v2, 0x28a0, v109
	v_lshl_add_u64 v[10:11], v[8:9], 0, v[68:69]
	s_waitcnt vmcnt(5)
	ds_write2_b32 v2, v42, v43 offset1:1
	v_add_u32_e32 v2, 0x28a8, v109
	ds_write2_b32 v2, v44, v45 offset1:1
	v_add_u32_e32 v2, 0x2cb0, v109
	s_waitcnt vmcnt(4)
	ds_write2_b32 v2, v46, v47 offset1:1
	v_add_u32_e32 v2, 0x2cb8, v109
	ds_write2_b32 v2, v48, v49 offset1:1
	v_add_u32_e32 v2, 0x30c0, v109
	s_waitcnt vmcnt(3)
	ds_write2_b32 v2, v50, v51 offset1:1
	v_add_u32_e32 v2, 0x30c8, v109
	ds_write2_b32 v2, v52, v53 offset1:1
	v_add_u32_e32 v2, 0x34d0, v109
	s_waitcnt vmcnt(2)
	ds_write2_b32 v2, v54, v55 offset1:1
	v_add_u32_e32 v2, 0x34d8, v109
	ds_write2_b32 v2, v56, v57 offset1:1
	v_add_u32_e32 v2, 0x38e0, v109
	s_waitcnt vmcnt(1)
	ds_write2_b32 v2, v58, v59 offset1:1
	v_add_u32_e32 v2, 0x38e8, v109
	ds_write2_b32 v2, v60, v61 offset1:1
	v_add_u32_e32 v2, 0x3cf0, v109
	s_waitcnt vmcnt(0)
	ds_write2_b32 v2, v62, v63 offset1:1
	v_add_u32_e32 v2, 0x3cf8, v109
	ds_write2_b32 v2, v64, v65 offset1:1
	s_waitcnt lgkmcnt(0)
	ds_read2_b32 v[188:189], v111 offset1:65
	ds_read2_b32 v[190:191], v111 offset0:130 offset1:195
	ds_read2_b32 v[192:193], v12 offset0:4 offset1:69
	ds_read2_b32 v[194:195], v12 offset0:134 offset1:199
	ds_read2_b32 v[196:197], v111 offset0:8 offset1:73
	ds_read2_b32 v[198:199], v111 offset0:138 offset1:203
	ds_read2_b32 v[200:201], v12 offset0:12 offset1:77
	ds_read2_b32 v[202:203], v12 offset0:142 offset1:207
	s_waitcnt lgkmcnt(7)
	ds_read2_b32 v[204:205], v111 offset0:16 offset1:81
	ds_read2_b32 v[206:207], v111 offset0:146 offset1:211
	ds_read2_b32 v[208:209], v12 offset0:20 offset1:85
	ds_read2_b32 v[210:211], v12 offset0:150 offset1:215
	ds_read2_b32 v[212:213], v111 offset0:24 offset1:89
	ds_read2_b32 v[214:215], v111 offset0:154 offset1:219
	ds_read2_b32 v[216:217], v12 offset0:28 offset1:93
	ds_read2_b32 v[218:219], v12 offset0:158 offset1:223
	s_waitcnt lgkmcnt(8)
	v_cvt_pk_bf16_f32 v2, v188, v189
	v_cvt_pk_bf16_f32 v3, v190, v191
	v_cvt_pk_bf16_f32 v4, v192, v193
	v_cvt_pk_bf16_f32 v5, v194, v195
	global_store_dwordx4 v[10:11], v[2:5], off
	s_nop 1
	v_or_b32_e32 v10, s2, v112
	v_lshlrev_b32_e32 v68, 11, v10
	v_cvt_pk_bf16_f32 v2, v196, v197
	v_cvt_pk_bf16_f32 v3, v198, v199
	v_cvt_pk_bf16_f32 v4, v200, v201
	v_cvt_pk_bf16_f32 v5, v202, v203
	v_lshl_add_u64 v[10:11], v[8:9], 0, v[68:69]
	global_store_dwordx4 v[10:11], v[2:5], off
	s_nop 1
	v_or_b32_e32 v10, s2, v113
	v_lshlrev_b32_e32 v68, 11, v10
	s_waitcnt lgkmcnt(7)
	ds_read2_b32 v[188:189], v111 offset0:32 offset1:97
	ds_read2_b32 v[190:191], v111 offset0:162 offset1:227
	ds_read2_b32 v[192:193], v12 offset0:36 offset1:101
	ds_read2_b32 v[194:195], v12 offset0:166 offset1:231
	ds_read2_b32 v[196:197], v111 offset0:40 offset1:105
	ds_read2_b32 v[198:199], v111 offset0:170 offset1:235
	ds_read2_b32 v[200:201], v12 offset0:44 offset1:109
	ds_read2_b32 v[202:203], v12 offset0:174 offset1:239
	s_waitcnt lgkmcnt(8)
	v_cvt_pk_bf16_f32 v2, v204, v205
	v_cvt_pk_bf16_f32 v3, v206, v207
	v_cvt_pk_bf16_f32 v4, v208, v209
	v_cvt_pk_bf16_f32 v5, v210, v211
	v_lshl_add_u64 v[10:11], v[8:9], 0, v[68:69]
	global_store_dwordx4 v[10:11], v[2:5], off
	s_nop 1
	v_or_b32_e32 v10, s2, v114
	v_lshlrev_b32_e32 v68, 11, v10
	v_cvt_pk_bf16_f32 v2, v212, v213
	v_cvt_pk_bf16_f32 v3, v214, v215
	v_cvt_pk_bf16_f32 v4, v216, v217
	v_cvt_pk_bf16_f32 v5, v218, v219
	v_lshl_add_u64 v[10:11], v[8:9], 0, v[68:69]
	global_store_dwordx4 v[10:11], v[2:5], off
	s_nop 1
	v_or_b32_e32 v10, s2, v115
	v_lshlrev_b32_e32 v68, 11, v10
	s_waitcnt lgkmcnt(7)
	ds_read2_b32 v[204:205], v111 offset0:48 offset1:113
	ds_read2_b32 v[206:207], v111 offset0:178 offset1:243
	ds_read2_b32 v[208:209], v12 offset0:52 offset1:117
	ds_read2_b32 v[210:211], v12 offset0:182 offset1:247
	ds_read2_b32 v[212:213], v111 offset0:56 offset1:121
	ds_read2_b32 v[214:215], v111 offset0:186 offset1:251
	ds_read2_b32 v[216:217], v12 offset0:60 offset1:125
	ds_read2_b32 v[218:219], v12 offset0:190 offset1:255
	s_waitcnt lgkmcnt(8)
	v_cvt_pk_bf16_f32 v2, v188, v189
	v_cvt_pk_bf16_f32 v3, v190, v191
	v_cvt_pk_bf16_f32 v4, v192, v193
	v_cvt_pk_bf16_f32 v5, v194, v195
	v_lshl_add_u64 v[10:11], v[8:9], 0, v[68:69]
	global_store_dwordx4 v[10:11], v[2:5], off
	s_nop 1
	v_or_b32_e32 v10, s2, v116
	v_lshlrev_b32_e32 v68, 11, v10
	v_cvt_pk_bf16_f32 v2, v196, v197
	v_cvt_pk_bf16_f32 v3, v198, v199
	v_cvt_pk_bf16_f32 v4, v200, v201
	v_cvt_pk_bf16_f32 v5, v202, v203
	v_lshl_add_u64 v[10:11], v[8:9], 0, v[68:69]
	global_store_dwordx4 v[10:11], v[2:5], off
	s_nop 1
	v_or_b32_e32 v10, s2, v117
	v_lshlrev_b32_e32 v68, 11, v10
	s_waitcnt lgkmcnt(0)
	v_cvt_pk_bf16_f32 v2, v204, v205
	v_cvt_pk_bf16_f32 v3, v206, v207
	v_cvt_pk_bf16_f32 v4, v208, v209
	v_cvt_pk_bf16_f32 v5, v210, v211
	v_lshl_add_u64 v[10:11], v[8:9], 0, v[68:69]
	global_store_dwordx4 v[10:11], v[2:5], off
	s_nop 1
	s_nop 0
	v_cvt_pk_bf16_f32 v2, v212, v213
	v_cvt_pk_bf16_f32 v3, v214, v215
	v_cvt_pk_bf16_f32 v4, v216, v217
	v_or_b32_e32 v5, s2, v118
	v_lshlrev_b32_e32 v68, 11, v5
	v_cvt_pk_bf16_f32 v5, v218, v219
	v_lshl_add_u64 v[6:7], v[8:9], 0, v[68:69]
	global_store_dwordx4 v[6:7], v[2:5], off
	s_nop 1
	s_waitcnt lgkmcnt(0)

.LBB0_485:
	s_waitcnt vmcnt(0)
	v_pk_mul_f32 v[2:3], v[2:3], v[218:219] op_sel_hi:[1,0]
	v_add_u32_e32 v6, 0x1040, v19
	ds_write2_b32 v6, v2, v3 offset1:1
	v_pk_mul_f32 v[2:3], v[4:5], v[218:219] op_sel_hi:[1,0]
	v_add_u32_e32 v4, 0x1048, v19
	ds_write2_b32 v4, v2, v3 offset1:1
	s_waitcnt lgkmcnt(0)
	v_add_u32_e32 v10, 0x400, v111
	ds_read2_b32 v[188:189], v111 offset1:65
	ds_read2_b32 v[190:191], v111 offset0:130 offset1:195
	ds_read2_b32 v[192:193], v10 offset0:4 offset1:69
	ds_read2_b32 v[194:195], v10 offset0:134 offset1:199
	ds_read2_b32 v[196:197], v111 offset0:8 offset1:73
	ds_read2_b32 v[198:199], v111 offset0:138 offset1:203
	ds_read2_b32 v[200:201], v10 offset0:12 offset1:77
	ds_read2_b32 v[202:203], v10 offset0:142 offset1:207
	s_waitcnt lgkmcnt(7)
	ds_read2_b32 v[204:205], v111 offset0:16 offset1:81
	ds_read2_b32 v[206:207], v111 offset0:146 offset1:211
	ds_read2_b32 v[208:209], v10 offset0:20 offset1:85
	ds_read2_b32 v[210:211], v10 offset0:150 offset1:215
	ds_read2_b32 v[212:213], v111 offset0:24 offset1:89
	ds_read2_b32 v[214:215], v111 offset0:154 offset1:219
	ds_read2_b32 v[216:217], v10 offset0:28 offset1:93
	ds_read2_b32 v[218:219], v10 offset0:158 offset1:223
	s_waitcnt lgkmcnt(8)
	v_cvt_pk_bf16_f32 v4, v188, v189
	v_cvt_pk_bf16_f32 v5, v190, v191
	s_lshl_b32 s12, s24, 1
	v_cvt_pk_bf16_f32 v6, v192, v193
	v_add_u32_e32 v68, s3, v110
	v_lshl_add_u64 v[2:3], v[76:77], 0, s[12:13]
	v_cvt_pk_bf16_f32 v7, v194, v195
	v_lshlrev_b64 v[8:9], 11, v[68:69]
	v_lshl_add_u64 v[8:9], v[2:3], 0, v[8:9]
	global_store_dwordx4 v[8:9], v[4:7], off
	s_nop 1
	v_add_u32_e32 v68, s3, v112
	v_cvt_pk_bf16_f32 v4, v196, v197
	v_cvt_pk_bf16_f32 v5, v198, v199
	v_cvt_pk_bf16_f32 v6, v200, v201
	v_cvt_pk_bf16_f32 v7, v202, v203
	v_lshlrev_b64 v[8:9], 11, v[68:69]
	v_lshl_add_u64 v[8:9], v[2:3], 0, v[8:9]
	global_store_dwordx4 v[8:9], v[4:7], off
	s_nop 1
	v_add_u32_e32 v68, s3, v113
	s_waitcnt lgkmcnt(7)
	ds_read2_b32 v[188:189], v111 offset0:32 offset1:97
	ds_read2_b32 v[190:191], v111 offset0:162 offset1:227
	ds_read2_b32 v[192:193], v10 offset0:36 offset1:101
	ds_read2_b32 v[194:195], v10 offset0:166 offset1:231
	ds_read2_b32 v[196:197], v111 offset0:40 offset1:105
	ds_read2_b32 v[198:199], v111 offset0:170 offset1:235
	ds_read2_b32 v[200:201], v10 offset0:44 offset1:109
	ds_read2_b32 v[202:203], v10 offset0:174 offset1:239
	s_waitcnt lgkmcnt(8)
	v_cvt_pk_bf16_f32 v4, v204, v205
	v_cvt_pk_bf16_f32 v5, v206, v207
	v_cvt_pk_bf16_f32 v6, v208, v209
	v_cvt_pk_bf16_f32 v7, v210, v211
	v_lshlrev_b64 v[8:9], 11, v[68:69]
	v_lshl_add_u64 v[8:9], v[2:3], 0, v[8:9]
	global_store_dwordx4 v[8:9], v[4:7], off
	s_nop 1
	v_add_u32_e32 v68, s3, v114
	v_cvt_pk_bf16_f32 v4, v212, v213
	v_cvt_pk_bf16_f32 v5, v214, v215
	v_cvt_pk_bf16_f32 v6, v216, v217
	v_cvt_pk_bf16_f32 v7, v218, v219
	v_lshlrev_b64 v[8:9], 11, v[68:69]
	v_lshl_add_u64 v[8:9], v[2:3], 0, v[8:9]
	global_store_dwordx4 v[8:9], v[4:7], off
	s_nop 1
	v_add_u32_e32 v68, s3, v115
	s_waitcnt lgkmcnt(7)
	ds_read2_b32 v[204:205], v111 offset0:48 offset1:113
	ds_read2_b32 v[206:207], v111 offset0:178 offset1:243
	ds_read2_b32 v[208:209], v10 offset0:52 offset1:117
	ds_read2_b32 v[210:211], v10 offset0:182 offset1:247
	ds_read2_b32 v[212:213], v111 offset0:56 offset1:121
	ds_read2_b32 v[214:215], v111 offset0:186 offset1:251
	ds_read2_b32 v[216:217], v10 offset0:60 offset1:125
	ds_read2_b32 v[218:219], v10 offset0:190 offset1:255
	s_waitcnt lgkmcnt(8)
	v_cvt_pk_bf16_f32 v4, v188, v189
	v_cvt_pk_bf16_f32 v5, v190, v191
	v_cvt_pk_bf16_f32 v6, v192, v193
	v_cvt_pk_bf16_f32 v7, v194, v195
	v_lshlrev_b64 v[8:9], 11, v[68:69]
	v_lshl_add_u64 v[8:9], v[2:3], 0, v[8:9]
	global_store_dwordx4 v[8:9], v[4:7], off
	s_nop 1
	v_add_u32_e32 v68, s3, v116
	v_cvt_pk_bf16_f32 v4, v196, v197
	v_cvt_pk_bf16_f32 v5, v198, v199
	v_cvt_pk_bf16_f32 v6, v200, v201
	v_cvt_pk_bf16_f32 v7, v202, v203
	v_lshlrev_b64 v[8:9], 11, v[68:69]
	v_lshl_add_u64 v[8:9], v[2:3], 0, v[8:9]
	global_store_dwordx4 v[8:9], v[4:7], off
	s_nop 1
	v_add_u32_e32 v68, s3, v117
	s_waitcnt lgkmcnt(0)
	v_cvt_pk_bf16_f32 v4, v204, v205
	v_cvt_pk_bf16_f32 v5, v206, v207
	v_cvt_pk_bf16_f32 v6, v208, v209
	v_cvt_pk_bf16_f32 v7, v210, v211
	v_lshlrev_b64 v[8:9], 11, v[68:69]
	v_lshl_add_u64 v[8:9], v[2:3], 0, v[8:9]
	global_store_dwordx4 v[8:9], v[4:7], off
	s_nop 1
	v_add_u32_e32 v68, s3, v118
	v_cvt_pk_bf16_f32 v4, v212, v213
	v_cvt_pk_bf16_f32 v5, v214, v215
	v_cvt_pk_bf16_f32 v6, v216, v217
	v_cvt_pk_bf16_f32 v7, v218, v219
	v_lshlrev_b64 v[8:9], 11, v[68:69]
	v_lshl_add_u64 v[2:3], v[2:3], 0, v[8:9]
	global_store_dwordx4 v[2:3], v[4:7], off
	s_nop 1
	s_waitcnt lgkmcnt(0)

.LBB0_487:
	s_andn2_b64 vcc, exec, s[0:1]
	s_cbranch_vccnz .LBB0_544
	s_add_i32 s3, s29, 0xfffff7c0
	s_cmpk_gt_u32 s3, 0x2bf
	s_mov_b64 s[0:1], -1
	s_cbranch_scc0 .LBB0_518
	s_cmpk_gt_u32 s3, 0x57f
	s_cbranch_scc0 .LBB0_491
	s_add_i32 s0, s31, 0xfffdf000
	s_and_b32 s2, s0, 0x3c0
	s_add_i32 s0, s39, 0xffffdf00
	s_and_b32 s0, s0, 0x7fffffc0
	s_addk_i32 s0, 0xea00
	v_or_b32_e32 v68, s0, v66
	s_lshl_b32 s12, s2, 2
	v_or_b32_e32 v4, 4, v68
	v_mov_b32_e32 v5, v69
	v_lshl_add_u64 v[62:63], v[94:95], 0, s[12:13]
	v_lshlrev_b64 v[2:3], 12, v[68:69]
	v_lshlrev_b64 v[4:5], 12, v[4:5]
	v_lshl_add_u64 v[2:3], v[62:63], 0, v[2:3]
	s_waitcnt vmcnt(0)
	v_lshl_add_u64 v[6:7], v[62:63], 0, v[4:5]
	global_load_dwordx4 v[2:5], v[2:3], off nt
	s_nop 0
	global_load_dwordx4 v[6:9], v[6:7], off nt
	v_or_b32_e32 v10, 8, v68
	v_mov_b32_e32 v11, v69
	v_or_b32_e32 v12, 12, v68
	v_mov_b32_e32 v13, v69
	v_lshlrev_b64 v[10:11], 12, v[10:11]
	v_lshlrev_b64 v[12:13], 12, v[12:13]
	v_lshl_add_u64 v[10:11], v[62:63], 0, v[10:11]
	v_lshl_add_u64 v[14:15], v[62:63], 0, v[12:13]
	global_load_dwordx4 v[10:13], v[10:11], off nt
	s_nop 0
	global_load_dwordx4 v[14:17], v[14:15], off nt
	v_or_b32_e32 v18, 16, v68
	v_mov_b32_e32 v19, v69
	v_or_b32_e32 v20, 20, v68
	v_mov_b32_e32 v21, v69
	v_lshlrev_b64 v[18:19], 12, v[18:19]
	v_lshlrev_b64 v[20:21], 12, v[20:21]
	v_lshl_add_u64 v[18:19], v[62:63], 0, v[18:19]
	v_lshl_add_u64 v[22:23], v[62:63], 0, v[20:21]
	global_load_dwordx4 v[18:21], v[18:19], off nt
	s_nop 0
	global_load_dwordx4 v[22:25], v[22:23], off nt
	v_or_b32_e32 v26, 24, v68
	v_mov_b32_e32 v27, v69
	v_or_b32_e32 v28, 28, v68
	v_mov_b32_e32 v29, v69
	v_lshlrev_b64 v[26:27], 12, v[26:27]
	v_lshlrev_b64 v[28:29], 12, v[28:29]
	v_lshl_add_u64 v[26:27], v[62:63], 0, v[26:27]
	v_lshl_add_u64 v[30:31], v[62:63], 0, v[28:29]
	global_load_dwordx4 v[26:29], v[26:27], off nt
	s_nop 0
	global_load_dwordx4 v[30:33], v[30:31], off nt
	v_or_b32_e32 v34, 32, v68
	v_mov_b32_e32 v35, v69
	v_or_b32_e32 v36, 36, v68
	v_mov_b32_e32 v37, v69
	v_lshlrev_b64 v[34:35], 12, v[34:35]
	v_lshlrev_b64 v[36:37], 12, v[36:37]
	v_lshl_add_u64 v[34:35], v[62:63], 0, v[34:35]
	v_lshl_add_u64 v[38:39], v[62:63], 0, v[36:37]
	global_load_dwordx4 v[34:37], v[34:35], off nt
	s_nop 0
	global_load_dwordx4 v[38:41], v[38:39], off nt
	v_or_b32_e32 v42, 40, v68
	v_mov_b32_e32 v43, v69
	v_or_b32_e32 v44, 44, v68
	v_mov_b32_e32 v45, v69
	v_lshlrev_b64 v[42:43], 12, v[42:43]
	v_lshlrev_b64 v[44:45], 12, v[44:45]
	v_lshl_add_u64 v[42:43], v[62:63], 0, v[42:43]
	v_lshl_add_u64 v[46:47], v[62:63], 0, v[44:45]
	global_load_dwordx4 v[42:45], v[42:43], off nt
	s_nop 0
	global_load_dwordx4 v[46:49], v[46:47], off nt
	v_or_b32_e32 v50, 48, v68
	v_mov_b32_e32 v51, v69
	v_lshlrev_b64 v[50:51], 12, v[50:51]
	v_lshl_add_u64 v[50:51], v[62:63], 0, v[50:51]
	v_or_b32_e32 v54, 52, v68
	v_mov_b32_e32 v55, v69
	global_load_dwordx4 v[50:53], v[50:51], off nt
	v_lshlrev_b64 v[54:55], 12, v[54:55]
	v_lshl_add_u64 v[54:55], v[62:63], 0, v[54:55]
	v_or_b32_e32 v58, 56, v68
	v_mov_b32_e32 v59, v69
	global_load_dwordx4 v[54:57], v[54:55], off nt
	v_lshlrev_b64 v[58:59], 12, v[58:59]
	v_lshl_add_u64 v[58:59], v[62:63], 0, v[58:59]
	v_or_b32_e32 v68, 60, v68
	global_load_dwordx4 v[58:61], v[58:59], off nt
	v_lshlrev_b64 v[64:65], 12, v[68:69]
	v_lshl_add_u64 v[62:63], v[62:63], 0, v[64:65]
	global_load_dwordx4 v[62:65], v[62:63], off nt
	s_mov_b32 s1, s13
	s_waitcnt vmcnt(15)
	ds_write2_b32 v109, v2, v3 offset1:1
	ds_write2_b32 v109, v4, v5 offset0:2 offset1:3
	v_add_u32_e32 v2, 0x410, v109
	s_waitcnt vmcnt(14)
	ds_write2_b32 v2, v6, v7 offset1:1
	v_add_u32_e32 v2, 0x418, v109
	ds_write2_b32 v2, v8, v9 offset1:1
	v_add_u32_e32 v2, 0x820, v109
	v_lshl_add_u64 v[8:9], s[0:1], 1, v[78:79]
	s_mov_b64 s[0:1], 0
	s_waitcnt vmcnt(13)
	ds_write2_b32 v2, v10, v11 offset1:1
	v_add_u32_e32 v2, 0x828, v109
	ds_write2_b32 v2, v12, v13 offset1:1
	v_add_u32_e32 v2, 0xc30, v109
	s_waitcnt vmcnt(12)
	ds_write2_b32 v2, v14, v15 offset1:1
	v_add_u32_e32 v2, 0xc38, v109
	ds_write2_b32 v2, v16, v17 offset1:1
	v_add_u32_e32 v2, 0x1040, v109
	v_or_b32_e32 v10, s2, v110
	s_waitcnt vmcnt(11)
	ds_write2_b32 v2, v18, v19 offset1:1
	v_add_u32_e32 v2, 0x1048, v109
	ds_write2_b32 v2, v20, v21 offset1:1
	v_add_u32_e32 v2, 0x1450, v109
	s_waitcnt vmcnt(10)
	ds_write2_b32 v2, v22, v23 offset1:1
	v_add_u32_e32 v2, 0x1458, v109
	ds_write2_b32 v2, v24, v25 offset1:1
	v_add_u32_e32 v2, 0x1860, v109
	v_mul_u32_u24_e32 v10, 0xb00, v10
	s_waitcnt vmcnt(9)
	ds_write2_b32 v2, v26, v27 offset1:1
	v_add_u32_e32 v2, 0x1868, v109
	ds_write2_b32 v2, v28, v29 offset1:1
	v_add_u32_e32 v2, 0x1c70, v109
	s_waitcnt vmcnt(8)
	ds_write2_b32 v2, v30, v31 offset1:1
	v_add_u32_e32 v2, 0x1c78, v109
	ds_write2_b32 v2, v32, v33 offset1:1
	v_add_u32_e32 v2, 0x2080, v109
	v_add_u32_e32 v12, 0x400, v111
	s_waitcnt vmcnt(7)
	ds_write2_b32 v2, v34, v35 offset1:1
	v_add_u32_e32 v2, 0x2088, v109
	ds_write2_b32 v2, v36, v37 offset1:1
	v_add_u32_e32 v2, 0x2490, v109
	s_waitcnt vmcnt(6)
	ds_write2_b32 v2, v38, v39 offset1:1
	v_add_u32_e32 v2, 0x2498, v109
	ds_write2_b32 v2, v40, v41 offset1:1
	v_add_u32_e32 v2, 0x28a0, v109
	v_lshlrev_b32_e32 v68, 1, v10
	s_waitcnt vmcnt(5)
	ds_write2_b32 v2, v42, v43 offset1:1
	v_add_u32_e32 v2, 0x28a8, v109
	ds_write2_b32 v2, v44, v45 offset1:1
	v_add_u32_e32 v2, 0x2cb0, v109
	s_waitcnt vmcnt(4)
	ds_write2_b32 v2, v46, v47 offset1:1
	v_add_u32_e32 v2, 0x2cb8, v109
	ds_write2_b32 v2, v48, v49 offset1:1
	v_add_u32_e32 v2, 0x30c0, v109
	s_waitcnt vmcnt(3)
	ds_write2_b32 v2, v50, v51 offset1:1
	v_add_u32_e32 v2, 0x30c8, v109
	ds_write2_b32 v2, v52, v53 offset1:1
	v_add_u32_e32 v2, 0x34d0, v109
	v_lshl_add_u64 v[10:11], v[8:9], 0, v[68:69]
	s_waitcnt vmcnt(2)
	ds_write2_b32 v2, v54, v55 offset1:1
	v_add_u32_e32 v2, 0x34d8, v109
	ds_write2_b32 v2, v56, v57 offset1:1
	v_add_u32_e32 v2, 0x38e0, v109
	s_waitcnt vmcnt(1)
	ds_write2_b32 v2, v58, v59 offset1:1
	v_add_u32_e32 v2, 0x38e8, v109
	ds_write2_b32 v2, v60, v61 offset1:1
	v_add_u32_e32 v2, 0x3cf0, v109
	s_waitcnt vmcnt(0)
	ds_write2_b32 v2, v62, v63 offset1:1
	v_add_u32_e32 v2, 0x3cf8, v109
	ds_write2_b32 v2, v64, v65 offset1:1
	s_waitcnt lgkmcnt(0)
	ds_read2_b32 v[188:189], v111 offset1:65
	ds_read2_b32 v[190:191], v111 offset0:130 offset1:195
	ds_read2_b32 v[192:193], v12 offset0:4 offset1:69
	ds_read2_b32 v[194:195], v12 offset0:134 offset1:199
	ds_read2_b32 v[196:197], v111 offset0:8 offset1:73
	ds_read2_b32 v[198:199], v111 offset0:138 offset1:203
	ds_read2_b32 v[200:201], v12 offset0:12 offset1:77
	ds_read2_b32 v[202:203], v12 offset0:142 offset1:207
	s_waitcnt lgkmcnt(7)
	ds_read2_b32 v[204:205], v111 offset0:16 offset1:81
	ds_read2_b32 v[206:207], v111 offset0:146 offset1:211
	ds_read2_b32 v[208:209], v12 offset0:20 offset1:85
	ds_read2_b32 v[210:211], v12 offset0:150 offset1:215
	ds_read2_b32 v[212:213], v111 offset0:24 offset1:89
	ds_read2_b32 v[214:215], v111 offset0:154 offset1:219
	ds_read2_b32 v[216:217], v12 offset0:28 offset1:93
	ds_read2_b32 v[218:219], v12 offset0:158 offset1:223
	s_waitcnt lgkmcnt(8)
	v_cvt_pk_bf16_f32 v2, v188, v189
	v_cvt_pk_bf16_f32 v3, v190, v191
	v_cvt_pk_bf16_f32 v4, v192, v193
	v_cvt_pk_bf16_f32 v5, v194, v195
	global_store_dwordx4 v[10:11], v[2:5], off
	s_nop 1
	v_or_b32_e32 v10, s2, v112
	v_mul_u32_u24_e32 v10, 0xb00, v10
	v_cvt_pk_bf16_f32 v2, v196, v197
	v_lshlrev_b32_e32 v68, 1, v10
	v_cvt_pk_bf16_f32 v3, v198, v199
	v_lshl_add_u64 v[10:11], v[8:9], 0, v[68:69]
	v_cvt_pk_bf16_f32 v4, v200, v201
	v_cvt_pk_bf16_f32 v5, v202, v203
	global_store_dwordx4 v[10:11], v[2:5], off
	s_nop 1
	v_or_b32_e32 v10, s2, v113
	v_mul_u32_u24_e32 v10, 0xb00, v10
	s_waitcnt lgkmcnt(7)
	ds_read2_b32 v[188:189], v111 offset0:32 offset1:97
	ds_read2_b32 v[190:191], v111 offset0:162 offset1:227
	ds_read2_b32 v[192:193], v12 offset0:36 offset1:101
	ds_read2_b32 v[194:195], v12 offset0:166 offset1:231
	ds_read2_b32 v[196:197], v111 offset0:40 offset1:105
	ds_read2_b32 v[198:199], v111 offset0:170 offset1:235
	ds_read2_b32 v[200:201], v12 offset0:44 offset1:109
	ds_read2_b32 v[202:203], v12 offset0:174 offset1:239
	s_waitcnt lgkmcnt(8)
	v_cvt_pk_bf16_f32 v2, v204, v205
	v_lshlrev_b32_e32 v68, 1, v10
	v_cvt_pk_bf16_f32 v3, v206, v207
	v_lshl_add_u64 v[10:11], v[8:9], 0, v[68:69]
	v_cvt_pk_bf16_f32 v4, v208, v209
	v_cvt_pk_bf16_f32 v5, v210, v211
	global_store_dwordx4 v[10:11], v[2:5], off
	s_nop 1
	v_or_b32_e32 v10, s2, v114
	v_mul_u32_u24_e32 v10, 0xb00, v10
	v_cvt_pk_bf16_f32 v2, v212, v213
	v_lshlrev_b32_e32 v68, 1, v10
	v_cvt_pk_bf16_f32 v3, v214, v215
	v_lshl_add_u64 v[10:11], v[8:9], 0, v[68:69]
	v_cvt_pk_bf16_f32 v4, v216, v217
	v_cvt_pk_bf16_f32 v5, v218, v219
	global_store_dwordx4 v[10:11], v[2:5], off
	s_nop 1
	v_or_b32_e32 v10, s2, v115
	v_mul_u32_u24_e32 v10, 0xb00, v10
	s_waitcnt lgkmcnt(7)
	ds_read2_b32 v[204:205], v111 offset0:48 offset1:113
	ds_read2_b32 v[206:207], v111 offset0:178 offset1:243
	ds_read2_b32 v[208:209], v12 offset0:52 offset1:117
	ds_read2_b32 v[210:211], v12 offset0:182 offset1:247
	ds_read2_b32 v[212:213], v111 offset0:56 offset1:121
	ds_read2_b32 v[214:215], v111 offset0:186 offset1:251
	ds_read2_b32 v[216:217], v12 offset0:60 offset1:125
	ds_read2_b32 v[218:219], v12 offset0:190 offset1:255
	s_waitcnt lgkmcnt(8)
	v_cvt_pk_bf16_f32 v2, v188, v189
	v_lshlrev_b32_e32 v68, 1, v10
	v_cvt_pk_bf16_f32 v3, v190, v191
	v_lshl_add_u64 v[10:11], v[8:9], 0, v[68:69]
	v_cvt_pk_bf16_f32 v4, v192, v193
	v_cvt_pk_bf16_f32 v5, v194, v195
	global_store_dwordx4 v[10:11], v[2:5], off
	s_nop 1
	v_or_b32_e32 v10, s2, v116
	v_mul_u32_u24_e32 v10, 0xb00, v10
	v_cvt_pk_bf16_f32 v2, v196, v197
	v_lshlrev_b32_e32 v68, 1, v10
	v_cvt_pk_bf16_f32 v3, v198, v199
	v_lshl_add_u64 v[10:11], v[8:9], 0, v[68:69]
	v_cvt_pk_bf16_f32 v4, v200, v201
	v_cvt_pk_bf16_f32 v5, v202, v203
	global_store_dwordx4 v[10:11], v[2:5], off
	s_nop 1
	v_or_b32_e32 v10, s2, v117
	s_waitcnt lgkmcnt(0)
	v_cvt_pk_bf16_f32 v2, v204, v205
	v_mul_u32_u24_e32 v10, 0xb00, v10
	v_cvt_pk_bf16_f32 v3, v206, v207
	v_lshlrev_b32_e32 v68, 1, v10
	v_cvt_pk_bf16_f32 v4, v208, v209
	v_cvt_pk_bf16_f32 v5, v210, v211
	v_lshl_add_u64 v[10:11], v[8:9], 0, v[68:69]
	global_store_dwordx4 v[10:11], v[2:5], off
	s_nop 1
	s_nop 0
	v_cvt_pk_bf16_f32 v2, v212, v213
	v_cvt_pk_bf16_f32 v3, v214, v215
	v_cvt_pk_bf16_f32 v4, v216, v217
	v_cvt_pk_bf16_f32 v5, v218, v219
	v_or_b32_e32 v6, s2, v118
	v_mul_u32_u24_e32 v6, 0xb00, v6
	v_lshlrev_b32_e32 v68, 1, v6
	v_lshl_add_u64 v[6:7], v[8:9], 0, v[68:69]
	global_store_dwordx4 v[6:7], v[2:5], off
	s_nop 1
	s_waitcnt lgkmcnt(0)

.LBB0_516:
	s_waitcnt vmcnt(0)
	v_pk_mul_f32 v[2:3], v[2:3], v[218:219] op_sel_hi:[1,0]
	v_add_u32_e32 v6, 0x1040, v19
	ds_write2_b32 v6, v2, v3 offset1:1
	v_pk_mul_f32 v[2:3], v[4:5], v[218:219] op_sel_hi:[1,0]
	v_add_u32_e32 v4, 0x1048, v19
	ds_write2_b32 v4, v2, v3 offset1:1
	s_lshl_b32 s0, s25, 6
	s_waitcnt lgkmcnt(0)
	s_and_b32 s0, 0xffff, s0
	s_lshl_b32 s1, s0, 1
	v_add_u32_e32 v10, 0x400, v111
	ds_read2_b32 v[188:189], v111 offset1:65
	ds_read2_b32 v[190:191], v111 offset0:130 offset1:195
	ds_read2_b32 v[192:193], v10 offset0:4 offset1:69
	ds_read2_b32 v[194:195], v10 offset0:134 offset1:199
	ds_read2_b32 v[196:197], v111 offset0:8 offset1:73
	ds_read2_b32 v[198:199], v111 offset0:138 offset1:203
	ds_read2_b32 v[200:201], v10 offset0:12 offset1:77
	ds_read2_b32 v[202:203], v10 offset0:142 offset1:207
	s_and_b32 s1, s1, 0x1f00
	s_and_b32 s0, s0, 64
	s_waitcnt lgkmcnt(7)
	ds_read2_b32 v[204:205], v111 offset0:16 offset1:81
	ds_read2_b32 v[206:207], v111 offset0:146 offset1:211
	ds_read2_b32 v[208:209], v10 offset0:20 offset1:85
	ds_read2_b32 v[210:211], v10 offset0:150 offset1:215
	ds_read2_b32 v[212:213], v111 offset0:24 offset1:89
	ds_read2_b32 v[214:215], v111 offset0:154 offset1:219
	ds_read2_b32 v[216:217], v10 offset0:28 offset1:93
	ds_read2_b32 v[218:219], v10 offset0:158 offset1:223
	s_waitcnt lgkmcnt(8)
	v_cvt_pk_bf16_f32 v4, v188, v189
	s_or_b32 s0, s0, s1
	v_cvt_pk_bf16_f32 v5, v190, v191
	s_bitset1_b32 s0, 7
	v_cvt_pk_bf16_f32 v6, v192, v193
	s_lshl_b32 s12, s24, 1
	v_cvt_pk_bf16_f32 v7, v194, v195
	v_or_b32_e32 v8, s0, v110
	v_lshl_add_u64 v[2:3], v[80:81], 0, s[12:13]
	v_lshlrev_b32_e32 v68, 11, v8
	v_lshl_add_u64 v[8:9], v[2:3], 0, v[68:69]
	global_store_dwordx4 v[8:9], v[4:7], off
	s_nop 1
	v_cvt_pk_bf16_f32 v4, v196, v197
	v_cvt_pk_bf16_f32 v5, v198, v199
	v_cvt_pk_bf16_f32 v6, v200, v201
	v_cvt_pk_bf16_f32 v7, v202, v203
	v_or_b32_e32 v8, s0, v112
	v_lshlrev_b32_e32 v68, 11, v8
	v_lshl_add_u64 v[8:9], v[2:3], 0, v[68:69]
	global_store_dwordx4 v[8:9], v[4:7], off
	s_nop 1
	s_waitcnt lgkmcnt(7)
	ds_read2_b32 v[188:189], v111 offset0:32 offset1:97
	ds_read2_b32 v[190:191], v111 offset0:162 offset1:227
	ds_read2_b32 v[192:193], v10 offset0:36 offset1:101
	ds_read2_b32 v[194:195], v10 offset0:166 offset1:231
	ds_read2_b32 v[196:197], v111 offset0:40 offset1:105
	ds_read2_b32 v[198:199], v111 offset0:170 offset1:235
	ds_read2_b32 v[200:201], v10 offset0:44 offset1:109
	ds_read2_b32 v[202:203], v10 offset0:174 offset1:239
	s_waitcnt lgkmcnt(8)
	v_cvt_pk_bf16_f32 v4, v204, v205
	v_cvt_pk_bf16_f32 v5, v206, v207
	v_cvt_pk_bf16_f32 v6, v208, v209
	v_cvt_pk_bf16_f32 v7, v210, v211
	v_or_b32_e32 v8, s0, v113
	v_lshlrev_b32_e32 v68, 11, v8
	v_lshl_add_u64 v[8:9], v[2:3], 0, v[68:69]
	global_store_dwordx4 v[8:9], v[4:7], off
	s_nop 1
	v_cvt_pk_bf16_f32 v4, v212, v213
	v_cvt_pk_bf16_f32 v5, v214, v215
	v_cvt_pk_bf16_f32 v6, v216, v217
	v_cvt_pk_bf16_f32 v7, v218, v219
	v_or_b32_e32 v8, s0, v114
	v_lshlrev_b32_e32 v68, 11, v8
	v_lshl_add_u64 v[8:9], v[2:3], 0, v[68:69]
	global_store_dwordx4 v[8:9], v[4:7], off
	s_nop 1
	s_waitcnt lgkmcnt(7)
	ds_read2_b32 v[204:205], v111 offset0:48 offset1:113
	ds_read2_b32 v[206:207], v111 offset0:178 offset1:243
	ds_read2_b32 v[208:209], v10 offset0:52 offset1:117
	ds_read2_b32 v[210:211], v10 offset0:182 offset1:247
	ds_read2_b32 v[212:213], v111 offset0:56 offset1:121
	ds_read2_b32 v[214:215], v111 offset0:186 offset1:251
	ds_read2_b32 v[216:217], v10 offset0:60 offset1:125
	ds_read2_b32 v[218:219], v10 offset0:190 offset1:255
	s_waitcnt lgkmcnt(8)
	v_cvt_pk_bf16_f32 v4, v188, v189
	v_cvt_pk_bf16_f32 v5, v190, v191
	v_cvt_pk_bf16_f32 v6, v192, v193
	v_cvt_pk_bf16_f32 v7, v194, v195
	v_or_b32_e32 v8, s0, v115
	v_lshlrev_b32_e32 v68, 11, v8
	v_lshl_add_u64 v[8:9], v[2:3], 0, v[68:69]
	global_store_dwordx4 v[8:9], v[4:7], off
	s_nop 1
	v_cvt_pk_bf16_f32 v4, v196, v197
	v_cvt_pk_bf16_f32 v5, v198, v199
	v_cvt_pk_bf16_f32 v6, v200, v201
	v_cvt_pk_bf16_f32 v7, v202, v203
	v_or_b32_e32 v8, s0, v116
	v_lshlrev_b32_e32 v68, 11, v8
	v_lshl_add_u64 v[8:9], v[2:3], 0, v[68:69]
	global_store_dwordx4 v[8:9], v[4:7], off
	s_nop 1
	s_waitcnt lgkmcnt(0)
	v_cvt_pk_bf16_f32 v4, v204, v205
	v_cvt_pk_bf16_f32 v5, v206, v207
	v_cvt_pk_bf16_f32 v6, v208, v209
	v_cvt_pk_bf16_f32 v7, v210, v211
	v_or_b32_e32 v8, s0, v117
	v_lshlrev_b32_e32 v68, 11, v8
	v_lshl_add_u64 v[8:9], v[2:3], 0, v[68:69]
	global_store_dwordx4 v[8:9], v[4:7], off
	s_nop 1
	v_cvt_pk_bf16_f32 v4, v212, v213
	v_cvt_pk_bf16_f32 v5, v214, v215
	v_cvt_pk_bf16_f32 v6, v216, v217
	v_cvt_pk_bf16_f32 v7, v218, v219
	v_or_b32_e32 v8, s0, v118
	v_lshlrev_b32_e32 v68, 11, v8
	v_lshl_add_u64 v[2:3], v[2:3], 0, v[68:69]
	global_store_dwordx4 v[2:3], v[4:7], off
	s_nop 1
	s_waitcnt lgkmcnt(0)

.LBB0_543:
	s_waitcnt vmcnt(0)
	v_pk_mul_f32 v[2:3], v[2:3], v[218:219] op_sel_hi:[1,0]
	v_add_u32_e32 v6, 0x1040, v19
	ds_write2_b32 v6, v2, v3 offset1:1
	v_pk_mul_f32 v[2:3], v[4:5], v[218:219] op_sel_hi:[1,0]
	v_add_u32_e32 v4, 0x1048, v19
	ds_write2_b32 v4, v2, v3 offset1:1
	s_waitcnt lgkmcnt(0)
	v_add_u32_e32 v10, 0x400, v111
	ds_read2_b32 v[188:189], v111 offset1:65
	ds_read2_b32 v[190:191], v111 offset0:130 offset1:195
	ds_read2_b32 v[192:193], v10 offset0:4 offset1:69
	ds_read2_b32 v[194:195], v10 offset0:134 offset1:199
	ds_read2_b32 v[196:197], v111 offset0:8 offset1:73
	ds_read2_b32 v[198:199], v111 offset0:138 offset1:203
	ds_read2_b32 v[200:201], v10 offset0:12 offset1:77
	ds_read2_b32 v[202:203], v10 offset0:142 offset1:207
	s_lshl_b32 s0, s24, 6
	s_lshl_b32 s1, s24, 7
	s_waitcnt lgkmcnt(7)
	ds_read2_b32 v[204:205], v111 offset0:16 offset1:81
	ds_read2_b32 v[206:207], v111 offset0:146 offset1:211
	ds_read2_b32 v[208:209], v10 offset0:20 offset1:85
	ds_read2_b32 v[210:211], v10 offset0:150 offset1:215
	ds_read2_b32 v[212:213], v111 offset0:24 offset1:89
	ds_read2_b32 v[214:215], v111 offset0:154 offset1:219
	ds_read2_b32 v[216:217], v10 offset0:28 offset1:93
	ds_read2_b32 v[218:219], v10 offset0:158 offset1:223
	s_waitcnt lgkmcnt(8)
	v_cvt_pk_bf16_f32 v4, v188, v189
	s_and_b32 s1, s1, 0x1f00
	s_and_b32 s0, s0, 64
	v_cvt_pk_bf16_f32 v5, v190, v191
	s_or_b32 s0, s1, s0
	v_cvt_pk_bf16_f32 v6, v192, v193
	s_lshl_b32 s12, s3, 1
	v_cvt_pk_bf16_f32 v7, v194, v195
	v_or_b32_e32 v8, s0, v110
	v_lshl_add_u64 v[2:3], v[80:81], 0, s[12:13]
	v_lshlrev_b32_e32 v68, 11, v8
	v_lshl_add_u64 v[8:9], v[2:3], 0, v[68:69]
	global_store_dwordx4 v[8:9], v[4:7], off
	s_nop 1
	v_cvt_pk_bf16_f32 v4, v196, v197
	v_cvt_pk_bf16_f32 v5, v198, v199
	v_cvt_pk_bf16_f32 v6, v200, v201
	v_cvt_pk_bf16_f32 v7, v202, v203
	v_or_b32_e32 v8, s0, v112
	v_lshlrev_b32_e32 v68, 11, v8
	v_lshl_add_u64 v[8:9], v[2:3], 0, v[68:69]
	global_store_dwordx4 v[8:9], v[4:7], off
	s_nop 1
	s_waitcnt lgkmcnt(7)
	ds_read2_b32 v[188:189], v111 offset0:32 offset1:97
	ds_read2_b32 v[190:191], v111 offset0:162 offset1:227
	ds_read2_b32 v[192:193], v10 offset0:36 offset1:101
	ds_read2_b32 v[194:195], v10 offset0:166 offset1:231
	ds_read2_b32 v[196:197], v111 offset0:40 offset1:105
	ds_read2_b32 v[198:199], v111 offset0:170 offset1:235
	ds_read2_b32 v[200:201], v10 offset0:44 offset1:109
	ds_read2_b32 v[202:203], v10 offset0:174 offset1:239
	s_waitcnt lgkmcnt(8)
	v_cvt_pk_bf16_f32 v4, v204, v205
	v_cvt_pk_bf16_f32 v5, v206, v207
	v_cvt_pk_bf16_f32 v6, v208, v209
	v_cvt_pk_bf16_f32 v7, v210, v211
	v_or_b32_e32 v8, s0, v113
	v_lshlrev_b32_e32 v68, 11, v8
	v_lshl_add_u64 v[8:9], v[2:3], 0, v[68:69]
	global_store_dwordx4 v[8:9], v[4:7], off
	s_nop 1
	v_cvt_pk_bf16_f32 v4, v212, v213
	v_cvt_pk_bf16_f32 v5, v214, v215
	v_cvt_pk_bf16_f32 v6, v216, v217
	v_cvt_pk_bf16_f32 v7, v218, v219
	v_or_b32_e32 v8, s0, v114
	v_lshlrev_b32_e32 v68, 11, v8
	v_lshl_add_u64 v[8:9], v[2:3], 0, v[68:69]
	global_store_dwordx4 v[8:9], v[4:7], off
	s_nop 1
	s_waitcnt lgkmcnt(7)
	ds_read2_b32 v[204:205], v111 offset0:48 offset1:113
	ds_read2_b32 v[206:207], v111 offset0:178 offset1:243
	ds_read2_b32 v[208:209], v10 offset0:52 offset1:117
	ds_read2_b32 v[210:211], v10 offset0:182 offset1:247
	ds_read2_b32 v[212:213], v111 offset0:56 offset1:121
	ds_read2_b32 v[214:215], v111 offset0:186 offset1:251
	ds_read2_b32 v[216:217], v10 offset0:60 offset1:125
	ds_read2_b32 v[218:219], v10 offset0:190 offset1:255
	s_waitcnt lgkmcnt(8)
	v_cvt_pk_bf16_f32 v4, v188, v189
	v_cvt_pk_bf16_f32 v5, v190, v191
	v_cvt_pk_bf16_f32 v6, v192, v193
	v_cvt_pk_bf16_f32 v7, v194, v195
	v_or_b32_e32 v8, s0, v115
	v_lshlrev_b32_e32 v68, 11, v8
	v_lshl_add_u64 v[8:9], v[2:3], 0, v[68:69]
	global_store_dwordx4 v[8:9], v[4:7], off
	s_nop 1
	v_cvt_pk_bf16_f32 v4, v196, v197
	v_cvt_pk_bf16_f32 v5, v198, v199
	v_cvt_pk_bf16_f32 v6, v200, v201
	v_cvt_pk_bf16_f32 v7, v202, v203
	v_or_b32_e32 v8, s0, v116
	v_lshlrev_b32_e32 v68, 11, v8
	v_lshl_add_u64 v[8:9], v[2:3], 0, v[68:69]
	global_store_dwordx4 v[8:9], v[4:7], off
	s_nop 1
	s_waitcnt lgkmcnt(0)
	v_cvt_pk_bf16_f32 v4, v204, v205
	v_cvt_pk_bf16_f32 v5, v206, v207
	v_cvt_pk_bf16_f32 v6, v208, v209
	v_cvt_pk_bf16_f32 v7, v210, v211
	v_or_b32_e32 v8, s0, v117
	v_lshlrev_b32_e32 v68, 11, v8
	v_lshl_add_u64 v[8:9], v[2:3], 0, v[68:69]
	global_store_dwordx4 v[8:9], v[4:7], off
	s_nop 1
	v_cvt_pk_bf16_f32 v4, v212, v213
	v_cvt_pk_bf16_f32 v5, v214, v215
	v_cvt_pk_bf16_f32 v6, v216, v217
	v_cvt_pk_bf16_f32 v7, v218, v219
	v_or_b32_e32 v8, s0, v118
	v_lshlrev_b32_e32 v68, 11, v8
	v_lshl_add_u64 v[2:3], v[2:3], 0, v[68:69]
	global_store_dwordx4 v[2:3], v[4:7], off
	s_nop 1
	s_waitcnt lgkmcnt(0)

.LBB0_545:
	s_andn2_b64 vcc, exec, s[0:1]
	s_cbranch_vccnz .LBB0_439
	s_cmpk_gt_i32 s29, 0x2bf
	s_mov_b64 s[0:1], -1
	s_cbranch_scc0 .LBB0_576
	s_cmpk_gt_u32 s29, 0x57f
	s_cbranch_scc0 .LBB0_549
	s_and_b32 s0, s39, 0x7fffffc0
	s_addk_i32 s0, 0xea00
	s_and_b32 s2, s31, 0x3c0
	v_or_b32_e32 v68, s0, v66
	s_lshl_b32 s12, s2, 2
	v_or_b32_e32 v4, 4, v68
	v_mov_b32_e32 v5, v69
	v_lshl_add_u64 v[62:63], v[100:101], 0, s[12:13]
	v_lshlrev_b64 v[2:3], 12, v[68:69]
	v_lshlrev_b64 v[4:5], 12, v[4:5]
	v_lshl_add_u64 v[2:3], v[62:63], 0, v[2:3]
	s_waitcnt vmcnt(0)
	v_lshl_add_u64 v[6:7], v[62:63], 0, v[4:5]
	global_load_dwordx4 v[2:5], v[2:3], off nt
	s_nop 0
	global_load_dwordx4 v[6:9], v[6:7], off nt
	v_or_b32_e32 v10, 8, v68
	v_mov_b32_e32 v11, v69
	v_or_b32_e32 v12, 12, v68
	v_mov_b32_e32 v13, v69
	v_lshlrev_b64 v[10:11], 12, v[10:11]
	v_lshlrev_b64 v[12:13], 12, v[12:13]
	v_lshl_add_u64 v[10:11], v[62:63], 0, v[10:11]
	v_lshl_add_u64 v[14:15], v[62:63], 0, v[12:13]
	global_load_dwordx4 v[10:13], v[10:11], off nt
	s_nop 0
	global_load_dwordx4 v[14:17], v[14:15], off nt
	v_or_b32_e32 v18, 16, v68
	v_mov_b32_e32 v19, v69
	v_or_b32_e32 v20, 20, v68
	v_mov_b32_e32 v21, v69
	v_lshlrev_b64 v[18:19], 12, v[18:19]
	v_lshlrev_b64 v[20:21], 12, v[20:21]
	v_lshl_add_u64 v[18:19], v[62:63], 0, v[18:19]
	v_lshl_add_u64 v[22:23], v[62:63], 0, v[20:21]
	global_load_dwordx4 v[18:21], v[18:19], off nt
	s_nop 0
	global_load_dwordx4 v[22:25], v[22:23], off nt
	v_or_b32_e32 v26, 24, v68
	v_mov_b32_e32 v27, v69
	v_or_b32_e32 v28, 28, v68
	v_mov_b32_e32 v29, v69
	v_lshlrev_b64 v[26:27], 12, v[26:27]
	v_lshlrev_b64 v[28:29], 12, v[28:29]
	v_lshl_add_u64 v[26:27], v[62:63], 0, v[26:27]
	v_lshl_add_u64 v[30:31], v[62:63], 0, v[28:29]
	global_load_dwordx4 v[26:29], v[26:27], off nt
	s_nop 0
	global_load_dwordx4 v[30:33], v[30:31], off nt
	v_or_b32_e32 v34, 32, v68
	v_mov_b32_e32 v35, v69
	v_or_b32_e32 v36, 36, v68
	v_mov_b32_e32 v37, v69
	v_lshlrev_b64 v[34:35], 12, v[34:35]
	v_lshlrev_b64 v[36:37], 12, v[36:37]
	v_lshl_add_u64 v[34:35], v[62:63], 0, v[34:35]
	v_lshl_add_u64 v[38:39], v[62:63], 0, v[36:37]
	global_load_dwordx4 v[34:37], v[34:35], off nt
	s_nop 0
	global_load_dwordx4 v[38:41], v[38:39], off nt
	v_or_b32_e32 v42, 40, v68
	v_mov_b32_e32 v43, v69
	v_or_b32_e32 v44, 44, v68
	v_mov_b32_e32 v45, v69
	v_lshlrev_b64 v[42:43], 12, v[42:43]
	v_lshlrev_b64 v[44:45], 12, v[44:45]
	v_lshl_add_u64 v[42:43], v[62:63], 0, v[42:43]
	v_lshl_add_u64 v[46:47], v[62:63], 0, v[44:45]
	global_load_dwordx4 v[42:45], v[42:43], off nt
	s_nop 0
	global_load_dwordx4 v[46:49], v[46:47], off nt
	v_or_b32_e32 v50, 48, v68
	v_mov_b32_e32 v51, v69
	v_lshlrev_b64 v[50:51], 12, v[50:51]
	v_lshl_add_u64 v[50:51], v[62:63], 0, v[50:51]
	v_or_b32_e32 v54, 52, v68
	v_mov_b32_e32 v55, v69
	global_load_dwordx4 v[50:53], v[50:51], off nt
	v_lshlrev_b64 v[54:55], 12, v[54:55]
	v_lshl_add_u64 v[54:55], v[62:63], 0, v[54:55]
	v_or_b32_e32 v58, 56, v68
	v_mov_b32_e32 v59, v69
	global_load_dwordx4 v[54:57], v[54:55], off nt
	v_lshlrev_b64 v[58:59], 12, v[58:59]
	v_lshl_add_u64 v[58:59], v[62:63], 0, v[58:59]
	v_or_b32_e32 v68, 60, v68
	global_load_dwordx4 v[58:61], v[58:59], off nt
	v_lshlrev_b64 v[64:65], 12, v[68:69]
	v_lshl_add_u64 v[62:63], v[62:63], 0, v[64:65]
	global_load_dwordx4 v[62:65], v[62:63], off nt
	v_add_u32_e32 v68, 0x410, v109
	s_mov_b32 s1, s13
	s_waitcnt vmcnt(15)
	ds_write2_b32 v109, v2, v3 offset1:1
	ds_write2_b32 v109, v4, v5 offset0:2 offset1:3
	s_waitcnt vmcnt(14)
	ds_write2_b32 v68, v6, v7 offset1:1
	v_add_u32_e32 v2, 0x418, v109
	ds_write2_b32 v2, v8, v9 offset1:1
	v_add_u32_e32 v2, 0x820, v109
	v_lshl_add_u64 v[8:9], s[0:1], 1, v[82:83]
	s_mov_b64 s[0:1], 0
	s_waitcnt vmcnt(13)
	ds_write2_b32 v2, v10, v11 offset1:1
	v_add_u32_e32 v2, 0x828, v109
	ds_write2_b32 v2, v12, v13 offset1:1
	v_add_u32_e32 v2, 0xc30, v109
	s_waitcnt vmcnt(12)
	ds_write2_b32 v2, v14, v15 offset1:1
	v_add_u32_e32 v2, 0xc38, v109
	ds_write2_b32 v2, v16, v17 offset1:1
	v_add_u32_e32 v2, 0x1040, v109
	v_or_b32_e32 v10, s2, v110
	s_waitcnt vmcnt(11)
	ds_write2_b32 v2, v18, v19 offset1:1
	v_add_u32_e32 v2, 0x1048, v109
	ds_write2_b32 v2, v20, v21 offset1:1
	v_add_u32_e32 v2, 0x1450, v109
	s_waitcnt vmcnt(10)
	ds_write2_b32 v2, v22, v23 offset1:1
	v_add_u32_e32 v2, 0x1458, v109
	ds_write2_b32 v2, v24, v25 offset1:1
	v_add_u32_e32 v2, 0x1860, v109
	v_mul_u32_u24_e32 v10, 0xb00, v10
	s_waitcnt vmcnt(9)
	ds_write2_b32 v2, v26, v27 offset1:1
	v_add_u32_e32 v2, 0x1868, v109
	ds_write2_b32 v2, v28, v29 offset1:1
	v_add_u32_e32 v2, 0x1c70, v109
	s_waitcnt vmcnt(8)
	ds_write2_b32 v2, v30, v31 offset1:1
	v_add_u32_e32 v2, 0x1c78, v109
	ds_write2_b32 v2, v32, v33 offset1:1
	v_add_u32_e32 v2, 0x2080, v109
	v_add_u32_e32 v12, 0x400, v111
	s_waitcnt vmcnt(7)
	ds_write2_b32 v2, v34, v35 offset1:1
	v_add_u32_e32 v2, 0x2088, v109
	ds_write2_b32 v2, v36, v37 offset1:1
	v_add_u32_e32 v2, 0x2490, v109
	s_waitcnt vmcnt(6)
	ds_write2_b32 v2, v38, v39 offset1:1
	v_add_u32_e32 v2, 0x2498, v109
	ds_write2_b32 v2, v40, v41 offset1:1
	v_add_u32_e32 v2, 0x28a0, v109
	v_lshlrev_b32_e32 v68, 1, v10
	s_waitcnt vmcnt(5)
	ds_write2_b32 v2, v42, v43 offset1:1
	v_add_u32_e32 v2, 0x28a8, v109
	ds_write2_b32 v2, v44, v45 offset1:1
	v_add_u32_e32 v2, 0x2cb0, v109
	s_waitcnt vmcnt(4)
	ds_write2_b32 v2, v46, v47 offset1:1
	v_add_u32_e32 v2, 0x2cb8, v109
	ds_write2_b32 v2, v48, v49 offset1:1
	v_add_u32_e32 v2, 0x30c0, v109
	s_waitcnt vmcnt(3)
	ds_write2_b32 v2, v50, v51 offset1:1
	v_add_u32_e32 v2, 0x30c8, v109
	ds_write2_b32 v2, v52, v53 offset1:1
	v_add_u32_e32 v2, 0x34d0, v109
	v_lshl_add_u64 v[10:11], v[8:9], 0, v[68:69]
	s_waitcnt vmcnt(2)
	ds_write2_b32 v2, v54, v55 offset1:1
	v_add_u32_e32 v2, 0x34d8, v109
	ds_write2_b32 v2, v56, v57 offset1:1
	v_add_u32_e32 v2, 0x38e0, v109
	s_waitcnt vmcnt(1)
	ds_write2_b32 v2, v58, v59 offset1:1
	v_add_u32_e32 v2, 0x38e8, v109
	ds_write2_b32 v2, v60, v61 offset1:1
	v_add_u32_e32 v2, 0x3cf0, v109
	s_waitcnt vmcnt(0)
	ds_write2_b32 v2, v62, v63 offset1:1
	v_add_u32_e32 v2, 0x3cf8, v109
	ds_write2_b32 v2, v64, v65 offset1:1
	s_waitcnt lgkmcnt(0)
	ds_read2_b32 v[188:189], v111 offset1:65
	ds_read2_b32 v[190:191], v111 offset0:130 offset1:195
	ds_read2_b32 v[192:193], v12 offset0:4 offset1:69
	ds_read2_b32 v[194:195], v12 offset0:134 offset1:199
	ds_read2_b32 v[196:197], v111 offset0:8 offset1:73
	ds_read2_b32 v[198:199], v111 offset0:138 offset1:203
	ds_read2_b32 v[200:201], v12 offset0:12 offset1:77
	ds_read2_b32 v[202:203], v12 offset0:142 offset1:207
	s_waitcnt lgkmcnt(7)
	ds_read2_b32 v[204:205], v111 offset0:16 offset1:81
	ds_read2_b32 v[206:207], v111 offset0:146 offset1:211
	ds_read2_b32 v[208:209], v12 offset0:20 offset1:85
	ds_read2_b32 v[210:211], v12 offset0:150 offset1:215
	ds_read2_b32 v[212:213], v111 offset0:24 offset1:89
	ds_read2_b32 v[214:215], v111 offset0:154 offset1:219
	ds_read2_b32 v[216:217], v12 offset0:28 offset1:93
	ds_read2_b32 v[218:219], v12 offset0:158 offset1:223
	s_waitcnt lgkmcnt(8)
	v_cvt_pk_bf16_f32 v2, v188, v189
	v_cvt_pk_bf16_f32 v3, v190, v191
	v_cvt_pk_bf16_f32 v4, v192, v193
	v_cvt_pk_bf16_f32 v5, v194, v195
	global_store_dwordx4 v[10:11], v[2:5], off
	s_nop 1
	v_or_b32_e32 v10, s2, v112
	v_mul_u32_u24_e32 v10, 0xb00, v10
	v_cvt_pk_bf16_f32 v2, v196, v197
	v_lshlrev_b32_e32 v68, 1, v10
	v_cvt_pk_bf16_f32 v3, v198, v199
	v_lshl_add_u64 v[10:11], v[8:9], 0, v[68:69]
	v_cvt_pk_bf16_f32 v4, v200, v201
	v_cvt_pk_bf16_f32 v5, v202, v203
	global_store_dwordx4 v[10:11], v[2:5], off
	s_nop 1
	v_or_b32_e32 v10, s2, v113
	v_mul_u32_u24_e32 v10, 0xb00, v10
	s_waitcnt lgkmcnt(7)
	ds_read2_b32 v[188:189], v111 offset0:32 offset1:97
	ds_read2_b32 v[190:191], v111 offset0:162 offset1:227
	ds_read2_b32 v[192:193], v12 offset0:36 offset1:101
	ds_read2_b32 v[194:195], v12 offset0:166 offset1:231
	ds_read2_b32 v[196:197], v111 offset0:40 offset1:105
	ds_read2_b32 v[198:199], v111 offset0:170 offset1:235
	ds_read2_b32 v[200:201], v12 offset0:44 offset1:109
	ds_read2_b32 v[202:203], v12 offset0:174 offset1:239
	s_waitcnt lgkmcnt(8)
	v_cvt_pk_bf16_f32 v2, v204, v205
	v_lshlrev_b32_e32 v68, 1, v10
	v_cvt_pk_bf16_f32 v3, v206, v207
	v_lshl_add_u64 v[10:11], v[8:9], 0, v[68:69]
	v_cvt_pk_bf16_f32 v4, v208, v209
	v_cvt_pk_bf16_f32 v5, v210, v211
	global_store_dwordx4 v[10:11], v[2:5], off
	s_nop 1
	v_or_b32_e32 v10, s2, v114
	v_mul_u32_u24_e32 v10, 0xb00, v10
	v_cvt_pk_bf16_f32 v2, v212, v213
	v_lshlrev_b32_e32 v68, 1, v10
	v_cvt_pk_bf16_f32 v3, v214, v215
	v_lshl_add_u64 v[10:11], v[8:9], 0, v[68:69]
	v_cvt_pk_bf16_f32 v4, v216, v217
	v_cvt_pk_bf16_f32 v5, v218, v219
	global_store_dwordx4 v[10:11], v[2:5], off
	s_nop 1
	v_or_b32_e32 v10, s2, v115
	v_mul_u32_u24_e32 v10, 0xb00, v10
	s_waitcnt lgkmcnt(7)
	ds_read2_b32 v[204:205], v111 offset0:48 offset1:113
	ds_read2_b32 v[206:207], v111 offset0:178 offset1:243
	ds_read2_b32 v[208:209], v12 offset0:52 offset1:117
	ds_read2_b32 v[210:211], v12 offset0:182 offset1:247
	ds_read2_b32 v[212:213], v111 offset0:56 offset1:121
	ds_read2_b32 v[214:215], v111 offset0:186 offset1:251
	ds_read2_b32 v[216:217], v12 offset0:60 offset1:125
	ds_read2_b32 v[218:219], v12 offset0:190 offset1:255
	s_waitcnt lgkmcnt(8)
	v_cvt_pk_bf16_f32 v2, v188, v189
	v_lshlrev_b32_e32 v68, 1, v10
	v_cvt_pk_bf16_f32 v3, v190, v191
	v_lshl_add_u64 v[10:11], v[8:9], 0, v[68:69]
	v_cvt_pk_bf16_f32 v4, v192, v193
	v_cvt_pk_bf16_f32 v5, v194, v195
	global_store_dwordx4 v[10:11], v[2:5], off
	s_nop 1
	v_or_b32_e32 v10, s2, v116
	v_mul_u32_u24_e32 v10, 0xb00, v10
	v_cvt_pk_bf16_f32 v2, v196, v197
	v_lshlrev_b32_e32 v68, 1, v10
	v_cvt_pk_bf16_f32 v3, v198, v199
	v_lshl_add_u64 v[10:11], v[8:9], 0, v[68:69]
	v_cvt_pk_bf16_f32 v4, v200, v201
	v_cvt_pk_bf16_f32 v5, v202, v203
	global_store_dwordx4 v[10:11], v[2:5], off
	s_nop 1
	v_or_b32_e32 v10, s2, v117
	s_waitcnt lgkmcnt(0)
	v_cvt_pk_bf16_f32 v2, v204, v205
	v_mul_u32_u24_e32 v10, 0xb00, v10
	v_cvt_pk_bf16_f32 v3, v206, v207
	v_lshlrev_b32_e32 v68, 1, v10
	v_cvt_pk_bf16_f32 v4, v208, v209
	v_cvt_pk_bf16_f32 v5, v210, v211
	v_lshl_add_u64 v[10:11], v[8:9], 0, v[68:69]
	global_store_dwordx4 v[10:11], v[2:5], off
	s_nop 1
	v_or_b32_e32 v10, s2, v118
	v_cvt_pk_bf16_f32 v2, v212, v213
	v_cvt_pk_bf16_f32 v3, v214, v215
	v_cvt_pk_bf16_f32 v4, v216, v217
	v_cvt_pk_bf16_f32 v5, v218, v219
	v_mul_u32_u24_e32 v6, 0xb00, v10
	v_lshlrev_b32_e32 v68, 1, v6
	v_lshl_add_u64 v[6:7], v[8:9], 0, v[68:69]
	global_store_dwordx4 v[6:7], v[2:5], off
	s_nop 1
	s_waitcnt lgkmcnt(0)

.LBB0_574:
	s_waitcnt vmcnt(0)
	v_pk_mul_f32 v[2:3], v[2:3], v[218:219] op_sel_hi:[1,0]
	v_add_u32_e32 v6, 0x1040, v19
	ds_write2_b32 v6, v2, v3 offset1:1
	v_pk_mul_f32 v[2:3], v[4:5], v[218:219] op_sel_hi:[1,0]
	v_add_u32_e32 v4, 0x1048, v19
	ds_write2_b32 v4, v2, v3 offset1:1
	s_lshl_b32 s0, s24, 6
	s_waitcnt lgkmcnt(0)
	s_and_b32 s0, 0xffff, s0
	s_lshl_b32 s1, s0, 1
	v_add_u32_e32 v10, 0x400, v111
	ds_read2_b32 v[188:189], v111 offset1:65
	ds_read2_b32 v[190:191], v111 offset0:130 offset1:195
	ds_read2_b32 v[192:193], v10 offset0:4 offset1:69
	ds_read2_b32 v[194:195], v10 offset0:134 offset1:199
	ds_read2_b32 v[196:197], v111 offset0:8 offset1:73
	ds_read2_b32 v[198:199], v111 offset0:138 offset1:203
	ds_read2_b32 v[200:201], v10 offset0:12 offset1:77
	ds_read2_b32 v[202:203], v10 offset0:142 offset1:207
	s_and_b32 s1, s1, 0x1f00
	s_and_b32 s0, s0, 64
	s_waitcnt lgkmcnt(7)
	ds_read2_b32 v[204:205], v111 offset0:16 offset1:81
	ds_read2_b32 v[206:207], v111 offset0:146 offset1:211
	ds_read2_b32 v[208:209], v10 offset0:20 offset1:85
	ds_read2_b32 v[210:211], v10 offset0:150 offset1:215
	ds_read2_b32 v[212:213], v111 offset0:24 offset1:89
	ds_read2_b32 v[214:215], v111 offset0:154 offset1:219
	ds_read2_b32 v[216:217], v10 offset0:28 offset1:93
	ds_read2_b32 v[218:219], v10 offset0:158 offset1:223
	s_waitcnt lgkmcnt(8)
	v_cvt_pk_bf16_f32 v4, v188, v189
	s_or_b32 s0, s0, s1
	v_cvt_pk_bf16_f32 v5, v190, v191
	s_bitset1_b32 s0, 7
	v_cvt_pk_bf16_f32 v6, v192, v193
	s_lshl_b32 s12, s3, 1
	v_cvt_pk_bf16_f32 v7, v194, v195
	v_or_b32_e32 v8, s0, v110
	v_lshl_add_u64 v[2:3], v[84:85], 0, s[12:13]
	v_lshlrev_b32_e32 v68, 11, v8
	v_lshl_add_u64 v[8:9], v[2:3], 0, v[68:69]
	global_store_dwordx4 v[8:9], v[4:7], off
	s_nop 1
	v_cvt_pk_bf16_f32 v4, v196, v197
	v_cvt_pk_bf16_f32 v5, v198, v199
	v_cvt_pk_bf16_f32 v6, v200, v201
	v_cvt_pk_bf16_f32 v7, v202, v203
	v_or_b32_e32 v8, s0, v112
	v_lshlrev_b32_e32 v68, 11, v8
	v_lshl_add_u64 v[8:9], v[2:3], 0, v[68:69]
	global_store_dwordx4 v[8:9], v[4:7], off
	s_nop 1
	s_waitcnt lgkmcnt(7)
	ds_read2_b32 v[188:189], v111 offset0:32 offset1:97
	ds_read2_b32 v[190:191], v111 offset0:162 offset1:227
	ds_read2_b32 v[192:193], v10 offset0:36 offset1:101
	ds_read2_b32 v[194:195], v10 offset0:166 offset1:231
	ds_read2_b32 v[196:197], v111 offset0:40 offset1:105
	ds_read2_b32 v[198:199], v111 offset0:170 offset1:235
	ds_read2_b32 v[200:201], v10 offset0:44 offset1:109
	ds_read2_b32 v[202:203], v10 offset0:174 offset1:239
	s_waitcnt lgkmcnt(8)
	v_cvt_pk_bf16_f32 v4, v204, v205
	v_cvt_pk_bf16_f32 v5, v206, v207
	v_cvt_pk_bf16_f32 v6, v208, v209
	v_cvt_pk_bf16_f32 v7, v210, v211
	v_or_b32_e32 v8, s0, v113
	v_lshlrev_b32_e32 v68, 11, v8
	v_lshl_add_u64 v[8:9], v[2:3], 0, v[68:69]
	global_store_dwordx4 v[8:9], v[4:7], off
	s_nop 1
	v_cvt_pk_bf16_f32 v4, v212, v213
	v_cvt_pk_bf16_f32 v5, v214, v215
	v_cvt_pk_bf16_f32 v6, v216, v217
	v_cvt_pk_bf16_f32 v7, v218, v219
	v_or_b32_e32 v8, s0, v114
	v_lshlrev_b32_e32 v68, 11, v8
	v_lshl_add_u64 v[8:9], v[2:3], 0, v[68:69]
	global_store_dwordx4 v[8:9], v[4:7], off
	s_nop 1
	s_waitcnt lgkmcnt(7)
	ds_read2_b32 v[204:205], v111 offset0:48 offset1:113
	ds_read2_b32 v[206:207], v111 offset0:178 offset1:243
	ds_read2_b32 v[208:209], v10 offset0:52 offset1:117
	ds_read2_b32 v[210:211], v10 offset0:182 offset1:247
	ds_read2_b32 v[212:213], v111 offset0:56 offset1:121
	ds_read2_b32 v[214:215], v111 offset0:186 offset1:251
	ds_read2_b32 v[216:217], v10 offset0:60 offset1:125
	ds_read2_b32 v[218:219], v10 offset0:190 offset1:255
	s_waitcnt lgkmcnt(8)
	v_cvt_pk_bf16_f32 v4, v188, v189
	v_cvt_pk_bf16_f32 v5, v190, v191
	v_cvt_pk_bf16_f32 v6, v192, v193
	v_cvt_pk_bf16_f32 v7, v194, v195
	v_or_b32_e32 v8, s0, v115
	v_lshlrev_b32_e32 v68, 11, v8
	v_lshl_add_u64 v[8:9], v[2:3], 0, v[68:69]
	global_store_dwordx4 v[8:9], v[4:7], off
	s_nop 1
	v_cvt_pk_bf16_f32 v4, v196, v197
	v_cvt_pk_bf16_f32 v5, v198, v199
	v_cvt_pk_bf16_f32 v6, v200, v201
	v_cvt_pk_bf16_f32 v7, v202, v203
	v_or_b32_e32 v8, s0, v116
	v_lshlrev_b32_e32 v68, 11, v8
	v_lshl_add_u64 v[8:9], v[2:3], 0, v[68:69]
	global_store_dwordx4 v[8:9], v[4:7], off
	s_nop 1
	s_waitcnt lgkmcnt(0)
	v_cvt_pk_bf16_f32 v4, v204, v205
	v_cvt_pk_bf16_f32 v5, v206, v207
	v_cvt_pk_bf16_f32 v6, v208, v209
	v_cvt_pk_bf16_f32 v7, v210, v211
	v_or_b32_e32 v8, s0, v117
	v_lshlrev_b32_e32 v68, 11, v8
	v_lshl_add_u64 v[8:9], v[2:3], 0, v[68:69]
	global_store_dwordx4 v[8:9], v[4:7], off
	s_nop 1
	v_cvt_pk_bf16_f32 v4, v212, v213
	v_cvt_pk_bf16_f32 v5, v214, v215
	v_cvt_pk_bf16_f32 v6, v216, v217
	v_cvt_pk_bf16_f32 v7, v218, v219
	v_or_b32_e32 v8, s0, v118
	v_lshlrev_b32_e32 v68, 11, v8
	v_lshl_add_u64 v[2:3], v[2:3], 0, v[68:69]
	global_store_dwordx4 v[2:3], v[4:7], off
	s_nop 1
	s_waitcnt lgkmcnt(0)

.LBB0_1032:
	s_waitcnt vmcnt(0)
	v_pk_mul_f32 v[2:3], v[2:3], v[10:11] op_sel_hi:[1,0]
	v_add_u32_e32 v6, 0x1040, v19
	s_mulk_i32 s3, 0xea00
	ds_write2_b32 v6, v2, v3 offset1:1
	v_pk_mul_f32 v[2:3], v[4:5], v[10:11] op_sel_hi:[1,0]
	v_add_u32_e32 v4, 0x1048, v19
	s_add_i32 s1, s29, s3
	ds_write2_b32 v4, v2, v3 offset1:1
	s_and_b32 s0, s6, 64
	s_and_b32 s1, s1, 0xffffff00
	s_waitcnt lgkmcnt(0)
	s_or_b32 s0, s1, s0
	v_or_b32_e32 v10, s0, v110
	v_add_u32_e32 v12, 0x400, v111
	ds_read2_b32 v[188:189], v111 offset1:65
	ds_read2_b32 v[190:191], v111 offset0:130 offset1:195
	ds_read2_b32 v[192:193], v12 offset0:4 offset1:69
	ds_read2_b32 v[194:195], v12 offset0:134 offset1:199
	ds_read2_b32 v[196:197], v111 offset0:8 offset1:73
	ds_read2_b32 v[198:199], v111 offset0:138 offset1:203
	ds_read2_b32 v[200:201], v12 offset0:12 offset1:77
	ds_read2_b32 v[202:203], v12 offset0:142 offset1:207
	v_ashrrev_i32_e32 v11, 31, v10
	s_waitcnt lgkmcnt(7)
	ds_read2_b32 v[204:205], v111 offset0:16 offset1:81
	ds_read2_b32 v[206:207], v111 offset0:146 offset1:211
	ds_read2_b32 v[208:209], v12 offset0:20 offset1:85
	ds_read2_b32 v[210:211], v12 offset0:150 offset1:215
	ds_read2_b32 v[212:213], v111 offset0:24 offset1:89
	ds_read2_b32 v[214:215], v111 offset0:154 offset1:219
	ds_read2_b32 v[216:217], v12 offset0:28 offset1:93
	ds_read2_b32 v[218:219], v12 offset0:158 offset1:223
	s_waitcnt lgkmcnt(8)
	v_cvt_pk_bf16_f32 v2, v188, v189
	v_lshl_add_u64 v[6:7], s[10:11], 1, v[84:85]
	v_lshlrev_b64 v[10:11], 11, v[10:11]
	v_cvt_pk_bf16_f32 v3, v190, v191
	v_lshl_add_u64 v[10:11], v[6:7], 0, v[10:11]
	v_cvt_pk_bf16_f32 v4, v192, v193
	v_cvt_pk_bf16_f32 v5, v194, v195
	global_store_dwordx4 v[10:11], v[2:5], off
	s_nop 1
	v_or_b32_e32 v10, s0, v112
	v_ashrrev_i32_e32 v11, 31, v10
	v_cvt_pk_bf16_f32 v2, v196, v197
	v_lshlrev_b64 v[10:11], 11, v[10:11]
	v_cvt_pk_bf16_f32 v3, v198, v199
	v_lshl_add_u64 v[10:11], v[6:7], 0, v[10:11]
	v_cvt_pk_bf16_f32 v4, v200, v201
	v_cvt_pk_bf16_f32 v5, v202, v203
	global_store_dwordx4 v[10:11], v[2:5], off
	s_nop 1
	v_or_b32_e32 v10, s0, v113
	v_ashrrev_i32_e32 v11, 31, v10
	s_waitcnt lgkmcnt(7)
	ds_read2_b32 v[188:189], v111 offset0:32 offset1:97
	ds_read2_b32 v[190:191], v111 offset0:162 offset1:227
	ds_read2_b32 v[192:193], v12 offset0:36 offset1:101
	ds_read2_b32 v[194:195], v12 offset0:166 offset1:231
	ds_read2_b32 v[196:197], v111 offset0:40 offset1:105
	ds_read2_b32 v[198:199], v111 offset0:170 offset1:235
	ds_read2_b32 v[200:201], v12 offset0:44 offset1:109
	ds_read2_b32 v[202:203], v12 offset0:174 offset1:239
	s_waitcnt lgkmcnt(8)
	v_cvt_pk_bf16_f32 v2, v204, v205
	v_lshlrev_b64 v[10:11], 11, v[10:11]
	v_cvt_pk_bf16_f32 v3, v206, v207
	v_lshl_add_u64 v[10:11], v[6:7], 0, v[10:11]
	v_cvt_pk_bf16_f32 v4, v208, v209
	v_cvt_pk_bf16_f32 v5, v210, v211
	global_store_dwordx4 v[10:11], v[2:5], off
	s_nop 1
	v_or_b32_e32 v10, s0, v114
	v_ashrrev_i32_e32 v11, 31, v10
	v_cvt_pk_bf16_f32 v2, v212, v213
	v_lshlrev_b64 v[10:11], 11, v[10:11]
	v_cvt_pk_bf16_f32 v3, v214, v215
	v_lshl_add_u64 v[10:11], v[6:7], 0, v[10:11]
	v_cvt_pk_bf16_f32 v4, v216, v217
	v_cvt_pk_bf16_f32 v5, v218, v219
	global_store_dwordx4 v[10:11], v[2:5], off
	s_nop 1
	v_or_b32_e32 v10, s0, v115
	v_ashrrev_i32_e32 v11, 31, v10
	s_waitcnt lgkmcnt(7)
	ds_read2_b32 v[204:205], v111 offset0:48 offset1:113
	ds_read2_b32 v[206:207], v111 offset0:178 offset1:243
	ds_read2_b32 v[208:209], v12 offset0:52 offset1:117
	ds_read2_b32 v[210:211], v12 offset0:182 offset1:247
	ds_read2_b32 v[212:213], v111 offset0:56 offset1:121
	ds_read2_b32 v[214:215], v111 offset0:186 offset1:251
	ds_read2_b32 v[216:217], v12 offset0:60 offset1:125
	ds_read2_b32 v[218:219], v12 offset0:190 offset1:255
	s_waitcnt lgkmcnt(8)
	v_cvt_pk_bf16_f32 v2, v188, v189
	v_lshlrev_b64 v[10:11], 11, v[10:11]
	v_cvt_pk_bf16_f32 v3, v190, v191
	v_lshl_add_u64 v[10:11], v[6:7], 0, v[10:11]
	v_cvt_pk_bf16_f32 v4, v192, v193
	v_cvt_pk_bf16_f32 v5, v194, v195
	global_store_dwordx4 v[10:11], v[2:5], off
	s_nop 1
	v_or_b32_e32 v10, s0, v116
	v_ashrrev_i32_e32 v11, 31, v10
	v_cvt_pk_bf16_f32 v2, v196, v197
	v_lshlrev_b64 v[10:11], 11, v[10:11]
	v_cvt_pk_bf16_f32 v3, v198, v199
	v_lshl_add_u64 v[10:11], v[6:7], 0, v[10:11]
	v_cvt_pk_bf16_f32 v4, v200, v201
	v_cvt_pk_bf16_f32 v5, v202, v203
	global_store_dwordx4 v[10:11], v[2:5], off
	s_nop 1
	v_or_b32_e32 v10, s0, v117
	v_ashrrev_i32_e32 v11, 31, v10
	s_waitcnt lgkmcnt(0)
	v_cvt_pk_bf16_f32 v2, v204, v205
	v_lshlrev_b64 v[10:11], 11, v[10:11]
	v_cvt_pk_bf16_f32 v3, v206, v207
	v_lshl_add_u64 v[10:11], v[6:7], 0, v[10:11]
	v_cvt_pk_bf16_f32 v4, v208, v209
	v_cvt_pk_bf16_f32 v5, v210, v211
	global_store_dwordx4 v[10:11], v[2:5], off
	s_nop 1
	v_or_b32_e32 v10, s0, v118
	v_ashrrev_i32_e32 v11, 31, v10
	v_cvt_pk_bf16_f32 v2, v212, v213
	v_lshlrev_b64 v[10:11], 11, v[10:11]
	v_cvt_pk_bf16_f32 v3, v214, v215
	v_lshl_add_u64 v[6:7], v[6:7], 0, v[10:11]
	v_cvt_pk_bf16_f32 v4, v216, v217
	v_cvt_pk_bf16_f32 v5, v218, v219
	global_store_dwordx4 v[6:7], v[2:5], off
	s_nop 1
	s_waitcnt lgkmcnt(0)

.LBB0_1034:
	s_cmpk_gt_i32 s26, 0x83f
	s_mov_b64 s[0:1], -1
	s_cbranch_scc0 .LBB0_1139
	s_cmpk_gt_u32 s26, 0x107f
	s_cbranch_scc0 .LBB0_1081
	s_cmpk_gt_u32 s26, 0x167f
	s_cbranch_scc0 .LBB0_1050
	s_cmpk_gt_u32 s26, 0x177f
	s_cbranch_scc0 .LBB0_1047
	s_cmpk_gt_u32 s26, 0x197f
	s_cbranch_scc0 .LBB0_1040
	s_and_b32 s0, s31, 0x7fffffc0
	s_addk_i32 s0, 0x9a00
	s_and_b32 s3, s27, 0x3c0
	v_or_b32_e32 v68, s0, v66
	s_lshl_b32 s16, s3, 2
	v_or_b32_e32 v4, 4, v68
	v_mov_b32_e32 v5, v69
	v_lshl_add_u64 v[62:63], v[86:87], 0, s[16:17]
	v_lshlrev_b64 v[2:3], 12, v[68:69]
	v_lshlrev_b64 v[4:5], 12, v[4:5]
	v_lshl_add_u64 v[2:3], v[62:63], 0, v[2:3]
	v_lshl_add_u64 v[6:7], v[62:63], 0, v[4:5]
	global_load_dwordx4 v[2:5], v[2:3], off nt
	s_nop 0
	global_load_dwordx4 v[6:9], v[6:7], off nt
	v_or_b32_e32 v10, 8, v68
	v_mov_b32_e32 v11, v69
	v_or_b32_e32 v12, 12, v68
	v_mov_b32_e32 v13, v69
	v_lshlrev_b64 v[10:11], 12, v[10:11]
	v_lshlrev_b64 v[12:13], 12, v[12:13]
	v_lshl_add_u64 v[10:11], v[62:63], 0, v[10:11]
	v_lshl_add_u64 v[14:15], v[62:63], 0, v[12:13]
	global_load_dwordx4 v[10:13], v[10:11], off nt
	s_nop 0
	global_load_dwordx4 v[14:17], v[14:15], off nt
	v_or_b32_e32 v18, 16, v68
	v_mov_b32_e32 v19, v69
	v_or_b32_e32 v20, 20, v68
	v_mov_b32_e32 v21, v69
	v_lshlrev_b64 v[18:19], 12, v[18:19]
	v_lshlrev_b64 v[20:21], 12, v[20:21]
	v_lshl_add_u64 v[18:19], v[62:63], 0, v[18:19]
	v_lshl_add_u64 v[22:23], v[62:63], 0, v[20:21]
	global_load_dwordx4 v[18:21], v[18:19], off nt
	s_nop 0
	global_load_dwordx4 v[22:25], v[22:23], off nt
	v_or_b32_e32 v26, 24, v68
	v_mov_b32_e32 v27, v69
	v_or_b32_e32 v28, 28, v68
	v_mov_b32_e32 v29, v69
	v_lshlrev_b64 v[26:27], 12, v[26:27]
	v_lshlrev_b64 v[28:29], 12, v[28:29]
	v_lshl_add_u64 v[26:27], v[62:63], 0, v[26:27]
	v_lshl_add_u64 v[30:31], v[62:63], 0, v[28:29]
	global_load_dwordx4 v[26:29], v[26:27], off nt
	s_nop 0
	global_load_dwordx4 v[30:33], v[30:31], off nt
	v_or_b32_e32 v34, 32, v68
	v_mov_b32_e32 v35, v69
	v_or_b32_e32 v36, 36, v68
	v_mov_b32_e32 v37, v69
	v_lshlrev_b64 v[34:35], 12, v[34:35]
	v_lshlrev_b64 v[36:37], 12, v[36:37]
	v_lshl_add_u64 v[34:35], v[62:63], 0, v[34:35]
	v_lshl_add_u64 v[38:39], v[62:63], 0, v[36:37]
	global_load_dwordx4 v[34:37], v[34:35], off nt
	s_nop 0
	global_load_dwordx4 v[38:41], v[38:39], off nt
	v_or_b32_e32 v42, 40, v68
	v_mov_b32_e32 v43, v69
	v_or_b32_e32 v44, 44, v68
	v_mov_b32_e32 v45, v69
	v_lshlrev_b64 v[42:43], 12, v[42:43]
	v_lshlrev_b64 v[44:45], 12, v[44:45]
	v_lshl_add_u64 v[42:43], v[62:63], 0, v[42:43]
	v_lshl_add_u64 v[46:47], v[62:63], 0, v[44:45]
	global_load_dwordx4 v[42:45], v[42:43], off nt
	s_nop 0
	global_load_dwordx4 v[46:49], v[46:47], off nt
	v_or_b32_e32 v50, 48, v68
	v_mov_b32_e32 v51, v69
	v_lshlrev_b64 v[50:51], 12, v[50:51]
	v_lshl_add_u64 v[50:51], v[62:63], 0, v[50:51]
	v_or_b32_e32 v54, 52, v68
	v_mov_b32_e32 v55, v69
	global_load_dwordx4 v[50:53], v[50:51], off nt
	v_lshlrev_b64 v[54:55], 12, v[54:55]
	v_lshl_add_u64 v[54:55], v[62:63], 0, v[54:55]
	v_or_b32_e32 v58, 56, v68
	v_mov_b32_e32 v59, v69
	global_load_dwordx4 v[54:57], v[54:55], off nt
	v_lshlrev_b64 v[58:59], 12, v[58:59]
	v_lshl_add_u64 v[58:59], v[62:63], 0, v[58:59]
	v_or_b32_e32 v68, 60, v68
	global_load_dwordx4 v[58:61], v[58:59], off nt
	v_lshlrev_b64 v[64:65], 12, v[68:69]
	v_lshl_add_u64 v[62:63], v[62:63], 0, v[64:65]
	global_load_dwordx4 v[62:65], v[62:63], off nt
	v_add_u32_e32 v68, 0x410, v109
	s_mov_b32 s1, s17
	s_waitcnt vmcnt(15)
	ds_write2_b32 v109, v2, v3 offset1:1
	ds_write2_b32 v109, v4, v5 offset0:2 offset1:3
	s_waitcnt vmcnt(14)
	ds_write2_b32 v68, v6, v7 offset1:1
	v_add_u32_e32 v2, 0x418, v109
	ds_write2_b32 v2, v8, v9 offset1:1
	v_add_u32_e32 v2, 0x820, v109
	v_lshl_add_u64 v[8:9], s[0:1], 1, v[70:71]
	s_mov_b64 s[0:1], 0
	s_waitcnt vmcnt(13)
	ds_write2_b32 v2, v10, v11 offset1:1
	v_add_u32_e32 v2, 0x828, v109
	ds_write2_b32 v2, v12, v13 offset1:1
	v_add_u32_e32 v2, 0xc30, v109
	s_waitcnt vmcnt(12)
	ds_write2_b32 v2, v14, v15 offset1:1
	v_add_u32_e32 v2, 0xc38, v109
	ds_write2_b32 v2, v16, v17 offset1:1
	v_add_u32_e32 v2, 0x1040, v109
	v_add_u32_e32 v12, 0x400, v111
	s_waitcnt vmcnt(11)
	ds_write2_b32 v2, v18, v19 offset1:1
	v_add_u32_e32 v2, 0x1048, v109
	ds_write2_b32 v2, v20, v21 offset1:1
	v_add_u32_e32 v2, 0x1450, v109
	s_waitcnt vmcnt(10)
	ds_write2_b32 v2, v22, v23 offset1:1
	v_add_u32_e32 v2, 0x1458, v109
	ds_write2_b32 v2, v24, v25 offset1:1
	v_add_u32_e32 v2, 0x1860, v109
	v_or_b32_e32 v10, s3, v110
	s_waitcnt vmcnt(9)
	ds_write2_b32 v2, v26, v27 offset1:1
	v_add_u32_e32 v2, 0x1868, v109
	ds_write2_b32 v2, v28, v29 offset1:1
	v_add_u32_e32 v2, 0x1c70, v109
	s_waitcnt vmcnt(8)
	ds_write2_b32 v2, v30, v31 offset1:1
	v_add_u32_e32 v2, 0x1c78, v109
	ds_write2_b32 v2, v32, v33 offset1:1
	v_add_u32_e32 v2, 0x2080, v109
	v_lshlrev_b32_e32 v68, 11, v10
	s_waitcnt vmcnt(7)
	ds_write2_b32 v2, v34, v35 offset1:1
	v_add_u32_e32 v2, 0x2088, v109
	ds_write2_b32 v2, v36, v37 offset1:1
	v_add_u32_e32 v2, 0x2490, v109
	s_waitcnt vmcnt(6)
	ds_write2_b32 v2, v38, v39 offset1:1
	v_add_u32_e32 v2, 0x2498, v109
	ds_write2_b32 v2, v40, v41 offset1:1
	v_add_u32_e32 v2, 0x28a0, v109
	v_lshl_add_u64 v[10:11], v[8:9], 0, v[68:69]
	s_waitcnt vmcnt(5)
	ds_write2_b32 v2, v42, v43 offset1:1
	v_add_u32_e32 v2, 0x28a8, v109
	ds_write2_b32 v2, v44, v45 offset1:1
	v_add_u32_e32 v2, 0x2cb0, v109
	s_waitcnt vmcnt(4)
	ds_write2_b32 v2, v46, v47 offset1:1
	v_add_u32_e32 v2, 0x2cb8, v109
	ds_write2_b32 v2, v48, v49 offset1:1
	v_add_u32_e32 v2, 0x30c0, v109
	s_waitcnt vmcnt(3)
	ds_write2_b32 v2, v50, v51 offset1:1
	v_add_u32_e32 v2, 0x30c8, v109
	ds_write2_b32 v2, v52, v53 offset1:1
	v_add_u32_e32 v2, 0x34d0, v109
	s_waitcnt vmcnt(2)
	ds_write2_b32 v2, v54, v55 offset1:1
	v_add_u32_e32 v2, 0x34d8, v109
	ds_write2_b32 v2, v56, v57 offset1:1
	v_add_u32_e32 v2, 0x38e0, v109
	s_waitcnt vmcnt(1)
	ds_write2_b32 v2, v58, v59 offset1:1
	v_add_u32_e32 v2, 0x38e8, v109
	ds_write2_b32 v2, v60, v61 offset1:1
	v_add_u32_e32 v2, 0x3cf0, v109
	s_waitcnt vmcnt(0)
	ds_write2_b32 v2, v62, v63 offset1:1
	v_add_u32_e32 v2, 0x3cf8, v109
	ds_write2_b32 v2, v64, v65 offset1:1
	s_waitcnt lgkmcnt(0)
	ds_read2_b32 v[188:189], v111 offset1:65
	ds_read2_b32 v[190:191], v111 offset0:130 offset1:195
	ds_read2_b32 v[192:193], v12 offset0:4 offset1:69
	ds_read2_b32 v[194:195], v12 offset0:134 offset1:199
	ds_read2_b32 v[196:197], v111 offset0:8 offset1:73
	ds_read2_b32 v[198:199], v111 offset0:138 offset1:203
	ds_read2_b32 v[200:201], v12 offset0:12 offset1:77
	ds_read2_b32 v[202:203], v12 offset0:142 offset1:207
	s_waitcnt lgkmcnt(7)
	ds_read2_b32 v[204:205], v111 offset0:16 offset1:81
	ds_read2_b32 v[206:207], v111 offset0:146 offset1:211
	ds_read2_b32 v[208:209], v12 offset0:20 offset1:85
	ds_read2_b32 v[210:211], v12 offset0:150 offset1:215
	ds_read2_b32 v[212:213], v111 offset0:24 offset1:89
	ds_read2_b32 v[214:215], v111 offset0:154 offset1:219
	ds_read2_b32 v[216:217], v12 offset0:28 offset1:93
	ds_read2_b32 v[218:219], v12 offset0:158 offset1:223
	s_waitcnt lgkmcnt(8)
	v_cvt_pk_bf16_f32 v2, v188, v189
	v_cvt_pk_bf16_f32 v3, v190, v191
	v_cvt_pk_bf16_f32 v4, v192, v193
	v_cvt_pk_bf16_f32 v5, v194, v195
	global_store_dwordx4 v[10:11], v[2:5], off
	s_nop 1
	v_or_b32_e32 v10, s3, v112
	v_lshlrev_b32_e32 v68, 11, v10
	v_cvt_pk_bf16_f32 v2, v196, v197
	v_cvt_pk_bf16_f32 v3, v198, v199
	v_cvt_pk_bf16_f32 v4, v200, v201
	v_cvt_pk_bf16_f32 v5, v202, v203
	v_lshl_add_u64 v[10:11], v[8:9], 0, v[68:69]
	global_store_dwordx4 v[10:11], v[2:5], off
	s_nop 1
	v_or_b32_e32 v10, s3, v113
	v_lshlrev_b32_e32 v68, 11, v10
	s_waitcnt lgkmcnt(7)
	ds_read2_b32 v[188:189], v111 offset0:32 offset1:97
	ds_read2_b32 v[190:191], v111 offset0:162 offset1:227
	ds_read2_b32 v[192:193], v12 offset0:36 offset1:101
	ds_read2_b32 v[194:195], v12 offset0:166 offset1:231
	ds_read2_b32 v[196:197], v111 offset0:40 offset1:105
	ds_read2_b32 v[198:199], v111 offset0:170 offset1:235
	ds_read2_b32 v[200:201], v12 offset0:44 offset1:109
	ds_read2_b32 v[202:203], v12 offset0:174 offset1:239
	s_waitcnt lgkmcnt(8)
	v_cvt_pk_bf16_f32 v2, v204, v205
	v_cvt_pk_bf16_f32 v3, v206, v207
	v_cvt_pk_bf16_f32 v4, v208, v209
	v_cvt_pk_bf16_f32 v5, v210, v211
	v_lshl_add_u64 v[10:11], v[8:9], 0, v[68:69]
	global_store_dwordx4 v[10:11], v[2:5], off
	s_nop 1
	v_or_b32_e32 v10, s3, v114
	v_lshlrev_b32_e32 v68, 11, v10
	v_cvt_pk_bf16_f32 v2, v212, v213
	v_cvt_pk_bf16_f32 v3, v214, v215
	v_cvt_pk_bf16_f32 v4, v216, v217
	v_cvt_pk_bf16_f32 v5, v218, v219
	v_lshl_add_u64 v[10:11], v[8:9], 0, v[68:69]
	global_store_dwordx4 v[10:11], v[2:5], off
	s_nop 1
	v_or_b32_e32 v10, s3, v115
	v_lshlrev_b32_e32 v68, 11, v10
	s_waitcnt lgkmcnt(7)
	ds_read2_b32 v[204:205], v111 offset0:48 offset1:113
	ds_read2_b32 v[206:207], v111 offset0:178 offset1:243
	ds_read2_b32 v[208:209], v12 offset0:52 offset1:117
	ds_read2_b32 v[210:211], v12 offset0:182 offset1:247
	ds_read2_b32 v[212:213], v111 offset0:56 offset1:121
	ds_read2_b32 v[214:215], v111 offset0:186 offset1:251
	ds_read2_b32 v[216:217], v12 offset0:60 offset1:125
	ds_read2_b32 v[218:219], v12 offset0:190 offset1:255
	s_waitcnt lgkmcnt(8)
	v_cvt_pk_bf16_f32 v2, v188, v189
	v_cvt_pk_bf16_f32 v3, v190, v191
	v_cvt_pk_bf16_f32 v4, v192, v193
	v_cvt_pk_bf16_f32 v5, v194, v195
	v_lshl_add_u64 v[10:11], v[8:9], 0, v[68:69]
	global_store_dwordx4 v[10:11], v[2:5], off
	s_nop 1
	v_or_b32_e32 v10, s3, v116
	v_lshlrev_b32_e32 v68, 11, v10
	v_cvt_pk_bf16_f32 v2, v196, v197
	v_cvt_pk_bf16_f32 v3, v198, v199
	v_cvt_pk_bf16_f32 v4, v200, v201
	v_cvt_pk_bf16_f32 v5, v202, v203
	v_lshl_add_u64 v[10:11], v[8:9], 0, v[68:69]
	global_store_dwordx4 v[10:11], v[2:5], off
	s_nop 1
	v_or_b32_e32 v10, s3, v117
	v_lshlrev_b32_e32 v68, 11, v10
	s_waitcnt lgkmcnt(0)
	v_cvt_pk_bf16_f32 v2, v204, v205
	v_cvt_pk_bf16_f32 v3, v206, v207
	v_cvt_pk_bf16_f32 v4, v208, v209
	v_cvt_pk_bf16_f32 v5, v210, v211
	v_lshl_add_u64 v[10:11], v[8:9], 0, v[68:69]
	global_store_dwordx4 v[10:11], v[2:5], off
	s_nop 1
	s_nop 0
	v_cvt_pk_bf16_f32 v2, v212, v213
	v_cvt_pk_bf16_f32 v3, v214, v215
	v_cvt_pk_bf16_f32 v4, v216, v217
	v_or_b32_e32 v5, s3, v118
	v_lshlrev_b32_e32 v68, 11, v5
	v_cvt_pk_bf16_f32 v5, v218, v219
	v_lshl_add_u64 v[6:7], v[8:9], 0, v[68:69]
	global_store_dwordx4 v[6:7], v[2:5], off
	s_nop 1
	s_waitcnt lgkmcnt(0)

.LBB0_1045:
	s_and_b32 s0, s35, 0x3fc0
	s_addk_i32 s0, 0xd100
	v_or_b32_e32 v68, s0, v66
	s_lshl_b32 s16, s6, 2
	v_or_b32_e32 v4, 4, v68
	v_mov_b32_e32 v5, v69
	v_lshl_add_u64 v[62:63], v[88:89], 0, s[16:17]
	v_lshlrev_b64 v[2:3], 13, v[68:69]
	v_lshlrev_b64 v[4:5], 13, v[4:5]
	v_lshl_add_u64 v[2:3], v[62:63], 0, v[2:3]
	v_lshl_add_u64 v[6:7], v[62:63], 0, v[4:5]
	v_or_b32_e32 v10, 8, v68
	v_mov_b32_e32 v11, v69
	v_or_b32_e32 v12, 12, v68
	v_mov_b32_e32 v13, v69
	global_load_dwordx4 v[2:5], v[2:3], off nt
	s_nop 0
	global_load_dwordx4 v[6:9], v[6:7], off nt
	v_lshlrev_b64 v[10:11], 13, v[10:11]
	v_lshlrev_b64 v[12:13], 13, v[12:13]
	v_lshl_add_u64 v[10:11], v[62:63], 0, v[10:11]
	v_lshl_add_u64 v[14:15], v[62:63], 0, v[12:13]
	global_load_dwordx4 v[10:13], v[10:11], off nt
	s_nop 0
	global_load_dwordx4 v[14:17], v[14:15], off nt
	v_or_b32_e32 v18, 16, v68
	v_mov_b32_e32 v19, v69
	v_or_b32_e32 v20, 20, v68
	v_mov_b32_e32 v21, v69
	v_lshlrev_b64 v[18:19], 13, v[18:19]
	v_lshlrev_b64 v[20:21], 13, v[20:21]
	v_lshl_add_u64 v[18:19], v[62:63], 0, v[18:19]
	v_lshl_add_u64 v[22:23], v[62:63], 0, v[20:21]
	global_load_dwordx4 v[18:21], v[18:19], off nt
	s_nop 0
	global_load_dwordx4 v[22:25], v[22:23], off nt
	v_or_b32_e32 v26, 24, v68
	v_mov_b32_e32 v27, v69
	v_or_b32_e32 v28, 28, v68
	v_mov_b32_e32 v29, v69
	v_lshlrev_b64 v[26:27], 13, v[26:27]
	v_lshlrev_b64 v[28:29], 13, v[28:29]
	v_lshl_add_u64 v[26:27], v[62:63], 0, v[26:27]
	v_lshl_add_u64 v[30:31], v[62:63], 0, v[28:29]
	global_load_dwordx4 v[26:29], v[26:27], off nt
	s_nop 0
	global_load_dwordx4 v[30:33], v[30:31], off nt
	v_or_b32_e32 v34, 32, v68
	v_mov_b32_e32 v35, v69
	v_or_b32_e32 v36, 36, v68
	v_mov_b32_e32 v37, v69
	v_lshlrev_b64 v[34:35], 13, v[34:35]
	v_lshlrev_b64 v[36:37], 13, v[36:37]
	v_lshl_add_u64 v[34:35], v[62:63], 0, v[34:35]
	v_lshl_add_u64 v[38:39], v[62:63], 0, v[36:37]
	global_load_dwordx4 v[34:37], v[34:35], off nt
	s_nop 0
	global_load_dwordx4 v[38:41], v[38:39], off nt
	v_or_b32_e32 v42, 40, v68
	v_mov_b32_e32 v43, v69
	v_or_b32_e32 v44, 44, v68
	v_mov_b32_e32 v45, v69
	v_lshlrev_b64 v[42:43], 13, v[42:43]
	v_lshlrev_b64 v[44:45], 13, v[44:45]
	v_lshl_add_u64 v[42:43], v[62:63], 0, v[42:43]
	v_lshl_add_u64 v[46:47], v[62:63], 0, v[44:45]
	global_load_dwordx4 v[42:45], v[42:43], off nt
	s_nop 0
	global_load_dwordx4 v[46:49], v[46:47], off nt
	v_or_b32_e32 v50, 48, v68
	v_mov_b32_e32 v51, v69
	v_lshlrev_b64 v[50:51], 13, v[50:51]
	v_lshl_add_u64 v[50:51], v[62:63], 0, v[50:51]
	v_or_b32_e32 v54, 52, v68
	v_mov_b32_e32 v55, v69
	global_load_dwordx4 v[50:53], v[50:51], off nt
	v_lshlrev_b64 v[54:55], 13, v[54:55]
	v_lshl_add_u64 v[54:55], v[62:63], 0, v[54:55]
	v_or_b32_e32 v58, 56, v68
	v_mov_b32_e32 v59, v69
	global_load_dwordx4 v[54:57], v[54:55], off nt
	v_lshlrev_b64 v[58:59], 13, v[58:59]
	v_lshl_add_u64 v[58:59], v[62:63], 0, v[58:59]
	v_or_b32_e32 v68, 60, v68
	global_load_dwordx4 v[58:61], v[58:59], off nt
	v_lshlrev_b64 v[64:65], 13, v[68:69]
	v_lshl_add_u64 v[62:63], v[62:63], 0, v[64:65]
	global_load_dwordx4 v[62:65], v[62:63], off nt
	v_add_u32_e32 v68, 0x410, v109
	v_add_u32_e32 v106, 0x418, v109
	s_mov_b32 s1, s17
	s_waitcnt vmcnt(15)
	ds_write2_b32 v109, v2, v3 offset1:1
	ds_write2_b32 v109, v4, v5 offset0:2 offset1:3
	s_waitcnt vmcnt(14)
	ds_write2_b32 v68, v6, v7 offset1:1
	ds_write2_b32 v106, v8, v9 offset1:1
	v_add_u32_e32 v2, 0x820, v109
	v_add_u32_e32 v68, s3, v110
	v_lshl_add_u64 v[8:9], s[0:1], 1, v[72:73]
	s_waitcnt vmcnt(13)
	ds_write2_b32 v2, v10, v11 offset1:1
	v_add_u32_e32 v2, 0x828, v109
	ds_write2_b32 v2, v12, v13 offset1:1
	v_add_u32_e32 v2, 0xc30, v109
	s_waitcnt vmcnt(12)
	ds_write2_b32 v2, v14, v15 offset1:1
	v_add_u32_e32 v2, 0xc38, v109
	ds_write2_b32 v2, v16, v17 offset1:1
	v_add_u32_e32 v2, 0x1040, v109
	v_add_u32_e32 v12, 0x400, v111
	s_waitcnt vmcnt(11)
	ds_write2_b32 v2, v18, v19 offset1:1
	v_add_u32_e32 v2, 0x1048, v109
	ds_write2_b32 v2, v20, v21 offset1:1
	v_add_u32_e32 v2, 0x1450, v109
	s_waitcnt vmcnt(10)
	ds_write2_b32 v2, v22, v23 offset1:1
	v_add_u32_e32 v2, 0x1458, v109
	ds_write2_b32 v2, v24, v25 offset1:1
	v_add_u32_e32 v2, 0x1860, v109
	v_lshlrev_b64 v[10:11], 11, v[68:69]
	s_waitcnt vmcnt(9)
	ds_write2_b32 v2, v26, v27 offset1:1
	v_add_u32_e32 v2, 0x1868, v109
	ds_write2_b32 v2, v28, v29 offset1:1
	v_add_u32_e32 v2, 0x1c70, v109
	s_waitcnt vmcnt(8)
	ds_write2_b32 v2, v30, v31 offset1:1
	v_add_u32_e32 v2, 0x1c78, v109
	ds_write2_b32 v2, v32, v33 offset1:1
	v_add_u32_e32 v2, 0x2080, v109
	v_lshl_add_u64 v[10:11], v[8:9], 0, v[10:11]
	s_waitcnt vmcnt(7)
	ds_write2_b32 v2, v34, v35 offset1:1
	v_add_u32_e32 v2, 0x2088, v109
	ds_write2_b32 v2, v36, v37 offset1:1
	v_add_u32_e32 v2, 0x2490, v109
	s_waitcnt vmcnt(6)
	ds_write2_b32 v2, v38, v39 offset1:1
	v_add_u32_e32 v2, 0x2498, v109
	ds_write2_b32 v2, v40, v41 offset1:1
	v_add_u32_e32 v2, 0x28a0, v109
	v_add_u32_e32 v68, s3, v112
	s_waitcnt vmcnt(5)
	ds_write2_b32 v2, v42, v43 offset1:1
	v_add_u32_e32 v2, 0x28a8, v109
	ds_write2_b32 v2, v44, v45 offset1:1
	v_add_u32_e32 v2, 0x2cb0, v109
	s_waitcnt vmcnt(4)
	ds_write2_b32 v2, v46, v47 offset1:1
	v_add_u32_e32 v2, 0x2cb8, v109
	ds_write2_b32 v2, v48, v49 offset1:1
	v_add_u32_e32 v2, 0x30c0, v109
	s_waitcnt vmcnt(3)
	ds_write2_b32 v2, v50, v51 offset1:1
	v_add_u32_e32 v2, 0x30c8, v109
	ds_write2_b32 v2, v52, v53 offset1:1
	v_add_u32_e32 v2, 0x34d0, v109
	s_waitcnt vmcnt(2)
	ds_write2_b32 v2, v54, v55 offset1:1
	v_add_u32_e32 v2, 0x34d8, v109
	ds_write2_b32 v2, v56, v57 offset1:1
	v_add_u32_e32 v2, 0x38e0, v109
	s_waitcnt vmcnt(1)
	ds_write2_b32 v2, v58, v59 offset1:1
	v_add_u32_e32 v2, 0x38e8, v109
	ds_write2_b32 v2, v60, v61 offset1:1
	v_add_u32_e32 v2, 0x3cf0, v109
	s_waitcnt vmcnt(0)
	ds_write2_b32 v2, v62, v63 offset1:1
	v_add_u32_e32 v2, 0x3cf8, v109
	ds_write2_b32 v2, v64, v65 offset1:1
	s_waitcnt lgkmcnt(0)
	ds_read2_b32 v[188:189], v111 offset1:65
	ds_read2_b32 v[190:191], v111 offset0:130 offset1:195
	ds_read2_b32 v[192:193], v12 offset0:4 offset1:69
	ds_read2_b32 v[194:195], v12 offset0:134 offset1:199
	ds_read2_b32 v[196:197], v111 offset0:8 offset1:73
	ds_read2_b32 v[198:199], v111 offset0:138 offset1:203
	ds_read2_b32 v[200:201], v12 offset0:12 offset1:77
	ds_read2_b32 v[202:203], v12 offset0:142 offset1:207
	s_waitcnt lgkmcnt(7)
	ds_read2_b32 v[204:205], v111 offset0:16 offset1:81
	ds_read2_b32 v[206:207], v111 offset0:146 offset1:211
	ds_read2_b32 v[208:209], v12 offset0:20 offset1:85
	ds_read2_b32 v[210:211], v12 offset0:150 offset1:215
	ds_read2_b32 v[212:213], v111 offset0:24 offset1:89
	ds_read2_b32 v[214:215], v111 offset0:154 offset1:219
	ds_read2_b32 v[216:217], v12 offset0:28 offset1:93
	ds_read2_b32 v[218:219], v12 offset0:158 offset1:223
	s_waitcnt lgkmcnt(8)
	v_cvt_pk_bf16_f32 v2, v188, v189
	v_cvt_pk_bf16_f32 v3, v190, v191
	v_cvt_pk_bf16_f32 v4, v192, v193
	v_cvt_pk_bf16_f32 v5, v194, v195
	global_store_dwordx4 v[10:11], v[2:5], off
	s_nop 1
	v_lshlrev_b64 v[10:11], 11, v[68:69]
	v_lshl_add_u64 v[10:11], v[8:9], 0, v[10:11]
	v_cvt_pk_bf16_f32 v2, v196, v197
	v_cvt_pk_bf16_f32 v3, v198, v199
	v_cvt_pk_bf16_f32 v4, v200, v201
	v_cvt_pk_bf16_f32 v5, v202, v203
	global_store_dwordx4 v[10:11], v[2:5], off
	s_nop 1
	v_add_u32_e32 v68, s3, v113
	v_lshlrev_b64 v[10:11], 11, v[68:69]
	s_waitcnt lgkmcnt(7)
	ds_read2_b32 v[188:189], v111 offset0:32 offset1:97
	ds_read2_b32 v[190:191], v111 offset0:162 offset1:227
	ds_read2_b32 v[192:193], v12 offset0:36 offset1:101
	ds_read2_b32 v[194:195], v12 offset0:166 offset1:231
	ds_read2_b32 v[196:197], v111 offset0:40 offset1:105
	ds_read2_b32 v[198:199], v111 offset0:170 offset1:235
	ds_read2_b32 v[200:201], v12 offset0:44 offset1:109
	ds_read2_b32 v[202:203], v12 offset0:174 offset1:239
	s_waitcnt lgkmcnt(8)
	v_cvt_pk_bf16_f32 v2, v204, v205
	v_cvt_pk_bf16_f32 v3, v206, v207
	v_cvt_pk_bf16_f32 v4, v208, v209
	v_cvt_pk_bf16_f32 v5, v210, v211
	v_lshl_add_u64 v[10:11], v[8:9], 0, v[10:11]
	global_store_dwordx4 v[10:11], v[2:5], off
	s_nop 1
	v_add_u32_e32 v68, s3, v114
	v_lshlrev_b64 v[10:11], 11, v[68:69]
	v_cvt_pk_bf16_f32 v2, v212, v213
	v_cvt_pk_bf16_f32 v3, v214, v215
	v_cvt_pk_bf16_f32 v4, v216, v217
	v_cvt_pk_bf16_f32 v5, v218, v219
	v_lshl_add_u64 v[10:11], v[8:9], 0, v[10:11]
	global_store_dwordx4 v[10:11], v[2:5], off
	s_nop 1
	v_add_u32_e32 v68, s3, v115
	v_lshlrev_b64 v[10:11], 11, v[68:69]
	s_waitcnt lgkmcnt(7)
	ds_read2_b32 v[204:205], v111 offset0:48 offset1:113
	ds_read2_b32 v[206:207], v111 offset0:178 offset1:243
	ds_read2_b32 v[208:209], v12 offset0:52 offset1:117
	ds_read2_b32 v[210:211], v12 offset0:182 offset1:247
	ds_read2_b32 v[212:213], v111 offset0:56 offset1:121
	ds_read2_b32 v[214:215], v111 offset0:186 offset1:251
	ds_read2_b32 v[216:217], v12 offset0:60 offset1:125
	ds_read2_b32 v[218:219], v12 offset0:190 offset1:255
	s_waitcnt lgkmcnt(8)
	v_cvt_pk_bf16_f32 v2, v188, v189
	v_cvt_pk_bf16_f32 v3, v190, v191
	v_cvt_pk_bf16_f32 v4, v192, v193
	v_cvt_pk_bf16_f32 v5, v194, v195
	v_lshl_add_u64 v[10:11], v[8:9], 0, v[10:11]
	global_store_dwordx4 v[10:11], v[2:5], off
	s_nop 1
	v_add_u32_e32 v68, s3, v116
	v_lshlrev_b64 v[10:11], 11, v[68:69]
	v_cvt_pk_bf16_f32 v2, v196, v197
	v_cvt_pk_bf16_f32 v3, v198, v199
	v_cvt_pk_bf16_f32 v4, v200, v201
	v_cvt_pk_bf16_f32 v5, v202, v203
	v_lshl_add_u64 v[10:11], v[8:9], 0, v[10:11]
	global_store_dwordx4 v[10:11], v[2:5], off
	s_nop 1
	v_add_u32_e32 v68, s3, v117
	v_lshlrev_b64 v[10:11], 11, v[68:69]
	s_waitcnt lgkmcnt(0)
	v_cvt_pk_bf16_f32 v2, v204, v205
	v_cvt_pk_bf16_f32 v3, v206, v207
	v_cvt_pk_bf16_f32 v4, v208, v209
	v_cvt_pk_bf16_f32 v5, v210, v211
	v_lshl_add_u64 v[10:11], v[8:9], 0, v[10:11]
	global_store_dwordx4 v[10:11], v[2:5], off
	s_nop 1
	v_add_u32_e32 v68, s3, v118
	v_lshlrev_b64 v[10:11], 11, v[68:69]
	v_cvt_pk_bf16_f32 v2, v212, v213
	v_cvt_pk_bf16_f32 v3, v214, v215
	v_cvt_pk_bf16_f32 v4, v216, v217
	v_cvt_pk_bf16_f32 v5, v218, v219
	v_lshl_add_u64 v[6:7], v[8:9], 0, v[10:11]
	global_store_dwordx4 v[6:7], v[2:5], off
	s_nop 1
	s_waitcnt lgkmcnt(0)

.LBB0_1047:
	s_andn2_b64 vcc, exec, s[0:1]
	s_cbranch_vccnz .LBB0_1049
	s_and_b32 s0, s31, 0x7fc0
	s_addk_i32 s0, 0xa600
	s_and_b32 s3, s27, 0x3c0
	v_or_b32_e32 v68, s0, v66
	s_lshl_b32 s16, s3, 2
	v_or_b32_e32 v4, 4, v68
	v_mov_b32_e32 v5, v69
	v_lshl_add_u64 v[62:63], v[90:91], 0, s[16:17]
	v_lshlrev_b64 v[2:3], 12, v[68:69]
	v_lshlrev_b64 v[4:5], 12, v[4:5]
	v_lshl_add_u64 v[2:3], v[62:63], 0, v[2:3]
	v_lshl_add_u64 v[6:7], v[62:63], 0, v[4:5]
	global_load_dwordx4 v[2:5], v[2:3], off nt
	s_nop 0
	global_load_dwordx4 v[6:9], v[6:7], off nt
	v_or_b32_e32 v10, 8, v68
	v_mov_b32_e32 v11, v69
	v_or_b32_e32 v12, 12, v68
	v_mov_b32_e32 v13, v69
	v_lshlrev_b64 v[10:11], 12, v[10:11]
	v_lshlrev_b64 v[12:13], 12, v[12:13]
	v_lshl_add_u64 v[10:11], v[62:63], 0, v[10:11]
	v_lshl_add_u64 v[14:15], v[62:63], 0, v[12:13]
	global_load_dwordx4 v[10:13], v[10:11], off nt
	s_nop 0
	global_load_dwordx4 v[14:17], v[14:15], off nt
	v_or_b32_e32 v18, 16, v68
	v_mov_b32_e32 v19, v69
	v_or_b32_e32 v20, 20, v68
	v_mov_b32_e32 v21, v69
	v_lshlrev_b64 v[18:19], 12, v[18:19]
	v_lshlrev_b64 v[20:21], 12, v[20:21]
	v_lshl_add_u64 v[18:19], v[62:63], 0, v[18:19]
	v_lshl_add_u64 v[22:23], v[62:63], 0, v[20:21]
	global_load_dwordx4 v[18:21], v[18:19], off nt
	s_nop 0
	global_load_dwordx4 v[22:25], v[22:23], off nt
	v_or_b32_e32 v26, 24, v68
	v_mov_b32_e32 v27, v69
	v_or_b32_e32 v28, 28, v68
	v_mov_b32_e32 v29, v69
	v_lshlrev_b64 v[26:27], 12, v[26:27]
	v_lshlrev_b64 v[28:29], 12, v[28:29]
	v_lshl_add_u64 v[26:27], v[62:63], 0, v[26:27]
	v_lshl_add_u64 v[30:31], v[62:63], 0, v[28:29]
	global_load_dwordx4 v[26:29], v[26:27], off nt
	s_nop 0
	global_load_dwordx4 v[30:33], v[30:31], off nt
	v_or_b32_e32 v34, 32, v68
	v_mov_b32_e32 v35, v69
	v_or_b32_e32 v36, 36, v68
	v_mov_b32_e32 v37, v69
	v_lshlrev_b64 v[34:35], 12, v[34:35]
	v_lshlrev_b64 v[36:37], 12, v[36:37]
	v_lshl_add_u64 v[34:35], v[62:63], 0, v[34:35]
	v_lshl_add_u64 v[38:39], v[62:63], 0, v[36:37]
	global_load_dwordx4 v[34:37], v[34:35], off nt
	s_nop 0
	global_load_dwordx4 v[38:41], v[38:39], off nt
	v_or_b32_e32 v42, 40, v68
	v_mov_b32_e32 v43, v69
	v_or_b32_e32 v44, 44, v68
	v_mov_b32_e32 v45, v69
	v_lshlrev_b64 v[42:43], 12, v[42:43]
	v_lshlrev_b64 v[44:45], 12, v[44:45]
	v_lshl_add_u64 v[42:43], v[62:63], 0, v[42:43]
	v_lshl_add_u64 v[46:47], v[62:63], 0, v[44:45]
	global_load_dwordx4 v[42:45], v[42:43], off nt
	s_nop 0
	global_load_dwordx4 v[46:49], v[46:47], off nt
	v_or_b32_e32 v50, 48, v68
	v_mov_b32_e32 v51, v69
	v_lshlrev_b64 v[50:51], 12, v[50:51]
	v_lshl_add_u64 v[50:51], v[62:63], 0, v[50:51]
	v_or_b32_e32 v54, 52, v68
	v_mov_b32_e32 v55, v69
	global_load_dwordx4 v[50:53], v[50:51], off nt
	v_lshlrev_b64 v[54:55], 12, v[54:55]
	v_lshl_add_u64 v[54:55], v[62:63], 0, v[54:55]
	v_or_b32_e32 v58, 56, v68
	v_mov_b32_e32 v59, v69
	global_load_dwordx4 v[54:57], v[54:55], off nt
	v_lshlrev_b64 v[58:59], 12, v[58:59]
	v_lshl_add_u64 v[58:59], v[62:63], 0, v[58:59]
	v_or_b32_e32 v68, 60, v68
	global_load_dwordx4 v[58:61], v[58:59], off nt
	v_lshlrev_b64 v[64:65], 12, v[68:69]
	v_lshl_add_u64 v[62:63], v[62:63], 0, v[64:65]
	global_load_dwordx4 v[62:65], v[62:63], off nt
	v_add_u32_e32 v68, 0x410, v109
	s_mov_b32 s1, s17
	s_waitcnt vmcnt(15)
	ds_write2_b32 v109, v2, v3 offset1:1
	ds_write2_b32 v109, v4, v5 offset0:2 offset1:3
	s_waitcnt vmcnt(14)
	ds_write2_b32 v68, v6, v7 offset1:1
	v_add_u32_e32 v2, 0x418, v109
	ds_write2_b32 v2, v8, v9 offset1:1
	v_add_u32_e32 v2, 0x820, v109
	v_lshl_add_u64 v[8:9], s[0:1], 1, v[74:75]
	s_waitcnt vmcnt(13)
	ds_write2_b32 v2, v10, v11 offset1:1
	v_add_u32_e32 v2, 0x828, v109
	ds_write2_b32 v2, v12, v13 offset1:1
	v_add_u32_e32 v2, 0xc30, v109
	s_waitcnt vmcnt(12)
	ds_write2_b32 v2, v14, v15 offset1:1
	v_add_u32_e32 v2, 0xc38, v109
	ds_write2_b32 v2, v16, v17 offset1:1
	v_add_u32_e32 v2, 0x1040, v109
	v_add_u32_e32 v12, 0x400, v111
	s_waitcnt vmcnt(11)
	ds_write2_b32 v2, v18, v19 offset1:1
	v_add_u32_e32 v2, 0x1048, v109
	ds_write2_b32 v2, v20, v21 offset1:1
	v_add_u32_e32 v2, 0x1450, v109
	s_waitcnt vmcnt(10)
	ds_write2_b32 v2, v22, v23 offset1:1
	v_add_u32_e32 v2, 0x1458, v109
	ds_write2_b32 v2, v24, v25 offset1:1
	v_add_u32_e32 v2, 0x1860, v109
	v_or_b32_e32 v10, s3, v110
	s_waitcnt vmcnt(9)
	ds_write2_b32 v2, v26, v27 offset1:1
	v_add_u32_e32 v2, 0x1868, v109
	ds_write2_b32 v2, v28, v29 offset1:1
	v_add_u32_e32 v2, 0x1c70, v109
	s_waitcnt vmcnt(8)
	ds_write2_b32 v2, v30, v31 offset1:1
	v_add_u32_e32 v2, 0x1c78, v109
	ds_write2_b32 v2, v32, v33 offset1:1
	v_add_u32_e32 v2, 0x2080, v109
	v_lshlrev_b32_e32 v68, 11, v10
	s_waitcnt vmcnt(7)
	ds_write2_b32 v2, v34, v35 offset1:1
	v_add_u32_e32 v2, 0x2088, v109
	ds_write2_b32 v2, v36, v37 offset1:1
	v_add_u32_e32 v2, 0x2490, v109
	s_waitcnt vmcnt(6)
	ds_write2_b32 v2, v38, v39 offset1:1
	v_add_u32_e32 v2, 0x2498, v109
	ds_write2_b32 v2, v40, v41 offset1:1
	v_add_u32_e32 v2, 0x28a0, v109
	v_lshl_add_u64 v[10:11], v[8:9], 0, v[68:69]
	s_waitcnt vmcnt(5)
	ds_write2_b32 v2, v42, v43 offset1:1
	v_add_u32_e32 v2, 0x28a8, v109
	ds_write2_b32 v2, v44, v45 offset1:1
	v_add_u32_e32 v2, 0x2cb0, v109
	s_waitcnt vmcnt(4)
	ds_write2_b32 v2, v46, v47 offset1:1
	v_add_u32_e32 v2, 0x2cb8, v109
	ds_write2_b32 v2, v48, v49 offset1:1
	v_add_u32_e32 v2, 0x30c0, v109
	s_waitcnt vmcnt(3)
	ds_write2_b32 v2, v50, v51 offset1:1
	v_add_u32_e32 v2, 0x30c8, v109
	ds_write2_b32 v2, v52, v53 offset1:1
	v_add_u32_e32 v2, 0x34d0, v109
	s_waitcnt vmcnt(2)
	ds_write2_b32 v2, v54, v55 offset1:1
	v_add_u32_e32 v2, 0x34d8, v109
	ds_write2_b32 v2, v56, v57 offset1:1
	v_add_u32_e32 v2, 0x38e0, v109
	s_waitcnt vmcnt(1)
	ds_write2_b32 v2, v58, v59 offset1:1
	v_add_u32_e32 v2, 0x38e8, v109
	ds_write2_b32 v2, v60, v61 offset1:1
	v_add_u32_e32 v2, 0x3cf0, v109
	s_waitcnt vmcnt(0)
	ds_write2_b32 v2, v62, v63 offset1:1
	v_add_u32_e32 v2, 0x3cf8, v109
	ds_write2_b32 v2, v64, v65 offset1:1
	s_waitcnt lgkmcnt(0)
	ds_read2_b32 v[188:189], v111 offset1:65
	ds_read2_b32 v[190:191], v111 offset0:130 offset1:195
	ds_read2_b32 v[192:193], v12 offset0:4 offset1:69
	ds_read2_b32 v[194:195], v12 offset0:134 offset1:199
	ds_read2_b32 v[196:197], v111 offset0:8 offset1:73
	ds_read2_b32 v[198:199], v111 offset0:138 offset1:203
	ds_read2_b32 v[200:201], v12 offset0:12 offset1:77
	ds_read2_b32 v[202:203], v12 offset0:142 offset1:207
	s_waitcnt lgkmcnt(7)
	ds_read2_b32 v[204:205], v111 offset0:16 offset1:81
	ds_read2_b32 v[206:207], v111 offset0:146 offset1:211
	ds_read2_b32 v[208:209], v12 offset0:20 offset1:85
	ds_read2_b32 v[210:211], v12 offset0:150 offset1:215
	ds_read2_b32 v[212:213], v111 offset0:24 offset1:89
	ds_read2_b32 v[214:215], v111 offset0:154 offset1:219
	ds_read2_b32 v[216:217], v12 offset0:28 offset1:93
	ds_read2_b32 v[218:219], v12 offset0:158 offset1:223
	s_waitcnt lgkmcnt(8)
	v_cvt_pk_bf16_f32 v2, v188, v189
	v_cvt_pk_bf16_f32 v3, v190, v191
	v_cvt_pk_bf16_f32 v4, v192, v193
	v_cvt_pk_bf16_f32 v5, v194, v195
	global_store_dwordx4 v[10:11], v[2:5], off
	s_nop 1
	v_or_b32_e32 v10, s3, v112
	v_lshlrev_b32_e32 v68, 11, v10
	v_cvt_pk_bf16_f32 v2, v196, v197
	v_cvt_pk_bf16_f32 v3, v198, v199
	v_cvt_pk_bf16_f32 v4, v200, v201
	v_cvt_pk_bf16_f32 v5, v202, v203
	v_lshl_add_u64 v[10:11], v[8:9], 0, v[68:69]
	global_store_dwordx4 v[10:11], v[2:5], off
	s_nop 1
	v_or_b32_e32 v10, s3, v113
	v_lshlrev_b32_e32 v68, 11, v10
	s_waitcnt lgkmcnt(7)
	ds_read2_b32 v[188:189], v111 offset0:32 offset1:97
	ds_read2_b32 v[190:191], v111 offset0:162 offset1:227
	ds_read2_b32 v[192:193], v12 offset0:36 offset1:101
	ds_read2_b32 v[194:195], v12 offset0:166 offset1:231
	ds_read2_b32 v[196:197], v111 offset0:40 offset1:105
	ds_read2_b32 v[198:199], v111 offset0:170 offset1:235
	ds_read2_b32 v[200:201], v12 offset0:44 offset1:109
	ds_read2_b32 v[202:203], v12 offset0:174 offset1:239
	s_waitcnt lgkmcnt(8)
	v_cvt_pk_bf16_f32 v2, v204, v205
	v_cvt_pk_bf16_f32 v3, v206, v207
	v_cvt_pk_bf16_f32 v4, v208, v209
	v_cvt_pk_bf16_f32 v5, v210, v211
	v_lshl_add_u64 v[10:11], v[8:9], 0, v[68:69]
	global_store_dwordx4 v[10:11], v[2:5], off
	s_nop 1
	v_or_b32_e32 v10, s3, v114
	v_lshlrev_b32_e32 v68, 11, v10
	v_cvt_pk_bf16_f32 v2, v212, v213
	v_cvt_pk_bf16_f32 v3, v214, v215
	v_cvt_pk_bf16_f32 v4, v216, v217
	v_cvt_pk_bf16_f32 v5, v218, v219
	v_lshl_add_u64 v[10:11], v[8:9], 0, v[68:69]
	global_store_dwordx4 v[10:11], v[2:5], off
	s_nop 1
	v_or_b32_e32 v10, s3, v115
	v_lshlrev_b32_e32 v68, 11, v10
	s_waitcnt lgkmcnt(7)
	ds_read2_b32 v[204:205], v111 offset0:48 offset1:113
	ds_read2_b32 v[206:207], v111 offset0:178 offset1:243
	ds_read2_b32 v[208:209], v12 offset0:52 offset1:117
	ds_read2_b32 v[210:211], v12 offset0:182 offset1:247
	ds_read2_b32 v[212:213], v111 offset0:56 offset1:121
	ds_read2_b32 v[214:215], v111 offset0:186 offset1:251
	ds_read2_b32 v[216:217], v12 offset0:60 offset1:125
	ds_read2_b32 v[218:219], v12 offset0:190 offset1:255
	s_waitcnt lgkmcnt(8)
	v_cvt_pk_bf16_f32 v2, v188, v189
	v_cvt_pk_bf16_f32 v3, v190, v191
	v_cvt_pk_bf16_f32 v4, v192, v193
	v_cvt_pk_bf16_f32 v5, v194, v195
	v_lshl_add_u64 v[10:11], v[8:9], 0, v[68:69]
	global_store_dwordx4 v[10:11], v[2:5], off
	s_nop 1
	v_or_b32_e32 v10, s3, v116
	v_lshlrev_b32_e32 v68, 11, v10
	v_cvt_pk_bf16_f32 v2, v196, v197
	v_cvt_pk_bf16_f32 v3, v198, v199
	v_cvt_pk_bf16_f32 v4, v200, v201
	v_cvt_pk_bf16_f32 v5, v202, v203
	v_lshl_add_u64 v[10:11], v[8:9], 0, v[68:69]
	global_store_dwordx4 v[10:11], v[2:5], off
	s_nop 1
	v_or_b32_e32 v10, s3, v117
	v_lshlrev_b32_e32 v68, 11, v10
	s_waitcnt lgkmcnt(0)
	v_cvt_pk_bf16_f32 v2, v204, v205
	v_cvt_pk_bf16_f32 v3, v206, v207
	v_cvt_pk_bf16_f32 v4, v208, v209
	v_cvt_pk_bf16_f32 v5, v210, v211
	v_lshl_add_u64 v[10:11], v[8:9], 0, v[68:69]
	global_store_dwordx4 v[10:11], v[2:5], off
	s_nop 1
	s_nop 0
	v_cvt_pk_bf16_f32 v2, v212, v213
	v_cvt_pk_bf16_f32 v3, v214, v215
	v_cvt_pk_bf16_f32 v4, v216, v217
	v_or_b32_e32 v5, s3, v118
	v_lshlrev_b32_e32 v68, 11, v5
	v_cvt_pk_bf16_f32 v5, v218, v219
	v_lshl_add_u64 v[6:7], v[8:9], 0, v[68:69]
	global_store_dwordx4 v[6:7], v[2:5], off
	s_nop 1
	s_waitcnt lgkmcnt(0)

.LBB0_1079:
	s_waitcnt vmcnt(0)
	v_pk_mul_f32 v[2:3], v[2:3], v[10:11] op_sel_hi:[1,0]
	v_add_u32_e32 v6, 0x1040, v19
	ds_write2_b32 v6, v2, v3 offset1:1
	v_pk_mul_f32 v[2:3], v[4:5], v[10:11] op_sel_hi:[1,0]
	v_add_u32_e32 v4, 0x1048, v19
	ds_write2_b32 v4, v2, v3 offset1:1
	s_waitcnt lgkmcnt(0)
	v_add_u32_e32 v12, 0x400, v111
	ds_read2_b32 v[188:189], v111 offset1:65
	ds_read2_b32 v[190:191], v111 offset0:130 offset1:195
	ds_read2_b32 v[192:193], v12 offset0:4 offset1:69
	ds_read2_b32 v[194:195], v12 offset0:134 offset1:199
	ds_read2_b32 v[196:197], v111 offset0:8 offset1:73
	ds_read2_b32 v[198:199], v111 offset0:138 offset1:203
	ds_read2_b32 v[200:201], v12 offset0:12 offset1:77
	ds_read2_b32 v[202:203], v12 offset0:142 offset1:207
	s_waitcnt lgkmcnt(7)
	ds_read2_b32 v[204:205], v111 offset0:16 offset1:81
	ds_read2_b32 v[206:207], v111 offset0:146 offset1:211
	ds_read2_b32 v[208:209], v12 offset0:20 offset1:85
	ds_read2_b32 v[210:211], v12 offset0:150 offset1:215
	ds_read2_b32 v[212:213], v111 offset0:24 offset1:89
	ds_read2_b32 v[214:215], v111 offset0:154 offset1:219
	ds_read2_b32 v[216:217], v12 offset0:28 offset1:93
	ds_read2_b32 v[218:219], v12 offset0:158 offset1:223
	s_waitcnt lgkmcnt(8)
	v_cvt_pk_bf16_f32 v2, v188, v189
	s_lshl_b32 s16, s10, 1
	v_add_u32_e32 v68, s3, v110
	v_cvt_pk_bf16_f32 v3, v190, v191
	v_lshl_add_u64 v[8:9], v[76:77], 0, s[16:17]
	v_lshlrev_b64 v[10:11], 11, v[68:69]
	v_cvt_pk_bf16_f32 v4, v192, v193
	v_cvt_pk_bf16_f32 v5, v194, v195
	v_lshl_add_u64 v[10:11], v[8:9], 0, v[10:11]
	global_store_dwordx4 v[10:11], v[2:5], off
	s_nop 1
	v_add_u32_e32 v68, s3, v112
	v_lshlrev_b64 v[10:11], 11, v[68:69]
	v_cvt_pk_bf16_f32 v2, v196, v197
	v_cvt_pk_bf16_f32 v3, v198, v199
	v_cvt_pk_bf16_f32 v4, v200, v201
	v_cvt_pk_bf16_f32 v5, v202, v203
	v_lshl_add_u64 v[10:11], v[8:9], 0, v[10:11]
	global_store_dwordx4 v[10:11], v[2:5], off
	s_nop 1
	v_add_u32_e32 v68, s3, v113
	v_lshlrev_b64 v[10:11], 11, v[68:69]
	s_waitcnt lgkmcnt(7)
	ds_read2_b32 v[188:189], v111 offset0:32 offset1:97
	ds_read2_b32 v[190:191], v111 offset0:162 offset1:227
	ds_read2_b32 v[192:193], v12 offset0:36 offset1:101
	ds_read2_b32 v[194:195], v12 offset0:166 offset1:231
	ds_read2_b32 v[196:197], v111 offset0:40 offset1:105
	ds_read2_b32 v[198:199], v111 offset0:170 offset1:235
	ds_read2_b32 v[200:201], v12 offset0:44 offset1:109
	ds_read2_b32 v[202:203], v12 offset0:174 offset1:239
	s_waitcnt lgkmcnt(8)
	v_cvt_pk_bf16_f32 v2, v204, v205
	v_cvt_pk_bf16_f32 v3, v206, v207
	v_cvt_pk_bf16_f32 v4, v208, v209
	v_cvt_pk_bf16_f32 v5, v210, v211
	v_lshl_add_u64 v[10:11], v[8:9], 0, v[10:11]
	global_store_dwordx4 v[10:11], v[2:5], off
	s_nop 1
	v_add_u32_e32 v68, s3, v114
	v_lshlrev_b64 v[10:11], 11, v[68:69]
	v_cvt_pk_bf16_f32 v2, v212, v213
	v_cvt_pk_bf16_f32 v3, v214, v215
	v_cvt_pk_bf16_f32 v4, v216, v217
	v_cvt_pk_bf16_f32 v5, v218, v219
	v_lshl_add_u64 v[10:11], v[8:9], 0, v[10:11]
	global_store_dwordx4 v[10:11], v[2:5], off
	s_nop 1
	v_add_u32_e32 v68, s3, v115
	v_lshlrev_b64 v[10:11], 11, v[68:69]
	s_waitcnt lgkmcnt(7)
	ds_read2_b32 v[204:205], v111 offset0:48 offset1:113
	ds_read2_b32 v[206:207], v111 offset0:178 offset1:243
	ds_read2_b32 v[208:209], v12 offset0:52 offset1:117
	ds_read2_b32 v[210:211], v12 offset0:182 offset1:247
	ds_read2_b32 v[212:213], v111 offset0:56 offset1:121
	ds_read2_b32 v[214:215], v111 offset0:186 offset1:251
	ds_read2_b32 v[216:217], v12 offset0:60 offset1:125
	ds_read2_b32 v[218:219], v12 offset0:190 offset1:255
	s_waitcnt lgkmcnt(8)
	v_cvt_pk_bf16_f32 v2, v188, v189
	v_cvt_pk_bf16_f32 v3, v190, v191
	v_cvt_pk_bf16_f32 v4, v192, v193
	v_cvt_pk_bf16_f32 v5, v194, v195
	v_lshl_add_u64 v[10:11], v[8:9], 0, v[10:11]
	global_store_dwordx4 v[10:11], v[2:5], off
	s_nop 1
	v_add_u32_e32 v68, s3, v116
	v_lshlrev_b64 v[10:11], 11, v[68:69]
	v_cvt_pk_bf16_f32 v2, v196, v197
	v_cvt_pk_bf16_f32 v3, v198, v199
	v_cvt_pk_bf16_f32 v4, v200, v201
	v_cvt_pk_bf16_f32 v5, v202, v203
	v_lshl_add_u64 v[10:11], v[8:9], 0, v[10:11]
	global_store_dwordx4 v[10:11], v[2:5], off
	s_nop 1
	v_add_u32_e32 v68, s3, v117
	v_lshlrev_b64 v[10:11], 11, v[68:69]
	s_waitcnt lgkmcnt(0)
	v_cvt_pk_bf16_f32 v2, v204, v205
	v_cvt_pk_bf16_f32 v3, v206, v207
	v_cvt_pk_bf16_f32 v4, v208, v209
	v_cvt_pk_bf16_f32 v5, v210, v211
	v_lshl_add_u64 v[10:11], v[8:9], 0, v[10:11]
	global_store_dwordx4 v[10:11], v[2:5], off
	s_nop 1
	v_add_u32_e32 v68, s3, v118
	v_lshlrev_b64 v[10:11], 11, v[68:69]
	v_cvt_pk_bf16_f32 v2, v212, v213
	v_cvt_pk_bf16_f32 v3, v214, v215
	v_cvt_pk_bf16_f32 v4, v216, v217
	v_cvt_pk_bf16_f32 v5, v218, v219
	v_lshl_add_u64 v[6:7], v[8:9], 0, v[10:11]
	global_store_dwordx4 v[6:7], v[2:5], off
	s_nop 1
	s_waitcnt lgkmcnt(0)

.LBB0_1081:
	s_andn2_b64 vcc, exec, s[0:1]
	s_cbranch_vccnz .LBB0_1138
	s_add_i32 s3, s26, 0xfffff7c0
	s_cmpk_gt_u32 s3, 0x2bf
	s_mov_b64 s[0:1], -1
	s_cbranch_scc0 .LBB0_1112
	s_cmpk_gt_u32 s3, 0x57f
	s_cbranch_scc0 .LBB0_1085
	s_add_i32 s0, s27, 0xfffdf000
	s_and_b32 s6, s0, 0x3c0
	s_add_i32 s0, s31, 0xffffdf00
	s_and_b32 s0, s0, 0x7fffffc0
	s_addk_i32 s0, 0xea00
	v_or_b32_e32 v68, s0, v66
	s_lshl_b32 s16, s6, 2
	v_or_b32_e32 v4, 4, v68
	v_mov_b32_e32 v5, v69
	v_lshl_add_u64 v[62:63], v[94:95], 0, s[16:17]
	v_lshlrev_b64 v[2:3], 12, v[68:69]
	v_lshlrev_b64 v[4:5], 12, v[4:5]
	v_lshl_add_u64 v[2:3], v[62:63], 0, v[2:3]
	v_lshl_add_u64 v[6:7], v[62:63], 0, v[4:5]
	global_load_dwordx4 v[2:5], v[2:3], off nt
	s_nop 0
	global_load_dwordx4 v[6:9], v[6:7], off nt
	v_or_b32_e32 v10, 8, v68
	v_mov_b32_e32 v11, v69
	v_or_b32_e32 v12, 12, v68
	v_mov_b32_e32 v13, v69
	v_lshlrev_b64 v[10:11], 12, v[10:11]
	v_lshlrev_b64 v[12:13], 12, v[12:13]
	v_lshl_add_u64 v[10:11], v[62:63], 0, v[10:11]
	v_lshl_add_u64 v[14:15], v[62:63], 0, v[12:13]
	global_load_dwordx4 v[10:13], v[10:11], off nt
	s_nop 0
	global_load_dwordx4 v[14:17], v[14:15], off nt
	v_or_b32_e32 v18, 16, v68
	v_mov_b32_e32 v19, v69
	v_or_b32_e32 v20, 20, v68
	v_mov_b32_e32 v21, v69
	v_lshlrev_b64 v[18:19], 12, v[18:19]
	v_lshlrev_b64 v[20:21], 12, v[20:21]
	v_lshl_add_u64 v[18:19], v[62:63], 0, v[18:19]
	v_lshl_add_u64 v[22:23], v[62:63], 0, v[20:21]
	global_load_dwordx4 v[18:21], v[18:19], off nt
	s_nop 0
	global_load_dwordx4 v[22:25], v[22:23], off nt
	v_or_b32_e32 v26, 24, v68
	v_mov_b32_e32 v27, v69
	v_or_b32_e32 v28, 28, v68
	v_mov_b32_e32 v29, v69
	v_lshlrev_b64 v[26:27], 12, v[26:27]
	v_lshlrev_b64 v[28:29], 12, v[28:29]
	v_lshl_add_u64 v[26:27], v[62:63], 0, v[26:27]
	v_lshl_add_u64 v[30:31], v[62:63], 0, v[28:29]
	global_load_dwordx4 v[26:29], v[26:27], off nt
	s_nop 0
	global_load_dwordx4 v[30:33], v[30:31], off nt
	v_or_b32_e32 v34, 32, v68
	v_mov_b32_e32 v35, v69
	v_or_b32_e32 v36, 36, v68
	v_mov_b32_e32 v37, v69
	v_lshlrev_b64 v[34:35], 12, v[34:35]
	v_lshlrev_b64 v[36:37], 12, v[36:37]
	v_lshl_add_u64 v[34:35], v[62:63], 0, v[34:35]
	v_lshl_add_u64 v[38:39], v[62:63], 0, v[36:37]
	global_load_dwordx4 v[34:37], v[34:35], off nt
	s_nop 0
	global_load_dwordx4 v[38:41], v[38:39], off nt
	v_or_b32_e32 v42, 40, v68
	v_mov_b32_e32 v43, v69
	v_or_b32_e32 v44, 44, v68
	v_mov_b32_e32 v45, v69
	v_lshlrev_b64 v[42:43], 12, v[42:43]
	v_lshlrev_b64 v[44:45], 12, v[44:45]
	v_lshl_add_u64 v[42:43], v[62:63], 0, v[42:43]
	v_lshl_add_u64 v[46:47], v[62:63], 0, v[44:45]
	global_load_dwordx4 v[42:45], v[42:43], off nt
	s_nop 0
	global_load_dwordx4 v[46:49], v[46:47], off nt
	v_or_b32_e32 v50, 48, v68
	v_mov_b32_e32 v51, v69
	v_lshlrev_b64 v[50:51], 12, v[50:51]
	v_lshl_add_u64 v[50:51], v[62:63], 0, v[50:51]
	v_or_b32_e32 v54, 52, v68
	v_mov_b32_e32 v55, v69
	global_load_dwordx4 v[50:53], v[50:51], off nt
	v_lshlrev_b64 v[54:55], 12, v[54:55]
	v_lshl_add_u64 v[54:55], v[62:63], 0, v[54:55]
	v_or_b32_e32 v58, 56, v68
	v_mov_b32_e32 v59, v69
	global_load_dwordx4 v[54:57], v[54:55], off nt
	v_lshlrev_b64 v[58:59], 12, v[58:59]
	v_lshl_add_u64 v[58:59], v[62:63], 0, v[58:59]
	v_or_b32_e32 v68, 60, v68
	global_load_dwordx4 v[58:61], v[58:59], off nt
	v_lshlrev_b64 v[64:65], 12, v[68:69]
	v_lshl_add_u64 v[62:63], v[62:63], 0, v[64:65]
	global_load_dwordx4 v[62:65], v[62:63], off nt
	s_mov_b32 s1, s17
	s_waitcnt vmcnt(15)
	ds_write2_b32 v109, v2, v3 offset1:1
	ds_write2_b32 v109, v4, v5 offset0:2 offset1:3
	v_add_u32_e32 v2, 0x410, v109
	s_waitcnt vmcnt(14)
	ds_write2_b32 v2, v6, v7 offset1:1
	v_add_u32_e32 v2, 0x418, v109
	ds_write2_b32 v2, v8, v9 offset1:1
	v_add_u32_e32 v2, 0x820, v109
	v_lshl_add_u64 v[8:9], s[0:1], 1, v[78:79]
	s_mov_b64 s[0:1], 0
	s_waitcnt vmcnt(13)
	ds_write2_b32 v2, v10, v11 offset1:1
	v_add_u32_e32 v2, 0x828, v109
	ds_write2_b32 v2, v12, v13 offset1:1
	v_add_u32_e32 v2, 0xc30, v109
	s_waitcnt vmcnt(12)
	ds_write2_b32 v2, v14, v15 offset1:1
	v_add_u32_e32 v2, 0xc38, v109
	ds_write2_b32 v2, v16, v17 offset1:1
	v_add_u32_e32 v2, 0x1040, v109
	v_or_b32_e32 v10, s6, v110
	s_waitcnt vmcnt(11)
	ds_write2_b32 v2, v18, v19 offset1:1
	v_add_u32_e32 v2, 0x1048, v109
	ds_write2_b32 v2, v20, v21 offset1:1
	v_add_u32_e32 v2, 0x1450, v109
	s_waitcnt vmcnt(10)
	ds_write2_b32 v2, v22, v23 offset1:1
	v_add_u32_e32 v2, 0x1458, v109
	ds_write2_b32 v2, v24, v25 offset1:1
	v_add_u32_e32 v2, 0x1860, v109
	v_mul_u32_u24_e32 v10, 0xb00, v10
	s_waitcnt vmcnt(9)
	ds_write2_b32 v2, v26, v27 offset1:1
	v_add_u32_e32 v2, 0x1868, v109
	ds_write2_b32 v2, v28, v29 offset1:1
	v_add_u32_e32 v2, 0x1c70, v109
	s_waitcnt vmcnt(8)
	ds_write2_b32 v2, v30, v31 offset1:1
	v_add_u32_e32 v2, 0x1c78, v109
	ds_write2_b32 v2, v32, v33 offset1:1
	v_add_u32_e32 v2, 0x2080, v109
	v_add_u32_e32 v12, 0x400, v111
	s_waitcnt vmcnt(7)
	ds_write2_b32 v2, v34, v35 offset1:1
	v_add_u32_e32 v2, 0x2088, v109
	ds_write2_b32 v2, v36, v37 offset1:1
	v_add_u32_e32 v2, 0x2490, v109
	s_waitcnt vmcnt(6)
	ds_write2_b32 v2, v38, v39 offset1:1
	v_add_u32_e32 v2, 0x2498, v109
	ds_write2_b32 v2, v40, v41 offset1:1
	v_add_u32_e32 v2, 0x28a0, v109
	v_lshlrev_b32_e32 v68, 1, v10
	s_waitcnt vmcnt(5)
	ds_write2_b32 v2, v42, v43 offset1:1
	v_add_u32_e32 v2, 0x28a8, v109
	ds_write2_b32 v2, v44, v45 offset1:1
	v_add_u32_e32 v2, 0x2cb0, v109
	s_waitcnt vmcnt(4)
	ds_write2_b32 v2, v46, v47 offset1:1
	v_add_u32_e32 v2, 0x2cb8, v109
	ds_write2_b32 v2, v48, v49 offset1:1
	v_add_u32_e32 v2, 0x30c0, v109
	s_waitcnt vmcnt(3)
	ds_write2_b32 v2, v50, v51 offset1:1
	v_add_u32_e32 v2, 0x30c8, v109
	ds_write2_b32 v2, v52, v53 offset1:1
	v_add_u32_e32 v2, 0x34d0, v109
	v_lshl_add_u64 v[10:11], v[8:9], 0, v[68:69]
	s_waitcnt vmcnt(2)
	ds_write2_b32 v2, v54, v55 offset1:1
	v_add_u32_e32 v2, 0x34d8, v109
	ds_write2_b32 v2, v56, v57 offset1:1
	v_add_u32_e32 v2, 0x38e0, v109
	s_waitcnt vmcnt(1)
	ds_write2_b32 v2, v58, v59 offset1:1
	v_add_u32_e32 v2, 0x38e8, v109
	ds_write2_b32 v2, v60, v61 offset1:1
	v_add_u32_e32 v2, 0x3cf0, v109
	s_waitcnt vmcnt(0)
	ds_write2_b32 v2, v62, v63 offset1:1
	v_add_u32_e32 v2, 0x3cf8, v109
	ds_write2_b32 v2, v64, v65 offset1:1
	s_waitcnt lgkmcnt(0)
	ds_read2_b32 v[188:189], v111 offset1:65
	ds_read2_b32 v[190:191], v111 offset0:130 offset1:195
	ds_read2_b32 v[192:193], v12 offset0:4 offset1:69
	ds_read2_b32 v[194:195], v12 offset0:134 offset1:199
	ds_read2_b32 v[196:197], v111 offset0:8 offset1:73
	ds_read2_b32 v[198:199], v111 offset0:138 offset1:203
	ds_read2_b32 v[200:201], v12 offset0:12 offset1:77
	ds_read2_b32 v[202:203], v12 offset0:142 offset1:207
	s_waitcnt lgkmcnt(7)
	ds_read2_b32 v[204:205], v111 offset0:16 offset1:81
	ds_read2_b32 v[206:207], v111 offset0:146 offset1:211
	ds_read2_b32 v[208:209], v12 offset0:20 offset1:85
	ds_read2_b32 v[210:211], v12 offset0:150 offset1:215
	ds_read2_b32 v[212:213], v111 offset0:24 offset1:89
	ds_read2_b32 v[214:215], v111 offset0:154 offset1:219
	ds_read2_b32 v[216:217], v12 offset0:28 offset1:93
	ds_read2_b32 v[218:219], v12 offset0:158 offset1:223
	s_waitcnt lgkmcnt(8)
	v_cvt_pk_bf16_f32 v2, v188, v189
	v_cvt_pk_bf16_f32 v3, v190, v191
	v_cvt_pk_bf16_f32 v4, v192, v193
	v_cvt_pk_bf16_f32 v5, v194, v195
	global_store_dwordx4 v[10:11], v[2:5], off
	s_nop 1
	v_or_b32_e32 v10, s6, v112
	v_mul_u32_u24_e32 v10, 0xb00, v10
	v_cvt_pk_bf16_f32 v2, v196, v197
	v_lshlrev_b32_e32 v68, 1, v10
	v_cvt_pk_bf16_f32 v3, v198, v199
	v_lshl_add_u64 v[10:11], v[8:9], 0, v[68:69]
	v_cvt_pk_bf16_f32 v4, v200, v201
	v_cvt_pk_bf16_f32 v5, v202, v203
	global_store_dwordx4 v[10:11], v[2:5], off
	s_nop 1
	v_or_b32_e32 v10, s6, v113
	v_mul_u32_u24_e32 v10, 0xb00, v10
	s_waitcnt lgkmcnt(7)
	ds_read2_b32 v[188:189], v111 offset0:32 offset1:97
	ds_read2_b32 v[190:191], v111 offset0:162 offset1:227
	ds_read2_b32 v[192:193], v12 offset0:36 offset1:101
	ds_read2_b32 v[194:195], v12 offset0:166 offset1:231
	ds_read2_b32 v[196:197], v111 offset0:40 offset1:105
	ds_read2_b32 v[198:199], v111 offset0:170 offset1:235
	ds_read2_b32 v[200:201], v12 offset0:44 offset1:109
	ds_read2_b32 v[202:203], v12 offset0:174 offset1:239
	s_waitcnt lgkmcnt(8)
	v_cvt_pk_bf16_f32 v2, v204, v205
	v_lshlrev_b32_e32 v68, 1, v10
	v_cvt_pk_bf16_f32 v3, v206, v207
	v_lshl_add_u64 v[10:11], v[8:9], 0, v[68:69]
	v_cvt_pk_bf16_f32 v4, v208, v209
	v_cvt_pk_bf16_f32 v5, v210, v211
	global_store_dwordx4 v[10:11], v[2:5], off
	s_nop 1
	v_or_b32_e32 v10, s6, v114
	v_mul_u32_u24_e32 v10, 0xb00, v10
	v_cvt_pk_bf16_f32 v2, v212, v213
	v_lshlrev_b32_e32 v68, 1, v10
	v_cvt_pk_bf16_f32 v3, v214, v215
	v_lshl_add_u64 v[10:11], v[8:9], 0, v[68:69]
	v_cvt_pk_bf16_f32 v4, v216, v217
	v_cvt_pk_bf16_f32 v5, v218, v219
	global_store_dwordx4 v[10:11], v[2:5], off
	s_nop 1
	v_or_b32_e32 v10, s6, v115
	v_mul_u32_u24_e32 v10, 0xb00, v10
	s_waitcnt lgkmcnt(7)
	ds_read2_b32 v[204:205], v111 offset0:48 offset1:113
	ds_read2_b32 v[206:207], v111 offset0:178 offset1:243
	ds_read2_b32 v[208:209], v12 offset0:52 offset1:117
	ds_read2_b32 v[210:211], v12 offset0:182 offset1:247
	ds_read2_b32 v[212:213], v111 offset0:56 offset1:121
	ds_read2_b32 v[214:215], v111 offset0:186 offset1:251
	ds_read2_b32 v[216:217], v12 offset0:60 offset1:125
	ds_read2_b32 v[218:219], v12 offset0:190 offset1:255
	s_waitcnt lgkmcnt(8)
	v_cvt_pk_bf16_f32 v2, v188, v189
	v_lshlrev_b32_e32 v68, 1, v10
	v_cvt_pk_bf16_f32 v3, v190, v191
	v_lshl_add_u64 v[10:11], v[8:9], 0, v[68:69]
	v_cvt_pk_bf16_f32 v4, v192, v193
	v_cvt_pk_bf16_f32 v5, v194, v195
	global_store_dwordx4 v[10:11], v[2:5], off
	s_nop 1
	v_or_b32_e32 v10, s6, v116
	v_mul_u32_u24_e32 v10, 0xb00, v10
	v_cvt_pk_bf16_f32 v2, v196, v197
	v_lshlrev_b32_e32 v68, 1, v10
	v_cvt_pk_bf16_f32 v3, v198, v199
	v_lshl_add_u64 v[10:11], v[8:9], 0, v[68:69]
	v_cvt_pk_bf16_f32 v4, v200, v201
	v_cvt_pk_bf16_f32 v5, v202, v203
	global_store_dwordx4 v[10:11], v[2:5], off
	s_nop 1
	v_or_b32_e32 v10, s6, v117
	s_waitcnt lgkmcnt(0)
	v_cvt_pk_bf16_f32 v2, v204, v205
	v_mul_u32_u24_e32 v10, 0xb00, v10
	v_cvt_pk_bf16_f32 v3, v206, v207
	v_lshlrev_b32_e32 v68, 1, v10
	v_cvt_pk_bf16_f32 v4, v208, v209
	v_cvt_pk_bf16_f32 v5, v210, v211
	v_lshl_add_u64 v[10:11], v[8:9], 0, v[68:69]
	global_store_dwordx4 v[10:11], v[2:5], off
	s_nop 1
	s_nop 0
	v_cvt_pk_bf16_f32 v2, v212, v213
	v_cvt_pk_bf16_f32 v3, v214, v215
	v_cvt_pk_bf16_f32 v4, v216, v217
	v_cvt_pk_bf16_f32 v5, v218, v219
	v_or_b32_e32 v6, s6, v118
	v_mul_u32_u24_e32 v6, 0xb00, v6
	v_lshlrev_b32_e32 v68, 1, v6
	v_lshl_add_u64 v[6:7], v[8:9], 0, v[68:69]
	global_store_dwordx4 v[6:7], v[2:5], off
	s_nop 1
	s_waitcnt lgkmcnt(0)

.LBB0_1110:
	s_waitcnt vmcnt(0)
	v_pk_mul_f32 v[2:3], v[2:3], v[10:11] op_sel_hi:[1,0]
	v_add_u32_e32 v6, 0x1040, v19
	s_lshl_b32 s0, s11, 6
	ds_write2_b32 v6, v2, v3 offset1:1
	v_pk_mul_f32 v[2:3], v[4:5], v[10:11] op_sel_hi:[1,0]
	v_add_u32_e32 v4, 0x1048, v19
	s_and_b32 s0, 0xffff, s0
	ds_write2_b32 v4, v2, v3 offset1:1
	s_lshl_b32 s1, s0, 1
	s_waitcnt lgkmcnt(0)
	s_and_b32 s0, s0, 64
	s_and_b32 s1, s1, 0x1f00
	s_or_b32 s0, s0, s1
	v_add_u32_e32 v12, 0x400, v111
	ds_read2_b32 v[188:189], v111 offset1:65
	ds_read2_b32 v[190:191], v111 offset0:130 offset1:195
	ds_read2_b32 v[192:193], v12 offset0:4 offset1:69
	ds_read2_b32 v[194:195], v12 offset0:134 offset1:199
	ds_read2_b32 v[196:197], v111 offset0:8 offset1:73
	ds_read2_b32 v[198:199], v111 offset0:138 offset1:203
	ds_read2_b32 v[200:201], v12 offset0:12 offset1:77
	ds_read2_b32 v[202:203], v12 offset0:142 offset1:207
	s_bitset1_b32 s0, 7
	s_waitcnt lgkmcnt(7)
	ds_read2_b32 v[204:205], v111 offset0:16 offset1:81
	ds_read2_b32 v[206:207], v111 offset0:146 offset1:211
	ds_read2_b32 v[208:209], v12 offset0:20 offset1:85
	ds_read2_b32 v[210:211], v12 offset0:150 offset1:215
	ds_read2_b32 v[212:213], v111 offset0:24 offset1:89
	ds_read2_b32 v[214:215], v111 offset0:154 offset1:219
	ds_read2_b32 v[216:217], v12 offset0:28 offset1:93
	ds_read2_b32 v[218:219], v12 offset0:158 offset1:223
	s_waitcnt lgkmcnt(8)
	v_cvt_pk_bf16_f32 v2, v188, v189
	s_lshl_b32 s16, s10, 1
	v_or_b32_e32 v10, s0, v110
	v_cvt_pk_bf16_f32 v3, v190, v191
	v_lshl_add_u64 v[8:9], v[80:81], 0, s[16:17]
	v_lshlrev_b32_e32 v68, 11, v10
	v_cvt_pk_bf16_f32 v4, v192, v193
	v_cvt_pk_bf16_f32 v5, v194, v195
	v_lshl_add_u64 v[10:11], v[8:9], 0, v[68:69]
	global_store_dwordx4 v[10:11], v[2:5], off
	s_nop 1
	v_or_b32_e32 v10, s0, v112
	v_lshlrev_b32_e32 v68, 11, v10
	v_cvt_pk_bf16_f32 v2, v196, v197
	v_cvt_pk_bf16_f32 v3, v198, v199
	v_cvt_pk_bf16_f32 v4, v200, v201
	v_cvt_pk_bf16_f32 v5, v202, v203
	v_lshl_add_u64 v[10:11], v[8:9], 0, v[68:69]
	global_store_dwordx4 v[10:11], v[2:5], off
	s_nop 1
	v_or_b32_e32 v10, s0, v113
	v_lshlrev_b32_e32 v68, 11, v10
	s_waitcnt lgkmcnt(7)
	ds_read2_b32 v[188:189], v111 offset0:32 offset1:97
	ds_read2_b32 v[190:191], v111 offset0:162 offset1:227
	ds_read2_b32 v[192:193], v12 offset0:36 offset1:101
	ds_read2_b32 v[194:195], v12 offset0:166 offset1:231
	ds_read2_b32 v[196:197], v111 offset0:40 offset1:105
	ds_read2_b32 v[198:199], v111 offset0:170 offset1:235
	ds_read2_b32 v[200:201], v12 offset0:44 offset1:109
	ds_read2_b32 v[202:203], v12 offset0:174 offset1:239
	s_waitcnt lgkmcnt(8)
	v_cvt_pk_bf16_f32 v2, v204, v205
	v_cvt_pk_bf16_f32 v3, v206, v207
	v_cvt_pk_bf16_f32 v4, v208, v209
	v_cvt_pk_bf16_f32 v5, v210, v211
	v_lshl_add_u64 v[10:11], v[8:9], 0, v[68:69]
	global_store_dwordx4 v[10:11], v[2:5], off
	s_nop 1
	v_or_b32_e32 v10, s0, v114
	v_lshlrev_b32_e32 v68, 11, v10
	v_cvt_pk_bf16_f32 v2, v212, v213
	v_cvt_pk_bf16_f32 v3, v214, v215
	v_cvt_pk_bf16_f32 v4, v216, v217
	v_cvt_pk_bf16_f32 v5, v218, v219
	v_lshl_add_u64 v[10:11], v[8:9], 0, v[68:69]
	global_store_dwordx4 v[10:11], v[2:5], off
	s_nop 1
	v_or_b32_e32 v10, s0, v115
	v_lshlrev_b32_e32 v68, 11, v10
	s_waitcnt lgkmcnt(7)
	ds_read2_b32 v[204:205], v111 offset0:48 offset1:113
	ds_read2_b32 v[206:207], v111 offset0:178 offset1:243
	ds_read2_b32 v[208:209], v12 offset0:52 offset1:117
	ds_read2_b32 v[210:211], v12 offset0:182 offset1:247
	ds_read2_b32 v[212:213], v111 offset0:56 offset1:121
	ds_read2_b32 v[214:215], v111 offset0:186 offset1:251
	ds_read2_b32 v[216:217], v12 offset0:60 offset1:125
	ds_read2_b32 v[218:219], v12 offset0:190 offset1:255
	s_waitcnt lgkmcnt(8)
	v_cvt_pk_bf16_f32 v2, v188, v189
	v_cvt_pk_bf16_f32 v3, v190, v191
	v_cvt_pk_bf16_f32 v4, v192, v193
	v_cvt_pk_bf16_f32 v5, v194, v195
	v_lshl_add_u64 v[10:11], v[8:9], 0, v[68:69]
	global_store_dwordx4 v[10:11], v[2:5], off
	s_nop 1
	v_or_b32_e32 v10, s0, v116
	v_lshlrev_b32_e32 v68, 11, v10
	v_cvt_pk_bf16_f32 v2, v196, v197
	v_cvt_pk_bf16_f32 v3, v198, v199
	v_cvt_pk_bf16_f32 v4, v200, v201
	v_cvt_pk_bf16_f32 v5, v202, v203
	v_lshl_add_u64 v[10:11], v[8:9], 0, v[68:69]
	global_store_dwordx4 v[10:11], v[2:5], off
	s_nop 1
	v_or_b32_e32 v10, s0, v117
	v_lshlrev_b32_e32 v68, 11, v10
	s_waitcnt lgkmcnt(0)
	v_cvt_pk_bf16_f32 v2, v204, v205
	v_cvt_pk_bf16_f32 v3, v206, v207
	v_cvt_pk_bf16_f32 v4, v208, v209
	v_cvt_pk_bf16_f32 v5, v210, v211
	v_lshl_add_u64 v[10:11], v[8:9], 0, v[68:69]
	global_store_dwordx4 v[10:11], v[2:5], off
	s_nop 1
	s_nop 0
	v_cvt_pk_bf16_f32 v2, v212, v213
	v_cvt_pk_bf16_f32 v3, v214, v215
	v_cvt_pk_bf16_f32 v4, v216, v217
	v_or_b32_e32 v5, s0, v118
	v_lshlrev_b32_e32 v68, 11, v5
	v_cvt_pk_bf16_f32 v5, v218, v219
	v_lshl_add_u64 v[6:7], v[8:9], 0, v[68:69]
	global_store_dwordx4 v[6:7], v[2:5], off
	s_nop 1
	s_waitcnt lgkmcnt(0)

.LBB0_1137:
	s_waitcnt vmcnt(0)
	v_pk_mul_f32 v[2:3], v[2:3], v[10:11] op_sel_hi:[1,0]
	v_add_u32_e32 v6, 0x1040, v19
	ds_write2_b32 v6, v2, v3 offset1:1
	v_pk_mul_f32 v[2:3], v[4:5], v[10:11] op_sel_hi:[1,0]
	v_add_u32_e32 v4, 0x1048, v19
	ds_write2_b32 v4, v2, v3 offset1:1
	s_waitcnt lgkmcnt(0)
	s_lshl_b32 s0, s3, 6
	s_lshl_b32 s1, s3, 7
	s_and_b32 s1, s1, 0x1f00
	s_and_b32 s0, s0, 64
	v_add_u32_e32 v12, 0x400, v111
	ds_read2_b32 v[188:189], v111 offset1:65
	ds_read2_b32 v[190:191], v111 offset0:130 offset1:195
	ds_read2_b32 v[192:193], v12 offset0:4 offset1:69
	ds_read2_b32 v[194:195], v12 offset0:134 offset1:199
	ds_read2_b32 v[196:197], v111 offset0:8 offset1:73
	ds_read2_b32 v[198:199], v111 offset0:138 offset1:203
	ds_read2_b32 v[200:201], v12 offset0:12 offset1:77
	ds_read2_b32 v[202:203], v12 offset0:142 offset1:207
	s_or_b32 s0, s1, s0
	s_waitcnt lgkmcnt(7)
	ds_read2_b32 v[204:205], v111 offset0:16 offset1:81
	ds_read2_b32 v[206:207], v111 offset0:146 offset1:211
	ds_read2_b32 v[208:209], v12 offset0:20 offset1:85
	ds_read2_b32 v[210:211], v12 offset0:150 offset1:215
	ds_read2_b32 v[212:213], v111 offset0:24 offset1:89
	ds_read2_b32 v[214:215], v111 offset0:154 offset1:219
	ds_read2_b32 v[216:217], v12 offset0:28 offset1:93
	ds_read2_b32 v[218:219], v12 offset0:158 offset1:223
	s_waitcnt lgkmcnt(8)
	v_cvt_pk_bf16_f32 v2, v188, v189
	s_lshl_b32 s16, s10, 1
	v_or_b32_e32 v10, s0, v110
	v_cvt_pk_bf16_f32 v3, v190, v191
	v_lshl_add_u64 v[8:9], v[80:81], 0, s[16:17]
	v_lshlrev_b32_e32 v68, 11, v10
	v_cvt_pk_bf16_f32 v4, v192, v193
	v_cvt_pk_bf16_f32 v5, v194, v195
	v_lshl_add_u64 v[10:11], v[8:9], 0, v[68:69]
	global_store_dwordx4 v[10:11], v[2:5], off
	s_nop 1
	v_or_b32_e32 v10, s0, v112
	v_lshlrev_b32_e32 v68, 11, v10
	v_cvt_pk_bf16_f32 v2, v196, v197
	v_cvt_pk_bf16_f32 v3, v198, v199
	v_cvt_pk_bf16_f32 v4, v200, v201
	v_cvt_pk_bf16_f32 v5, v202, v203
	v_lshl_add_u64 v[10:11], v[8:9], 0, v[68:69]
	global_store_dwordx4 v[10:11], v[2:5], off
	s_nop 1
	v_or_b32_e32 v10, s0, v113
	v_lshlrev_b32_e32 v68, 11, v10
	s_waitcnt lgkmcnt(7)
	ds_read2_b32 v[188:189], v111 offset0:32 offset1:97
	ds_read2_b32 v[190:191], v111 offset0:162 offset1:227
	ds_read2_b32 v[192:193], v12 offset0:36 offset1:101
	ds_read2_b32 v[194:195], v12 offset0:166 offset1:231
	ds_read2_b32 v[196:197], v111 offset0:40 offset1:105
	ds_read2_b32 v[198:199], v111 offset0:170 offset1:235
	ds_read2_b32 v[200:201], v12 offset0:44 offset1:109
	ds_read2_b32 v[202:203], v12 offset0:174 offset1:239
	s_waitcnt lgkmcnt(8)
	v_cvt_pk_bf16_f32 v2, v204, v205
	v_cvt_pk_bf16_f32 v3, v206, v207
	v_cvt_pk_bf16_f32 v4, v208, v209
	v_cvt_pk_bf16_f32 v5, v210, v211
	v_lshl_add_u64 v[10:11], v[8:9], 0, v[68:69]
	global_store_dwordx4 v[10:11], v[2:5], off
	s_nop 1
	v_or_b32_e32 v10, s0, v114
	v_lshlrev_b32_e32 v68, 11, v10
	v_cvt_pk_bf16_f32 v2, v212, v213
	v_cvt_pk_bf16_f32 v3, v214, v215
	v_cvt_pk_bf16_f32 v4, v216, v217
	v_cvt_pk_bf16_f32 v5, v218, v219
	v_lshl_add_u64 v[10:11], v[8:9], 0, v[68:69]
	global_store_dwordx4 v[10:11], v[2:5], off
	s_nop 1
	v_or_b32_e32 v10, s0, v115
	v_lshlrev_b32_e32 v68, 11, v10
	s_waitcnt lgkmcnt(7)
	ds_read2_b32 v[204:205], v111 offset0:48 offset1:113
	ds_read2_b32 v[206:207], v111 offset0:178 offset1:243
	ds_read2_b32 v[208:209], v12 offset0:52 offset1:117
	ds_read2_b32 v[210:211], v12 offset0:182 offset1:247
	ds_read2_b32 v[212:213], v111 offset0:56 offset1:121
	ds_read2_b32 v[214:215], v111 offset0:186 offset1:251
	ds_read2_b32 v[216:217], v12 offset0:60 offset1:125
	ds_read2_b32 v[218:219], v12 offset0:190 offset1:255
	s_waitcnt lgkmcnt(8)
	v_cvt_pk_bf16_f32 v2, v188, v189
	v_cvt_pk_bf16_f32 v3, v190, v191
	v_cvt_pk_bf16_f32 v4, v192, v193
	v_cvt_pk_bf16_f32 v5, v194, v195
	v_lshl_add_u64 v[10:11], v[8:9], 0, v[68:69]
	global_store_dwordx4 v[10:11], v[2:5], off
	s_nop 1
	v_or_b32_e32 v10, s0, v116
	v_lshlrev_b32_e32 v68, 11, v10
	v_cvt_pk_bf16_f32 v2, v196, v197
	v_cvt_pk_bf16_f32 v3, v198, v199
	v_cvt_pk_bf16_f32 v4, v200, v201
	v_cvt_pk_bf16_f32 v5, v202, v203
	v_lshl_add_u64 v[10:11], v[8:9], 0, v[68:69]
	global_store_dwordx4 v[10:11], v[2:5], off
	s_nop 1
	v_or_b32_e32 v10, s0, v117
	v_lshlrev_b32_e32 v68, 11, v10
	s_waitcnt lgkmcnt(0)
	v_cvt_pk_bf16_f32 v2, v204, v205
	v_cvt_pk_bf16_f32 v3, v206, v207
	v_cvt_pk_bf16_f32 v4, v208, v209
	v_cvt_pk_bf16_f32 v5, v210, v211
	v_lshl_add_u64 v[10:11], v[8:9], 0, v[68:69]
	global_store_dwordx4 v[10:11], v[2:5], off
	s_nop 1
	s_nop 0
	v_cvt_pk_bf16_f32 v2, v212, v213
	v_cvt_pk_bf16_f32 v3, v214, v215
	v_cvt_pk_bf16_f32 v4, v216, v217
	v_or_b32_e32 v5, s0, v118
	v_lshlrev_b32_e32 v68, 11, v5
	v_cvt_pk_bf16_f32 v5, v218, v219
	v_lshl_add_u64 v[6:7], v[8:9], 0, v[68:69]
	global_store_dwordx4 v[6:7], v[2:5], off
	s_nop 1
	s_waitcnt lgkmcnt(0)

.LBB0_1139:
	s_andn2_b64 vcc, exec, s[0:1]
	s_cbranch_vccnz .LBB0_1033
	s_cmpk_gt_i32 s26, 0x2bf
	s_mov_b64 s[0:1], -1
	s_cbranch_scc0 .LBB0_1170
	s_cmpk_gt_u32 s26, 0x57f
	s_cbranch_scc0 .LBB0_1143
	s_and_b32 s0, s31, 0x7fffffc0
	s_addk_i32 s0, 0xea00
	s_and_b32 s3, s27, 0x3c0
	v_or_b32_e32 v68, s0, v66
	s_lshl_b32 s16, s3, 2
	v_or_b32_e32 v4, 4, v68
	v_mov_b32_e32 v5, v69
	v_lshl_add_u64 v[62:63], v[100:101], 0, s[16:17]
	v_lshlrev_b64 v[2:3], 12, v[68:69]
	v_lshlrev_b64 v[4:5], 12, v[4:5]
	v_lshl_add_u64 v[2:3], v[62:63], 0, v[2:3]
	v_lshl_add_u64 v[6:7], v[62:63], 0, v[4:5]
	global_load_dwordx4 v[2:5], v[2:3], off nt
	s_nop 0
	global_load_dwordx4 v[6:9], v[6:7], off nt
	v_or_b32_e32 v10, 8, v68
	v_mov_b32_e32 v11, v69
	v_or_b32_e32 v12, 12, v68
	v_mov_b32_e32 v13, v69
	v_lshlrev_b64 v[10:11], 12, v[10:11]
	v_lshlrev_b64 v[12:13], 12, v[12:13]
	v_lshl_add_u64 v[10:11], v[62:63], 0, v[10:11]
	v_lshl_add_u64 v[14:15], v[62:63], 0, v[12:13]
	global_load_dwordx4 v[10:13], v[10:11], off nt
	s_nop 0
	global_load_dwordx4 v[14:17], v[14:15], off nt
	v_or_b32_e32 v18, 16, v68
	v_mov_b32_e32 v19, v69
	v_or_b32_e32 v20, 20, v68
	v_mov_b32_e32 v21, v69
	v_lshlrev_b64 v[18:19], 12, v[18:19]
	v_lshlrev_b64 v[20:21], 12, v[20:21]
	v_lshl_add_u64 v[18:19], v[62:63], 0, v[18:19]
	v_lshl_add_u64 v[22:23], v[62:63], 0, v[20:21]
	global_load_dwordx4 v[18:21], v[18:19], off nt
	s_nop 0
	global_load_dwordx4 v[22:25], v[22:23], off nt
	v_or_b32_e32 v26, 24, v68
	v_mov_b32_e32 v27, v69
	v_or_b32_e32 v28, 28, v68
	v_mov_b32_e32 v29, v69
	v_lshlrev_b64 v[26:27], 12, v[26:27]
	v_lshlrev_b64 v[28:29], 12, v[28:29]
	v_lshl_add_u64 v[26:27], v[62:63], 0, v[26:27]
	v_lshl_add_u64 v[30:31], v[62:63], 0, v[28:29]
	global_load_dwordx4 v[26:29], v[26:27], off nt
	s_nop 0
	global_load_dwordx4 v[30:33], v[30:31], off nt
	v_or_b32_e32 v34, 32, v68
	v_mov_b32_e32 v35, v69
	v_or_b32_e32 v36, 36, v68
	v_mov_b32_e32 v37, v69
	v_lshlrev_b64 v[34:35], 12, v[34:35]
	v_lshlrev_b64 v[36:37], 12, v[36:37]
	v_lshl_add_u64 v[34:35], v[62:63], 0, v[34:35]
	v_lshl_add_u64 v[38:39], v[62:63], 0, v[36:37]
	global_load_dwordx4 v[34:37], v[34:35], off nt
	s_nop 0
	global_load_dwordx4 v[38:41], v[38:39], off nt
	v_or_b32_e32 v42, 40, v68
	v_mov_b32_e32 v43, v69
	v_or_b32_e32 v44, 44, v68
	v_mov_b32_e32 v45, v69
	v_lshlrev_b64 v[42:43], 12, v[42:43]
	v_lshlrev_b64 v[44:45], 12, v[44:45]
	v_lshl_add_u64 v[42:43], v[62:63], 0, v[42:43]
	v_lshl_add_u64 v[46:47], v[62:63], 0, v[44:45]
	global_load_dwordx4 v[42:45], v[42:43], off nt
	s_nop 0
	global_load_dwordx4 v[46:49], v[46:47], off nt
	v_or_b32_e32 v50, 48, v68
	v_mov_b32_e32 v51, v69
	v_lshlrev_b64 v[50:51], 12, v[50:51]
	v_lshl_add_u64 v[50:51], v[62:63], 0, v[50:51]
	v_or_b32_e32 v54, 52, v68
	v_mov_b32_e32 v55, v69
	global_load_dwordx4 v[50:53], v[50:51], off nt
	v_lshlrev_b64 v[54:55], 12, v[54:55]
	v_lshl_add_u64 v[54:55], v[62:63], 0, v[54:55]
	v_or_b32_e32 v58, 56, v68
	v_mov_b32_e32 v59, v69
	global_load_dwordx4 v[54:57], v[54:55], off nt
	v_lshlrev_b64 v[58:59], 12, v[58:59]
	v_lshl_add_u64 v[58:59], v[62:63], 0, v[58:59]
	v_or_b32_e32 v68, 60, v68
	global_load_dwordx4 v[58:61], v[58:59], off nt
	v_lshlrev_b64 v[64:65], 12, v[68:69]
	v_lshl_add_u64 v[62:63], v[62:63], 0, v[64:65]
	global_load_dwordx4 v[62:65], v[62:63], off nt
	v_add_u32_e32 v68, 0x410, v109
	s_mov_b32 s1, s17
	s_waitcnt vmcnt(15)
	ds_write2_b32 v109, v2, v3 offset1:1
	ds_write2_b32 v109, v4, v5 offset0:2 offset1:3
	s_waitcnt vmcnt(14)
	ds_write2_b32 v68, v6, v7 offset1:1
	v_add_u32_e32 v2, 0x418, v109
	ds_write2_b32 v2, v8, v9 offset1:1
	v_add_u32_e32 v2, 0x820, v109
	v_lshl_add_u64 v[8:9], s[0:1], 1, v[82:83]
	s_mov_b64 s[0:1], 0
	s_waitcnt vmcnt(13)
	ds_write2_b32 v2, v10, v11 offset1:1
	v_add_u32_e32 v2, 0x828, v109
	ds_write2_b32 v2, v12, v13 offset1:1
	v_add_u32_e32 v2, 0xc30, v109
	s_waitcnt vmcnt(12)
	ds_write2_b32 v2, v14, v15 offset1:1
	v_add_u32_e32 v2, 0xc38, v109
	ds_write2_b32 v2, v16, v17 offset1:1
	v_add_u32_e32 v2, 0x1040, v109
	v_or_b32_e32 v10, s3, v110
	s_waitcnt vmcnt(11)
	ds_write2_b32 v2, v18, v19 offset1:1
	v_add_u32_e32 v2, 0x1048, v109
	ds_write2_b32 v2, v20, v21 offset1:1
	v_add_u32_e32 v2, 0x1450, v109
	s_waitcnt vmcnt(10)
	ds_write2_b32 v2, v22, v23 offset1:1
	v_add_u32_e32 v2, 0x1458, v109
	ds_write2_b32 v2, v24, v25 offset1:1
	v_add_u32_e32 v2, 0x1860, v109
	v_mul_u32_u24_e32 v10, 0xb00, v10
	s_waitcnt vmcnt(9)
	ds_write2_b32 v2, v26, v27 offset1:1
	v_add_u32_e32 v2, 0x1868, v109
	ds_write2_b32 v2, v28, v29 offset1:1
	v_add_u32_e32 v2, 0x1c70, v109
	s_waitcnt vmcnt(8)
	ds_write2_b32 v2, v30, v31 offset1:1
	v_add_u32_e32 v2, 0x1c78, v109
	ds_write2_b32 v2, v32, v33 offset1:1
	v_add_u32_e32 v2, 0x2080, v109
	v_add_u32_e32 v12, 0x400, v111
	s_waitcnt vmcnt(7)
	ds_write2_b32 v2, v34, v35 offset1:1
	v_add_u32_e32 v2, 0x2088, v109
	ds_write2_b32 v2, v36, v37 offset1:1
	v_add_u32_e32 v2, 0x2490, v109
	s_waitcnt vmcnt(6)
	ds_write2_b32 v2, v38, v39 offset1:1
	v_add_u32_e32 v2, 0x2498, v109
	ds_write2_b32 v2, v40, v41 offset1:1
	v_add_u32_e32 v2, 0x28a0, v109
	v_lshlrev_b32_e32 v68, 1, v10
	s_waitcnt vmcnt(5)
	ds_write2_b32 v2, v42, v43 offset1:1
	v_add_u32_e32 v2, 0x28a8, v109
	ds_write2_b32 v2, v44, v45 offset1:1
	v_add_u32_e32 v2, 0x2cb0, v109
	s_waitcnt vmcnt(4)
	ds_write2_b32 v2, v46, v47 offset1:1
	v_add_u32_e32 v2, 0x2cb8, v109
	ds_write2_b32 v2, v48, v49 offset1:1
	v_add_u32_e32 v2, 0x30c0, v109
	s_waitcnt vmcnt(3)
	ds_write2_b32 v2, v50, v51 offset1:1
	v_add_u32_e32 v2, 0x30c8, v109
	ds_write2_b32 v2, v52, v53 offset1:1
	v_add_u32_e32 v2, 0x34d0, v109
	v_lshl_add_u64 v[10:11], v[8:9], 0, v[68:69]
	s_waitcnt vmcnt(2)
	ds_write2_b32 v2, v54, v55 offset1:1
	v_add_u32_e32 v2, 0x34d8, v109
	ds_write2_b32 v2, v56, v57 offset1:1
	v_add_u32_e32 v2, 0x38e0, v109
	s_waitcnt vmcnt(1)
	ds_write2_b32 v2, v58, v59 offset1:1
	v_add_u32_e32 v2, 0x38e8, v109
	ds_write2_b32 v2, v60, v61 offset1:1
	v_add_u32_e32 v2, 0x3cf0, v109
	s_waitcnt vmcnt(0)
	ds_write2_b32 v2, v62, v63 offset1:1
	v_add_u32_e32 v2, 0x3cf8, v109
	ds_write2_b32 v2, v64, v65 offset1:1
	s_waitcnt lgkmcnt(0)
	ds_read2_b32 v[188:189], v111 offset1:65
	ds_read2_b32 v[190:191], v111 offset0:130 offset1:195
	ds_read2_b32 v[192:193], v12 offset0:4 offset1:69
	ds_read2_b32 v[194:195], v12 offset0:134 offset1:199
	ds_read2_b32 v[196:197], v111 offset0:8 offset1:73
	ds_read2_b32 v[198:199], v111 offset0:138 offset1:203
	ds_read2_b32 v[200:201], v12 offset0:12 offset1:77
	ds_read2_b32 v[202:203], v12 offset0:142 offset1:207
	s_waitcnt lgkmcnt(7)
	ds_read2_b32 v[204:205], v111 offset0:16 offset1:81
	ds_read2_b32 v[206:207], v111 offset0:146 offset1:211
	ds_read2_b32 v[208:209], v12 offset0:20 offset1:85
	ds_read2_b32 v[210:211], v12 offset0:150 offset1:215
	ds_read2_b32 v[212:213], v111 offset0:24 offset1:89
	ds_read2_b32 v[214:215], v111 offset0:154 offset1:219
	ds_read2_b32 v[216:217], v12 offset0:28 offset1:93
	ds_read2_b32 v[218:219], v12 offset0:158 offset1:223
	s_waitcnt lgkmcnt(8)
	v_cvt_pk_bf16_f32 v2, v188, v189
	v_cvt_pk_bf16_f32 v3, v190, v191
	v_cvt_pk_bf16_f32 v4, v192, v193
	v_cvt_pk_bf16_f32 v5, v194, v195
	global_store_dwordx4 v[10:11], v[2:5], off
	s_nop 1
	v_or_b32_e32 v10, s3, v112
	v_mul_u32_u24_e32 v10, 0xb00, v10
	v_cvt_pk_bf16_f32 v2, v196, v197
	v_lshlrev_b32_e32 v68, 1, v10
	v_cvt_pk_bf16_f32 v3, v198, v199
	v_lshl_add_u64 v[10:11], v[8:9], 0, v[68:69]
	v_cvt_pk_bf16_f32 v4, v200, v201
	v_cvt_pk_bf16_f32 v5, v202, v203
	global_store_dwordx4 v[10:11], v[2:5], off
	s_nop 1
	v_or_b32_e32 v10, s3, v113
	v_mul_u32_u24_e32 v10, 0xb00, v10
	s_waitcnt lgkmcnt(7)
	ds_read2_b32 v[188:189], v111 offset0:32 offset1:97
	ds_read2_b32 v[190:191], v111 offset0:162 offset1:227
	ds_read2_b32 v[192:193], v12 offset0:36 offset1:101
	ds_read2_b32 v[194:195], v12 offset0:166 offset1:231
	ds_read2_b32 v[196:197], v111 offset0:40 offset1:105
	ds_read2_b32 v[198:199], v111 offset0:170 offset1:235
	ds_read2_b32 v[200:201], v12 offset0:44 offset1:109
	ds_read2_b32 v[202:203], v12 offset0:174 offset1:239
	s_waitcnt lgkmcnt(8)
	v_cvt_pk_bf16_f32 v2, v204, v205
	v_lshlrev_b32_e32 v68, 1, v10
	v_cvt_pk_bf16_f32 v3, v206, v207
	v_lshl_add_u64 v[10:11], v[8:9], 0, v[68:69]
	v_cvt_pk_bf16_f32 v4, v208, v209
	v_cvt_pk_bf16_f32 v5, v210, v211
	global_store_dwordx4 v[10:11], v[2:5], off
	s_nop 1
	v_or_b32_e32 v10, s3, v114
	v_mul_u32_u24_e32 v10, 0xb00, v10
	v_cvt_pk_bf16_f32 v2, v212, v213
	v_lshlrev_b32_e32 v68, 1, v10
	v_cvt_pk_bf16_f32 v3, v214, v215
	v_lshl_add_u64 v[10:11], v[8:9], 0, v[68:69]
	v_cvt_pk_bf16_f32 v4, v216, v217
	v_cvt_pk_bf16_f32 v5, v218, v219
	global_store_dwordx4 v[10:11], v[2:5], off
	s_nop 1
	v_or_b32_e32 v10, s3, v115
	v_mul_u32_u24_e32 v10, 0xb00, v10
	s_waitcnt lgkmcnt(7)
	ds_read2_b32 v[204:205], v111 offset0:48 offset1:113
	ds_read2_b32 v[206:207], v111 offset0:178 offset1:243
	ds_read2_b32 v[208:209], v12 offset0:52 offset1:117
	ds_read2_b32 v[210:211], v12 offset0:182 offset1:247
	ds_read2_b32 v[212:213], v111 offset0:56 offset1:121
	ds_read2_b32 v[214:215], v111 offset0:186 offset1:251
	ds_read2_b32 v[216:217], v12 offset0:60 offset1:125
	ds_read2_b32 v[218:219], v12 offset0:190 offset1:255
	s_waitcnt lgkmcnt(8)
	v_cvt_pk_bf16_f32 v2, v188, v189
	v_lshlrev_b32_e32 v68, 1, v10
	v_cvt_pk_bf16_f32 v3, v190, v191
	v_lshl_add_u64 v[10:11], v[8:9], 0, v[68:69]
	v_cvt_pk_bf16_f32 v4, v192, v193
	v_cvt_pk_bf16_f32 v5, v194, v195
	global_store_dwordx4 v[10:11], v[2:5], off
	s_nop 1
	v_or_b32_e32 v10, s3, v116
	v_mul_u32_u24_e32 v10, 0xb00, v10
	v_cvt_pk_bf16_f32 v2, v196, v197
	v_lshlrev_b32_e32 v68, 1, v10
	v_cvt_pk_bf16_f32 v3, v198, v199
	v_lshl_add_u64 v[10:11], v[8:9], 0, v[68:69]
	v_cvt_pk_bf16_f32 v4, v200, v201
	v_cvt_pk_bf16_f32 v5, v202, v203
	global_store_dwordx4 v[10:11], v[2:5], off
	s_nop 1
	v_or_b32_e32 v10, s3, v117
	s_waitcnt lgkmcnt(0)
	v_cvt_pk_bf16_f32 v2, v204, v205
	v_mul_u32_u24_e32 v10, 0xb00, v10
	v_cvt_pk_bf16_f32 v3, v206, v207
	v_lshlrev_b32_e32 v68, 1, v10
	v_cvt_pk_bf16_f32 v4, v208, v209
	v_cvt_pk_bf16_f32 v5, v210, v211
	v_lshl_add_u64 v[10:11], v[8:9], 0, v[68:69]
	global_store_dwordx4 v[10:11], v[2:5], off
	s_nop 1
	v_or_b32_e32 v10, s3, v118
	v_cvt_pk_bf16_f32 v2, v212, v213
	v_cvt_pk_bf16_f32 v3, v214, v215
	v_cvt_pk_bf16_f32 v4, v216, v217
	v_cvt_pk_bf16_f32 v5, v218, v219
	v_mul_u32_u24_e32 v6, 0xb00, v10
	v_lshlrev_b32_e32 v68, 1, v6
	v_lshl_add_u64 v[6:7], v[8:9], 0, v[68:69]
	global_store_dwordx4 v[6:7], v[2:5], off
	s_nop 1
	s_waitcnt lgkmcnt(0)

.LBB0_1168:
	s_waitcnt vmcnt(0)
	v_pk_mul_f32 v[2:3], v[2:3], v[10:11] op_sel_hi:[1,0]
	v_add_u32_e32 v6, 0x1040, v19
	s_lshl_b32 s0, s10, 6
	ds_write2_b32 v6, v2, v3 offset1:1
	v_pk_mul_f32 v[2:3], v[4:5], v[10:11] op_sel_hi:[1,0]
	v_add_u32_e32 v4, 0x1048, v19
	s_and_b32 s0, 0xffff, s0
	ds_write2_b32 v4, v2, v3 offset1:1
	s_lshl_b32 s1, s0, 1
	s_waitcnt lgkmcnt(0)
	s_and_b32 s0, s0, 64
	s_and_b32 s1, s1, 0x1f00
	s_or_b32 s0, s0, s1
	v_add_u32_e32 v12, 0x400, v111
	ds_read2_b32 v[188:189], v111 offset1:65
	ds_read2_b32 v[190:191], v111 offset0:130 offset1:195
	ds_read2_b32 v[192:193], v12 offset0:4 offset1:69
	ds_read2_b32 v[194:195], v12 offset0:134 offset1:199
	ds_read2_b32 v[196:197], v111 offset0:8 offset1:73
	ds_read2_b32 v[198:199], v111 offset0:138 offset1:203
	ds_read2_b32 v[200:201], v12 offset0:12 offset1:77
	ds_read2_b32 v[202:203], v12 offset0:142 offset1:207
	s_bitset1_b32 s0, 7
	s_waitcnt lgkmcnt(7)
	ds_read2_b32 v[204:205], v111 offset0:16 offset1:81
	ds_read2_b32 v[206:207], v111 offset0:146 offset1:211
	ds_read2_b32 v[208:209], v12 offset0:20 offset1:85
	ds_read2_b32 v[210:211], v12 offset0:150 offset1:215
	ds_read2_b32 v[212:213], v111 offset0:24 offset1:89
	ds_read2_b32 v[214:215], v111 offset0:154 offset1:219
	ds_read2_b32 v[216:217], v12 offset0:28 offset1:93
	ds_read2_b32 v[218:219], v12 offset0:158 offset1:223
	s_waitcnt lgkmcnt(8)
	v_cvt_pk_bf16_f32 v2, v188, v189
	s_lshl_b32 s16, s3, 1
	v_or_b32_e32 v10, s0, v110
	v_cvt_pk_bf16_f32 v3, v190, v191
	v_lshl_add_u64 v[8:9], v[84:85], 0, s[16:17]
	v_lshlrev_b32_e32 v68, 11, v10
	v_cvt_pk_bf16_f32 v4, v192, v193
	v_cvt_pk_bf16_f32 v5, v194, v195
	v_lshl_add_u64 v[10:11], v[8:9], 0, v[68:69]
	global_store_dwordx4 v[10:11], v[2:5], off
	s_nop 1
	v_or_b32_e32 v10, s0, v112
	v_lshlrev_b32_e32 v68, 11, v10
	v_cvt_pk_bf16_f32 v2, v196, v197
	v_cvt_pk_bf16_f32 v3, v198, v199
	v_cvt_pk_bf16_f32 v4, v200, v201
	v_cvt_pk_bf16_f32 v5, v202, v203
	v_lshl_add_u64 v[10:11], v[8:9], 0, v[68:69]
	global_store_dwordx4 v[10:11], v[2:5], off
	s_nop 1
	v_or_b32_e32 v10, s0, v113
	v_lshlrev_b32_e32 v68, 11, v10
	s_waitcnt lgkmcnt(7)
	ds_read2_b32 v[188:189], v111 offset0:32 offset1:97
	ds_read2_b32 v[190:191], v111 offset0:162 offset1:227
	ds_read2_b32 v[192:193], v12 offset0:36 offset1:101
	ds_read2_b32 v[194:195], v12 offset0:166 offset1:231
	ds_read2_b32 v[196:197], v111 offset0:40 offset1:105
	ds_read2_b32 v[198:199], v111 offset0:170 offset1:235
	ds_read2_b32 v[200:201], v12 offset0:44 offset1:109
	ds_read2_b32 v[202:203], v12 offset0:174 offset1:239
	s_waitcnt lgkmcnt(8)
	v_cvt_pk_bf16_f32 v2, v204, v205
	v_cvt_pk_bf16_f32 v3, v206, v207
	v_cvt_pk_bf16_f32 v4, v208, v209
	v_cvt_pk_bf16_f32 v5, v210, v211
	v_lshl_add_u64 v[10:11], v[8:9], 0, v[68:69]
	global_store_dwordx4 v[10:11], v[2:5], off
	s_nop 1
	v_or_b32_e32 v10, s0, v114
	v_lshlrev_b32_e32 v68, 11, v10
	v_cvt_pk_bf16_f32 v2, v212, v213
	v_cvt_pk_bf16_f32 v3, v214, v215
	v_cvt_pk_bf16_f32 v4, v216, v217
	v_cvt_pk_bf16_f32 v5, v218, v219
	v_lshl_add_u64 v[10:11], v[8:9], 0, v[68:69]
	global_store_dwordx4 v[10:11], v[2:5], off
	s_nop 1
	v_or_b32_e32 v10, s0, v115
	v_lshlrev_b32_e32 v68, 11, v10
	s_waitcnt lgkmcnt(7)
	ds_read2_b32 v[204:205], v111 offset0:48 offset1:113
	ds_read2_b32 v[206:207], v111 offset0:178 offset1:243
	ds_read2_b32 v[208:209], v12 offset0:52 offset1:117
	ds_read2_b32 v[210:211], v12 offset0:182 offset1:247
	ds_read2_b32 v[212:213], v111 offset0:56 offset1:121
	ds_read2_b32 v[214:215], v111 offset0:186 offset1:251
	ds_read2_b32 v[216:217], v12 offset0:60 offset1:125
	ds_read2_b32 v[218:219], v12 offset0:190 offset1:255
	s_waitcnt lgkmcnt(8)
	v_cvt_pk_bf16_f32 v2, v188, v189
	v_cvt_pk_bf16_f32 v3, v190, v191
	v_cvt_pk_bf16_f32 v4, v192, v193
	v_cvt_pk_bf16_f32 v5, v194, v195
	v_lshl_add_u64 v[10:11], v[8:9], 0, v[68:69]
	global_store_dwordx4 v[10:11], v[2:5], off
	s_nop 1
	v_or_b32_e32 v10, s0, v116
	v_lshlrev_b32_e32 v68, 11, v10
	v_cvt_pk_bf16_f32 v2, v196, v197
	v_cvt_pk_bf16_f32 v3, v198, v199
	v_cvt_pk_bf16_f32 v4, v200, v201
	v_cvt_pk_bf16_f32 v5, v202, v203
	v_lshl_add_u64 v[10:11], v[8:9], 0, v[68:69]
	global_store_dwordx4 v[10:11], v[2:5], off
	s_nop 1
	v_or_b32_e32 v10, s0, v117
	v_lshlrev_b32_e32 v68, 11, v10
	s_waitcnt lgkmcnt(0)
	v_cvt_pk_bf16_f32 v2, v204, v205
	v_cvt_pk_bf16_f32 v3, v206, v207
	v_cvt_pk_bf16_f32 v4, v208, v209
	v_cvt_pk_bf16_f32 v5, v210, v211
	v_lshl_add_u64 v[10:11], v[8:9], 0, v[68:69]
	global_store_dwordx4 v[10:11], v[2:5], off
	s_nop 1
	s_nop 0
	v_cvt_pk_bf16_f32 v2, v212, v213
	v_cvt_pk_bf16_f32 v3, v214, v215
	v_cvt_pk_bf16_f32 v4, v216, v217
	v_or_b32_e32 v5, s0, v118
	v_lshlrev_b32_e32 v68, 11, v5
	v_cvt_pk_bf16_f32 v5, v218, v219
	v_lshl_add_u64 v[6:7], v[8:9], 0, v[68:69]
	global_store_dwordx4 v[6:7], v[2:5], off
	s_nop 1
	s_waitcnt lgkmcnt(0)

.LBB0_1512:
	s_waitcnt vmcnt(0)
	v_pk_mul_f32 v[2:3], v[2:3], v[10:11] op_sel_hi:[1,0]
	v_add_u32_e32 v6, 0x1040, v19
	s_mulk_i32 s4, 0xea00
	ds_write2_b32 v6, v2, v3 offset1:1
	v_pk_mul_f32 v[2:3], v[4:5], v[10:11] op_sel_hi:[1,0]
	v_add_u32_e32 v4, 0x1048, v19
	s_add_i32 s1, s24, s4
	ds_write2_b32 v4, v2, v3 offset1:1
	s_and_b32 s0, s10, 64
	s_and_b32 s1, s1, 0xffffff00
	s_waitcnt lgkmcnt(0)
	s_or_b32 s0, s1, s0
	v_or_b32_e32 v10, s0, v90
	v_add_u32_e32 v12, 0x400, v91
	ds_read2_b32 v[188:189], v91 offset1:65
	ds_read2_b32 v[190:191], v91 offset0:130 offset1:195
	ds_read2_b32 v[192:193], v12 offset0:4 offset1:69
	ds_read2_b32 v[194:195], v12 offset0:134 offset1:199
	ds_read2_b32 v[196:197], v91 offset0:8 offset1:73
	ds_read2_b32 v[198:199], v91 offset0:138 offset1:203
	ds_read2_b32 v[200:201], v12 offset0:12 offset1:77
	ds_read2_b32 v[202:203], v12 offset0:142 offset1:207
	v_ashrrev_i32_e32 v11, 31, v10
	s_waitcnt lgkmcnt(7)
	ds_read2_b32 v[204:205], v91 offset0:16 offset1:81
	ds_read2_b32 v[206:207], v91 offset0:146 offset1:211
	ds_read2_b32 v[208:209], v12 offset0:20 offset1:85
	ds_read2_b32 v[210:211], v12 offset0:150 offset1:215
	ds_read2_b32 v[212:213], v91 offset0:24 offset1:89
	ds_read2_b32 v[214:215], v91 offset0:154 offset1:219
	ds_read2_b32 v[216:217], v12 offset0:28 offset1:93
	ds_read2_b32 v[218:219], v12 offset0:158 offset1:223
	s_waitcnt lgkmcnt(8)
	v_cvt_pk_bf16_f32 v2, v188, v189
	v_lshl_add_u64 v[6:7], s[14:15], 1, v[74:75]
	v_lshlrev_b64 v[10:11], 11, v[10:11]
	v_cvt_pk_bf16_f32 v3, v190, v191
	v_lshl_add_u64 v[10:11], v[6:7], 0, v[10:11]
	v_cvt_pk_bf16_f32 v4, v192, v193
	v_cvt_pk_bf16_f32 v5, v194, v195
	global_store_dwordx4 v[10:11], v[2:5], off
	s_nop 1
	v_or_b32_e32 v10, s0, v92
	v_ashrrev_i32_e32 v11, 31, v10
	v_cvt_pk_bf16_f32 v2, v196, v197
	v_lshlrev_b64 v[10:11], 11, v[10:11]
	v_cvt_pk_bf16_f32 v3, v198, v199
	v_lshl_add_u64 v[10:11], v[6:7], 0, v[10:11]
	v_cvt_pk_bf16_f32 v4, v200, v201
	v_cvt_pk_bf16_f32 v5, v202, v203
	global_store_dwordx4 v[10:11], v[2:5], off
	s_nop 1
	v_or_b32_e32 v10, s0, v93
	v_ashrrev_i32_e32 v11, 31, v10
	s_waitcnt lgkmcnt(7)
	ds_read2_b32 v[188:189], v91 offset0:32 offset1:97
	ds_read2_b32 v[190:191], v91 offset0:162 offset1:227
	ds_read2_b32 v[192:193], v12 offset0:36 offset1:101
	ds_read2_b32 v[194:195], v12 offset0:166 offset1:231
	ds_read2_b32 v[196:197], v91 offset0:40 offset1:105
	ds_read2_b32 v[198:199], v91 offset0:170 offset1:235
	ds_read2_b32 v[200:201], v12 offset0:44 offset1:109
	ds_read2_b32 v[202:203], v12 offset0:174 offset1:239
	s_waitcnt lgkmcnt(8)
	v_cvt_pk_bf16_f32 v2, v204, v205
	v_lshlrev_b64 v[10:11], 11, v[10:11]
	v_cvt_pk_bf16_f32 v3, v206, v207
	v_lshl_add_u64 v[10:11], v[6:7], 0, v[10:11]
	v_cvt_pk_bf16_f32 v4, v208, v209
	v_cvt_pk_bf16_f32 v5, v210, v211
	global_store_dwordx4 v[10:11], v[2:5], off
	s_nop 1
	v_or_b32_e32 v10, s0, v94
	v_ashrrev_i32_e32 v11, 31, v10
	v_cvt_pk_bf16_f32 v2, v212, v213
	v_lshlrev_b64 v[10:11], 11, v[10:11]
	v_cvt_pk_bf16_f32 v3, v214, v215
	v_lshl_add_u64 v[10:11], v[6:7], 0, v[10:11]
	v_cvt_pk_bf16_f32 v4, v216, v217
	v_cvt_pk_bf16_f32 v5, v218, v219
	global_store_dwordx4 v[10:11], v[2:5], off
	s_nop 1
	v_or_b32_e32 v10, s0, v95
	v_ashrrev_i32_e32 v11, 31, v10
	s_waitcnt lgkmcnt(7)
	ds_read2_b32 v[204:205], v91 offset0:48 offset1:113
	ds_read2_b32 v[206:207], v91 offset0:178 offset1:243
	ds_read2_b32 v[208:209], v12 offset0:52 offset1:117
	ds_read2_b32 v[210:211], v12 offset0:182 offset1:247
	ds_read2_b32 v[212:213], v91 offset0:56 offset1:121
	ds_read2_b32 v[214:215], v91 offset0:186 offset1:251
	ds_read2_b32 v[216:217], v12 offset0:60 offset1:125
	ds_read2_b32 v[218:219], v12 offset0:190 offset1:255
	s_waitcnt lgkmcnt(8)
	v_cvt_pk_bf16_f32 v2, v188, v189
	v_lshlrev_b64 v[10:11], 11, v[10:11]
	v_cvt_pk_bf16_f32 v3, v190, v191
	v_lshl_add_u64 v[10:11], v[6:7], 0, v[10:11]
	v_cvt_pk_bf16_f32 v4, v192, v193
	v_cvt_pk_bf16_f32 v5, v194, v195
	global_store_dwordx4 v[10:11], v[2:5], off
	s_nop 1
	v_or_b32_e32 v10, s0, v96
	v_ashrrev_i32_e32 v11, 31, v10
	v_cvt_pk_bf16_f32 v2, v196, v197
	v_lshlrev_b64 v[10:11], 11, v[10:11]
	v_cvt_pk_bf16_f32 v3, v198, v199
	v_lshl_add_u64 v[10:11], v[6:7], 0, v[10:11]
	v_cvt_pk_bf16_f32 v4, v200, v201
	v_cvt_pk_bf16_f32 v5, v202, v203
	global_store_dwordx4 v[10:11], v[2:5], off
	s_nop 1
	v_or_b32_e32 v10, s0, v97
	v_ashrrev_i32_e32 v11, 31, v10
	s_waitcnt lgkmcnt(0)
	v_cvt_pk_bf16_f32 v2, v204, v205
	v_lshlrev_b64 v[10:11], 11, v[10:11]
	v_cvt_pk_bf16_f32 v3, v206, v207
	v_lshl_add_u64 v[10:11], v[6:7], 0, v[10:11]
	v_cvt_pk_bf16_f32 v4, v208, v209
	v_cvt_pk_bf16_f32 v5, v210, v211
	global_store_dwordx4 v[10:11], v[2:5], off
	s_nop 1
	v_or_b32_e32 v10, s0, v98
	v_ashrrev_i32_e32 v11, 31, v10
	v_cvt_pk_bf16_f32 v2, v212, v213
	v_lshlrev_b64 v[10:11], 11, v[10:11]
	v_cvt_pk_bf16_f32 v3, v214, v215
	v_lshl_add_u64 v[6:7], v[6:7], 0, v[10:11]
	v_cvt_pk_bf16_f32 v4, v216, v217
	v_cvt_pk_bf16_f32 v5, v218, v219
	global_store_dwordx4 v[6:7], v[2:5], off
	s_nop 1
	s_waitcnt lgkmcnt(0)

.LBB0_1540:
	s_waitcnt vmcnt(0)
	v_pk_mul_f32 v[2:3], v[2:3], v[218:219] op_sel_hi:[1,0]
	v_add_u32_e32 v6, 0x1040, v19
	s_lshl_b32 s4, s16, 6
	ds_write2_b32 v6, v2, v3 offset1:1
	v_pk_mul_f32 v[2:3], v[4:5], v[218:219] op_sel_hi:[1,0]
	v_add_u32_e32 v4, 0x1048, v19
	s_and_b32 s4, 0xffff, s4
	ds_write2_b32 v4, v2, v3 offset1:1
	s_lshl_b32 s10, s4, 1
	s_waitcnt lgkmcnt(0)
	s_and_b32 s4, s4, 64
	s_and_b32 s10, s10, 0x1f00
	s_or_b32 s10, s4, s10
	v_add_u32_e32 v12, 0x400, v91
	ds_read2_b32 v[188:189], v91 offset1:65
	ds_read2_b32 v[190:191], v91 offset0:130 offset1:195
	ds_read2_b32 v[192:193], v12 offset0:4 offset1:69
	ds_read2_b32 v[194:195], v12 offset0:134 offset1:199
	ds_read2_b32 v[196:197], v91 offset0:8 offset1:73
	ds_read2_b32 v[198:199], v91 offset0:138 offset1:203
	ds_read2_b32 v[200:201], v12 offset0:12 offset1:77
	ds_read2_b32 v[202:203], v12 offset0:142 offset1:207
	s_bitset1_b32 s10, 7
	s_waitcnt lgkmcnt(7)
	ds_read2_b32 v[204:205], v91 offset0:16 offset1:81
	ds_read2_b32 v[206:207], v91 offset0:146 offset1:211
	ds_read2_b32 v[208:209], v12 offset0:20 offset1:85
	ds_read2_b32 v[210:211], v12 offset0:150 offset1:215
	ds_read2_b32 v[212:213], v91 offset0:24 offset1:89
	ds_read2_b32 v[214:215], v91 offset0:154 offset1:219
	ds_read2_b32 v[216:217], v12 offset0:28 offset1:93
	ds_read2_b32 v[218:219], v12 offset0:158 offset1:223
	s_waitcnt lgkmcnt(8)
	v_cvt_pk_bf16_f32 v2, v188, v189
	s_lshl_b32 s4, s15, 1
	v_or_b32_e32 v10, s10, v90
	v_cvt_pk_bf16_f32 v3, v190, v191
	v_lshl_add_u64 v[8:9], v[70:71], 0, s[4:5]
	v_lshlrev_b32_e32 v68, 11, v10
	v_cvt_pk_bf16_f32 v4, v192, v193
	v_cvt_pk_bf16_f32 v5, v194, v195
	v_lshl_add_u64 v[10:11], v[8:9], 0, v[68:69]
	global_store_dwordx4 v[10:11], v[2:5], off
	s_nop 1
	v_or_b32_e32 v10, s10, v92
	v_lshlrev_b32_e32 v68, 11, v10
	v_cvt_pk_bf16_f32 v2, v196, v197
	v_cvt_pk_bf16_f32 v3, v198, v199
	v_cvt_pk_bf16_f32 v4, v200, v201
	v_cvt_pk_bf16_f32 v5, v202, v203
	v_lshl_add_u64 v[10:11], v[8:9], 0, v[68:69]
	global_store_dwordx4 v[10:11], v[2:5], off
	s_nop 1
	v_or_b32_e32 v10, s10, v93
	v_lshlrev_b32_e32 v68, 11, v10
	s_waitcnt lgkmcnt(7)
	ds_read2_b32 v[188:189], v91 offset0:32 offset1:97
	ds_read2_b32 v[190:191], v91 offset0:162 offset1:227
	ds_read2_b32 v[192:193], v12 offset0:36 offset1:101
	ds_read2_b32 v[194:195], v12 offset0:166 offset1:231
	ds_read2_b32 v[196:197], v91 offset0:40 offset1:105
	ds_read2_b32 v[198:199], v91 offset0:170 offset1:235
	ds_read2_b32 v[200:201], v12 offset0:44 offset1:109
	ds_read2_b32 v[202:203], v12 offset0:174 offset1:239
	s_waitcnt lgkmcnt(8)
	v_cvt_pk_bf16_f32 v2, v204, v205
	v_cvt_pk_bf16_f32 v3, v206, v207
	v_cvt_pk_bf16_f32 v4, v208, v209
	v_cvt_pk_bf16_f32 v5, v210, v211
	v_lshl_add_u64 v[10:11], v[8:9], 0, v[68:69]
	global_store_dwordx4 v[10:11], v[2:5], off
	s_nop 1
	v_or_b32_e32 v10, s10, v94
	v_lshlrev_b32_e32 v68, 11, v10
	v_cvt_pk_bf16_f32 v2, v212, v213
	v_cvt_pk_bf16_f32 v3, v214, v215
	v_cvt_pk_bf16_f32 v4, v216, v217
	v_cvt_pk_bf16_f32 v5, v218, v219
	v_lshl_add_u64 v[10:11], v[8:9], 0, v[68:69]
	global_store_dwordx4 v[10:11], v[2:5], off
	s_nop 1
	v_or_b32_e32 v10, s10, v95
	v_lshlrev_b32_e32 v68, 11, v10
	s_waitcnt lgkmcnt(7)
	ds_read2_b32 v[204:205], v91 offset0:48 offset1:113
	ds_read2_b32 v[206:207], v91 offset0:178 offset1:243
	ds_read2_b32 v[208:209], v12 offset0:52 offset1:117
	ds_read2_b32 v[210:211], v12 offset0:182 offset1:247
	ds_read2_b32 v[212:213], v91 offset0:56 offset1:121
	ds_read2_b32 v[214:215], v91 offset0:186 offset1:251
	ds_read2_b32 v[216:217], v12 offset0:60 offset1:125
	ds_read2_b32 v[218:219], v12 offset0:190 offset1:255
	s_waitcnt lgkmcnt(8)
	v_cvt_pk_bf16_f32 v2, v188, v189
	v_cvt_pk_bf16_f32 v3, v190, v191
	v_cvt_pk_bf16_f32 v4, v192, v193
	v_cvt_pk_bf16_f32 v5, v194, v195
	v_lshl_add_u64 v[10:11], v[8:9], 0, v[68:69]
	global_store_dwordx4 v[10:11], v[2:5], off
	s_nop 1
	v_or_b32_e32 v10, s10, v96
	v_lshlrev_b32_e32 v68, 11, v10
	v_cvt_pk_bf16_f32 v2, v196, v197
	v_cvt_pk_bf16_f32 v3, v198, v199
	v_cvt_pk_bf16_f32 v4, v200, v201
	v_cvt_pk_bf16_f32 v5, v202, v203
	v_lshl_add_u64 v[10:11], v[8:9], 0, v[68:69]
	global_store_dwordx4 v[10:11], v[2:5], off
	s_nop 1
	v_or_b32_e32 v10, s10, v97
	v_lshlrev_b32_e32 v68, 11, v10
	s_waitcnt lgkmcnt(0)
	v_cvt_pk_bf16_f32 v2, v204, v205
	v_cvt_pk_bf16_f32 v3, v206, v207
	v_cvt_pk_bf16_f32 v4, v208, v209
	v_cvt_pk_bf16_f32 v5, v210, v211
	v_lshl_add_u64 v[10:11], v[8:9], 0, v[68:69]
	global_store_dwordx4 v[10:11], v[2:5], off
	s_nop 1
	s_nop 0
	v_cvt_pk_bf16_f32 v2, v212, v213
	v_cvt_pk_bf16_f32 v3, v214, v215
	v_cvt_pk_bf16_f32 v4, v216, v217
	v_or_b32_e32 v5, s10, v98
	v_lshlrev_b32_e32 v68, 11, v5
	v_cvt_pk_bf16_f32 v5, v218, v219
	v_lshl_add_u64 v[6:7], v[8:9], 0, v[68:69]
	global_store_dwordx4 v[6:7], v[2:5], off
	s_nop 1
	s_waitcnt lgkmcnt(0)
	s_mov_b64 s[10:11], 0

.LBB0_1566:
	s_waitcnt vmcnt(0)
	v_pk_mul_f32 v[2:3], v[2:3], v[218:219] op_sel_hi:[1,0]
	v_add_u32_e32 v6, 0x1040, v19
	ds_write2_b32 v6, v2, v3 offset1:1
	v_pk_mul_f32 v[2:3], v[4:5], v[218:219] op_sel_hi:[1,0]
	v_add_u32_e32 v4, 0x1048, v19
	ds_write2_b32 v4, v2, v3 offset1:1
	s_waitcnt lgkmcnt(0)
	s_lshl_b32 s0, s14, 6
	s_lshl_b32 s1, s14, 7
	s_and_b32 s1, s1, 0x1f00
	s_and_b32 s0, s0, 64
	v_add_u32_e32 v12, 0x400, v91
	ds_read2_b32 v[188:189], v91 offset1:65
	ds_read2_b32 v[190:191], v91 offset0:130 offset1:195
	ds_read2_b32 v[192:193], v12 offset0:4 offset1:69
	ds_read2_b32 v[194:195], v12 offset0:134 offset1:199
	ds_read2_b32 v[196:197], v91 offset0:8 offset1:73
	ds_read2_b32 v[198:199], v91 offset0:138 offset1:203
	ds_read2_b32 v[200:201], v12 offset0:12 offset1:77
	ds_read2_b32 v[202:203], v12 offset0:142 offset1:207
	s_or_b32 s0, s1, s0
	s_waitcnt lgkmcnt(7)
	ds_read2_b32 v[204:205], v91 offset0:16 offset1:81
	ds_read2_b32 v[206:207], v91 offset0:146 offset1:211
	ds_read2_b32 v[208:209], v12 offset0:20 offset1:85
	ds_read2_b32 v[210:211], v12 offset0:150 offset1:215
	ds_read2_b32 v[212:213], v91 offset0:24 offset1:89
	ds_read2_b32 v[214:215], v91 offset0:154 offset1:219
	ds_read2_b32 v[216:217], v12 offset0:28 offset1:93
	ds_read2_b32 v[218:219], v12 offset0:158 offset1:223
	s_waitcnt lgkmcnt(8)
	v_cvt_pk_bf16_f32 v2, v188, v189
	s_lshl_b32 s4, s15, 1
	v_or_b32_e32 v10, s0, v90
	v_cvt_pk_bf16_f32 v3, v190, v191
	v_lshl_add_u64 v[8:9], v[70:71], 0, s[4:5]
	v_lshlrev_b32_e32 v68, 11, v10
	v_cvt_pk_bf16_f32 v4, v192, v193
	v_cvt_pk_bf16_f32 v5, v194, v195
	v_lshl_add_u64 v[10:11], v[8:9], 0, v[68:69]
	global_store_dwordx4 v[10:11], v[2:5], off
	s_nop 1
	v_or_b32_e32 v10, s0, v92
	v_lshlrev_b32_e32 v68, 11, v10
	v_cvt_pk_bf16_f32 v2, v196, v197
	v_cvt_pk_bf16_f32 v3, v198, v199
	v_cvt_pk_bf16_f32 v4, v200, v201
	v_cvt_pk_bf16_f32 v5, v202, v203
	v_lshl_add_u64 v[10:11], v[8:9], 0, v[68:69]
	global_store_dwordx4 v[10:11], v[2:5], off
	s_nop 1
	v_or_b32_e32 v10, s0, v93
	v_lshlrev_b32_e32 v68, 11, v10
	s_waitcnt lgkmcnt(7)
	ds_read2_b32 v[188:189], v91 offset0:32 offset1:97
	ds_read2_b32 v[190:191], v91 offset0:162 offset1:227
	ds_read2_b32 v[192:193], v12 offset0:36 offset1:101
	ds_read2_b32 v[194:195], v12 offset0:166 offset1:231
	ds_read2_b32 v[196:197], v91 offset0:40 offset1:105
	ds_read2_b32 v[198:199], v91 offset0:170 offset1:235
	ds_read2_b32 v[200:201], v12 offset0:44 offset1:109
	ds_read2_b32 v[202:203], v12 offset0:174 offset1:239
	s_waitcnt lgkmcnt(8)
	v_cvt_pk_bf16_f32 v2, v204, v205
	v_cvt_pk_bf16_f32 v3, v206, v207
	v_cvt_pk_bf16_f32 v4, v208, v209
	v_cvt_pk_bf16_f32 v5, v210, v211
	v_lshl_add_u64 v[10:11], v[8:9], 0, v[68:69]
	global_store_dwordx4 v[10:11], v[2:5], off
	s_nop 1
	v_or_b32_e32 v10, s0, v94
	v_lshlrev_b32_e32 v68, 11, v10
	v_cvt_pk_bf16_f32 v2, v212, v213
	v_cvt_pk_bf16_f32 v3, v214, v215
	v_cvt_pk_bf16_f32 v4, v216, v217
	v_cvt_pk_bf16_f32 v5, v218, v219
	v_lshl_add_u64 v[10:11], v[8:9], 0, v[68:69]
	global_store_dwordx4 v[10:11], v[2:5], off
	s_nop 1
	v_or_b32_e32 v10, s0, v95
	v_lshlrev_b32_e32 v68, 11, v10
	s_waitcnt lgkmcnt(7)
	ds_read2_b32 v[204:205], v91 offset0:48 offset1:113
	ds_read2_b32 v[206:207], v91 offset0:178 offset1:243
	ds_read2_b32 v[208:209], v12 offset0:52 offset1:117
	ds_read2_b32 v[210:211], v12 offset0:182 offset1:247
	ds_read2_b32 v[212:213], v91 offset0:56 offset1:121
	ds_read2_b32 v[214:215], v91 offset0:186 offset1:251
	ds_read2_b32 v[216:217], v12 offset0:60 offset1:125
	ds_read2_b32 v[218:219], v12 offset0:190 offset1:255
	s_waitcnt lgkmcnt(8)
	v_cvt_pk_bf16_f32 v2, v188, v189
	v_cvt_pk_bf16_f32 v3, v190, v191
	v_cvt_pk_bf16_f32 v4, v192, v193
	v_cvt_pk_bf16_f32 v5, v194, v195
	v_lshl_add_u64 v[10:11], v[8:9], 0, v[68:69]
	global_store_dwordx4 v[10:11], v[2:5], off
	s_nop 1
	v_or_b32_e32 v10, s0, v96
	v_lshlrev_b32_e32 v68, 11, v10
	v_cvt_pk_bf16_f32 v2, v196, v197
	v_cvt_pk_bf16_f32 v3, v198, v199
	v_cvt_pk_bf16_f32 v4, v200, v201
	v_cvt_pk_bf16_f32 v5, v202, v203
	v_lshl_add_u64 v[10:11], v[8:9], 0, v[68:69]
	global_store_dwordx4 v[10:11], v[2:5], off
	s_nop 1
	v_or_b32_e32 v10, s0, v97
	v_lshlrev_b32_e32 v68, 11, v10
	s_waitcnt lgkmcnt(0)
	v_cvt_pk_bf16_f32 v2, v204, v205
	v_cvt_pk_bf16_f32 v3, v206, v207
	v_cvt_pk_bf16_f32 v4, v208, v209
	v_cvt_pk_bf16_f32 v5, v210, v211
	v_lshl_add_u64 v[10:11], v[8:9], 0, v[68:69]
	global_store_dwordx4 v[10:11], v[2:5], off
	s_nop 1
	s_nop 0
	v_cvt_pk_bf16_f32 v2, v212, v213
	v_cvt_pk_bf16_f32 v3, v214, v215
	v_cvt_pk_bf16_f32 v4, v216, v217
	v_or_b32_e32 v5, s0, v98
	v_lshlrev_b32_e32 v68, 11, v5
	v_cvt_pk_bf16_f32 v5, v218, v219
	v_lshl_add_u64 v[6:7], v[8:9], 0, v[68:69]
	global_store_dwordx4 v[6:7], v[2:5], off
	s_nop 1
	s_waitcnt lgkmcnt(0)
	s_mov_b64 s[0:1], 0

.LBB0_1568:
	s_cmpk_gt_i32 s3, 0x2bf
	s_mov_b64 s[0:1], -1
	s_cbranch_scc0 .LBB0_1598
	s_cmpk_gt_u32 s3, 0x57f
	s_cbranch_scc0 .LBB0_1571
	s_and_b32 s0, s26, 0x7fffffc0
	s_addk_i32 s0, 0xea00
	s_and_b32 s10, s12, 0x3c0
	v_or_b32_e32 v68, s0, v66
	s_lshl_b32 s4, s10, 2
	v_or_b32_e32 v4, 4, v68
	v_mov_b32_e32 v5, v69
	v_lshl_add_u64 v[62:63], v[80:81], 0, s[4:5]
	v_lshlrev_b64 v[2:3], 12, v[68:69]
	v_lshlrev_b64 v[4:5], 12, v[4:5]
	v_lshl_add_u64 v[2:3], v[62:63], 0, v[2:3]
	s_waitcnt vmcnt(0)
	v_lshl_add_u64 v[6:7], v[62:63], 0, v[4:5]
	global_load_dwordx4 v[2:5], v[2:3], off nt
	s_nop 0
	global_load_dwordx4 v[6:9], v[6:7], off nt
	v_or_b32_e32 v10, 8, v68
	v_mov_b32_e32 v11, v69
	v_or_b32_e32 v12, 12, v68
	v_mov_b32_e32 v13, v69
	v_lshlrev_b64 v[10:11], 12, v[10:11]
	v_lshlrev_b64 v[12:13], 12, v[12:13]
	v_lshl_add_u64 v[10:11], v[62:63], 0, v[10:11]
	v_lshl_add_u64 v[14:15], v[62:63], 0, v[12:13]
	global_load_dwordx4 v[10:13], v[10:11], off nt
	s_nop 0
	global_load_dwordx4 v[14:17], v[14:15], off nt
	v_or_b32_e32 v18, 16, v68
	v_mov_b32_e32 v19, v69
	v_or_b32_e32 v20, 20, v68
	v_mov_b32_e32 v21, v69
	v_lshlrev_b64 v[18:19], 12, v[18:19]
	v_lshlrev_b64 v[20:21], 12, v[20:21]
	v_lshl_add_u64 v[18:19], v[62:63], 0, v[18:19]
	v_lshl_add_u64 v[22:23], v[62:63], 0, v[20:21]
	global_load_dwordx4 v[18:21], v[18:19], off nt
	s_nop 0
	global_load_dwordx4 v[22:25], v[22:23], off nt
	v_or_b32_e32 v26, 24, v68
	v_mov_b32_e32 v27, v69
	v_or_b32_e32 v28, 28, v68
	v_mov_b32_e32 v29, v69
	v_lshlrev_b64 v[26:27], 12, v[26:27]
	v_lshlrev_b64 v[28:29], 12, v[28:29]
	v_lshl_add_u64 v[26:27], v[62:63], 0, v[26:27]
	v_lshl_add_u64 v[30:31], v[62:63], 0, v[28:29]
	global_load_dwordx4 v[26:29], v[26:27], off nt
	s_nop 0
	global_load_dwordx4 v[30:33], v[30:31], off nt
	v_or_b32_e32 v34, 32, v68
	v_mov_b32_e32 v35, v69
	v_or_b32_e32 v36, 36, v68
	v_mov_b32_e32 v37, v69
	v_lshlrev_b64 v[34:35], 12, v[34:35]
	v_lshlrev_b64 v[36:37], 12, v[36:37]
	v_lshl_add_u64 v[34:35], v[62:63], 0, v[34:35]
	v_lshl_add_u64 v[38:39], v[62:63], 0, v[36:37]
	global_load_dwordx4 v[34:37], v[34:35], off nt
	s_nop 0
	global_load_dwordx4 v[38:41], v[38:39], off nt
	v_or_b32_e32 v42, 40, v68
	v_mov_b32_e32 v43, v69
	v_or_b32_e32 v44, 44, v68
	v_mov_b32_e32 v45, v69
	v_lshlrev_b64 v[42:43], 12, v[42:43]
	v_lshlrev_b64 v[44:45], 12, v[44:45]
	v_lshl_add_u64 v[42:43], v[62:63], 0, v[42:43]
	v_lshl_add_u64 v[46:47], v[62:63], 0, v[44:45]
	global_load_dwordx4 v[42:45], v[42:43], off nt
	s_nop 0
	global_load_dwordx4 v[46:49], v[46:47], off nt
	v_or_b32_e32 v50, 48, v68
	v_mov_b32_e32 v51, v69
	v_lshlrev_b64 v[50:51], 12, v[50:51]
	v_lshl_add_u64 v[50:51], v[62:63], 0, v[50:51]
	v_or_b32_e32 v54, 52, v68
	v_mov_b32_e32 v55, v69
	global_load_dwordx4 v[50:53], v[50:51], off nt
	v_lshlrev_b64 v[54:55], 12, v[54:55]
	v_lshl_add_u64 v[54:55], v[62:63], 0, v[54:55]
	v_or_b32_e32 v58, 56, v68
	v_mov_b32_e32 v59, v69
	global_load_dwordx4 v[54:57], v[54:55], off nt
	v_lshlrev_b64 v[58:59], 12, v[58:59]
	v_lshl_add_u64 v[58:59], v[62:63], 0, v[58:59]
	v_or_b32_e32 v68, 60, v68
	global_load_dwordx4 v[58:61], v[58:59], off nt
	v_lshlrev_b64 v[64:65], 12, v[68:69]
	v_lshl_add_u64 v[62:63], v[62:63], 0, v[64:65]
	global_load_dwordx4 v[62:65], v[62:63], off nt
	v_add_u32_e32 v68, v88, v89
	s_mov_b32 s1, s5
	s_waitcnt vmcnt(15)
	ds_write2_b32 v68, v2, v3 offset1:1
	ds_write2_b32 v68, v4, v5 offset0:2 offset1:3
	v_add_u32_e32 v2, 0x410, v68
	s_waitcnt vmcnt(14)
	ds_write2_b32 v2, v6, v7 offset1:1
	v_add_u32_e32 v2, 0x418, v68
	ds_write2_b32 v2, v8, v9 offset1:1
	v_add_u32_e32 v2, 0x820, v68
	v_lshl_add_u64 v[8:9], s[0:1], 1, v[72:73]
	s_mov_b64 s[0:1], 0
	s_waitcnt vmcnt(13)
	ds_write2_b32 v2, v10, v11 offset1:1
	v_add_u32_e32 v2, 0x828, v68
	ds_write2_b32 v2, v12, v13 offset1:1
	v_add_u32_e32 v2, 0xc30, v68
	s_waitcnt vmcnt(12)
	ds_write2_b32 v2, v14, v15 offset1:1
	v_add_u32_e32 v2, 0xc38, v68
	ds_write2_b32 v2, v16, v17 offset1:1
	v_add_u32_e32 v2, 0x1040, v68
	v_or_b32_e32 v10, s10, v90
	s_waitcnt vmcnt(11)
	ds_write2_b32 v2, v18, v19 offset1:1
	v_add_u32_e32 v2, 0x1048, v68
	ds_write2_b32 v2, v20, v21 offset1:1
	v_add_u32_e32 v2, 0x1450, v68
	s_waitcnt vmcnt(10)
	ds_write2_b32 v2, v22, v23 offset1:1
	v_add_u32_e32 v2, 0x1458, v68
	ds_write2_b32 v2, v24, v25 offset1:1
	v_add_u32_e32 v2, 0x1860, v68
	v_mul_u32_u24_e32 v10, 0xb00, v10
	s_waitcnt vmcnt(9)
	ds_write2_b32 v2, v26, v27 offset1:1
	v_add_u32_e32 v2, 0x1868, v68
	ds_write2_b32 v2, v28, v29 offset1:1
	v_add_u32_e32 v2, 0x1c70, v68
	s_waitcnt vmcnt(8)
	ds_write2_b32 v2, v30, v31 offset1:1
	v_add_u32_e32 v2, 0x1c78, v68
	ds_write2_b32 v2, v32, v33 offset1:1
	v_add_u32_e32 v2, 0x2080, v68
	v_add_u32_e32 v12, 0x400, v91
	s_waitcnt vmcnt(7)
	ds_write2_b32 v2, v34, v35 offset1:1
	v_add_u32_e32 v2, 0x2088, v68
	ds_write2_b32 v2, v36, v37 offset1:1
	v_add_u32_e32 v2, 0x2490, v68
	s_waitcnt vmcnt(6)
	ds_write2_b32 v2, v38, v39 offset1:1
	v_add_u32_e32 v2, 0x2498, v68
	ds_write2_b32 v2, v40, v41 offset1:1
	v_add_u32_e32 v2, 0x28a0, v68
	s_waitcnt vmcnt(5)
	ds_write2_b32 v2, v42, v43 offset1:1
	v_add_u32_e32 v2, 0x28a8, v68
	ds_write2_b32 v2, v44, v45 offset1:1
	v_add_u32_e32 v2, 0x2cb0, v68
	s_waitcnt vmcnt(4)
	ds_write2_b32 v2, v46, v47 offset1:1
	v_add_u32_e32 v2, 0x2cb8, v68
	ds_write2_b32 v2, v48, v49 offset1:1
	v_add_u32_e32 v2, 0x30c0, v68
	s_waitcnt vmcnt(3)
	ds_write2_b32 v2, v50, v51 offset1:1
	v_add_u32_e32 v2, 0x30c8, v68
	ds_write2_b32 v2, v52, v53 offset1:1
	v_add_u32_e32 v2, 0x34d0, v68
	s_waitcnt vmcnt(2)
	ds_write2_b32 v2, v54, v55 offset1:1
	v_add_u32_e32 v2, 0x34d8, v68
	ds_write2_b32 v2, v56, v57 offset1:1
	v_add_u32_e32 v2, 0x38e0, v68
	s_waitcnt vmcnt(1)
	ds_write2_b32 v2, v58, v59 offset1:1
	v_add_u32_e32 v2, 0x38e8, v68
	ds_write2_b32 v2, v60, v61 offset1:1
	v_add_u32_e32 v2, 0x3cf0, v68
	s_waitcnt vmcnt(0)
	ds_write2_b32 v2, v62, v63 offset1:1
	v_add_u32_e32 v2, 0x3cf8, v68
	ds_write2_b32 v2, v64, v65 offset1:1
	s_waitcnt lgkmcnt(0)
	ds_read2_b32 v[188:189], v91 offset1:65
	ds_read2_b32 v[190:191], v91 offset0:130 offset1:195
	ds_read2_b32 v[192:193], v12 offset0:4 offset1:69
	ds_read2_b32 v[194:195], v12 offset0:134 offset1:199
	ds_read2_b32 v[196:197], v91 offset0:8 offset1:73
	ds_read2_b32 v[198:199], v91 offset0:138 offset1:203
	ds_read2_b32 v[200:201], v12 offset0:12 offset1:77
	ds_read2_b32 v[202:203], v12 offset0:142 offset1:207
	s_waitcnt lgkmcnt(7)
	ds_read2_b32 v[204:205], v91 offset0:16 offset1:81
	ds_read2_b32 v[206:207], v91 offset0:146 offset1:211
	ds_read2_b32 v[208:209], v12 offset0:20 offset1:85
	ds_read2_b32 v[210:211], v12 offset0:150 offset1:215
	ds_read2_b32 v[212:213], v91 offset0:24 offset1:89
	ds_read2_b32 v[214:215], v91 offset0:154 offset1:219
	ds_read2_b32 v[216:217], v12 offset0:28 offset1:93
	ds_read2_b32 v[218:219], v12 offset0:158 offset1:223
	s_waitcnt lgkmcnt(8)
	v_cvt_pk_bf16_f32 v2, v188, v189
	v_lshlrev_b32_e32 v68, 1, v10
	v_cvt_pk_bf16_f32 v3, v190, v191
	v_lshl_add_u64 v[10:11], v[8:9], 0, v[68:69]
	v_cvt_pk_bf16_f32 v4, v192, v193
	v_cvt_pk_bf16_f32 v5, v194, v195
	global_store_dwordx4 v[10:11], v[2:5], off
	s_nop 1
	v_or_b32_e32 v10, s10, v92
	v_mul_u32_u24_e32 v10, 0xb00, v10
	v_cvt_pk_bf16_f32 v2, v196, v197
	v_lshlrev_b32_e32 v68, 1, v10
	v_cvt_pk_bf16_f32 v3, v198, v199
	v_lshl_add_u64 v[10:11], v[8:9], 0, v[68:69]
	v_cvt_pk_bf16_f32 v4, v200, v201
	v_cvt_pk_bf16_f32 v5, v202, v203
	global_store_dwordx4 v[10:11], v[2:5], off
	s_nop 1
	v_or_b32_e32 v10, s10, v93
	v_mul_u32_u24_e32 v10, 0xb00, v10
	s_waitcnt lgkmcnt(7)
	ds_read2_b32 v[188:189], v91 offset0:32 offset1:97
	ds_read2_b32 v[190:191], v91 offset0:162 offset1:227
	ds_read2_b32 v[192:193], v12 offset0:36 offset1:101
	ds_read2_b32 v[194:195], v12 offset0:166 offset1:231
	ds_read2_b32 v[196:197], v91 offset0:40 offset1:105
	ds_read2_b32 v[198:199], v91 offset0:170 offset1:235
	ds_read2_b32 v[200:201], v12 offset0:44 offset1:109
	ds_read2_b32 v[202:203], v12 offset0:174 offset1:239
	s_waitcnt lgkmcnt(8)
	v_cvt_pk_bf16_f32 v2, v204, v205
	v_lshlrev_b32_e32 v68, 1, v10
	v_cvt_pk_bf16_f32 v3, v206, v207
	v_lshl_add_u64 v[10:11], v[8:9], 0, v[68:69]
	v_cvt_pk_bf16_f32 v4, v208, v209
	v_cvt_pk_bf16_f32 v5, v210, v211
	global_store_dwordx4 v[10:11], v[2:5], off
	s_nop 1
	v_or_b32_e32 v10, s10, v94
	v_mul_u32_u24_e32 v10, 0xb00, v10
	v_cvt_pk_bf16_f32 v2, v212, v213
	v_lshlrev_b32_e32 v68, 1, v10
	v_cvt_pk_bf16_f32 v3, v214, v215
	v_lshl_add_u64 v[10:11], v[8:9], 0, v[68:69]
	v_cvt_pk_bf16_f32 v4, v216, v217
	v_cvt_pk_bf16_f32 v5, v218, v219
	global_store_dwordx4 v[10:11], v[2:5], off
	s_nop 1
	v_or_b32_e32 v10, s10, v95
	v_mul_u32_u24_e32 v10, 0xb00, v10
	s_waitcnt lgkmcnt(7)
	ds_read2_b32 v[204:205], v91 offset0:48 offset1:113
	ds_read2_b32 v[206:207], v91 offset0:178 offset1:243
	ds_read2_b32 v[208:209], v12 offset0:52 offset1:117
	ds_read2_b32 v[210:211], v12 offset0:182 offset1:247
	ds_read2_b32 v[212:213], v91 offset0:56 offset1:121
	ds_read2_b32 v[214:215], v91 offset0:186 offset1:251
	ds_read2_b32 v[216:217], v12 offset0:60 offset1:125
	ds_read2_b32 v[218:219], v12 offset0:190 offset1:255
	s_waitcnt lgkmcnt(8)
	v_cvt_pk_bf16_f32 v2, v188, v189
	v_lshlrev_b32_e32 v68, 1, v10
	v_cvt_pk_bf16_f32 v3, v190, v191
	v_lshl_add_u64 v[10:11], v[8:9], 0, v[68:69]
	v_cvt_pk_bf16_f32 v4, v192, v193
	v_cvt_pk_bf16_f32 v5, v194, v195
	global_store_dwordx4 v[10:11], v[2:5], off
	s_nop 1
	v_or_b32_e32 v10, s10, v96
	v_mul_u32_u24_e32 v10, 0xb00, v10
	v_cvt_pk_bf16_f32 v2, v196, v197
	v_lshlrev_b32_e32 v68, 1, v10
	v_cvt_pk_bf16_f32 v3, v198, v199
	v_lshl_add_u64 v[10:11], v[8:9], 0, v[68:69]
	v_cvt_pk_bf16_f32 v4, v200, v201
	v_cvt_pk_bf16_f32 v5, v202, v203
	global_store_dwordx4 v[10:11], v[2:5], off
	s_nop 1
	v_or_b32_e32 v10, s10, v97
	s_waitcnt lgkmcnt(0)
	v_cvt_pk_bf16_f32 v2, v204, v205
	v_mul_u32_u24_e32 v10, 0xb00, v10
	v_cvt_pk_bf16_f32 v3, v206, v207
	v_lshlrev_b32_e32 v68, 1, v10
	v_cvt_pk_bf16_f32 v4, v208, v209
	v_cvt_pk_bf16_f32 v5, v210, v211
	v_lshl_add_u64 v[10:11], v[8:9], 0, v[68:69]
	global_store_dwordx4 v[10:11], v[2:5], off
	s_nop 1
	s_nop 0
	v_cvt_pk_bf16_f32 v2, v212, v213
	v_cvt_pk_bf16_f32 v3, v214, v215
	v_cvt_pk_bf16_f32 v4, v216, v217
	v_cvt_pk_bf16_f32 v5, v218, v219
	v_or_b32_e32 v6, s10, v98
	v_mul_u32_u24_e32 v6, 0xb00, v6
	v_lshlrev_b32_e32 v68, 1, v6
	v_lshl_add_u64 v[6:7], v[8:9], 0, v[68:69]
	global_store_dwordx4 v[6:7], v[2:5], off
	s_nop 1
	s_waitcnt lgkmcnt(0)

.LBB0_1596:
	s_waitcnt vmcnt(0)
	v_pk_mul_f32 v[2:3], v[2:3], v[218:219] op_sel_hi:[1,0]
	v_add_u32_e32 v6, 0x1040, v19
	s_lshl_b32 s0, s15, 6
	ds_write2_b32 v6, v2, v3 offset1:1
	v_pk_mul_f32 v[2:3], v[4:5], v[218:219] op_sel_hi:[1,0]
	v_add_u32_e32 v4, 0x1048, v19
	s_and_b32 s0, 0xffff, s0
	ds_write2_b32 v4, v2, v3 offset1:1
	s_lshl_b32 s1, s0, 1
	s_waitcnt lgkmcnt(0)
	s_and_b32 s0, s0, 64
	s_and_b32 s1, s1, 0x1f00
	s_or_b32 s0, s0, s1
	v_add_u32_e32 v12, 0x400, v91
	ds_read2_b32 v[188:189], v91 offset1:65
	ds_read2_b32 v[190:191], v91 offset0:130 offset1:195
	ds_read2_b32 v[192:193], v12 offset0:4 offset1:69
	ds_read2_b32 v[194:195], v12 offset0:134 offset1:199
	ds_read2_b32 v[196:197], v91 offset0:8 offset1:73
	ds_read2_b32 v[198:199], v91 offset0:138 offset1:203
	ds_read2_b32 v[200:201], v12 offset0:12 offset1:77
	ds_read2_b32 v[202:203], v12 offset0:142 offset1:207
	s_bitset1_b32 s0, 7
	s_waitcnt lgkmcnt(7)
	ds_read2_b32 v[204:205], v91 offset0:16 offset1:81
	ds_read2_b32 v[206:207], v91 offset0:146 offset1:211
	ds_read2_b32 v[208:209], v12 offset0:20 offset1:85
	ds_read2_b32 v[210:211], v12 offset0:150 offset1:215
	ds_read2_b32 v[212:213], v91 offset0:24 offset1:89
	ds_read2_b32 v[214:215], v91 offset0:154 offset1:219
	ds_read2_b32 v[216:217], v12 offset0:28 offset1:93
	ds_read2_b32 v[218:219], v12 offset0:158 offset1:223
	s_waitcnt lgkmcnt(8)
	v_cvt_pk_bf16_f32 v2, v188, v189
	s_lshl_b32 s4, s14, 1
	v_or_b32_e32 v10, s0, v90
	v_cvt_pk_bf16_f32 v3, v190, v191
	v_lshl_add_u64 v[8:9], v[74:75], 0, s[4:5]
	v_lshlrev_b32_e32 v68, 11, v10
	v_cvt_pk_bf16_f32 v4, v192, v193
	v_cvt_pk_bf16_f32 v5, v194, v195
	v_lshl_add_u64 v[10:11], v[8:9], 0, v[68:69]
	global_store_dwordx4 v[10:11], v[2:5], off
	s_nop 1
	v_or_b32_e32 v10, s0, v92
	v_lshlrev_b32_e32 v68, 11, v10
	v_cvt_pk_bf16_f32 v2, v196, v197
	v_cvt_pk_bf16_f32 v3, v198, v199
	v_cvt_pk_bf16_f32 v4, v200, v201
	v_cvt_pk_bf16_f32 v5, v202, v203
	v_lshl_add_u64 v[10:11], v[8:9], 0, v[68:69]
	global_store_dwordx4 v[10:11], v[2:5], off
	s_nop 1
	v_or_b32_e32 v10, s0, v93
	v_lshlrev_b32_e32 v68, 11, v10
	s_waitcnt lgkmcnt(7)
	ds_read2_b32 v[188:189], v91 offset0:32 offset1:97
	ds_read2_b32 v[190:191], v91 offset0:162 offset1:227
	ds_read2_b32 v[192:193], v12 offset0:36 offset1:101
	ds_read2_b32 v[194:195], v12 offset0:166 offset1:231
	ds_read2_b32 v[196:197], v91 offset0:40 offset1:105
	ds_read2_b32 v[198:199], v91 offset0:170 offset1:235
	ds_read2_b32 v[200:201], v12 offset0:44 offset1:109
	ds_read2_b32 v[202:203], v12 offset0:174 offset1:239
	s_waitcnt lgkmcnt(8)
	v_cvt_pk_bf16_f32 v2, v204, v205
	v_cvt_pk_bf16_f32 v3, v206, v207
	v_cvt_pk_bf16_f32 v4, v208, v209
	v_cvt_pk_bf16_f32 v5, v210, v211
	v_lshl_add_u64 v[10:11], v[8:9], 0, v[68:69]
	global_store_dwordx4 v[10:11], v[2:5], off
	s_nop 1
	v_or_b32_e32 v10, s0, v94
	v_lshlrev_b32_e32 v68, 11, v10
	v_cvt_pk_bf16_f32 v2, v212, v213
	v_cvt_pk_bf16_f32 v3, v214, v215
	v_cvt_pk_bf16_f32 v4, v216, v217
	v_cvt_pk_bf16_f32 v5, v218, v219
	v_lshl_add_u64 v[10:11], v[8:9], 0, v[68:69]
	global_store_dwordx4 v[10:11], v[2:5], off
	s_nop 1
	v_or_b32_e32 v10, s0, v95
	v_lshlrev_b32_e32 v68, 11, v10
	s_waitcnt lgkmcnt(7)
	ds_read2_b32 v[204:205], v91 offset0:48 offset1:113
	ds_read2_b32 v[206:207], v91 offset0:178 offset1:243
	ds_read2_b32 v[208:209], v12 offset0:52 offset1:117
	ds_read2_b32 v[210:211], v12 offset0:182 offset1:247
	ds_read2_b32 v[212:213], v91 offset0:56 offset1:121
	ds_read2_b32 v[214:215], v91 offset0:186 offset1:251
	ds_read2_b32 v[216:217], v12 offset0:60 offset1:125
	ds_read2_b32 v[218:219], v12 offset0:190 offset1:255
	s_waitcnt lgkmcnt(8)
	v_cvt_pk_bf16_f32 v2, v188, v189
	v_cvt_pk_bf16_f32 v3, v190, v191
	v_cvt_pk_bf16_f32 v4, v192, v193
	v_cvt_pk_bf16_f32 v5, v194, v195
	v_lshl_add_u64 v[10:11], v[8:9], 0, v[68:69]
	global_store_dwordx4 v[10:11], v[2:5], off
	s_nop 1
	v_or_b32_e32 v10, s0, v96
	v_lshlrev_b32_e32 v68, 11, v10
	v_cvt_pk_bf16_f32 v2, v196, v197
	v_cvt_pk_bf16_f32 v3, v198, v199
	v_cvt_pk_bf16_f32 v4, v200, v201
	v_cvt_pk_bf16_f32 v5, v202, v203
	v_lshl_add_u64 v[10:11], v[8:9], 0, v[68:69]
	global_store_dwordx4 v[10:11], v[2:5], off
	s_nop 1
	v_or_b32_e32 v10, s0, v97
	v_lshlrev_b32_e32 v68, 11, v10
	s_waitcnt lgkmcnt(0)
	v_cvt_pk_bf16_f32 v2, v204, v205
	v_cvt_pk_bf16_f32 v3, v206, v207
	v_cvt_pk_bf16_f32 v4, v208, v209
	v_cvt_pk_bf16_f32 v5, v210, v211
	v_lshl_add_u64 v[10:11], v[8:9], 0, v[68:69]
	global_store_dwordx4 v[10:11], v[2:5], off
	s_nop 1
	s_nop 0
	v_cvt_pk_bf16_f32 v2, v212, v213
	v_cvt_pk_bf16_f32 v3, v214, v215
	v_cvt_pk_bf16_f32 v4, v216, v217
	v_or_b32_e32 v5, s0, v98
	v_lshlrev_b32_e32 v68, 11, v5
	v_cvt_pk_bf16_f32 v5, v218, v219
	v_lshl_add_u64 v[6:7], v[8:9], 0, v[68:69]
	global_store_dwordx4 v[6:7], v[2:5], off
	s_nop 1
	s_waitcnt lgkmcnt(0)

.LBB0_1734:
	s_waitcnt vmcnt(0)
	v_pk_mul_f32 v[2:3], v[2:3], v[10:11] op_sel_hi:[1,0]
	v_add_u32_e32 v6, 0xc30, v11
	s_mulk_i32 s10, 0xea00
	ds_write2_b32 v6, v2, v3 offset1:1
	v_pk_mul_f32 v[2:3], v[4:5], v[10:11] op_sel_hi:[1,0]
	v_add_u32_e32 v4, 0xc38, v11
	s_add_i32 s1, s24, s10
	ds_write2_b32 v4, v2, v3 offset1:1
	s_and_b32 s0, s14, 64
	s_and_b32 s1, s1, 0xffffff00
	s_waitcnt lgkmcnt(0)
	s_or_b32 s0, s1, s0
	v_or_b32_e32 v10, s0, v94
	ds_read2_b32 v[188:189], v95 offset1:65
	ds_read2_b32 v[190:191], v95 offset0:130 offset1:195
	ds_read2_b32 v[192:193], v145 offset0:4 offset1:69
	ds_read2_b32 v[194:195], v145 offset0:134 offset1:199
	ds_read2_b32 v[196:197], v95 offset0:8 offset1:73
	ds_read2_b32 v[198:199], v95 offset0:138 offset1:203
	ds_read2_b32 v[200:201], v145 offset0:12 offset1:77
	ds_read2_b32 v[202:203], v145 offset0:142 offset1:207
	v_ashrrev_i32_e32 v11, 31, v10
	s_waitcnt lgkmcnt(7)
	ds_read2_b32 v[204:205], v95 offset0:16 offset1:81
	ds_read2_b32 v[206:207], v95 offset0:146 offset1:211
	ds_read2_b32 v[208:209], v145 offset0:20 offset1:85
	ds_read2_b32 v[210:211], v145 offset0:150 offset1:215
	ds_read2_b32 v[212:213], v95 offset0:24 offset1:89
	ds_read2_b32 v[214:215], v95 offset0:154 offset1:219
	ds_read2_b32 v[216:217], v145 offset0:28 offset1:93
	ds_read2_b32 v[218:219], v145 offset0:158 offset1:223
	s_waitcnt lgkmcnt(8)
	v_cvt_pk_bf16_f32 v2, v188, v189
	v_lshl_add_u64 v[6:7], s[16:17], 1, v[74:75]
	v_lshlrev_b64 v[10:11], 11, v[10:11]
	v_cvt_pk_bf16_f32 v3, v190, v191
	v_lshl_add_u64 v[10:11], v[6:7], 0, v[10:11]
	v_cvt_pk_bf16_f32 v4, v192, v193
	v_cvt_pk_bf16_f32 v5, v194, v195
	global_store_dwordx4 v[10:11], v[2:5], off
	s_nop 1
	v_or_b32_e32 v10, s0, v96
	v_ashrrev_i32_e32 v11, 31, v10
	v_cvt_pk_bf16_f32 v2, v196, v197
	v_lshlrev_b64 v[10:11], 11, v[10:11]
	v_cvt_pk_bf16_f32 v3, v198, v199
	v_lshl_add_u64 v[10:11], v[6:7], 0, v[10:11]
	v_cvt_pk_bf16_f32 v4, v200, v201
	v_cvt_pk_bf16_f32 v5, v202, v203
	global_store_dwordx4 v[10:11], v[2:5], off
	s_nop 1
	v_or_b32_e32 v10, s0, v97
	v_ashrrev_i32_e32 v11, 31, v10
	s_waitcnt lgkmcnt(7)
	ds_read2_b32 v[188:189], v95 offset0:32 offset1:97
	ds_read2_b32 v[190:191], v95 offset0:162 offset1:227
	ds_read2_b32 v[192:193], v145 offset0:36 offset1:101
	ds_read2_b32 v[194:195], v145 offset0:166 offset1:231
	ds_read2_b32 v[196:197], v95 offset0:40 offset1:105
	ds_read2_b32 v[198:199], v95 offset0:170 offset1:235
	ds_read2_b32 v[200:201], v145 offset0:44 offset1:109
	ds_read2_b32 v[202:203], v145 offset0:174 offset1:239
	s_waitcnt lgkmcnt(8)
	v_cvt_pk_bf16_f32 v2, v204, v205
	v_lshlrev_b64 v[10:11], 11, v[10:11]
	v_cvt_pk_bf16_f32 v3, v206, v207
	v_lshl_add_u64 v[10:11], v[6:7], 0, v[10:11]
	v_cvt_pk_bf16_f32 v4, v208, v209
	v_cvt_pk_bf16_f32 v5, v210, v211
	global_store_dwordx4 v[10:11], v[2:5], off
	s_nop 1
	v_or_b32_e32 v10, s0, v98
	v_ashrrev_i32_e32 v11, 31, v10
	v_cvt_pk_bf16_f32 v2, v212, v213
	v_lshlrev_b64 v[10:11], 11, v[10:11]
	v_cvt_pk_bf16_f32 v3, v214, v215
	v_lshl_add_u64 v[10:11], v[6:7], 0, v[10:11]
	v_cvt_pk_bf16_f32 v4, v216, v217
	v_cvt_pk_bf16_f32 v5, v218, v219
	global_store_dwordx4 v[10:11], v[2:5], off
	s_nop 1
	v_or_b32_e32 v10, s0, v99
	v_ashrrev_i32_e32 v11, 31, v10
	s_waitcnt lgkmcnt(7)
	ds_read2_b32 v[204:205], v95 offset0:48 offset1:113
	ds_read2_b32 v[206:207], v95 offset0:178 offset1:243
	ds_read2_b32 v[208:209], v145 offset0:52 offset1:117
	ds_read2_b32 v[210:211], v145 offset0:182 offset1:247
	ds_read2_b32 v[212:213], v95 offset0:56 offset1:121
	ds_read2_b32 v[214:215], v95 offset0:186 offset1:251
	ds_read2_b32 v[216:217], v145 offset0:60 offset1:125
	ds_read2_b32 v[218:219], v145 offset0:190 offset1:255
	s_waitcnt lgkmcnt(8)
	v_cvt_pk_bf16_f32 v2, v188, v189
	v_lshlrev_b64 v[10:11], 11, v[10:11]
	v_cvt_pk_bf16_f32 v3, v190, v191
	v_lshl_add_u64 v[10:11], v[6:7], 0, v[10:11]
	v_cvt_pk_bf16_f32 v4, v192, v193
	v_cvt_pk_bf16_f32 v5, v194, v195
	global_store_dwordx4 v[10:11], v[2:5], off
	s_nop 1
	v_or_b32_e32 v10, s0, v100
	v_ashrrev_i32_e32 v11, 31, v10
	v_cvt_pk_bf16_f32 v2, v196, v197
	v_lshlrev_b64 v[10:11], 11, v[10:11]
	v_cvt_pk_bf16_f32 v3, v198, v199
	v_lshl_add_u64 v[10:11], v[6:7], 0, v[10:11]
	v_cvt_pk_bf16_f32 v4, v200, v201
	v_cvt_pk_bf16_f32 v5, v202, v203
	global_store_dwordx4 v[10:11], v[2:5], off
	s_nop 1
	v_or_b32_e32 v10, s0, v101
	v_ashrrev_i32_e32 v11, 31, v10
	s_waitcnt lgkmcnt(0)
	v_cvt_pk_bf16_f32 v2, v204, v205
	v_lshlrev_b64 v[10:11], 11, v[10:11]
	v_cvt_pk_bf16_f32 v3, v206, v207
	v_lshl_add_u64 v[10:11], v[6:7], 0, v[10:11]
	v_cvt_pk_bf16_f32 v4, v208, v209
	v_cvt_pk_bf16_f32 v5, v210, v211
	global_store_dwordx4 v[10:11], v[2:5], off
	s_nop 1
	v_or_b32_e32 v10, s0, v102
	v_ashrrev_i32_e32 v11, 31, v10
	v_cvt_pk_bf16_f32 v2, v212, v213
	v_lshlrev_b64 v[10:11], 11, v[10:11]
	v_cvt_pk_bf16_f32 v3, v214, v215
	v_lshl_add_u64 v[6:7], v[6:7], 0, v[10:11]
	v_cvt_pk_bf16_f32 v4, v216, v217
	v_cvt_pk_bf16_f32 v5, v218, v219
	global_store_dwordx4 v[6:7], v[2:5], off
	s_nop 1
	s_waitcnt lgkmcnt(0)

.LBB0_1736:
	s_cmpk_gt_i32 s3, 0x83f
	s_mov_b64 s[0:1], -1
	s_cbranch_scc0 .LBB0_1794
	s_add_i32 s16, s3, 0xfffff7c0
	s_cmpk_gt_u32 s16, 0x2bf
	s_cbranch_scc0 .LBB0_1767
	s_cmpk_gt_u32 s16, 0x57f
	s_cbranch_scc0 .LBB0_1740
	s_add_i32 s0, s22, 0xfffdf000
	s_and_b32 s12, s0, 0x3c0
	s_add_i32 s0, s26, 0xffffdf00
	s_and_b32 s0, s0, 0x7fffffc0
	s_addk_i32 s0, 0xea00
	v_or_b32_e32 v88, s0, v66
	s_lshl_b32 s10, s12, 2
	v_or_b32_e32 v4, 4, v88
	v_mov_b32_e32 v5, v89
	s_waitcnt vmcnt(0)
	v_or_b32_e32 v10, 8, v88
	v_mov_b32_e32 v11, v89
	v_or_b32_e32 v12, 12, v88
	v_mov_b32_e32 v13, v89
	v_or_b32_e32 v18, 16, v88
	v_mov_b32_e32 v19, v89
	v_or_b32_e32 v20, 20, v88
	v_mov_b32_e32 v21, v89
	v_or_b32_e32 v26, 24, v88
	v_mov_b32_e32 v27, v89
	v_or_b32_e32 v28, 28, v88
	v_mov_b32_e32 v29, v89
	v_or_b32_e32 v34, 32, v88
	v_mov_b32_e32 v35, v89
	v_or_b32_e32 v36, 36, v88
	v_mov_b32_e32 v37, v89
	v_or_b32_e32 v42, 40, v88
	v_mov_b32_e32 v43, v89
	v_or_b32_e32 v44, 44, v88
	v_mov_b32_e32 v45, v89
	v_or_b32_e32 v50, 48, v88
	v_mov_b32_e32 v51, v89
	v_or_b32_e32 v52, 52, v88
	v_mov_b32_e32 v53, v89
	v_lshl_add_u64 v[62:63], v[76:77], 0, s[10:11]
	v_lshlrev_b64 v[2:3], 12, v[88:89]
	v_lshlrev_b64 v[4:5], 12, v[4:5]
	v_lshlrev_b64 v[10:11], 12, v[10:11]
	v_lshlrev_b64 v[12:13], 12, v[12:13]
	v_lshlrev_b64 v[18:19], 12, v[18:19]
	v_lshlrev_b64 v[20:21], 12, v[20:21]
	v_lshlrev_b64 v[26:27], 12, v[26:27]
	v_lshlrev_b64 v[28:29], 12, v[28:29]
	v_lshlrev_b64 v[34:35], 12, v[34:35]
	v_lshlrev_b64 v[36:37], 12, v[36:37]
	v_lshlrev_b64 v[42:43], 12, v[42:43]
	v_lshlrev_b64 v[44:45], 12, v[44:45]
	v_lshlrev_b64 v[50:51], 12, v[50:51]
	v_lshlrev_b64 v[52:53], 12, v[52:53]
	v_lshl_add_u64 v[2:3], v[62:63], 0, v[2:3]
	v_lshl_add_u64 v[6:7], v[62:63], 0, v[4:5]
	v_lshl_add_u64 v[10:11], v[62:63], 0, v[10:11]
	v_lshl_add_u64 v[14:15], v[62:63], 0, v[12:13]
	v_lshl_add_u64 v[18:19], v[62:63], 0, v[18:19]
	v_lshl_add_u64 v[22:23], v[62:63], 0, v[20:21]
	v_lshl_add_u64 v[26:27], v[62:63], 0, v[26:27]
	v_lshl_add_u64 v[30:31], v[62:63], 0, v[28:29]
	v_lshl_add_u64 v[34:35], v[62:63], 0, v[34:35]
	v_lshl_add_u64 v[38:39], v[62:63], 0, v[36:37]
	v_lshl_add_u64 v[42:43], v[62:63], 0, v[42:43]
	v_lshl_add_u64 v[46:47], v[62:63], 0, v[44:45]
	v_lshl_add_u64 v[50:51], v[62:63], 0, v[50:51]
	v_lshl_add_u64 v[54:55], v[62:63], 0, v[52:53]
	global_load_dwordx4 v[2:5], v[2:3], off nt
	s_nop 0
	global_load_dwordx4 v[6:9], v[6:7], off nt
	s_nop 0
	global_load_dwordx4 v[10:13], v[10:11], off nt
	s_nop 0
	global_load_dwordx4 v[14:17], v[14:15], off nt
	s_nop 0
	global_load_dwordx4 v[18:21], v[18:19], off nt
	s_nop 0
	global_load_dwordx4 v[22:25], v[22:23], off nt
	s_nop 0
	global_load_dwordx4 v[26:29], v[26:27], off nt
	s_nop 0
	global_load_dwordx4 v[30:33], v[30:31], off nt
	s_nop 0
	global_load_dwordx4 v[34:37], v[34:35], off nt
	s_nop 0
	global_load_dwordx4 v[38:41], v[38:39], off nt
	s_nop 0
	global_load_dwordx4 v[42:45], v[42:43], off nt
	s_nop 0
	global_load_dwordx4 v[46:49], v[46:47], off nt
	s_nop 0
	global_load_dwordx4 v[50:53], v[50:51], off nt
	s_nop 0
	global_load_dwordx4 v[54:57], v[54:55], off nt
	v_or_b32_e32 v58, 56, v88
	v_mov_b32_e32 v59, v89
	v_lshlrev_b64 v[58:59], 12, v[58:59]
	v_lshl_add_u64 v[58:59], v[62:63], 0, v[58:59]
	v_or_b32_e32 v88, 60, v88
	global_load_dwordx4 v[58:61], v[58:59], off nt
	v_lshlrev_b64 v[64:65], 12, v[88:89]
	v_lshl_add_u64 v[62:63], v[62:63], 0, v[64:65]
	global_load_dwordx4 v[62:65], v[62:63], off nt
	s_mov_b32 s1, s11
	s_waitcnt vmcnt(15)
	ds_write2_b32 v93, v2, v3 offset1:1
	ds_write2_b32 v93, v4, v5 offset0:2 offset1:3
	s_waitcnt vmcnt(14)
	ds_write2_b32 v115, v6, v7 offset1:1
	ds_write2_b32 v116, v8, v9 offset1:1
	s_waitcnt vmcnt(13)
	ds_write2_b32 v117, v10, v11 offset1:1
	ds_write2_b32 v118, v12, v13 offset1:1
	s_waitcnt vmcnt(12)
	ds_write2_b32 v119, v14, v15 offset1:1
	ds_write2_b32 v120, v16, v17 offset1:1
	s_waitcnt vmcnt(11)
	ds_write2_b32 v121, v18, v19 offset1:1
	ds_write2_b32 v122, v20, v21 offset1:1
	s_waitcnt vmcnt(10)
	ds_write2_b32 v123, v22, v23 offset1:1
	ds_write2_b32 v124, v24, v25 offset1:1
	s_waitcnt vmcnt(9)
	ds_write2_b32 v125, v26, v27 offset1:1
	ds_write2_b32 v126, v28, v29 offset1:1
	s_waitcnt vmcnt(8)
	ds_write2_b32 v127, v30, v31 offset1:1
	ds_write2_b32 v128, v32, v33 offset1:1
	s_waitcnt vmcnt(7)
	ds_write2_b32 v129, v34, v35 offset1:1
	ds_write2_b32 v130, v36, v37 offset1:1
	s_waitcnt vmcnt(6)
	ds_write2_b32 v131, v38, v39 offset1:1
	ds_write2_b32 v132, v40, v41 offset1:1
	s_waitcnt vmcnt(5)
	ds_write2_b32 v133, v42, v43 offset1:1
	ds_write2_b32 v134, v44, v45 offset1:1
	s_waitcnt vmcnt(4)
	ds_write2_b32 v135, v46, v47 offset1:1
	ds_write2_b32 v136, v48, v49 offset1:1
	s_waitcnt vmcnt(3)
	ds_write2_b32 v137, v50, v51 offset1:1
	ds_write2_b32 v138, v52, v53 offset1:1
	s_waitcnt vmcnt(2)
	ds_write2_b32 v139, v54, v55 offset1:1
	ds_write2_b32 v140, v56, v57 offset1:1
	s_waitcnt vmcnt(1)
	ds_write2_b32 v141, v58, v59 offset1:1
	ds_write2_b32 v142, v60, v61 offset1:1
	s_waitcnt vmcnt(0)
	ds_write2_b32 v143, v62, v63 offset1:1
	ds_write2_b32 v144, v64, v65 offset1:1
	s_waitcnt lgkmcnt(0)
	v_or_b32_e32 v10, s12, v94
	ds_read2_b32 v[188:189], v95 offset1:65
	ds_read2_b32 v[190:191], v95 offset0:130 offset1:195
	ds_read2_b32 v[192:193], v145 offset0:4 offset1:69
	ds_read2_b32 v[194:195], v145 offset0:134 offset1:199
	ds_read2_b32 v[196:197], v95 offset0:8 offset1:73
	ds_read2_b32 v[198:199], v95 offset0:138 offset1:203
	ds_read2_b32 v[200:201], v145 offset0:12 offset1:77
	ds_read2_b32 v[202:203], v145 offset0:142 offset1:207
	v_mul_u32_u24_e32 v10, 0xb00, v10
	s_waitcnt lgkmcnt(7)
	ds_read2_b32 v[204:205], v95 offset0:16 offset1:81
	ds_read2_b32 v[206:207], v95 offset0:146 offset1:211
	ds_read2_b32 v[208:209], v145 offset0:20 offset1:85
	ds_read2_b32 v[210:211], v145 offset0:150 offset1:215
	ds_read2_b32 v[212:213], v95 offset0:24 offset1:89
	ds_read2_b32 v[214:215], v95 offset0:154 offset1:219
	ds_read2_b32 v[216:217], v145 offset0:28 offset1:93
	ds_read2_b32 v[218:219], v145 offset0:158 offset1:223
	s_waitcnt lgkmcnt(8)
	v_cvt_pk_bf16_f32 v2, v188, v189
	v_lshl_add_u64 v[8:9], s[0:1], 1, v[68:69]
	v_lshlrev_b32_e32 v88, 1, v10
	v_cvt_pk_bf16_f32 v3, v190, v191
	v_lshl_add_u64 v[10:11], v[8:9], 0, v[88:89]
	v_cvt_pk_bf16_f32 v4, v192, v193
	v_cvt_pk_bf16_f32 v5, v194, v195
	global_store_dwordx4 v[10:11], v[2:5], off
	s_nop 1
	v_or_b32_e32 v10, s12, v96
	v_mul_u32_u24_e32 v10, 0xb00, v10
	v_cvt_pk_bf16_f32 v2, v196, v197
	v_lshlrev_b32_e32 v88, 1, v10
	v_cvt_pk_bf16_f32 v3, v198, v199
	v_lshl_add_u64 v[10:11], v[8:9], 0, v[88:89]
	v_cvt_pk_bf16_f32 v4, v200, v201
	v_cvt_pk_bf16_f32 v5, v202, v203
	global_store_dwordx4 v[10:11], v[2:5], off
	s_nop 1
	v_or_b32_e32 v10, s12, v97
	v_mul_u32_u24_e32 v10, 0xb00, v10
	s_waitcnt lgkmcnt(7)
	ds_read2_b32 v[188:189], v95 offset0:32 offset1:97
	ds_read2_b32 v[190:191], v95 offset0:162 offset1:227
	ds_read2_b32 v[192:193], v145 offset0:36 offset1:101
	ds_read2_b32 v[194:195], v145 offset0:166 offset1:231
	ds_read2_b32 v[196:197], v95 offset0:40 offset1:105
	ds_read2_b32 v[198:199], v95 offset0:170 offset1:235
	ds_read2_b32 v[200:201], v145 offset0:44 offset1:109
	ds_read2_b32 v[202:203], v145 offset0:174 offset1:239
	s_waitcnt lgkmcnt(8)
	v_cvt_pk_bf16_f32 v2, v204, v205
	v_lshlrev_b32_e32 v88, 1, v10
	v_cvt_pk_bf16_f32 v3, v206, v207
	v_lshl_add_u64 v[10:11], v[8:9], 0, v[88:89]
	v_cvt_pk_bf16_f32 v4, v208, v209
	v_cvt_pk_bf16_f32 v5, v210, v211
	global_store_dwordx4 v[10:11], v[2:5], off
	s_nop 1
	v_or_b32_e32 v10, s12, v98
	v_mul_u32_u24_e32 v10, 0xb00, v10
	v_cvt_pk_bf16_f32 v2, v212, v213
	v_lshlrev_b32_e32 v88, 1, v10
	v_cvt_pk_bf16_f32 v3, v214, v215
	v_lshl_add_u64 v[10:11], v[8:9], 0, v[88:89]
	v_cvt_pk_bf16_f32 v4, v216, v217
	v_cvt_pk_bf16_f32 v5, v218, v219
	global_store_dwordx4 v[10:11], v[2:5], off
	s_nop 1
	v_or_b32_e32 v10, s12, v99
	v_mul_u32_u24_e32 v10, 0xb00, v10
	s_waitcnt lgkmcnt(7)
	ds_read2_b32 v[204:205], v95 offset0:48 offset1:113
	ds_read2_b32 v[206:207], v95 offset0:178 offset1:243
	ds_read2_b32 v[208:209], v145 offset0:52 offset1:117
	ds_read2_b32 v[210:211], v145 offset0:182 offset1:247
	ds_read2_b32 v[212:213], v95 offset0:56 offset1:121
	ds_read2_b32 v[214:215], v95 offset0:186 offset1:251
	ds_read2_b32 v[216:217], v145 offset0:60 offset1:125
	ds_read2_b32 v[218:219], v145 offset0:190 offset1:255
	s_waitcnt lgkmcnt(8)
	v_cvt_pk_bf16_f32 v2, v188, v189
	v_lshlrev_b32_e32 v88, 1, v10
	v_cvt_pk_bf16_f32 v3, v190, v191
	v_lshl_add_u64 v[10:11], v[8:9], 0, v[88:89]
	v_cvt_pk_bf16_f32 v4, v192, v193
	v_cvt_pk_bf16_f32 v5, v194, v195
	global_store_dwordx4 v[10:11], v[2:5], off
	s_nop 1
	v_or_b32_e32 v10, s12, v100
	v_mul_u32_u24_e32 v10, 0xb00, v10
	v_cvt_pk_bf16_f32 v2, v196, v197
	v_lshlrev_b32_e32 v88, 1, v10
	v_cvt_pk_bf16_f32 v3, v198, v199
	v_lshl_add_u64 v[10:11], v[8:9], 0, v[88:89]
	v_cvt_pk_bf16_f32 v4, v200, v201
	v_cvt_pk_bf16_f32 v5, v202, v203
	global_store_dwordx4 v[10:11], v[2:5], off
	s_nop 1
	v_or_b32_e32 v10, s12, v101
	s_waitcnt lgkmcnt(0)
	v_cvt_pk_bf16_f32 v2, v204, v205
	v_mul_u32_u24_e32 v10, 0xb00, v10
	v_cvt_pk_bf16_f32 v3, v206, v207
	v_lshlrev_b32_e32 v88, 1, v10
	v_cvt_pk_bf16_f32 v4, v208, v209
	v_cvt_pk_bf16_f32 v5, v210, v211
	v_lshl_add_u64 v[10:11], v[8:9], 0, v[88:89]
	global_store_dwordx4 v[10:11], v[2:5], off
	s_nop 1
	s_mov_b64 s[0:1], 0
	v_cvt_pk_bf16_f32 v2, v212, v213
	v_cvt_pk_bf16_f32 v3, v214, v215
	v_cvt_pk_bf16_f32 v4, v216, v217
	v_or_b32_e32 v5, s12, v102
	v_mul_u32_u24_e32 v5, 0xb00, v5
	v_lshlrev_b32_e32 v88, 1, v5
	v_cvt_pk_bf16_f32 v5, v218, v219
	v_lshl_add_u64 v[6:7], v[8:9], 0, v[88:89]
	global_store_dwordx4 v[6:7], v[2:5], off
	s_nop 1
	s_waitcnt lgkmcnt(0)

.LBB0_1765:
	s_waitcnt vmcnt(0)
	v_pk_mul_f32 v[2:3], v[2:3], v[10:11] op_sel_hi:[1,0]
	v_add_u32_e32 v6, 0xc30, v11
	s_lshl_b32 s0, s20, 6
	ds_write2_b32 v6, v2, v3 offset1:1
	v_pk_mul_f32 v[2:3], v[4:5], v[10:11] op_sel_hi:[1,0]
	v_add_u32_e32 v4, 0xc38, v11
	s_and_b32 s0, 0xffff, s0
	ds_write2_b32 v4, v2, v3 offset1:1
	s_lshl_b32 s1, s0, 1
	s_waitcnt lgkmcnt(0)
	s_and_b32 s0, s0, 64
	s_and_b32 s1, s1, 0x1f00
	s_or_b32 s0, s0, s1
	ds_read2_b32 v[188:189], v95 offset1:65
	ds_read2_b32 v[190:191], v95 offset0:130 offset1:195
	ds_read2_b32 v[192:193], v145 offset0:4 offset1:69
	ds_read2_b32 v[194:195], v145 offset0:134 offset1:199
	ds_read2_b32 v[196:197], v95 offset0:8 offset1:73
	ds_read2_b32 v[198:199], v95 offset0:138 offset1:203
	ds_read2_b32 v[200:201], v145 offset0:12 offset1:77
	ds_read2_b32 v[202:203], v145 offset0:142 offset1:207
	s_bitset1_b32 s0, 7
	s_waitcnt lgkmcnt(7)
	ds_read2_b32 v[204:205], v95 offset0:16 offset1:81
	ds_read2_b32 v[206:207], v95 offset0:146 offset1:211
	ds_read2_b32 v[208:209], v145 offset0:20 offset1:85
	ds_read2_b32 v[210:211], v145 offset0:150 offset1:215
	ds_read2_b32 v[212:213], v95 offset0:24 offset1:89
	ds_read2_b32 v[214:215], v95 offset0:154 offset1:219
	ds_read2_b32 v[216:217], v145 offset0:28 offset1:93
	ds_read2_b32 v[218:219], v145 offset0:158 offset1:223
	s_waitcnt lgkmcnt(8)
	v_cvt_pk_bf16_f32 v2, v188, v189
	s_lshl_b32 s10, s17, 1
	v_or_b32_e32 v10, s0, v94
	v_cvt_pk_bf16_f32 v3, v190, v191
	v_lshl_add_u64 v[6:7], v[70:71], 0, s[10:11]
	v_lshlrev_b32_e32 v88, 11, v10
	v_cvt_pk_bf16_f32 v4, v192, v193
	v_cvt_pk_bf16_f32 v5, v194, v195
	v_lshl_add_u64 v[10:11], v[6:7], 0, v[88:89]
	global_store_dwordx4 v[10:11], v[2:5], off
	s_nop 1
	v_or_b32_e32 v10, s0, v96
	v_lshlrev_b32_e32 v88, 11, v10
	v_cvt_pk_bf16_f32 v2, v196, v197
	v_cvt_pk_bf16_f32 v3, v198, v199
	v_cvt_pk_bf16_f32 v4, v200, v201
	v_cvt_pk_bf16_f32 v5, v202, v203
	v_lshl_add_u64 v[10:11], v[6:7], 0, v[88:89]
	global_store_dwordx4 v[10:11], v[2:5], off
	s_nop 1
	v_or_b32_e32 v10, s0, v97
	v_lshlrev_b32_e32 v88, 11, v10
	s_waitcnt lgkmcnt(7)
	ds_read2_b32 v[188:189], v95 offset0:32 offset1:97
	ds_read2_b32 v[190:191], v95 offset0:162 offset1:227
	ds_read2_b32 v[192:193], v145 offset0:36 offset1:101
	ds_read2_b32 v[194:195], v145 offset0:166 offset1:231
	ds_read2_b32 v[196:197], v95 offset0:40 offset1:105
	ds_read2_b32 v[198:199], v95 offset0:170 offset1:235
	ds_read2_b32 v[200:201], v145 offset0:44 offset1:109
	ds_read2_b32 v[202:203], v145 offset0:174 offset1:239
	s_waitcnt lgkmcnt(8)
	v_cvt_pk_bf16_f32 v2, v204, v205
	v_cvt_pk_bf16_f32 v3, v206, v207
	v_cvt_pk_bf16_f32 v4, v208, v209
	v_cvt_pk_bf16_f32 v5, v210, v211
	v_lshl_add_u64 v[10:11], v[6:7], 0, v[88:89]
	global_store_dwordx4 v[10:11], v[2:5], off
	s_nop 1
	v_or_b32_e32 v10, s0, v98
	v_lshlrev_b32_e32 v88, 11, v10
	v_cvt_pk_bf16_f32 v2, v212, v213
	v_cvt_pk_bf16_f32 v3, v214, v215
	v_cvt_pk_bf16_f32 v4, v216, v217
	v_cvt_pk_bf16_f32 v5, v218, v219
	v_lshl_add_u64 v[10:11], v[6:7], 0, v[88:89]
	global_store_dwordx4 v[10:11], v[2:5], off
	s_nop 1
	v_or_b32_e32 v10, s0, v99
	v_lshlrev_b32_e32 v88, 11, v10
	s_waitcnt lgkmcnt(7)
	ds_read2_b32 v[204:205], v95 offset0:48 offset1:113
	ds_read2_b32 v[206:207], v95 offset0:178 offset1:243
	ds_read2_b32 v[208:209], v145 offset0:52 offset1:117
	ds_read2_b32 v[210:211], v145 offset0:182 offset1:247
	ds_read2_b32 v[212:213], v95 offset0:56 offset1:121
	ds_read2_b32 v[214:215], v95 offset0:186 offset1:251
	ds_read2_b32 v[216:217], v145 offset0:60 offset1:125
	ds_read2_b32 v[218:219], v145 offset0:190 offset1:255
	s_waitcnt lgkmcnt(8)
	v_cvt_pk_bf16_f32 v2, v188, v189
	v_cvt_pk_bf16_f32 v3, v190, v191
	v_cvt_pk_bf16_f32 v4, v192, v193
	v_cvt_pk_bf16_f32 v5, v194, v195
	v_lshl_add_u64 v[10:11], v[6:7], 0, v[88:89]
	global_store_dwordx4 v[10:11], v[2:5], off
	s_nop 1
	v_or_b32_e32 v10, s0, v100
	v_lshlrev_b32_e32 v88, 11, v10
	v_cvt_pk_bf16_f32 v2, v196, v197
	v_cvt_pk_bf16_f32 v3, v198, v199
	v_cvt_pk_bf16_f32 v4, v200, v201
	v_cvt_pk_bf16_f32 v5, v202, v203
	v_lshl_add_u64 v[10:11], v[6:7], 0, v[88:89]
	global_store_dwordx4 v[10:11], v[2:5], off
	s_nop 1
	v_or_b32_e32 v10, s0, v101
	v_lshlrev_b32_e32 v88, 11, v10
	s_waitcnt lgkmcnt(0)
	v_cvt_pk_bf16_f32 v2, v204, v205
	v_cvt_pk_bf16_f32 v3, v206, v207
	v_cvt_pk_bf16_f32 v4, v208, v209
	v_cvt_pk_bf16_f32 v5, v210, v211
	v_lshl_add_u64 v[10:11], v[6:7], 0, v[88:89]
	global_store_dwordx4 v[10:11], v[2:5], off
	s_nop 1
	s_nop 0
	v_cvt_pk_bf16_f32 v2, v212, v213
	v_cvt_pk_bf16_f32 v3, v214, v215
	v_cvt_pk_bf16_f32 v4, v216, v217
	v_or_b32_e32 v5, s0, v102
	v_lshlrev_b32_e32 v88, 11, v5
	v_lshl_add_u64 v[6:7], v[6:7], 0, v[88:89]
	v_cvt_pk_bf16_f32 v5, v218, v219
	global_store_dwordx4 v[6:7], v[2:5], off
	s_nop 1
	s_waitcnt lgkmcnt(0)

.LBB0_1792:
	s_waitcnt vmcnt(0)
	v_pk_mul_f32 v[2:3], v[2:3], v[10:11] op_sel_hi:[1,0]
	v_add_u32_e32 v6, 0xc30, v11
	ds_write2_b32 v6, v2, v3 offset1:1
	v_pk_mul_f32 v[2:3], v[4:5], v[10:11] op_sel_hi:[1,0]
	v_add_u32_e32 v4, 0xc38, v11
	ds_write2_b32 v4, v2, v3 offset1:1
	s_waitcnt lgkmcnt(0)
	s_lshl_b32 s0, s16, 6
	s_lshl_b32 s1, s16, 7
	s_and_b32 s1, s1, 0x1f00
	s_and_b32 s0, s0, 64
	ds_read2_b32 v[188:189], v95 offset1:65
	ds_read2_b32 v[190:191], v95 offset0:130 offset1:195
	ds_read2_b32 v[192:193], v145 offset0:4 offset1:69
	ds_read2_b32 v[194:195], v145 offset0:134 offset1:199
	ds_read2_b32 v[196:197], v95 offset0:8 offset1:73
	ds_read2_b32 v[198:199], v95 offset0:138 offset1:203
	ds_read2_b32 v[200:201], v145 offset0:12 offset1:77
	ds_read2_b32 v[202:203], v145 offset0:142 offset1:207
	s_or_b32 s0, s1, s0
	s_waitcnt lgkmcnt(7)
	ds_read2_b32 v[204:205], v95 offset0:16 offset1:81
	ds_read2_b32 v[206:207], v95 offset0:146 offset1:211
	ds_read2_b32 v[208:209], v145 offset0:20 offset1:85
	ds_read2_b32 v[210:211], v145 offset0:150 offset1:215
	ds_read2_b32 v[212:213], v95 offset0:24 offset1:89
	ds_read2_b32 v[214:215], v95 offset0:154 offset1:219
	ds_read2_b32 v[216:217], v145 offset0:28 offset1:93
	ds_read2_b32 v[218:219], v145 offset0:158 offset1:223
	s_waitcnt lgkmcnt(8)
	v_cvt_pk_bf16_f32 v2, v188, v189
	s_lshl_b32 s10, s17, 1
	v_or_b32_e32 v10, s0, v94
	v_cvt_pk_bf16_f32 v3, v190, v191
	v_lshl_add_u64 v[8:9], v[70:71], 0, s[10:11]
	v_lshlrev_b32_e32 v88, 11, v10
	v_cvt_pk_bf16_f32 v4, v192, v193
	v_cvt_pk_bf16_f32 v5, v194, v195
	v_lshl_add_u64 v[10:11], v[8:9], 0, v[88:89]
	global_store_dwordx4 v[10:11], v[2:5], off
	s_nop 1
	v_or_b32_e32 v10, s0, v96
	v_lshlrev_b32_e32 v88, 11, v10
	v_cvt_pk_bf16_f32 v2, v196, v197
	v_cvt_pk_bf16_f32 v3, v198, v199
	v_cvt_pk_bf16_f32 v4, v200, v201
	v_cvt_pk_bf16_f32 v5, v202, v203
	v_lshl_add_u64 v[10:11], v[8:9], 0, v[88:89]
	global_store_dwordx4 v[10:11], v[2:5], off
	s_nop 1
	v_or_b32_e32 v10, s0, v97
	v_lshlrev_b32_e32 v88, 11, v10
	s_waitcnt lgkmcnt(7)
	ds_read2_b32 v[188:189], v95 offset0:32 offset1:97
	ds_read2_b32 v[190:191], v95 offset0:162 offset1:227
	ds_read2_b32 v[192:193], v145 offset0:36 offset1:101
	ds_read2_b32 v[194:195], v145 offset0:166 offset1:231
	ds_read2_b32 v[196:197], v95 offset0:40 offset1:105
	ds_read2_b32 v[198:199], v95 offset0:170 offset1:235
	ds_read2_b32 v[200:201], v145 offset0:44 offset1:109
	ds_read2_b32 v[202:203], v145 offset0:174 offset1:239
	s_waitcnt lgkmcnt(8)
	v_cvt_pk_bf16_f32 v2, v204, v205
	v_cvt_pk_bf16_f32 v3, v206, v207
	v_cvt_pk_bf16_f32 v4, v208, v209
	v_cvt_pk_bf16_f32 v5, v210, v211
	v_lshl_add_u64 v[10:11], v[8:9], 0, v[88:89]
	global_store_dwordx4 v[10:11], v[2:5], off
	s_nop 1
	v_or_b32_e32 v10, s0, v98
	v_lshlrev_b32_e32 v88, 11, v10
	v_cvt_pk_bf16_f32 v2, v212, v213
	v_cvt_pk_bf16_f32 v3, v214, v215
	v_cvt_pk_bf16_f32 v4, v216, v217
	v_cvt_pk_bf16_f32 v5, v218, v219
	v_lshl_add_u64 v[10:11], v[8:9], 0, v[88:89]
	global_store_dwordx4 v[10:11], v[2:5], off
	s_nop 1
	v_or_b32_e32 v10, s0, v99
	v_lshlrev_b32_e32 v88, 11, v10
	s_waitcnt lgkmcnt(7)
	ds_read2_b32 v[204:205], v95 offset0:48 offset1:113
	ds_read2_b32 v[206:207], v95 offset0:178 offset1:243
	ds_read2_b32 v[208:209], v145 offset0:52 offset1:117
	ds_read2_b32 v[210:211], v145 offset0:182 offset1:247
	ds_read2_b32 v[212:213], v95 offset0:56 offset1:121
	ds_read2_b32 v[214:215], v95 offset0:186 offset1:251
	ds_read2_b32 v[216:217], v145 offset0:60 offset1:125
	ds_read2_b32 v[218:219], v145 offset0:190 offset1:255
	s_waitcnt lgkmcnt(8)
	v_cvt_pk_bf16_f32 v2, v188, v189
	v_cvt_pk_bf16_f32 v3, v190, v191
	v_cvt_pk_bf16_f32 v4, v192, v193
	v_cvt_pk_bf16_f32 v5, v194, v195
	v_lshl_add_u64 v[10:11], v[8:9], 0, v[88:89]
	global_store_dwordx4 v[10:11], v[2:5], off
	s_nop 1
	v_or_b32_e32 v10, s0, v100
	v_lshlrev_b32_e32 v88, 11, v10
	v_cvt_pk_bf16_f32 v2, v196, v197
	v_cvt_pk_bf16_f32 v3, v198, v199
	v_cvt_pk_bf16_f32 v4, v200, v201
	v_cvt_pk_bf16_f32 v5, v202, v203
	v_lshl_add_u64 v[10:11], v[8:9], 0, v[88:89]
	global_store_dwordx4 v[10:11], v[2:5], off
	s_nop 1
	v_or_b32_e32 v10, s0, v101
	v_lshlrev_b32_e32 v88, 11, v10
	s_waitcnt lgkmcnt(0)
	v_cvt_pk_bf16_f32 v2, v204, v205
	v_cvt_pk_bf16_f32 v3, v206, v207
	v_cvt_pk_bf16_f32 v4, v208, v209
	v_cvt_pk_bf16_f32 v5, v210, v211
	v_lshl_add_u64 v[10:11], v[8:9], 0, v[88:89]
	global_store_dwordx4 v[10:11], v[2:5], off
	s_nop 1
	s_nop 0
	v_cvt_pk_bf16_f32 v2, v212, v213
	v_cvt_pk_bf16_f32 v3, v214, v215
	v_cvt_pk_bf16_f32 v4, v216, v217
	v_or_b32_e32 v5, s0, v102
	v_lshlrev_b32_e32 v88, 11, v5
	v_cvt_pk_bf16_f32 v5, v218, v219
	v_lshl_add_u64 v[6:7], v[8:9], 0, v[88:89]
	global_store_dwordx4 v[6:7], v[2:5], off
	s_nop 1
	s_waitcnt lgkmcnt(0)

.LBB0_1794:
	s_andn2_b64 vcc, exec, s[0:1]
	s_cbranch_vccnz .LBB0_1735
	s_cmpk_gt_i32 s3, 0x2bf
	s_mov_b64 s[0:1], -1
	s_cbranch_scc0 .LBB0_1825
	s_cmpk_gt_u32 s3, 0x57f
	s_cbranch_scc0 .LBB0_1798
	s_and_b32 s0, s26, 0x7fffffc0
	s_addk_i32 s0, 0xea00
	s_and_b32 s12, s22, 0x3c0
	v_or_b32_e32 v88, s0, v66
	s_lshl_b32 s10, s12, 2
	v_or_b32_e32 v4, 4, v88
	v_mov_b32_e32 v5, v89
	s_waitcnt vmcnt(0)
	v_or_b32_e32 v10, 8, v88
	v_mov_b32_e32 v11, v89
	v_or_b32_e32 v12, 12, v88
	v_mov_b32_e32 v13, v89
	v_or_b32_e32 v18, 16, v88
	v_mov_b32_e32 v19, v89
	v_or_b32_e32 v20, 20, v88
	v_mov_b32_e32 v21, v89
	v_or_b32_e32 v26, 24, v88
	v_mov_b32_e32 v27, v89
	v_or_b32_e32 v28, 28, v88
	v_mov_b32_e32 v29, v89
	v_or_b32_e32 v34, 32, v88
	v_mov_b32_e32 v35, v89
	v_or_b32_e32 v36, 36, v88
	v_mov_b32_e32 v37, v89
	v_or_b32_e32 v42, 40, v88
	v_mov_b32_e32 v43, v89
	v_or_b32_e32 v44, 44, v88
	v_mov_b32_e32 v45, v89
	v_or_b32_e32 v50, 48, v88
	v_mov_b32_e32 v51, v89
	v_or_b32_e32 v52, 52, v88
	v_mov_b32_e32 v53, v89
	v_lshl_add_u64 v[62:63], v[82:83], 0, s[10:11]
	v_lshlrev_b64 v[2:3], 12, v[88:89]
	v_lshlrev_b64 v[4:5], 12, v[4:5]
	v_lshlrev_b64 v[10:11], 12, v[10:11]
	v_lshlrev_b64 v[12:13], 12, v[12:13]
	v_lshlrev_b64 v[18:19], 12, v[18:19]
	v_lshlrev_b64 v[20:21], 12, v[20:21]
	v_lshlrev_b64 v[26:27], 12, v[26:27]
	v_lshlrev_b64 v[28:29], 12, v[28:29]
	v_lshlrev_b64 v[34:35], 12, v[34:35]
	v_lshlrev_b64 v[36:37], 12, v[36:37]
	v_lshlrev_b64 v[42:43], 12, v[42:43]
	v_lshlrev_b64 v[44:45], 12, v[44:45]
	v_lshlrev_b64 v[50:51], 12, v[50:51]
	v_lshlrev_b64 v[52:53], 12, v[52:53]
	v_lshl_add_u64 v[2:3], v[62:63], 0, v[2:3]
	v_lshl_add_u64 v[6:7], v[62:63], 0, v[4:5]
	v_lshl_add_u64 v[10:11], v[62:63], 0, v[10:11]
	v_lshl_add_u64 v[14:15], v[62:63], 0, v[12:13]
	v_lshl_add_u64 v[18:19], v[62:63], 0, v[18:19]
	v_lshl_add_u64 v[22:23], v[62:63], 0, v[20:21]
	v_lshl_add_u64 v[26:27], v[62:63], 0, v[26:27]
	v_lshl_add_u64 v[30:31], v[62:63], 0, v[28:29]
	v_lshl_add_u64 v[34:35], v[62:63], 0, v[34:35]
	v_lshl_add_u64 v[38:39], v[62:63], 0, v[36:37]
	v_lshl_add_u64 v[42:43], v[62:63], 0, v[42:43]
	v_lshl_add_u64 v[46:47], v[62:63], 0, v[44:45]
	v_lshl_add_u64 v[50:51], v[62:63], 0, v[50:51]
	v_lshl_add_u64 v[54:55], v[62:63], 0, v[52:53]
	global_load_dwordx4 v[2:5], v[2:3], off nt
	s_nop 0
	global_load_dwordx4 v[6:9], v[6:7], off nt
	s_nop 0
	global_load_dwordx4 v[10:13], v[10:11], off nt
	s_nop 0
	global_load_dwordx4 v[14:17], v[14:15], off nt
	s_nop 0
	global_load_dwordx4 v[18:21], v[18:19], off nt
	s_nop 0
	global_load_dwordx4 v[22:25], v[22:23], off nt
	s_nop 0
	global_load_dwordx4 v[26:29], v[26:27], off nt
	s_nop 0
	global_load_dwordx4 v[30:33], v[30:31], off nt
	s_nop 0
	global_load_dwordx4 v[34:37], v[34:35], off nt
	s_nop 0
	global_load_dwordx4 v[38:41], v[38:39], off nt
	s_nop 0
	global_load_dwordx4 v[42:45], v[42:43], off nt
	s_nop 0
	global_load_dwordx4 v[46:49], v[46:47], off nt
	s_nop 0
	global_load_dwordx4 v[50:53], v[50:51], off nt
	s_nop 0
	global_load_dwordx4 v[54:57], v[54:55], off nt
	v_or_b32_e32 v58, 56, v88
	v_mov_b32_e32 v59, v89
	v_lshlrev_b64 v[58:59], 12, v[58:59]
	v_lshl_add_u64 v[58:59], v[62:63], 0, v[58:59]
	v_or_b32_e32 v88, 60, v88
	global_load_dwordx4 v[58:61], v[58:59], off nt
	v_lshlrev_b64 v[64:65], 12, v[88:89]
	v_lshl_add_u64 v[62:63], v[62:63], 0, v[64:65]
	global_load_dwordx4 v[62:65], v[62:63], off nt
	s_mov_b32 s1, s11
	s_waitcnt vmcnt(15)
	ds_write2_b32 v93, v2, v3 offset1:1
	ds_write2_b32 v93, v4, v5 offset0:2 offset1:3
	s_waitcnt vmcnt(14)
	ds_write2_b32 v115, v6, v7 offset1:1
	ds_write2_b32 v116, v8, v9 offset1:1
	s_waitcnt vmcnt(13)
	ds_write2_b32 v117, v10, v11 offset1:1
	ds_write2_b32 v118, v12, v13 offset1:1
	s_waitcnt vmcnt(12)
	ds_write2_b32 v119, v14, v15 offset1:1
	ds_write2_b32 v120, v16, v17 offset1:1
	s_waitcnt vmcnt(11)
	ds_write2_b32 v121, v18, v19 offset1:1
	ds_write2_b32 v122, v20, v21 offset1:1
	s_waitcnt vmcnt(10)
	ds_write2_b32 v123, v22, v23 offset1:1
	ds_write2_b32 v124, v24, v25 offset1:1
	s_waitcnt vmcnt(9)
	ds_write2_b32 v125, v26, v27 offset1:1
	ds_write2_b32 v126, v28, v29 offset1:1
	s_waitcnt vmcnt(8)
	ds_write2_b32 v127, v30, v31 offset1:1
	ds_write2_b32 v128, v32, v33 offset1:1
	s_waitcnt vmcnt(7)
	ds_write2_b32 v129, v34, v35 offset1:1
	ds_write2_b32 v130, v36, v37 offset1:1
	s_waitcnt vmcnt(6)
	ds_write2_b32 v131, v38, v39 offset1:1
	ds_write2_b32 v132, v40, v41 offset1:1
	s_waitcnt vmcnt(5)
	ds_write2_b32 v133, v42, v43 offset1:1
	ds_write2_b32 v134, v44, v45 offset1:1
	s_waitcnt vmcnt(4)
	ds_write2_b32 v135, v46, v47 offset1:1
	ds_write2_b32 v136, v48, v49 offset1:1
	s_waitcnt vmcnt(3)
	ds_write2_b32 v137, v50, v51 offset1:1
	ds_write2_b32 v138, v52, v53 offset1:1
	s_waitcnt vmcnt(2)
	ds_write2_b32 v139, v54, v55 offset1:1
	ds_write2_b32 v140, v56, v57 offset1:1
	s_waitcnt vmcnt(1)
	ds_write2_b32 v141, v58, v59 offset1:1
	ds_write2_b32 v142, v60, v61 offset1:1
	s_waitcnt vmcnt(0)
	ds_write2_b32 v143, v62, v63 offset1:1
	ds_write2_b32 v144, v64, v65 offset1:1
	s_waitcnt lgkmcnt(0)
	v_or_b32_e32 v10, s12, v94
	ds_read2_b32 v[188:189], v95 offset1:65
	ds_read2_b32 v[190:191], v95 offset0:130 offset1:195
	ds_read2_b32 v[192:193], v145 offset0:4 offset1:69
	ds_read2_b32 v[194:195], v145 offset0:134 offset1:199
	ds_read2_b32 v[196:197], v95 offset0:8 offset1:73
	ds_read2_b32 v[198:199], v95 offset0:138 offset1:203
	ds_read2_b32 v[200:201], v145 offset0:12 offset1:77
	ds_read2_b32 v[202:203], v145 offset0:142 offset1:207
	v_mul_u32_u24_e32 v10, 0xb00, v10
	s_waitcnt lgkmcnt(7)
	ds_read2_b32 v[204:205], v95 offset0:16 offset1:81
	ds_read2_b32 v[206:207], v95 offset0:146 offset1:211
	ds_read2_b32 v[208:209], v145 offset0:20 offset1:85
	ds_read2_b32 v[210:211], v145 offset0:150 offset1:215
	ds_read2_b32 v[212:213], v95 offset0:24 offset1:89
	ds_read2_b32 v[214:215], v95 offset0:154 offset1:219
	ds_read2_b32 v[216:217], v145 offset0:28 offset1:93
	ds_read2_b32 v[218:219], v145 offset0:158 offset1:223
	s_waitcnt lgkmcnt(8)
	v_cvt_pk_bf16_f32 v2, v188, v189
	v_lshl_add_u64 v[8:9], s[0:1], 1, v[72:73]
	v_lshlrev_b32_e32 v88, 1, v10
	v_cvt_pk_bf16_f32 v3, v190, v191
	v_lshl_add_u64 v[10:11], v[8:9], 0, v[88:89]
	v_cvt_pk_bf16_f32 v4, v192, v193
	v_cvt_pk_bf16_f32 v5, v194, v195
	global_store_dwordx4 v[10:11], v[2:5], off
	s_nop 1
	v_or_b32_e32 v10, s12, v96
	v_mul_u32_u24_e32 v10, 0xb00, v10
	v_cvt_pk_bf16_f32 v2, v196, v197
	v_lshlrev_b32_e32 v88, 1, v10
	v_cvt_pk_bf16_f32 v3, v198, v199
	v_lshl_add_u64 v[10:11], v[8:9], 0, v[88:89]
	v_cvt_pk_bf16_f32 v4, v200, v201
	v_cvt_pk_bf16_f32 v5, v202, v203
	global_store_dwordx4 v[10:11], v[2:5], off
	s_nop 1
	v_or_b32_e32 v10, s12, v97
	v_mul_u32_u24_e32 v10, 0xb00, v10
	s_waitcnt lgkmcnt(7)
	ds_read2_b32 v[188:189], v95 offset0:32 offset1:97
	ds_read2_b32 v[190:191], v95 offset0:162 offset1:227
	ds_read2_b32 v[192:193], v145 offset0:36 offset1:101
	ds_read2_b32 v[194:195], v145 offset0:166 offset1:231
	ds_read2_b32 v[196:197], v95 offset0:40 offset1:105
	ds_read2_b32 v[198:199], v95 offset0:170 offset1:235
	ds_read2_b32 v[200:201], v145 offset0:44 offset1:109
	ds_read2_b32 v[202:203], v145 offset0:174 offset1:239
	s_waitcnt lgkmcnt(8)
	v_cvt_pk_bf16_f32 v2, v204, v205
	v_lshlrev_b32_e32 v88, 1, v10
	v_cvt_pk_bf16_f32 v3, v206, v207
	v_lshl_add_u64 v[10:11], v[8:9], 0, v[88:89]
	v_cvt_pk_bf16_f32 v4, v208, v209
	v_cvt_pk_bf16_f32 v5, v210, v211
	global_store_dwordx4 v[10:11], v[2:5], off
	s_nop 1
	v_or_b32_e32 v10, s12, v98
	v_mul_u32_u24_e32 v10, 0xb00, v10
	v_cvt_pk_bf16_f32 v2, v212, v213
	v_lshlrev_b32_e32 v88, 1, v10
	v_cvt_pk_bf16_f32 v3, v214, v215
	v_lshl_add_u64 v[10:11], v[8:9], 0, v[88:89]
	v_cvt_pk_bf16_f32 v4, v216, v217
	v_cvt_pk_bf16_f32 v5, v218, v219
	global_store_dwordx4 v[10:11], v[2:5], off
	s_nop 1
	v_or_b32_e32 v10, s12, v99
	v_mul_u32_u24_e32 v10, 0xb00, v10
	s_waitcnt lgkmcnt(7)
	ds_read2_b32 v[204:205], v95 offset0:48 offset1:113
	ds_read2_b32 v[206:207], v95 offset0:178 offset1:243
	ds_read2_b32 v[208:209], v145 offset0:52 offset1:117
	ds_read2_b32 v[210:211], v145 offset0:182 offset1:247
	ds_read2_b32 v[212:213], v95 offset0:56 offset1:121
	ds_read2_b32 v[214:215], v95 offset0:186 offset1:251
	ds_read2_b32 v[216:217], v145 offset0:60 offset1:125
	ds_read2_b32 v[218:219], v145 offset0:190 offset1:255
	s_waitcnt lgkmcnt(8)
	v_cvt_pk_bf16_f32 v2, v188, v189
	v_lshlrev_b32_e32 v88, 1, v10
	v_cvt_pk_bf16_f32 v3, v190, v191
	v_lshl_add_u64 v[10:11], v[8:9], 0, v[88:89]
	v_cvt_pk_bf16_f32 v4, v192, v193
	v_cvt_pk_bf16_f32 v5, v194, v195
	global_store_dwordx4 v[10:11], v[2:5], off
	s_nop 1
	v_or_b32_e32 v10, s12, v100
	v_mul_u32_u24_e32 v10, 0xb00, v10
	v_cvt_pk_bf16_f32 v2, v196, v197
	v_lshlrev_b32_e32 v88, 1, v10
	v_cvt_pk_bf16_f32 v3, v198, v199
	v_lshl_add_u64 v[10:11], v[8:9], 0, v[88:89]
	v_cvt_pk_bf16_f32 v4, v200, v201
	v_cvt_pk_bf16_f32 v5, v202, v203
	global_store_dwordx4 v[10:11], v[2:5], off
	s_nop 1
	v_or_b32_e32 v10, s12, v101
	s_waitcnt lgkmcnt(0)
	v_cvt_pk_bf16_f32 v2, v204, v205
	v_mul_u32_u24_e32 v10, 0xb00, v10
	v_cvt_pk_bf16_f32 v3, v206, v207
	v_lshlrev_b32_e32 v88, 1, v10
	v_cvt_pk_bf16_f32 v4, v208, v209
	v_cvt_pk_bf16_f32 v5, v210, v211
	v_lshl_add_u64 v[10:11], v[8:9], 0, v[88:89]
	global_store_dwordx4 v[10:11], v[2:5], off
	s_nop 1
	s_mov_b64 s[0:1], 0
	v_cvt_pk_bf16_f32 v2, v212, v213
	v_cvt_pk_bf16_f32 v3, v214, v215
	v_cvt_pk_bf16_f32 v4, v216, v217
	v_or_b32_e32 v5, s12, v102
	v_mul_u32_u24_e32 v5, 0xb00, v5
	v_lshlrev_b32_e32 v88, 1, v5
	v_cvt_pk_bf16_f32 v5, v218, v219
	v_lshl_add_u64 v[6:7], v[8:9], 0, v[88:89]
	global_store_dwordx4 v[6:7], v[2:5], off
	s_nop 1
	s_waitcnt lgkmcnt(0)

.LBB0_1823:
	s_waitcnt vmcnt(0)
	v_pk_mul_f32 v[2:3], v[2:3], v[10:11] op_sel_hi:[1,0]
	v_add_u32_e32 v6, 0xc30, v11
	s_lshl_b32 s0, s17, 6
	ds_write2_b32 v6, v2, v3 offset1:1
	v_pk_mul_f32 v[2:3], v[4:5], v[10:11] op_sel_hi:[1,0]
	v_add_u32_e32 v4, 0xc38, v11
	s_and_b32 s0, 0xffff, s0
	ds_write2_b32 v4, v2, v3 offset1:1
	s_lshl_b32 s1, s0, 1
	s_waitcnt lgkmcnt(0)
	s_and_b32 s0, s0, 64
	s_and_b32 s1, s1, 0x1f00
	s_or_b32 s0, s0, s1
	ds_read2_b32 v[188:189], v95 offset1:65
	ds_read2_b32 v[190:191], v95 offset0:130 offset1:195
	ds_read2_b32 v[192:193], v145 offset0:4 offset1:69
	ds_read2_b32 v[194:195], v145 offset0:134 offset1:199
	ds_read2_b32 v[196:197], v95 offset0:8 offset1:73
	ds_read2_b32 v[198:199], v95 offset0:138 offset1:203
	ds_read2_b32 v[200:201], v145 offset0:12 offset1:77
	ds_read2_b32 v[202:203], v145 offset0:142 offset1:207
	s_bitset1_b32 s0, 7
	s_waitcnt lgkmcnt(7)
	ds_read2_b32 v[204:205], v95 offset0:16 offset1:81
	ds_read2_b32 v[206:207], v95 offset0:146 offset1:211
	ds_read2_b32 v[208:209], v145 offset0:20 offset1:85
	ds_read2_b32 v[210:211], v145 offset0:150 offset1:215
	ds_read2_b32 v[212:213], v95 offset0:24 offset1:89
	ds_read2_b32 v[214:215], v95 offset0:154 offset1:219
	ds_read2_b32 v[216:217], v145 offset0:28 offset1:93
	ds_read2_b32 v[218:219], v145 offset0:158 offset1:223
	s_waitcnt lgkmcnt(8)
	v_cvt_pk_bf16_f32 v2, v188, v189
	s_lshl_b32 s10, s16, 1
	v_or_b32_e32 v10, s0, v94
	v_cvt_pk_bf16_f32 v3, v190, v191
	v_lshl_add_u64 v[6:7], v[74:75], 0, s[10:11]
	v_lshlrev_b32_e32 v88, 11, v10
	v_cvt_pk_bf16_f32 v4, v192, v193
	v_cvt_pk_bf16_f32 v5, v194, v195
	v_lshl_add_u64 v[10:11], v[6:7], 0, v[88:89]
	global_store_dwordx4 v[10:11], v[2:5], off
	s_nop 1
	v_or_b32_e32 v10, s0, v96
	v_lshlrev_b32_e32 v88, 11, v10
	v_cvt_pk_bf16_f32 v2, v196, v197
	v_cvt_pk_bf16_f32 v3, v198, v199
	v_cvt_pk_bf16_f32 v4, v200, v201
	v_cvt_pk_bf16_f32 v5, v202, v203
	v_lshl_add_u64 v[10:11], v[6:7], 0, v[88:89]
	global_store_dwordx4 v[10:11], v[2:5], off
	s_nop 1
	v_or_b32_e32 v10, s0, v97
	v_lshlrev_b32_e32 v88, 11, v10
	s_waitcnt lgkmcnt(7)
	ds_read2_b32 v[188:189], v95 offset0:32 offset1:97
	ds_read2_b32 v[190:191], v95 offset0:162 offset1:227
	ds_read2_b32 v[192:193], v145 offset0:36 offset1:101
	ds_read2_b32 v[194:195], v145 offset0:166 offset1:231
	ds_read2_b32 v[196:197], v95 offset0:40 offset1:105
	ds_read2_b32 v[198:199], v95 offset0:170 offset1:235
	ds_read2_b32 v[200:201], v145 offset0:44 offset1:109
	ds_read2_b32 v[202:203], v145 offset0:174 offset1:239
	s_waitcnt lgkmcnt(8)
	v_cvt_pk_bf16_f32 v2, v204, v205
	v_cvt_pk_bf16_f32 v3, v206, v207
	v_cvt_pk_bf16_f32 v4, v208, v209
	v_cvt_pk_bf16_f32 v5, v210, v211
	v_lshl_add_u64 v[10:11], v[6:7], 0, v[88:89]
	global_store_dwordx4 v[10:11], v[2:5], off
	s_nop 1
	v_or_b32_e32 v10, s0, v98
	v_lshlrev_b32_e32 v88, 11, v10
	v_cvt_pk_bf16_f32 v2, v212, v213
	v_cvt_pk_bf16_f32 v3, v214, v215
	v_cvt_pk_bf16_f32 v4, v216, v217
	v_cvt_pk_bf16_f32 v5, v218, v219
	v_lshl_add_u64 v[10:11], v[6:7], 0, v[88:89]
	global_store_dwordx4 v[10:11], v[2:5], off
	s_nop 1
	v_or_b32_e32 v10, s0, v99
	v_lshlrev_b32_e32 v88, 11, v10
	s_waitcnt lgkmcnt(7)
	ds_read2_b32 v[204:205], v95 offset0:48 offset1:113
	ds_read2_b32 v[206:207], v95 offset0:178 offset1:243
	ds_read2_b32 v[208:209], v145 offset0:52 offset1:117
	ds_read2_b32 v[210:211], v145 offset0:182 offset1:247
	ds_read2_b32 v[212:213], v95 offset0:56 offset1:121
	ds_read2_b32 v[214:215], v95 offset0:186 offset1:251
	ds_read2_b32 v[216:217], v145 offset0:60 offset1:125
	ds_read2_b32 v[218:219], v145 offset0:190 offset1:255
	s_waitcnt lgkmcnt(8)
	v_cvt_pk_bf16_f32 v2, v188, v189
	v_cvt_pk_bf16_f32 v3, v190, v191
	v_cvt_pk_bf16_f32 v4, v192, v193
	v_cvt_pk_bf16_f32 v5, v194, v195
	v_lshl_add_u64 v[10:11], v[6:7], 0, v[88:89]
	global_store_dwordx4 v[10:11], v[2:5], off
	s_nop 1
	v_or_b32_e32 v10, s0, v100
	v_lshlrev_b32_e32 v88, 11, v10
	v_cvt_pk_bf16_f32 v2, v196, v197
	v_cvt_pk_bf16_f32 v3, v198, v199
	v_cvt_pk_bf16_f32 v4, v200, v201
	v_cvt_pk_bf16_f32 v5, v202, v203
	v_lshl_add_u64 v[10:11], v[6:7], 0, v[88:89]
	global_store_dwordx4 v[10:11], v[2:5], off
	s_nop 1
	v_or_b32_e32 v10, s0, v101
	v_lshlrev_b32_e32 v88, 11, v10
	s_waitcnt lgkmcnt(0)
	v_cvt_pk_bf16_f32 v2, v204, v205
	v_cvt_pk_bf16_f32 v3, v206, v207
	v_cvt_pk_bf16_f32 v4, v208, v209
	v_cvt_pk_bf16_f32 v5, v210, v211
	v_lshl_add_u64 v[10:11], v[6:7], 0, v[88:89]
	global_store_dwordx4 v[10:11], v[2:5], off
	s_nop 1
	s_nop 0
	v_cvt_pk_bf16_f32 v2, v212, v213
	v_cvt_pk_bf16_f32 v3, v214, v215
	v_cvt_pk_bf16_f32 v4, v216, v217
	v_or_b32_e32 v5, s0, v102
	v_lshlrev_b32_e32 v88, 11, v5
	v_lshl_add_u64 v[6:7], v[6:7], 0, v[88:89]
	v_cvt_pk_bf16_f32 v5, v218, v219
	global_store_dwordx4 v[6:7], v[2:5], off
	s_nop 1
	s_waitcnt lgkmcnt(0)

.LBB0_1887:
	s_waitcnt vmcnt(0)
	v_pk_mul_f32 v[2:3], v[2:3], v[10:11] op_sel_hi:[1,0]
	v_add_u32_e32 v6, 0xc30, v19
	s_mulk_i32 s8, 0xea00
	ds_write2_b32 v6, v2, v3 offset1:1
	v_pk_mul_f32 v[2:3], v[4:5], v[10:11] op_sel_hi:[1,0]
	v_add_u32_e32 v4, 0xc38, v19
	s_add_i32 s1, s21, s8
	ds_write2_b32 v4, v2, v3 offset1:1
	s_and_b32 s0, s10, 64
	s_and_b32 s1, s1, 0xffffff00
	s_waitcnt lgkmcnt(0)
	s_or_b32 s0, s1, s0
	v_or_b32_e32 v10, s0, v94
	ds_read2_b32 v[188:189], v95 offset1:65
	ds_read2_b32 v[190:191], v95 offset0:130 offset1:195
	ds_read2_b32 v[192:193], v145 offset0:4 offset1:69
	ds_read2_b32 v[194:195], v145 offset0:134 offset1:199
	ds_read2_b32 v[196:197], v95 offset0:8 offset1:73
	ds_read2_b32 v[198:199], v95 offset0:138 offset1:203
	ds_read2_b32 v[200:201], v145 offset0:12 offset1:77
	ds_read2_b32 v[202:203], v145 offset0:142 offset1:207
	v_ashrrev_i32_e32 v11, 31, v10
	s_waitcnt lgkmcnt(7)
	ds_read2_b32 v[204:205], v95 offset0:16 offset1:81
	ds_read2_b32 v[206:207], v95 offset0:146 offset1:211
	ds_read2_b32 v[208:209], v145 offset0:20 offset1:85
	ds_read2_b32 v[210:211], v145 offset0:150 offset1:215
	ds_read2_b32 v[212:213], v95 offset0:24 offset1:89
	ds_read2_b32 v[214:215], v95 offset0:154 offset1:219
	ds_read2_b32 v[216:217], v145 offset0:28 offset1:93
	ds_read2_b32 v[218:219], v145 offset0:158 offset1:223
	s_waitcnt lgkmcnt(8)
	v_cvt_pk_bf16_f32 v2, v188, v189
	v_lshl_add_u64 v[6:7], s[14:15], 1, v[74:75]
	v_lshlrev_b64 v[10:11], 11, v[10:11]
	v_cvt_pk_bf16_f32 v3, v190, v191
	v_lshl_add_u64 v[10:11], v[6:7], 0, v[10:11]
	v_cvt_pk_bf16_f32 v4, v192, v193
	v_cvt_pk_bf16_f32 v5, v194, v195
	global_store_dwordx4 v[10:11], v[2:5], off
	s_nop 1
	v_or_b32_e32 v10, s0, v96
	v_ashrrev_i32_e32 v11, 31, v10
	v_cvt_pk_bf16_f32 v2, v196, v197
	v_lshlrev_b64 v[10:11], 11, v[10:11]
	v_cvt_pk_bf16_f32 v3, v198, v199
	v_lshl_add_u64 v[10:11], v[6:7], 0, v[10:11]
	v_cvt_pk_bf16_f32 v4, v200, v201
	v_cvt_pk_bf16_f32 v5, v202, v203
	global_store_dwordx4 v[10:11], v[2:5], off
	s_nop 1
	v_or_b32_e32 v10, s0, v97
	v_ashrrev_i32_e32 v11, 31, v10
	s_waitcnt lgkmcnt(7)
	ds_read2_b32 v[188:189], v95 offset0:32 offset1:97
	ds_read2_b32 v[190:191], v95 offset0:162 offset1:227
	ds_read2_b32 v[192:193], v145 offset0:36 offset1:101
	ds_read2_b32 v[194:195], v145 offset0:166 offset1:231
	ds_read2_b32 v[196:197], v95 offset0:40 offset1:105
	ds_read2_b32 v[198:199], v95 offset0:170 offset1:235
	ds_read2_b32 v[200:201], v145 offset0:44 offset1:109
	ds_read2_b32 v[202:203], v145 offset0:174 offset1:239
	s_waitcnt lgkmcnt(8)
	v_cvt_pk_bf16_f32 v2, v204, v205
	v_lshlrev_b64 v[10:11], 11, v[10:11]
	v_cvt_pk_bf16_f32 v3, v206, v207
	v_lshl_add_u64 v[10:11], v[6:7], 0, v[10:11]
	v_cvt_pk_bf16_f32 v4, v208, v209
	v_cvt_pk_bf16_f32 v5, v210, v211
	global_store_dwordx4 v[10:11], v[2:5], off
	s_nop 1
	v_or_b32_e32 v10, s0, v98
	v_ashrrev_i32_e32 v11, 31, v10
	v_cvt_pk_bf16_f32 v2, v212, v213
	v_lshlrev_b64 v[10:11], 11, v[10:11]
	v_cvt_pk_bf16_f32 v3, v214, v215
	v_lshl_add_u64 v[10:11], v[6:7], 0, v[10:11]
	v_cvt_pk_bf16_f32 v4, v216, v217
	v_cvt_pk_bf16_f32 v5, v218, v219
	global_store_dwordx4 v[10:11], v[2:5], off
	s_nop 1
	v_or_b32_e32 v10, s0, v99
	v_ashrrev_i32_e32 v11, 31, v10
	s_waitcnt lgkmcnt(7)
	ds_read2_b32 v[204:205], v95 offset0:48 offset1:113
	ds_read2_b32 v[206:207], v95 offset0:178 offset1:243
	ds_read2_b32 v[208:209], v145 offset0:52 offset1:117
	ds_read2_b32 v[210:211], v145 offset0:182 offset1:247
	ds_read2_b32 v[212:213], v95 offset0:56 offset1:121
	ds_read2_b32 v[214:215], v95 offset0:186 offset1:251
	ds_read2_b32 v[216:217], v145 offset0:60 offset1:125
	ds_read2_b32 v[218:219], v145 offset0:190 offset1:255
	s_waitcnt lgkmcnt(8)
	v_cvt_pk_bf16_f32 v2, v188, v189
	v_lshlrev_b64 v[10:11], 11, v[10:11]
	v_cvt_pk_bf16_f32 v3, v190, v191
	v_lshl_add_u64 v[10:11], v[6:7], 0, v[10:11]
	v_cvt_pk_bf16_f32 v4, v192, v193
	v_cvt_pk_bf16_f32 v5, v194, v195
	global_store_dwordx4 v[10:11], v[2:5], off
	s_nop 1
	v_or_b32_e32 v10, s0, v100
	v_ashrrev_i32_e32 v11, 31, v10
	v_cvt_pk_bf16_f32 v2, v196, v197
	v_lshlrev_b64 v[10:11], 11, v[10:11]
	v_cvt_pk_bf16_f32 v3, v198, v199
	v_lshl_add_u64 v[10:11], v[6:7], 0, v[10:11]
	v_cvt_pk_bf16_f32 v4, v200, v201
	v_cvt_pk_bf16_f32 v5, v202, v203
	global_store_dwordx4 v[10:11], v[2:5], off
	s_nop 1
	v_or_b32_e32 v10, s0, v101
	v_ashrrev_i32_e32 v11, 31, v10
	s_waitcnt lgkmcnt(0)
	v_cvt_pk_bf16_f32 v2, v204, v205
	v_lshlrev_b64 v[10:11], 11, v[10:11]
	v_cvt_pk_bf16_f32 v3, v206, v207
	v_lshl_add_u64 v[10:11], v[6:7], 0, v[10:11]
	v_cvt_pk_bf16_f32 v4, v208, v209
	v_cvt_pk_bf16_f32 v5, v210, v211
	global_store_dwordx4 v[10:11], v[2:5], off
	s_nop 1
	v_or_b32_e32 v10, s0, v102
	v_ashrrev_i32_e32 v11, 31, v10
	v_cvt_pk_bf16_f32 v2, v212, v213
	v_lshlrev_b64 v[10:11], 11, v[10:11]
	v_cvt_pk_bf16_f32 v3, v214, v215
	v_lshl_add_u64 v[6:7], v[6:7], 0, v[10:11]
	v_cvt_pk_bf16_f32 v4, v216, v217
	v_cvt_pk_bf16_f32 v5, v218, v219
	global_store_dwordx4 v[6:7], v[2:5], off
	s_nop 1
	s_waitcnt lgkmcnt(0)

.LBB0_1889:
	s_cmpk_gt_i32 s2, 0x83f
	s_mov_b64 s[0:1], -1
	s_cbranch_scc0 .LBB0_1947
	s_add_i32 s14, s2, 0xfffff7c0
	s_cmpk_gt_u32 s14, 0x2bf
	s_cbranch_scc0 .LBB0_1920
	s_cmpk_gt_u32 s14, 0x57f
	s_cbranch_scc0 .LBB0_1893
	s_add_i32 s0, s3, 0xfffdf000
	s_and_b32 s10, s0, 0x3c0
	s_add_i32 s0, s23, 0xffffdf00
	s_and_b32 s0, s0, 0x7fffffc0
	s_addk_i32 s0, 0xea00
	v_or_b32_e32 v88, s0, v66
	s_lshl_b32 s8, s10, 2
	v_or_b32_e32 v4, 4, v88
	v_mov_b32_e32 v5, v89
	s_waitcnt vmcnt(0)
	v_or_b32_e32 v10, 8, v88
	v_mov_b32_e32 v11, v89
	v_or_b32_e32 v12, 12, v88
	v_mov_b32_e32 v13, v89
	v_or_b32_e32 v18, 16, v88
	v_mov_b32_e32 v19, v89
	v_or_b32_e32 v20, 20, v88
	v_mov_b32_e32 v21, v89
	v_or_b32_e32 v26, 24, v88
	v_mov_b32_e32 v27, v89
	v_or_b32_e32 v28, 28, v88
	v_mov_b32_e32 v29, v89
	v_or_b32_e32 v34, 32, v88
	v_mov_b32_e32 v35, v89
	v_or_b32_e32 v36, 36, v88
	v_mov_b32_e32 v37, v89
	v_or_b32_e32 v42, 40, v88
	v_mov_b32_e32 v43, v89
	v_or_b32_e32 v44, 44, v88
	v_mov_b32_e32 v45, v89
	v_or_b32_e32 v50, 48, v88
	v_mov_b32_e32 v51, v89
	v_or_b32_e32 v52, 52, v88
	v_mov_b32_e32 v53, v89
	v_lshl_add_u64 v[62:63], v[76:77], 0, s[8:9]
	v_lshlrev_b64 v[2:3], 12, v[88:89]
	v_lshlrev_b64 v[4:5], 12, v[4:5]
	v_lshlrev_b64 v[10:11], 12, v[10:11]
	v_lshlrev_b64 v[12:13], 12, v[12:13]
	v_lshlrev_b64 v[18:19], 12, v[18:19]
	v_lshlrev_b64 v[20:21], 12, v[20:21]
	v_lshlrev_b64 v[26:27], 12, v[26:27]
	v_lshlrev_b64 v[28:29], 12, v[28:29]
	v_lshlrev_b64 v[34:35], 12, v[34:35]
	v_lshlrev_b64 v[36:37], 12, v[36:37]
	v_lshlrev_b64 v[42:43], 12, v[42:43]
	v_lshlrev_b64 v[44:45], 12, v[44:45]
	v_lshlrev_b64 v[50:51], 12, v[50:51]
	v_lshlrev_b64 v[52:53], 12, v[52:53]
	v_lshl_add_u64 v[2:3], v[62:63], 0, v[2:3]
	v_lshl_add_u64 v[6:7], v[62:63], 0, v[4:5]
	v_lshl_add_u64 v[10:11], v[62:63], 0, v[10:11]
	v_lshl_add_u64 v[14:15], v[62:63], 0, v[12:13]
	v_lshl_add_u64 v[18:19], v[62:63], 0, v[18:19]
	v_lshl_add_u64 v[22:23], v[62:63], 0, v[20:21]
	v_lshl_add_u64 v[26:27], v[62:63], 0, v[26:27]
	v_lshl_add_u64 v[30:31], v[62:63], 0, v[28:29]
	v_lshl_add_u64 v[34:35], v[62:63], 0, v[34:35]
	v_lshl_add_u64 v[38:39], v[62:63], 0, v[36:37]
	v_lshl_add_u64 v[42:43], v[62:63], 0, v[42:43]
	v_lshl_add_u64 v[46:47], v[62:63], 0, v[44:45]
	v_lshl_add_u64 v[50:51], v[62:63], 0, v[50:51]
	v_lshl_add_u64 v[54:55], v[62:63], 0, v[52:53]
	global_load_dwordx4 v[2:5], v[2:3], off nt
	s_nop 0
	global_load_dwordx4 v[6:9], v[6:7], off nt
	s_nop 0
	global_load_dwordx4 v[10:13], v[10:11], off nt
	s_nop 0
	global_load_dwordx4 v[14:17], v[14:15], off nt
	s_nop 0
	global_load_dwordx4 v[18:21], v[18:19], off nt
	s_nop 0
	global_load_dwordx4 v[22:25], v[22:23], off nt
	s_nop 0
	global_load_dwordx4 v[26:29], v[26:27], off nt
	s_nop 0
	global_load_dwordx4 v[30:33], v[30:31], off nt
	s_nop 0
	global_load_dwordx4 v[34:37], v[34:35], off nt
	s_nop 0
	global_load_dwordx4 v[38:41], v[38:39], off nt
	s_nop 0
	global_load_dwordx4 v[42:45], v[42:43], off nt
	s_nop 0
	global_load_dwordx4 v[46:49], v[46:47], off nt
	s_nop 0
	global_load_dwordx4 v[50:53], v[50:51], off nt
	s_nop 0
	global_load_dwordx4 v[54:57], v[54:55], off nt
	v_or_b32_e32 v58, 56, v88
	v_mov_b32_e32 v59, v89
	v_lshlrev_b64 v[58:59], 12, v[58:59]
	v_lshl_add_u64 v[58:59], v[62:63], 0, v[58:59]
	v_or_b32_e32 v88, 60, v88
	global_load_dwordx4 v[58:61], v[58:59], off nt
	v_lshlrev_b64 v[64:65], 12, v[88:89]
	v_lshl_add_u64 v[62:63], v[62:63], 0, v[64:65]
	global_load_dwordx4 v[62:65], v[62:63], off nt
	s_mov_b32 s1, s9
	s_waitcnt vmcnt(15)
	ds_write2_b32 v93, v2, v3 offset1:1
	ds_write2_b32 v93, v4, v5 offset0:2 offset1:3
	s_waitcnt vmcnt(14)
	ds_write2_b32 v115, v6, v7 offset1:1
	ds_write2_b32 v116, v8, v9 offset1:1
	s_waitcnt vmcnt(13)
	ds_write2_b32 v117, v10, v11 offset1:1
	ds_write2_b32 v118, v12, v13 offset1:1
	s_waitcnt vmcnt(12)
	ds_write2_b32 v119, v14, v15 offset1:1
	ds_write2_b32 v120, v16, v17 offset1:1
	s_waitcnt vmcnt(11)
	ds_write2_b32 v121, v18, v19 offset1:1
	ds_write2_b32 v122, v20, v21 offset1:1
	s_waitcnt vmcnt(10)
	ds_write2_b32 v123, v22, v23 offset1:1
	ds_write2_b32 v124, v24, v25 offset1:1
	s_waitcnt vmcnt(9)
	ds_write2_b32 v125, v26, v27 offset1:1
	ds_write2_b32 v126, v28, v29 offset1:1
	s_waitcnt vmcnt(8)
	ds_write2_b32 v127, v30, v31 offset1:1
	ds_write2_b32 v128, v32, v33 offset1:1
	s_waitcnt vmcnt(7)
	ds_write2_b32 v129, v34, v35 offset1:1
	ds_write2_b32 v130, v36, v37 offset1:1
	s_waitcnt vmcnt(6)
	ds_write2_b32 v131, v38, v39 offset1:1
	ds_write2_b32 v132, v40, v41 offset1:1
	s_waitcnt vmcnt(5)
	ds_write2_b32 v133, v42, v43 offset1:1
	ds_write2_b32 v134, v44, v45 offset1:1
	s_waitcnt vmcnt(4)
	ds_write2_b32 v135, v46, v47 offset1:1
	ds_write2_b32 v136, v48, v49 offset1:1
	s_waitcnt vmcnt(3)
	ds_write2_b32 v137, v50, v51 offset1:1
	ds_write2_b32 v138, v52, v53 offset1:1
	s_waitcnt vmcnt(2)
	ds_write2_b32 v139, v54, v55 offset1:1
	ds_write2_b32 v140, v56, v57 offset1:1
	s_waitcnt vmcnt(1)
	ds_write2_b32 v141, v58, v59 offset1:1
	ds_write2_b32 v142, v60, v61 offset1:1
	s_waitcnt vmcnt(0)
	ds_write2_b32 v143, v62, v63 offset1:1
	ds_write2_b32 v144, v64, v65 offset1:1
	s_waitcnt lgkmcnt(0)
	v_or_b32_e32 v10, s10, v94
	ds_read2_b32 v[188:189], v95 offset1:65
	ds_read2_b32 v[190:191], v95 offset0:130 offset1:195
	ds_read2_b32 v[192:193], v145 offset0:4 offset1:69
	ds_read2_b32 v[194:195], v145 offset0:134 offset1:199
	ds_read2_b32 v[196:197], v95 offset0:8 offset1:73
	ds_read2_b32 v[198:199], v95 offset0:138 offset1:203
	ds_read2_b32 v[200:201], v145 offset0:12 offset1:77
	ds_read2_b32 v[202:203], v145 offset0:142 offset1:207
	v_mul_u32_u24_e32 v10, 0xb00, v10
	s_waitcnt lgkmcnt(7)
	ds_read2_b32 v[204:205], v95 offset0:16 offset1:81
	ds_read2_b32 v[206:207], v95 offset0:146 offset1:211
	ds_read2_b32 v[208:209], v145 offset0:20 offset1:85
	ds_read2_b32 v[210:211], v145 offset0:150 offset1:215
	ds_read2_b32 v[212:213], v95 offset0:24 offset1:89
	ds_read2_b32 v[214:215], v95 offset0:154 offset1:219
	ds_read2_b32 v[216:217], v145 offset0:28 offset1:93
	ds_read2_b32 v[218:219], v145 offset0:158 offset1:223
	s_waitcnt lgkmcnt(8)
	v_cvt_pk_bf16_f32 v2, v188, v189
	v_lshl_add_u64 v[8:9], s[0:1], 1, v[68:69]
	v_lshlrev_b32_e32 v88, 1, v10
	v_cvt_pk_bf16_f32 v3, v190, v191
	v_lshl_add_u64 v[10:11], v[8:9], 0, v[88:89]
	v_cvt_pk_bf16_f32 v4, v192, v193
	v_cvt_pk_bf16_f32 v5, v194, v195
	global_store_dwordx4 v[10:11], v[2:5], off
	s_nop 1
	v_or_b32_e32 v10, s10, v96
	v_mul_u32_u24_e32 v10, 0xb00, v10
	v_cvt_pk_bf16_f32 v2, v196, v197
	v_lshlrev_b32_e32 v88, 1, v10
	v_cvt_pk_bf16_f32 v3, v198, v199
	v_lshl_add_u64 v[10:11], v[8:9], 0, v[88:89]
	v_cvt_pk_bf16_f32 v4, v200, v201
	v_cvt_pk_bf16_f32 v5, v202, v203
	global_store_dwordx4 v[10:11], v[2:5], off
	s_nop 1
	v_or_b32_e32 v10, s10, v97
	v_mul_u32_u24_e32 v10, 0xb00, v10
	s_waitcnt lgkmcnt(7)
	ds_read2_b32 v[188:189], v95 offset0:32 offset1:97
	ds_read2_b32 v[190:191], v95 offset0:162 offset1:227
	ds_read2_b32 v[192:193], v145 offset0:36 offset1:101
	ds_read2_b32 v[194:195], v145 offset0:166 offset1:231
	ds_read2_b32 v[196:197], v95 offset0:40 offset1:105
	ds_read2_b32 v[198:199], v95 offset0:170 offset1:235
	ds_read2_b32 v[200:201], v145 offset0:44 offset1:109
	ds_read2_b32 v[202:203], v145 offset0:174 offset1:239
	s_waitcnt lgkmcnt(8)
	v_cvt_pk_bf16_f32 v2, v204, v205
	v_lshlrev_b32_e32 v88, 1, v10
	v_cvt_pk_bf16_f32 v3, v206, v207
	v_lshl_add_u64 v[10:11], v[8:9], 0, v[88:89]
	v_cvt_pk_bf16_f32 v4, v208, v209
	v_cvt_pk_bf16_f32 v5, v210, v211
	global_store_dwordx4 v[10:11], v[2:5], off
	s_nop 1
	v_or_b32_e32 v10, s10, v98
	v_mul_u32_u24_e32 v10, 0xb00, v10
	v_cvt_pk_bf16_f32 v2, v212, v213
	v_lshlrev_b32_e32 v88, 1, v10
	v_cvt_pk_bf16_f32 v3, v214, v215
	v_lshl_add_u64 v[10:11], v[8:9], 0, v[88:89]
	v_cvt_pk_bf16_f32 v4, v216, v217
	v_cvt_pk_bf16_f32 v5, v218, v219
	global_store_dwordx4 v[10:11], v[2:5], off
	s_nop 1
	v_or_b32_e32 v10, s10, v99
	v_mul_u32_u24_e32 v10, 0xb00, v10
	s_waitcnt lgkmcnt(7)
	ds_read2_b32 v[204:205], v95 offset0:48 offset1:113
	ds_read2_b32 v[206:207], v95 offset0:178 offset1:243
	ds_read2_b32 v[208:209], v145 offset0:52 offset1:117
	ds_read2_b32 v[210:211], v145 offset0:182 offset1:247
	ds_read2_b32 v[212:213], v95 offset0:56 offset1:121
	ds_read2_b32 v[214:215], v95 offset0:186 offset1:251
	ds_read2_b32 v[216:217], v145 offset0:60 offset1:125
	ds_read2_b32 v[218:219], v145 offset0:190 offset1:255
	s_waitcnt lgkmcnt(8)
	v_cvt_pk_bf16_f32 v2, v188, v189
	v_lshlrev_b32_e32 v88, 1, v10
	v_cvt_pk_bf16_f32 v3, v190, v191
	v_lshl_add_u64 v[10:11], v[8:9], 0, v[88:89]
	v_cvt_pk_bf16_f32 v4, v192, v193
	v_cvt_pk_bf16_f32 v5, v194, v195
	global_store_dwordx4 v[10:11], v[2:5], off
	s_nop 1
	v_or_b32_e32 v10, s10, v100
	v_mul_u32_u24_e32 v10, 0xb00, v10
	v_cvt_pk_bf16_f32 v2, v196, v197
	v_lshlrev_b32_e32 v88, 1, v10
	v_cvt_pk_bf16_f32 v3, v198, v199
	v_lshl_add_u64 v[10:11], v[8:9], 0, v[88:89]
	v_cvt_pk_bf16_f32 v4, v200, v201
	v_cvt_pk_bf16_f32 v5, v202, v203
	global_store_dwordx4 v[10:11], v[2:5], off
	s_nop 1
	v_or_b32_e32 v10, s10, v101
	s_waitcnt lgkmcnt(0)
	v_cvt_pk_bf16_f32 v2, v204, v205
	v_mul_u32_u24_e32 v10, 0xb00, v10
	v_cvt_pk_bf16_f32 v3, v206, v207
	v_lshlrev_b32_e32 v88, 1, v10
	v_cvt_pk_bf16_f32 v4, v208, v209
	v_cvt_pk_bf16_f32 v5, v210, v211
	v_lshl_add_u64 v[10:11], v[8:9], 0, v[88:89]
	global_store_dwordx4 v[10:11], v[2:5], off
	s_nop 1
	s_mov_b64 s[0:1], 0
	v_cvt_pk_bf16_f32 v2, v212, v213
	v_cvt_pk_bf16_f32 v3, v214, v215
	v_cvt_pk_bf16_f32 v4, v216, v217
	v_or_b32_e32 v5, s10, v102
	v_mul_u32_u24_e32 v5, 0xb00, v5
	v_lshlrev_b32_e32 v88, 1, v5
	v_cvt_pk_bf16_f32 v5, v218, v219
	v_lshl_add_u64 v[6:7], v[8:9], 0, v[88:89]
	global_store_dwordx4 v[6:7], v[2:5], off
	s_nop 1
	s_waitcnt lgkmcnt(0)

.LBB0_1918:
	s_waitcnt vmcnt(0)
	v_pk_mul_f32 v[2:3], v[2:3], v[10:11] op_sel_hi:[1,0]
	v_add_u32_e32 v6, 0xc30, v11
	s_lshl_b32 s0, s16, 6
	ds_write2_b32 v6, v2, v3 offset1:1
	v_pk_mul_f32 v[2:3], v[4:5], v[10:11] op_sel_hi:[1,0]
	v_add_u32_e32 v4, 0xc38, v11
	s_and_b32 s0, 0xffff, s0
	ds_write2_b32 v4, v2, v3 offset1:1
	s_lshl_b32 s1, s0, 1
	s_waitcnt lgkmcnt(0)
	s_and_b32 s0, s0, 64
	s_and_b32 s1, s1, 0x1f00
	s_or_b32 s0, s0, s1
	ds_read2_b32 v[188:189], v95 offset1:65
	ds_read2_b32 v[190:191], v95 offset0:130 offset1:195
	ds_read2_b32 v[192:193], v145 offset0:4 offset1:69
	ds_read2_b32 v[194:195], v145 offset0:134 offset1:199
	ds_read2_b32 v[196:197], v95 offset0:8 offset1:73
	ds_read2_b32 v[198:199], v95 offset0:138 offset1:203
	ds_read2_b32 v[200:201], v145 offset0:12 offset1:77
	ds_read2_b32 v[202:203], v145 offset0:142 offset1:207
	s_bitset1_b32 s0, 7
	s_waitcnt lgkmcnt(7)
	ds_read2_b32 v[204:205], v95 offset0:16 offset1:81
	ds_read2_b32 v[206:207], v95 offset0:146 offset1:211
	ds_read2_b32 v[208:209], v145 offset0:20 offset1:85
	ds_read2_b32 v[210:211], v145 offset0:150 offset1:215
	ds_read2_b32 v[212:213], v95 offset0:24 offset1:89
	ds_read2_b32 v[214:215], v95 offset0:154 offset1:219
	ds_read2_b32 v[216:217], v145 offset0:28 offset1:93
	ds_read2_b32 v[218:219], v145 offset0:158 offset1:223
	s_waitcnt lgkmcnt(8)
	v_cvt_pk_bf16_f32 v2, v188, v189
	s_lshl_b32 s8, s15, 1
	v_or_b32_e32 v10, s0, v94
	v_cvt_pk_bf16_f32 v3, v190, v191
	v_lshl_add_u64 v[6:7], v[70:71], 0, s[8:9]
	v_lshlrev_b32_e32 v88, 11, v10
	v_cvt_pk_bf16_f32 v4, v192, v193
	v_cvt_pk_bf16_f32 v5, v194, v195
	v_lshl_add_u64 v[10:11], v[6:7], 0, v[88:89]
	global_store_dwordx4 v[10:11], v[2:5], off
	s_nop 1
	v_or_b32_e32 v10, s0, v96
	v_lshlrev_b32_e32 v88, 11, v10
	v_cvt_pk_bf16_f32 v2, v196, v197
	v_cvt_pk_bf16_f32 v3, v198, v199
	v_cvt_pk_bf16_f32 v4, v200, v201
	v_cvt_pk_bf16_f32 v5, v202, v203
	v_lshl_add_u64 v[10:11], v[6:7], 0, v[88:89]
	global_store_dwordx4 v[10:11], v[2:5], off
	s_nop 1
	v_or_b32_e32 v10, s0, v97
	v_lshlrev_b32_e32 v88, 11, v10
	s_waitcnt lgkmcnt(7)
	ds_read2_b32 v[188:189], v95 offset0:32 offset1:97
	ds_read2_b32 v[190:191], v95 offset0:162 offset1:227
	ds_read2_b32 v[192:193], v145 offset0:36 offset1:101
	ds_read2_b32 v[194:195], v145 offset0:166 offset1:231
	ds_read2_b32 v[196:197], v95 offset0:40 offset1:105
	ds_read2_b32 v[198:199], v95 offset0:170 offset1:235
	ds_read2_b32 v[200:201], v145 offset0:44 offset1:109
	ds_read2_b32 v[202:203], v145 offset0:174 offset1:239
	s_waitcnt lgkmcnt(8)
	v_cvt_pk_bf16_f32 v2, v204, v205
	v_cvt_pk_bf16_f32 v3, v206, v207
	v_cvt_pk_bf16_f32 v4, v208, v209
	v_cvt_pk_bf16_f32 v5, v210, v211
	v_lshl_add_u64 v[10:11], v[6:7], 0, v[88:89]
	global_store_dwordx4 v[10:11], v[2:5], off
	s_nop 1
	v_or_b32_e32 v10, s0, v98
	v_lshlrev_b32_e32 v88, 11, v10
	v_cvt_pk_bf16_f32 v2, v212, v213
	v_cvt_pk_bf16_f32 v3, v214, v215
	v_cvt_pk_bf16_f32 v4, v216, v217
	v_cvt_pk_bf16_f32 v5, v218, v219
	v_lshl_add_u64 v[10:11], v[6:7], 0, v[88:89]
	global_store_dwordx4 v[10:11], v[2:5], off
	s_nop 1
	v_or_b32_e32 v10, s0, v99
	v_lshlrev_b32_e32 v88, 11, v10
	s_waitcnt lgkmcnt(7)
	ds_read2_b32 v[204:205], v95 offset0:48 offset1:113
	ds_read2_b32 v[206:207], v95 offset0:178 offset1:243
	ds_read2_b32 v[208:209], v145 offset0:52 offset1:117
	ds_read2_b32 v[210:211], v145 offset0:182 offset1:247
	ds_read2_b32 v[212:213], v95 offset0:56 offset1:121
	ds_read2_b32 v[214:215], v95 offset0:186 offset1:251
	ds_read2_b32 v[216:217], v145 offset0:60 offset1:125
	ds_read2_b32 v[218:219], v145 offset0:190 offset1:255
	s_waitcnt lgkmcnt(8)
	v_cvt_pk_bf16_f32 v2, v188, v189
	v_cvt_pk_bf16_f32 v3, v190, v191
	v_cvt_pk_bf16_f32 v4, v192, v193
	v_cvt_pk_bf16_f32 v5, v194, v195
	v_lshl_add_u64 v[10:11], v[6:7], 0, v[88:89]
	global_store_dwordx4 v[10:11], v[2:5], off
	s_nop 1
	v_or_b32_e32 v10, s0, v100
	v_lshlrev_b32_e32 v88, 11, v10
	v_cvt_pk_bf16_f32 v2, v196, v197
	v_cvt_pk_bf16_f32 v3, v198, v199
	v_cvt_pk_bf16_f32 v4, v200, v201
	v_cvt_pk_bf16_f32 v5, v202, v203
	v_lshl_add_u64 v[10:11], v[6:7], 0, v[88:89]
	global_store_dwordx4 v[10:11], v[2:5], off
	s_nop 1
	v_or_b32_e32 v10, s0, v101
	v_lshlrev_b32_e32 v88, 11, v10
	s_waitcnt lgkmcnt(0)
	v_cvt_pk_bf16_f32 v2, v204, v205
	v_cvt_pk_bf16_f32 v3, v206, v207
	v_cvt_pk_bf16_f32 v4, v208, v209
	v_cvt_pk_bf16_f32 v5, v210, v211
	v_lshl_add_u64 v[10:11], v[6:7], 0, v[88:89]
	global_store_dwordx4 v[10:11], v[2:5], off
	s_nop 1
	s_nop 0
	v_cvt_pk_bf16_f32 v2, v212, v213
	v_cvt_pk_bf16_f32 v3, v214, v215
	v_cvt_pk_bf16_f32 v4, v216, v217
	v_or_b32_e32 v5, s0, v102
	v_lshlrev_b32_e32 v88, 11, v5
	v_lshl_add_u64 v[6:7], v[6:7], 0, v[88:89]
	v_cvt_pk_bf16_f32 v5, v218, v219
	global_store_dwordx4 v[6:7], v[2:5], off
	s_nop 1
	s_waitcnt lgkmcnt(0)

.LBB0_1945:
	s_waitcnt vmcnt(0)
	v_pk_mul_f32 v[2:3], v[2:3], v[10:11] op_sel_hi:[1,0]
	v_add_u32_e32 v6, 0xc30, v11
	ds_write2_b32 v6, v2, v3 offset1:1
	v_pk_mul_f32 v[2:3], v[4:5], v[10:11] op_sel_hi:[1,0]
	v_add_u32_e32 v4, 0xc38, v11
	ds_write2_b32 v4, v2, v3 offset1:1
	s_waitcnt lgkmcnt(0)
	s_lshl_b32 s0, s14, 6
	s_lshl_b32 s1, s14, 7
	s_and_b32 s1, s1, 0x1f00
	s_and_b32 s0, s0, 64
	ds_read2_b32 v[188:189], v95 offset1:65
	ds_read2_b32 v[190:191], v95 offset0:130 offset1:195
	ds_read2_b32 v[192:193], v145 offset0:4 offset1:69
	ds_read2_b32 v[194:195], v145 offset0:134 offset1:199
	ds_read2_b32 v[196:197], v95 offset0:8 offset1:73
	ds_read2_b32 v[198:199], v95 offset0:138 offset1:203
	ds_read2_b32 v[200:201], v145 offset0:12 offset1:77
	ds_read2_b32 v[202:203], v145 offset0:142 offset1:207
	s_or_b32 s0, s1, s0
	s_waitcnt lgkmcnt(7)
	ds_read2_b32 v[204:205], v95 offset0:16 offset1:81
	ds_read2_b32 v[206:207], v95 offset0:146 offset1:211
	ds_read2_b32 v[208:209], v145 offset0:20 offset1:85
	ds_read2_b32 v[210:211], v145 offset0:150 offset1:215
	ds_read2_b32 v[212:213], v95 offset0:24 offset1:89
	ds_read2_b32 v[214:215], v95 offset0:154 offset1:219
	ds_read2_b32 v[216:217], v145 offset0:28 offset1:93
	ds_read2_b32 v[218:219], v145 offset0:158 offset1:223
	s_waitcnt lgkmcnt(8)
	v_cvt_pk_bf16_f32 v2, v188, v189
	s_lshl_b32 s8, s15, 1
	v_or_b32_e32 v10, s0, v94
	v_cvt_pk_bf16_f32 v3, v190, v191
	v_lshl_add_u64 v[8:9], v[70:71], 0, s[8:9]
	v_lshlrev_b32_e32 v88, 11, v10
	v_cvt_pk_bf16_f32 v4, v192, v193
	v_cvt_pk_bf16_f32 v5, v194, v195
	v_lshl_add_u64 v[10:11], v[8:9], 0, v[88:89]
	global_store_dwordx4 v[10:11], v[2:5], off
	s_nop 1
	v_or_b32_e32 v10, s0, v96
	v_lshlrev_b32_e32 v88, 11, v10
	v_cvt_pk_bf16_f32 v2, v196, v197
	v_cvt_pk_bf16_f32 v3, v198, v199
	v_cvt_pk_bf16_f32 v4, v200, v201
	v_cvt_pk_bf16_f32 v5, v202, v203
	v_lshl_add_u64 v[10:11], v[8:9], 0, v[88:89]
	global_store_dwordx4 v[10:11], v[2:5], off
	s_nop 1
	v_or_b32_e32 v10, s0, v97
	v_lshlrev_b32_e32 v88, 11, v10
	s_waitcnt lgkmcnt(7)
	ds_read2_b32 v[188:189], v95 offset0:32 offset1:97
	ds_read2_b32 v[190:191], v95 offset0:162 offset1:227
	ds_read2_b32 v[192:193], v145 offset0:36 offset1:101
	ds_read2_b32 v[194:195], v145 offset0:166 offset1:231
	ds_read2_b32 v[196:197], v95 offset0:40 offset1:105
	ds_read2_b32 v[198:199], v95 offset0:170 offset1:235
	ds_read2_b32 v[200:201], v145 offset0:44 offset1:109
	ds_read2_b32 v[202:203], v145 offset0:174 offset1:239
	s_waitcnt lgkmcnt(8)
	v_cvt_pk_bf16_f32 v2, v204, v205
	v_cvt_pk_bf16_f32 v3, v206, v207
	v_cvt_pk_bf16_f32 v4, v208, v209
	v_cvt_pk_bf16_f32 v5, v210, v211
	v_lshl_add_u64 v[10:11], v[8:9], 0, v[88:89]
	global_store_dwordx4 v[10:11], v[2:5], off
	s_nop 1
	v_or_b32_e32 v10, s0, v98
	v_lshlrev_b32_e32 v88, 11, v10
	v_cvt_pk_bf16_f32 v2, v212, v213
	v_cvt_pk_bf16_f32 v3, v214, v215
	v_cvt_pk_bf16_f32 v4, v216, v217
	v_cvt_pk_bf16_f32 v5, v218, v219
	v_lshl_add_u64 v[10:11], v[8:9], 0, v[88:89]
	global_store_dwordx4 v[10:11], v[2:5], off
	s_nop 1
	v_or_b32_e32 v10, s0, v99
	v_lshlrev_b32_e32 v88, 11, v10
	s_waitcnt lgkmcnt(7)
	ds_read2_b32 v[204:205], v95 offset0:48 offset1:113
	ds_read2_b32 v[206:207], v95 offset0:178 offset1:243
	ds_read2_b32 v[208:209], v145 offset0:52 offset1:117
	ds_read2_b32 v[210:211], v145 offset0:182 offset1:247
	ds_read2_b32 v[212:213], v95 offset0:56 offset1:121
	ds_read2_b32 v[214:215], v95 offset0:186 offset1:251
	ds_read2_b32 v[216:217], v145 offset0:60 offset1:125
	ds_read2_b32 v[218:219], v145 offset0:190 offset1:255
	s_waitcnt lgkmcnt(8)
	v_cvt_pk_bf16_f32 v2, v188, v189
	v_cvt_pk_bf16_f32 v3, v190, v191
	v_cvt_pk_bf16_f32 v4, v192, v193
	v_cvt_pk_bf16_f32 v5, v194, v195
	v_lshl_add_u64 v[10:11], v[8:9], 0, v[88:89]
	global_store_dwordx4 v[10:11], v[2:5], off
	s_nop 1
	v_or_b32_e32 v10, s0, v100
	v_lshlrev_b32_e32 v88, 11, v10
	v_cvt_pk_bf16_f32 v2, v196, v197
	v_cvt_pk_bf16_f32 v3, v198, v199
	v_cvt_pk_bf16_f32 v4, v200, v201
	v_cvt_pk_bf16_f32 v5, v202, v203
	v_lshl_add_u64 v[10:11], v[8:9], 0, v[88:89]
	global_store_dwordx4 v[10:11], v[2:5], off
	s_nop 1
	v_or_b32_e32 v10, s0, v101
	v_lshlrev_b32_e32 v88, 11, v10
	s_waitcnt lgkmcnt(0)
	v_cvt_pk_bf16_f32 v2, v204, v205
	v_cvt_pk_bf16_f32 v3, v206, v207
	v_cvt_pk_bf16_f32 v4, v208, v209
	v_cvt_pk_bf16_f32 v5, v210, v211
	v_lshl_add_u64 v[10:11], v[8:9], 0, v[88:89]
	global_store_dwordx4 v[10:11], v[2:5], off
	s_nop 1
	s_nop 0
	v_cvt_pk_bf16_f32 v2, v212, v213
	v_cvt_pk_bf16_f32 v3, v214, v215
	v_cvt_pk_bf16_f32 v4, v216, v217
	v_or_b32_e32 v5, s0, v102
	v_lshlrev_b32_e32 v88, 11, v5
	v_cvt_pk_bf16_f32 v5, v218, v219
	v_lshl_add_u64 v[6:7], v[8:9], 0, v[88:89]
	global_store_dwordx4 v[6:7], v[2:5], off
	s_nop 1
	s_waitcnt lgkmcnt(0)

.LBB0_1947:
	s_andn2_b64 vcc, exec, s[0:1]
	s_cbranch_vccnz .LBB0_1888
	s_cmpk_gt_i32 s2, 0x2bf
	s_mov_b64 s[0:1], -1
	s_cbranch_scc0 .LBB0_1978
	s_cmpk_gt_u32 s2, 0x57f
	s_cbranch_scc0 .LBB0_1951
	s_and_b32 s0, s23, 0x7fffffc0
	s_addk_i32 s0, 0xea00
	s_and_b32 s10, s3, 0x3c0
	v_or_b32_e32 v88, s0, v66
	s_lshl_b32 s8, s10, 2
	v_or_b32_e32 v4, 4, v88
	v_mov_b32_e32 v5, v89
	s_waitcnt vmcnt(0)
	v_or_b32_e32 v10, 8, v88
	v_mov_b32_e32 v11, v89
	v_or_b32_e32 v12, 12, v88
	v_mov_b32_e32 v13, v89
	v_or_b32_e32 v18, 16, v88
	v_mov_b32_e32 v19, v89
	v_or_b32_e32 v20, 20, v88
	v_mov_b32_e32 v21, v89
	v_or_b32_e32 v26, 24, v88
	v_mov_b32_e32 v27, v89
	v_or_b32_e32 v28, 28, v88
	v_mov_b32_e32 v29, v89
	v_or_b32_e32 v34, 32, v88
	v_mov_b32_e32 v35, v89
	v_or_b32_e32 v36, 36, v88
	v_mov_b32_e32 v37, v89
	v_or_b32_e32 v42, 40, v88
	v_mov_b32_e32 v43, v89
	v_or_b32_e32 v44, 44, v88
	v_mov_b32_e32 v45, v89
	v_or_b32_e32 v50, 48, v88
	v_mov_b32_e32 v51, v89
	v_or_b32_e32 v52, 52, v88
	v_mov_b32_e32 v53, v89
	v_lshl_add_u64 v[62:63], v[82:83], 0, s[8:9]
	v_lshlrev_b64 v[2:3], 12, v[88:89]
	v_lshlrev_b64 v[4:5], 12, v[4:5]
	v_lshlrev_b64 v[10:11], 12, v[10:11]
	v_lshlrev_b64 v[12:13], 12, v[12:13]
	v_lshlrev_b64 v[18:19], 12, v[18:19]
	v_lshlrev_b64 v[20:21], 12, v[20:21]
	v_lshlrev_b64 v[26:27], 12, v[26:27]
	v_lshlrev_b64 v[28:29], 12, v[28:29]
	v_lshlrev_b64 v[34:35], 12, v[34:35]
	v_lshlrev_b64 v[36:37], 12, v[36:37]
	v_lshlrev_b64 v[42:43], 12, v[42:43]
	v_lshlrev_b64 v[44:45], 12, v[44:45]
	v_lshlrev_b64 v[50:51], 12, v[50:51]
	v_lshlrev_b64 v[52:53], 12, v[52:53]
	v_lshl_add_u64 v[2:3], v[62:63], 0, v[2:3]
	v_lshl_add_u64 v[6:7], v[62:63], 0, v[4:5]
	v_lshl_add_u64 v[10:11], v[62:63], 0, v[10:11]
	v_lshl_add_u64 v[14:15], v[62:63], 0, v[12:13]
	v_lshl_add_u64 v[18:19], v[62:63], 0, v[18:19]
	v_lshl_add_u64 v[22:23], v[62:63], 0, v[20:21]
	v_lshl_add_u64 v[26:27], v[62:63], 0, v[26:27]
	v_lshl_add_u64 v[30:31], v[62:63], 0, v[28:29]
	v_lshl_add_u64 v[34:35], v[62:63], 0, v[34:35]
	v_lshl_add_u64 v[38:39], v[62:63], 0, v[36:37]
	v_lshl_add_u64 v[42:43], v[62:63], 0, v[42:43]
	v_lshl_add_u64 v[46:47], v[62:63], 0, v[44:45]
	v_lshl_add_u64 v[50:51], v[62:63], 0, v[50:51]
	v_lshl_add_u64 v[54:55], v[62:63], 0, v[52:53]
	global_load_dwordx4 v[2:5], v[2:3], off nt
	s_nop 0
	global_load_dwordx4 v[6:9], v[6:7], off nt
	s_nop 0
	global_load_dwordx4 v[10:13], v[10:11], off nt
	s_nop 0
	global_load_dwordx4 v[14:17], v[14:15], off nt
	s_nop 0
	global_load_dwordx4 v[18:21], v[18:19], off nt
	s_nop 0
	global_load_dwordx4 v[22:25], v[22:23], off nt
	s_nop 0
	global_load_dwordx4 v[26:29], v[26:27], off nt
	s_nop 0
	global_load_dwordx4 v[30:33], v[30:31], off nt
	s_nop 0
	global_load_dwordx4 v[34:37], v[34:35], off nt
	s_nop 0
	global_load_dwordx4 v[38:41], v[38:39], off nt
	s_nop 0
	global_load_dwordx4 v[42:45], v[42:43], off nt
	s_nop 0
	global_load_dwordx4 v[46:49], v[46:47], off nt
	s_nop 0
	global_load_dwordx4 v[50:53], v[50:51], off nt
	s_nop 0
	global_load_dwordx4 v[54:57], v[54:55], off nt
	v_or_b32_e32 v58, 56, v88
	v_mov_b32_e32 v59, v89
	v_lshlrev_b64 v[58:59], 12, v[58:59]
	v_lshl_add_u64 v[58:59], v[62:63], 0, v[58:59]
	v_or_b32_e32 v88, 60, v88
	global_load_dwordx4 v[58:61], v[58:59], off nt
	v_lshlrev_b64 v[64:65], 12, v[88:89]
	v_lshl_add_u64 v[62:63], v[62:63], 0, v[64:65]
	global_load_dwordx4 v[62:65], v[62:63], off nt
	s_mov_b32 s1, s9
	s_waitcnt vmcnt(15)
	ds_write2_b32 v93, v2, v3 offset1:1
	ds_write2_b32 v93, v4, v5 offset0:2 offset1:3
	s_waitcnt vmcnt(14)
	ds_write2_b32 v115, v6, v7 offset1:1
	ds_write2_b32 v116, v8, v9 offset1:1
	s_waitcnt vmcnt(13)
	ds_write2_b32 v117, v10, v11 offset1:1
	ds_write2_b32 v118, v12, v13 offset1:1
	s_waitcnt vmcnt(12)
	ds_write2_b32 v119, v14, v15 offset1:1
	ds_write2_b32 v120, v16, v17 offset1:1
	s_waitcnt vmcnt(11)
	ds_write2_b32 v121, v18, v19 offset1:1
	ds_write2_b32 v122, v20, v21 offset1:1
	s_waitcnt vmcnt(10)
	ds_write2_b32 v123, v22, v23 offset1:1
	ds_write2_b32 v124, v24, v25 offset1:1
	s_waitcnt vmcnt(9)
	ds_write2_b32 v125, v26, v27 offset1:1
	ds_write2_b32 v126, v28, v29 offset1:1
	s_waitcnt vmcnt(8)
	ds_write2_b32 v127, v30, v31 offset1:1
	ds_write2_b32 v128, v32, v33 offset1:1
	s_waitcnt vmcnt(7)
	ds_write2_b32 v129, v34, v35 offset1:1
	ds_write2_b32 v130, v36, v37 offset1:1
	s_waitcnt vmcnt(6)
	ds_write2_b32 v131, v38, v39 offset1:1
	ds_write2_b32 v132, v40, v41 offset1:1
	s_waitcnt vmcnt(5)
	ds_write2_b32 v133, v42, v43 offset1:1
	ds_write2_b32 v134, v44, v45 offset1:1
	s_waitcnt vmcnt(4)
	ds_write2_b32 v135, v46, v47 offset1:1
	ds_write2_b32 v136, v48, v49 offset1:1
	s_waitcnt vmcnt(3)
	ds_write2_b32 v137, v50, v51 offset1:1
	ds_write2_b32 v138, v52, v53 offset1:1
	s_waitcnt vmcnt(2)
	ds_write2_b32 v139, v54, v55 offset1:1
	ds_write2_b32 v140, v56, v57 offset1:1
	s_waitcnt vmcnt(1)
	ds_write2_b32 v141, v58, v59 offset1:1
	ds_write2_b32 v142, v60, v61 offset1:1
	s_waitcnt vmcnt(0)
	ds_write2_b32 v143, v62, v63 offset1:1
	ds_write2_b32 v144, v64, v65 offset1:1
	s_waitcnt lgkmcnt(0)
	v_or_b32_e32 v10, s10, v94
	ds_read2_b32 v[188:189], v95 offset1:65
	ds_read2_b32 v[190:191], v95 offset0:130 offset1:195
	ds_read2_b32 v[192:193], v145 offset0:4 offset1:69
	ds_read2_b32 v[194:195], v145 offset0:134 offset1:199
	ds_read2_b32 v[196:197], v95 offset0:8 offset1:73
	ds_read2_b32 v[198:199], v95 offset0:138 offset1:203
	ds_read2_b32 v[200:201], v145 offset0:12 offset1:77
	ds_read2_b32 v[202:203], v145 offset0:142 offset1:207
	v_mul_u32_u24_e32 v10, 0xb00, v10
	s_waitcnt lgkmcnt(7)
	ds_read2_b32 v[204:205], v95 offset0:16 offset1:81
	ds_read2_b32 v[206:207], v95 offset0:146 offset1:211
	ds_read2_b32 v[208:209], v145 offset0:20 offset1:85
	ds_read2_b32 v[210:211], v145 offset0:150 offset1:215
	ds_read2_b32 v[212:213], v95 offset0:24 offset1:89
	ds_read2_b32 v[214:215], v95 offset0:154 offset1:219
	ds_read2_b32 v[216:217], v145 offset0:28 offset1:93
	ds_read2_b32 v[218:219], v145 offset0:158 offset1:223
	s_waitcnt lgkmcnt(8)
	v_cvt_pk_bf16_f32 v2, v188, v189
	v_lshl_add_u64 v[8:9], s[0:1], 1, v[72:73]
	v_lshlrev_b32_e32 v88, 1, v10
	v_cvt_pk_bf16_f32 v3, v190, v191
	v_lshl_add_u64 v[10:11], v[8:9], 0, v[88:89]
	v_cvt_pk_bf16_f32 v4, v192, v193
	v_cvt_pk_bf16_f32 v5, v194, v195
	global_store_dwordx4 v[10:11], v[2:5], off
	s_nop 1
	v_or_b32_e32 v10, s10, v96
	v_mul_u32_u24_e32 v10, 0xb00, v10
	v_cvt_pk_bf16_f32 v2, v196, v197
	v_lshlrev_b32_e32 v88, 1, v10
	v_cvt_pk_bf16_f32 v3, v198, v199
	v_lshl_add_u64 v[10:11], v[8:9], 0, v[88:89]
	v_cvt_pk_bf16_f32 v4, v200, v201
	v_cvt_pk_bf16_f32 v5, v202, v203
	global_store_dwordx4 v[10:11], v[2:5], off
	s_nop 1
	v_or_b32_e32 v10, s10, v97
	v_mul_u32_u24_e32 v10, 0xb00, v10
	s_waitcnt lgkmcnt(7)
	ds_read2_b32 v[188:189], v95 offset0:32 offset1:97
	ds_read2_b32 v[190:191], v95 offset0:162 offset1:227
	ds_read2_b32 v[192:193], v145 offset0:36 offset1:101
	ds_read2_b32 v[194:195], v145 offset0:166 offset1:231
	ds_read2_b32 v[196:197], v95 offset0:40 offset1:105
	ds_read2_b32 v[198:199], v95 offset0:170 offset1:235
	ds_read2_b32 v[200:201], v145 offset0:44 offset1:109
	ds_read2_b32 v[202:203], v145 offset0:174 offset1:239
	s_waitcnt lgkmcnt(8)
	v_cvt_pk_bf16_f32 v2, v204, v205
	v_lshlrev_b32_e32 v88, 1, v10
	v_cvt_pk_bf16_f32 v3, v206, v207
	v_lshl_add_u64 v[10:11], v[8:9], 0, v[88:89]
	v_cvt_pk_bf16_f32 v4, v208, v209
	v_cvt_pk_bf16_f32 v5, v210, v211
	global_store_dwordx4 v[10:11], v[2:5], off
	s_nop 1
	v_or_b32_e32 v10, s10, v98
	v_mul_u32_u24_e32 v10, 0xb00, v10
	v_cvt_pk_bf16_f32 v2, v212, v213
	v_lshlrev_b32_e32 v88, 1, v10
	v_cvt_pk_bf16_f32 v3, v214, v215
	v_lshl_add_u64 v[10:11], v[8:9], 0, v[88:89]
	v_cvt_pk_bf16_f32 v4, v216, v217
	v_cvt_pk_bf16_f32 v5, v218, v219
	global_store_dwordx4 v[10:11], v[2:5], off
	s_nop 1
	v_or_b32_e32 v10, s10, v99
	v_mul_u32_u24_e32 v10, 0xb00, v10
	s_waitcnt lgkmcnt(7)
	ds_read2_b32 v[204:205], v95 offset0:48 offset1:113
	ds_read2_b32 v[206:207], v95 offset0:178 offset1:243
	ds_read2_b32 v[208:209], v145 offset0:52 offset1:117
	ds_read2_b32 v[210:211], v145 offset0:182 offset1:247
	ds_read2_b32 v[212:213], v95 offset0:56 offset1:121
	ds_read2_b32 v[214:215], v95 offset0:186 offset1:251
	ds_read2_b32 v[216:217], v145 offset0:60 offset1:125
	ds_read2_b32 v[218:219], v145 offset0:190 offset1:255
	s_waitcnt lgkmcnt(8)
	v_cvt_pk_bf16_f32 v2, v188, v189
	v_lshlrev_b32_e32 v88, 1, v10
	v_cvt_pk_bf16_f32 v3, v190, v191
	v_lshl_add_u64 v[10:11], v[8:9], 0, v[88:89]
	v_cvt_pk_bf16_f32 v4, v192, v193
	v_cvt_pk_bf16_f32 v5, v194, v195
	global_store_dwordx4 v[10:11], v[2:5], off
	s_nop 1
	v_or_b32_e32 v10, s10, v100
	v_mul_u32_u24_e32 v10, 0xb00, v10
	v_cvt_pk_bf16_f32 v2, v196, v197
	v_lshlrev_b32_e32 v88, 1, v10
	v_cvt_pk_bf16_f32 v3, v198, v199
	v_lshl_add_u64 v[10:11], v[8:9], 0, v[88:89]
	v_cvt_pk_bf16_f32 v4, v200, v201
	v_cvt_pk_bf16_f32 v5, v202, v203
	global_store_dwordx4 v[10:11], v[2:5], off
	s_nop 1
	v_or_b32_e32 v10, s10, v101
	s_waitcnt lgkmcnt(0)
	v_cvt_pk_bf16_f32 v2, v204, v205
	v_mul_u32_u24_e32 v10, 0xb00, v10
	v_cvt_pk_bf16_f32 v3, v206, v207
	v_lshlrev_b32_e32 v88, 1, v10
	v_cvt_pk_bf16_f32 v4, v208, v209
	v_cvt_pk_bf16_f32 v5, v210, v211
	v_lshl_add_u64 v[10:11], v[8:9], 0, v[88:89]
	global_store_dwordx4 v[10:11], v[2:5], off
	s_nop 1
	s_mov_b64 s[0:1], 0
	v_cvt_pk_bf16_f32 v2, v212, v213
	v_cvt_pk_bf16_f32 v3, v214, v215
	v_cvt_pk_bf16_f32 v4, v216, v217
	v_or_b32_e32 v5, s10, v102
	v_mul_u32_u24_e32 v5, 0xb00, v5
	v_lshlrev_b32_e32 v88, 1, v5
	v_cvt_pk_bf16_f32 v5, v218, v219
	v_lshl_add_u64 v[6:7], v[8:9], 0, v[88:89]
	global_store_dwordx4 v[6:7], v[2:5], off
	s_nop 1
	s_waitcnt lgkmcnt(0)

.LBB0_1976:
	s_waitcnt vmcnt(0)
	v_pk_mul_f32 v[2:3], v[2:3], v[10:11] op_sel_hi:[1,0]
	v_add_u32_e32 v6, 0xc30, v11
	s_lshl_b32 s0, s15, 6
	ds_write2_b32 v6, v2, v3 offset1:1
	v_pk_mul_f32 v[2:3], v[4:5], v[10:11] op_sel_hi:[1,0]
	v_add_u32_e32 v4, 0xc38, v11
	s_and_b32 s0, 0xffff, s0
	ds_write2_b32 v4, v2, v3 offset1:1
	s_lshl_b32 s1, s0, 1
	s_waitcnt lgkmcnt(0)
	s_and_b32 s0, s0, 64
	s_and_b32 s1, s1, 0x1f00
	s_or_b32 s0, s0, s1
	ds_read2_b32 v[188:189], v95 offset1:65
	ds_read2_b32 v[190:191], v95 offset0:130 offset1:195
	ds_read2_b32 v[192:193], v145 offset0:4 offset1:69
	ds_read2_b32 v[194:195], v145 offset0:134 offset1:199
	ds_read2_b32 v[196:197], v95 offset0:8 offset1:73
	ds_read2_b32 v[198:199], v95 offset0:138 offset1:203
	ds_read2_b32 v[200:201], v145 offset0:12 offset1:77
	ds_read2_b32 v[202:203], v145 offset0:142 offset1:207
	s_bitset1_b32 s0, 7
	s_waitcnt lgkmcnt(7)
	ds_read2_b32 v[204:205], v95 offset0:16 offset1:81
	ds_read2_b32 v[206:207], v95 offset0:146 offset1:211
	ds_read2_b32 v[208:209], v145 offset0:20 offset1:85
	ds_read2_b32 v[210:211], v145 offset0:150 offset1:215
	ds_read2_b32 v[212:213], v95 offset0:24 offset1:89
	ds_read2_b32 v[214:215], v95 offset0:154 offset1:219
	ds_read2_b32 v[216:217], v145 offset0:28 offset1:93
	ds_read2_b32 v[218:219], v145 offset0:158 offset1:223
	s_waitcnt lgkmcnt(8)
	v_cvt_pk_bf16_f32 v2, v188, v189
	s_lshl_b32 s8, s14, 1
	v_or_b32_e32 v10, s0, v94
	v_cvt_pk_bf16_f32 v3, v190, v191
	v_lshl_add_u64 v[6:7], v[74:75], 0, s[8:9]
	v_lshlrev_b32_e32 v88, 11, v10
	v_cvt_pk_bf16_f32 v4, v192, v193
	v_cvt_pk_bf16_f32 v5, v194, v195
	v_lshl_add_u64 v[10:11], v[6:7], 0, v[88:89]
	global_store_dwordx4 v[10:11], v[2:5], off
	s_nop 1
	v_or_b32_e32 v10, s0, v96
	v_lshlrev_b32_e32 v88, 11, v10
	v_cvt_pk_bf16_f32 v2, v196, v197
	v_cvt_pk_bf16_f32 v3, v198, v199
	v_cvt_pk_bf16_f32 v4, v200, v201
	v_cvt_pk_bf16_f32 v5, v202, v203
	v_lshl_add_u64 v[10:11], v[6:7], 0, v[88:89]
	global_store_dwordx4 v[10:11], v[2:5], off
	s_nop 1
	v_or_b32_e32 v10, s0, v97
	v_lshlrev_b32_e32 v88, 11, v10
	s_waitcnt lgkmcnt(7)
	ds_read2_b32 v[188:189], v95 offset0:32 offset1:97
	ds_read2_b32 v[190:191], v95 offset0:162 offset1:227
	ds_read2_b32 v[192:193], v145 offset0:36 offset1:101
	ds_read2_b32 v[194:195], v145 offset0:166 offset1:231
	ds_read2_b32 v[196:197], v95 offset0:40 offset1:105
	ds_read2_b32 v[198:199], v95 offset0:170 offset1:235
	ds_read2_b32 v[200:201], v145 offset0:44 offset1:109
	ds_read2_b32 v[202:203], v145 offset0:174 offset1:239
	s_waitcnt lgkmcnt(8)
	v_cvt_pk_bf16_f32 v2, v204, v205
	v_cvt_pk_bf16_f32 v3, v206, v207
	v_cvt_pk_bf16_f32 v4, v208, v209
	v_cvt_pk_bf16_f32 v5, v210, v211
	v_lshl_add_u64 v[10:11], v[6:7], 0, v[88:89]
	global_store_dwordx4 v[10:11], v[2:5], off
	s_nop 1
	v_or_b32_e32 v10, s0, v98
	v_lshlrev_b32_e32 v88, 11, v10
	v_cvt_pk_bf16_f32 v2, v212, v213
	v_cvt_pk_bf16_f32 v3, v214, v215
	v_cvt_pk_bf16_f32 v4, v216, v217
	v_cvt_pk_bf16_f32 v5, v218, v219
	v_lshl_add_u64 v[10:11], v[6:7], 0, v[88:89]
	global_store_dwordx4 v[10:11], v[2:5], off
	s_nop 1
	v_or_b32_e32 v10, s0, v99
	v_lshlrev_b32_e32 v88, 11, v10
	s_waitcnt lgkmcnt(7)
	ds_read2_b32 v[204:205], v95 offset0:48 offset1:113
	ds_read2_b32 v[206:207], v95 offset0:178 offset1:243
	ds_read2_b32 v[208:209], v145 offset0:52 offset1:117
	ds_read2_b32 v[210:211], v145 offset0:182 offset1:247
	ds_read2_b32 v[212:213], v95 offset0:56 offset1:121
	ds_read2_b32 v[214:215], v95 offset0:186 offset1:251
	ds_read2_b32 v[216:217], v145 offset0:60 offset1:125
	ds_read2_b32 v[218:219], v145 offset0:190 offset1:255
	s_waitcnt lgkmcnt(8)
	v_cvt_pk_bf16_f32 v2, v188, v189
	v_cvt_pk_bf16_f32 v3, v190, v191
	v_cvt_pk_bf16_f32 v4, v192, v193
	v_cvt_pk_bf16_f32 v5, v194, v195
	v_lshl_add_u64 v[10:11], v[6:7], 0, v[88:89]
	global_store_dwordx4 v[10:11], v[2:5], off
	s_nop 1
	v_or_b32_e32 v10, s0, v100
	v_lshlrev_b32_e32 v88, 11, v10
	v_cvt_pk_bf16_f32 v2, v196, v197
	v_cvt_pk_bf16_f32 v3, v198, v199
	v_cvt_pk_bf16_f32 v4, v200, v201
	v_cvt_pk_bf16_f32 v5, v202, v203
	v_lshl_add_u64 v[10:11], v[6:7], 0, v[88:89]
	global_store_dwordx4 v[10:11], v[2:5], off
	s_nop 1
	v_or_b32_e32 v10, s0, v101
	v_lshlrev_b32_e32 v88, 11, v10
	s_waitcnt lgkmcnt(0)
	v_cvt_pk_bf16_f32 v2, v204, v205
	v_cvt_pk_bf16_f32 v3, v206, v207
	v_cvt_pk_bf16_f32 v4, v208, v209
	v_cvt_pk_bf16_f32 v5, v210, v211
	v_lshl_add_u64 v[10:11], v[6:7], 0, v[88:89]
	global_store_dwordx4 v[10:11], v[2:5], off
	s_nop 1
	s_nop 0
	v_cvt_pk_bf16_f32 v2, v212, v213
	v_cvt_pk_bf16_f32 v3, v214, v215
	v_cvt_pk_bf16_f32 v4, v216, v217
	v_or_b32_e32 v5, s0, v102
	v_lshlrev_b32_e32 v88, 11, v5
	v_lshl_add_u64 v[6:7], v[6:7], 0, v[88:89]
	v_cvt_pk_bf16_f32 v5, v218, v219
	global_store_dwordx4 v[6:7], v[2:5], off
	s_nop 1
	s_waitcnt lgkmcnt(0)
